# residual-GEMM epilogues: the last unit of a workgroup stores write-through (sc1) so the following grid barrier's L2 write-back is cheap
# baseline (speedup 1.0000x reference)
;     __device__ __forceinline__ void operator()(const f32x4 (&acc)[2][2][4][2], const Unit& u, int wr, int wc, int fr, int fq) const {
;         const int cond = u.pm < 64 ? 0 : (u.pm < 128 ? 1 : 2);
;         const float* gate = gate_l + cond * 9216;
;         const int col0 = u.pn * BM + wc * 32 + 4 * fq;
;         f32x4 gv[2][2];
; #pragma unroll
;         for (int bj = 0; bj < 2; ++bj)
; #pragma unroll
;             for (int n = 0; n < 2; ++n) gv[bj][n] = *(const f32x4*)(gate + col0 + bj * HALF + n * 16) * coef;
; #pragma unroll
;         for (int ai = 0; ai < 2; ++ai)
; #pragma unroll
;             for (int m = 0; m < 4; ++m) {
;                 const int row = u.pm * BM + ai * HALF + wr * 64 + m * 16 + fr;
;                 const float* s = row < MX_ ? src_main + (size_t)row * D_ : src_ctx + (size_t)(row - MX_) * D_;
;                 float* d = row < MX_ ? dst_main + (size_t)row * D_ : dst_ctx + (size_t)(row - MX_) * D_;
; #pragma unroll
;                 for (int bj = 0; bj < 2; ++bj)
; #pragma unroll
;                     for (int n = 0; n < 2; ++n) { const int off = col0 + bj * HALF + n * 16; const f32x4 xo = *(const f32x4*)(s + off); *(f32x4*)(d + off) = xo + gv[bj][n] * acc[ai][bj][m][n]; }
; __device__ __forceinline__ void modpass(const float* xs_main, const float* xs_ctx, const float* mod_l, const float* g, int i, bf16_t* H, int nrows, int gw, int NGW, int lane) {
;     ...
;         float ss = 0.f;
; #pragma unroll
;         for (int j = 0; j < 2; ++j)
; #pragma unroll
;             for (int q = 0; q < 2; ++q) ss += (v[j][q][0] * v[j][q][0] + v[j][q][1] * v[j][q][1]) + (v[j][q][2] * v[j][q][2] + v[j][q][3] * v[j][q][3]);
.LBB0_315:
	s_and_b64 vcc, exec, s[4:5]
	s_cbranch_vccnz .Lfmsel_a
	s_cmpk_lt_i32 s65, 0x80
	s_cselect_b32 s16, s62, 0x4800
	s_cmp_gt_i32 s65, 63
	s_cselect_b32 s16, s16, 0
	s_lshl_b32 s16, s16, 2
	s_add_u32 s26, s53, s16
	s_addc_u32 s27, s54, 0
	s_load_dwordx2 s[92:93], s[0:1], 0x30
	s_load_dwordx2 s[76:77], s[0:1], 0xb8
	v_lshl_add_u32 v144, s65, 8, v146
	v_lshl_or_b32 v145, s66, 8, v148
	v_lshlrev_b32_e32 v184, 2, v145
	v_lshl_add_u32 v207, v144, 12, v184
	global_load_dwordx4 v[198:201], v184, s[26:27]
	global_load_dwordx4 v[202:205], v184, s[26:27] offset:64
	global_load_dwordx4 v[208:211], v184, s[26:27] offset:512
	global_load_dwordx4 v[214:217], v184, s[26:27] offset:576
	v_add_u32_e32 v213, 0x10000, v207
	v_add_u32_e32 v218, 0x20000, v207
	v_add_u32_e32 v219, 0x30000, v207
	v_add_u32_e32 v250, 0x80000, v207
	v_add_u32_e32 v251, 0x90000, v207
	v_add_u32_e32 v222, 0xa0000, v207
	v_add_u32_e32 v223, 0xb0000, v207
	global_load_dwordx4 v[140:143], v207, s[8:9]
	global_load_dwordx4 v[152:155], v207, s[8:9] offset:64
	global_load_dwordx4 v[156:159], v207, s[8:9] offset:512
	global_load_dwordx4 v[160:163], v207, s[8:9] offset:576
	global_load_dwordx4 v[164:167], v213, s[8:9]
	global_load_dwordx4 v[168:171], v213, s[8:9] offset:64
	global_load_dwordx4 v[172:175], v213, s[8:9] offset:512
	global_load_dwordx4 v[176:179], v213, s[8:9] offset:576
	global_load_dwordx4 v[180:183], v218, s[8:9]
	global_load_dwordx4 v[186:189], v218, s[8:9] offset:64
	global_load_dwordx4 v[190:193], v218, s[8:9] offset:512
	global_load_dwordx4 v[194:197], v218, s[8:9] offset:576
	s_waitcnt vmcnt(12)
	v_pk_mul_f32 v[198:199], v[198:199], 0.5 op_sel_hi:[1,0]
	v_pk_mul_f32 v[200:201], v[200:201], 0.5 op_sel_hi:[1,0]
	v_pk_mul_f32 v[202:203], v[202:203], 0.5 op_sel_hi:[1,0]
	v_pk_mul_f32 v[204:205], v[204:205], 0.5 op_sel_hi:[1,0]
	v_pk_mul_f32 v[208:209], v[208:209], 0.5 op_sel_hi:[1,0]
	v_pk_mul_f32 v[210:211], v[210:211], 0.5 op_sel_hi:[1,0]
	v_pk_mul_f32 v[214:215], v[214:215], 0.5 op_sel_hi:[1,0]
	v_pk_mul_f32 v[216:217], v[216:217], 0.5 op_sel_hi:[1,0]
	s_waitcnt vmcnt(11)
	v_pk_fma_f32 v[124:125], v[124:125], v[198:199], v[140:141]
	v_pk_fma_f32 v[126:127], v[126:127], v[200:201], v[142:143]
	v_mul_f32_e32 v224, v124, v124
	v_fmac_f32_e32 v224, v125, v125
	v_fmac_f32_e32 v224, v126, v126
	v_fmac_f32_e32 v224, v127, v127
	s_waitcnt vmcnt(10)
	v_pk_fma_f32 v[120:121], v[120:121], v[202:203], v[152:153]
	v_pk_fma_f32 v[122:123], v[122:123], v[204:205], v[154:155]
	v_fmac_f32_e32 v224, v120, v120
	v_fmac_f32_e32 v224, v121, v121
	v_fmac_f32_e32 v224, v122, v122
	v_fmac_f32_e32 v224, v123, v123
	s_waitcnt vmcnt(9)
	v_pk_fma_f32 v[116:117], v[116:117], v[208:209], v[156:157]
	v_pk_fma_f32 v[118:119], v[118:119], v[210:211], v[158:159]
	v_fmac_f32_e32 v224, v116, v116
	v_fmac_f32_e32 v224, v117, v117
	v_fmac_f32_e32 v224, v118, v118
	v_fmac_f32_e32 v224, v119, v119
	s_waitcnt vmcnt(8)
	v_pk_fma_f32 v[108:109], v[108:109], v[214:215], v[160:161]
	v_pk_fma_f32 v[110:111], v[110:111], v[216:217], v[162:163]
	v_fmac_f32_e32 v224, v108, v108
	v_fmac_f32_e32 v224, v109, v109
	v_fmac_f32_e32 v224, v110, v110
	v_fmac_f32_e32 v224, v111, v111
	global_store_dwordx4 v207, v[124:127], s[10:11]
	global_store_dwordx4 v207, v[120:123], s[10:11] offset:64
	global_store_dwordx4 v207, v[116:119], s[10:11] offset:512
	global_store_dwordx4 v207, v[108:111], s[10:11] offset:576
	global_load_dwordx4 v[140:143], v219, s[8:9]
	global_load_dwordx4 v[152:155], v219, s[8:9] offset:64
	global_load_dwordx4 v[156:159], v219, s[8:9] offset:512
	global_load_dwordx4 v[160:163], v219, s[8:9] offset:576
	s_waitcnt vmcnt(15)
	v_pk_fma_f32 v[112:113], v[112:113], v[198:199], v[164:165]
	v_pk_fma_f32 v[114:115], v[114:115], v[200:201], v[166:167]
	v_mul_f32_e32 v225, v112, v112
	v_fmac_f32_e32 v225, v113, v113
	v_fmac_f32_e32 v225, v114, v114
	v_fmac_f32_e32 v225, v115, v115
	s_waitcnt vmcnt(14)
	v_pk_fma_f32 v[104:105], v[104:105], v[202:203], v[168:169]
	v_pk_fma_f32 v[106:107], v[106:107], v[204:205], v[170:171]
	v_fmac_f32_e32 v225, v104, v104
	v_fmac_f32_e32 v225, v105, v105
	v_fmac_f32_e32 v225, v106, v106
	v_fmac_f32_e32 v225, v107, v107
	s_waitcnt vmcnt(13)
	v_pk_fma_f32 v[100:101], v[100:101], v[208:209], v[172:173]
	v_pk_fma_f32 v[102:103], v[102:103], v[210:211], v[174:175]
	v_fmac_f32_e32 v225, v100, v100
	v_fmac_f32_e32 v225, v101, v101
	v_fmac_f32_e32 v225, v102, v102
	v_fmac_f32_e32 v225, v103, v103
	s_waitcnt vmcnt(12)
	v_pk_fma_f32 v[92:93], v[92:93], v[214:215], v[176:177]
	v_pk_fma_f32 v[94:95], v[94:95], v[216:217], v[178:179]
	v_fmac_f32_e32 v225, v92, v92
	v_fmac_f32_e32 v225, v93, v93
	v_fmac_f32_e32 v225, v94, v94
	v_fmac_f32_e32 v225, v95, v95
	global_store_dwordx4 v213, v[112:115], s[10:11]
	global_store_dwordx4 v213, v[104:107], s[10:11] offset:64
	global_store_dwordx4 v213, v[100:103], s[10:11] offset:512
	global_store_dwordx4 v213, v[92:95], s[10:11] offset:576
	global_load_dwordx4 v[164:167], v250, s[8:9]
	global_load_dwordx4 v[168:171], v250, s[8:9] offset:64
	global_load_dwordx4 v[172:175], v250, s[8:9] offset:512
	global_load_dwordx4 v[176:179], v250, s[8:9] offset:576
	s_waitcnt vmcnt(19)
	v_pk_fma_f32 v[96:97], v[96:97], v[198:199], v[180:181]
	v_pk_fma_f32 v[98:99], v[98:99], v[200:201], v[182:183]
	v_mul_f32_e32 v226, v96, v96
	v_fmac_f32_e32 v226, v97, v97
	v_fmac_f32_e32 v226, v98, v98
	v_fmac_f32_e32 v226, v99, v99
	s_waitcnt vmcnt(18)
	v_pk_fma_f32 v[88:89], v[88:89], v[202:203], v[186:187]
	v_pk_fma_f32 v[90:91], v[90:91], v[204:205], v[188:189]
	v_fmac_f32_e32 v226, v88, v88
	v_fmac_f32_e32 v226, v89, v89
	v_fmac_f32_e32 v226, v90, v90
	v_fmac_f32_e32 v226, v91, v91
	s_waitcnt vmcnt(17)
;     __device__ __forceinline__ void operator()(const f32x4 (&acc)[2][2][4][2], const Unit& u, int wr, int wc, int fr, int fq) const {
;     ...
;         for (int ai = 0; ai < 2; ++ai)
; #pragma unroll
;             for (int m = 0; m < 4; ++m) {
;                 const int row = u.pm * BM + ai * HALF + wr * 64 + m * 16 + fr;
;                 const float* s = row < MX_ ? src_main + (size_t)row * D_ : src_ctx + (size_t)(row - MX_) * D_;
;                 float* d = row < MX_ ? dst_main + (size_t)row * D_ : dst_ctx + (size_t)(row - MX_) * D_;
; #pragma unroll
;                 for (int bj = 0; bj < 2; ++bj)
; #pragma unroll
;                     for (int n = 0; n < 2; ++n) { const int off = col0 + bj * HALF + n * 16; const f32x4 xo = *(const f32x4*)(s + off); *(f32x4*)(d + off) = xo + gv[bj][n] * acc[ai][bj][m][n]; }
; __device__ __forceinline__ void modpass(const float* xs_main, const float* xs_ctx, const float* mod_l, const float* g, int i, bf16_t* H, int nrows, int gw, int NGW, int lane) {
;     ...
;         float ss = 0.f;
; #pragma unroll
;         for (int j = 0; j < 2; ++j)
; #pragma unroll
;             for (int q = 0; q < 2; ++q) ss += (v[j][q][0] * v[j][q][0] + v[j][q][1] * v[j][q][1]) + (v[j][q][2] * v[j][q][2] + v[j][q][3] * v[j][q][3]);
	v_pk_fma_f32 v[84:85], v[84:85], v[208:209], v[190:191]
	v_pk_fma_f32 v[86:87], v[86:87], v[210:211], v[192:193]
	v_fmac_f32_e32 v226, v84, v84
	v_fmac_f32_e32 v226, v85, v85
	v_fmac_f32_e32 v226, v86, v86
	v_fmac_f32_e32 v226, v87, v87
	s_waitcnt vmcnt(16)
	v_pk_fma_f32 v[76:77], v[76:77], v[214:215], v[194:195]
	v_pk_fma_f32 v[78:79], v[78:79], v[216:217], v[196:197]
	v_fmac_f32_e32 v226, v76, v76
	v_fmac_f32_e32 v226, v77, v77
	v_fmac_f32_e32 v226, v78, v78
	v_fmac_f32_e32 v226, v79, v79
	global_store_dwordx4 v218, v[96:99], s[10:11]
	global_store_dwordx4 v218, v[88:91], s[10:11] offset:64
	global_store_dwordx4 v218, v[84:87], s[10:11] offset:512
	global_store_dwordx4 v218, v[76:79], s[10:11] offset:576
	global_load_dwordx4 v[180:183], v251, s[8:9]
	global_load_dwordx4 v[186:189], v251, s[8:9] offset:64
	global_load_dwordx4 v[190:193], v251, s[8:9] offset:512
	global_load_dwordx4 v[194:197], v251, s[8:9] offset:576
	s_waitcnt vmcnt(19)
	v_pk_fma_f32 v[80:81], v[80:81], v[198:199], v[140:141]
	v_pk_fma_f32 v[82:83], v[82:83], v[200:201], v[142:143]
	v_mul_f32_e32 v227, v80, v80
	v_fmac_f32_e32 v227, v81, v81
	v_fmac_f32_e32 v227, v82, v82
	v_fmac_f32_e32 v227, v83, v83
	s_waitcnt vmcnt(18)
	v_pk_fma_f32 v[72:73], v[72:73], v[202:203], v[152:153]
	v_pk_fma_f32 v[74:75], v[74:75], v[204:205], v[154:155]
	v_fmac_f32_e32 v227, v72, v72
	v_fmac_f32_e32 v227, v73, v73
	v_fmac_f32_e32 v227, v74, v74
	v_fmac_f32_e32 v227, v75, v75
	s_waitcnt vmcnt(17)
	v_pk_fma_f32 v[68:69], v[68:69], v[208:209], v[156:157]
	v_pk_fma_f32 v[70:71], v[70:71], v[210:211], v[158:159]
	v_fmac_f32_e32 v227, v68, v68
	v_fmac_f32_e32 v227, v69, v69
	v_fmac_f32_e32 v227, v70, v70
	v_fmac_f32_e32 v227, v71, v71
	s_waitcnt vmcnt(16)
	v_pk_fma_f32 v[64:65], v[64:65], v[214:215], v[160:161]
	v_pk_fma_f32 v[66:67], v[66:67], v[216:217], v[162:163]
	v_fmac_f32_e32 v227, v64, v64
	v_fmac_f32_e32 v227, v65, v65
	v_fmac_f32_e32 v227, v66, v66
	v_fmac_f32_e32 v227, v67, v67
	global_store_dwordx4 v219, v[80:83], s[10:11]
	global_store_dwordx4 v219, v[72:75], s[10:11] offset:64
	global_store_dwordx4 v219, v[68:71], s[10:11] offset:512
	global_store_dwordx4 v219, v[64:67], s[10:11] offset:576
	global_load_dwordx4 v[140:143], v222, s[8:9]
	global_load_dwordx4 v[152:155], v222, s[8:9] offset:64
	global_load_dwordx4 v[156:159], v222, s[8:9] offset:512
	global_load_dwordx4 v[160:163], v222, s[8:9] offset:576
	s_waitcnt vmcnt(19)
	v_pk_fma_f32 v[60:61], v[60:61], v[198:199], v[164:165]
	v_pk_fma_f32 v[62:63], v[62:63], v[200:201], v[166:167]
	v_mul_f32_e32 v228, v60, v60
	v_fmac_f32_e32 v228, v61, v61
	v_fmac_f32_e32 v228, v62, v62
	v_fmac_f32_e32 v228, v63, v63
	s_waitcnt vmcnt(18)
	v_pk_fma_f32 v[56:57], v[56:57], v[202:203], v[168:169]
	v_pk_fma_f32 v[58:59], v[58:59], v[204:205], v[170:171]
	v_fmac_f32_e32 v228, v56, v56
	v_fmac_f32_e32 v228, v57, v57
	v_fmac_f32_e32 v228, v58, v58
	v_fmac_f32_e32 v228, v59, v59
	s_waitcnt vmcnt(17)
	v_pk_fma_f32 v[52:53], v[52:53], v[208:209], v[172:173]
	v_pk_fma_f32 v[54:55], v[54:55], v[210:211], v[174:175]
	v_fmac_f32_e32 v228, v52, v52
	v_fmac_f32_e32 v228, v53, v53
	v_fmac_f32_e32 v228, v54, v54
	v_fmac_f32_e32 v228, v55, v55
	s_waitcnt vmcnt(16)
	v_pk_fma_f32 v[44:45], v[44:45], v[214:215], v[176:177]
	v_pk_fma_f32 v[46:47], v[46:47], v[216:217], v[178:179]
	v_fmac_f32_e32 v228, v44, v44
	v_fmac_f32_e32 v228, v45, v45
	v_fmac_f32_e32 v228, v46, v46
	v_fmac_f32_e32 v228, v47, v47
	global_store_dwordx4 v250, v[60:63], s[10:11]
	global_store_dwordx4 v250, v[56:59], s[10:11] offset:64
	global_store_dwordx4 v250, v[52:55], s[10:11] offset:512
	global_store_dwordx4 v250, v[44:47], s[10:11] offset:576
	global_load_dwordx4 v[164:167], v223, s[8:9]
	global_load_dwordx4 v[168:171], v223, s[8:9] offset:64
	global_load_dwordx4 v[172:175], v223, s[8:9] offset:512
	global_load_dwordx4 v[176:179], v223, s[8:9] offset:576
	s_waitcnt vmcnt(19)
	v_pk_fma_f32 v[48:49], v[48:49], v[198:199], v[180:181]
	v_pk_fma_f32 v[50:51], v[50:51], v[200:201], v[182:183]
	v_mul_f32_e32 v229, v48, v48
	v_fmac_f32_e32 v229, v49, v49
	v_fmac_f32_e32 v229, v50, v50
	v_fmac_f32_e32 v229, v51, v51
	s_waitcnt vmcnt(18)
	v_pk_fma_f32 v[40:41], v[40:41], v[202:203], v[186:187]
	v_pk_fma_f32 v[42:43], v[42:43], v[204:205], v[188:189]
	v_fmac_f32_e32 v229, v40, v40
	v_fmac_f32_e32 v229, v41, v41
	v_fmac_f32_e32 v229, v42, v42
	v_fmac_f32_e32 v229, v43, v43
	s_waitcnt vmcnt(17)
	v_pk_fma_f32 v[36:37], v[36:37], v[208:209], v[190:191]
	v_pk_fma_f32 v[38:39], v[38:39], v[210:211], v[192:193]
	v_fmac_f32_e32 v229, v36, v36
	v_fmac_f32_e32 v229, v37, v37
	v_fmac_f32_e32 v229, v38, v38
	v_fmac_f32_e32 v229, v39, v39
	s_waitcnt vmcnt(16)
	v_pk_fma_f32 v[28:29], v[28:29], v[214:215], v[194:195]
	v_pk_fma_f32 v[30:31], v[30:31], v[216:217], v[196:197]
	v_fmac_f32_e32 v229, v28, v28
	v_fmac_f32_e32 v229, v29, v29
	v_fmac_f32_e32 v229, v30, v30
	v_fmac_f32_e32 v229, v31, v31
	global_store_dwordx4 v251, v[48:51], s[10:11]
	global_store_dwordx4 v251, v[40:43], s[10:11] offset:64
	global_store_dwordx4 v251, v[36:39], s[10:11] offset:512
	global_store_dwordx4 v251, v[28:31], s[10:11] offset:576
	s_waitcnt vmcnt(15)
;     __device__ __forceinline__ void operator()(const f32x4 (&acc)[2][2][4][2], const Unit& u, int wr, int wc, int fr, int fq) const {
;     ...
;         for (int ai = 0; ai < 2; ++ai)
; #pragma unroll
;             for (int m = 0; m < 4; ++m) {
;                 const int row = u.pm * BM + ai * HALF + wr * 64 + m * 16 + fr;
;                 const float* s = row < MX_ ? src_main + (size_t)row * D_ : src_ctx + (size_t)(row - MX_) * D_;
;                 float* d = row < MX_ ? dst_main + (size_t)row * D_ : dst_ctx + (size_t)(row - MX_) * D_;
; #pragma unroll
;                 for (int bj = 0; bj < 2; ++bj)
; #pragma unroll
;                     for (int n = 0; n < 2; ++n) { const int off = col0 + bj * HALF + n * 16; const f32x4 xo = *(const f32x4*)(s + off); *(f32x4*)(d + off) = xo + gv[bj][n] * acc[ai][bj][m][n]; }
; __device__ __forceinline__ void modpass(const float* xs_main, const float* xs_ctx, const float* mod_l, const float* g, int i, bf16_t* H, int nrows, int gw, int NGW, int lane) {
;     ...
;         const float rstd = 1.0f / sqrtf(wave_sum(ss) * (1.0f / D) + EPS);
	v_pk_fma_f32 v[32:33], v[32:33], v[198:199], v[140:141]
	v_pk_fma_f32 v[34:35], v[34:35], v[200:201], v[142:143]
	v_mul_f32_e32 v230, v32, v32
	v_fmac_f32_e32 v230, v33, v33
	v_fmac_f32_e32 v230, v34, v34
	v_fmac_f32_e32 v230, v35, v35
	s_waitcnt vmcnt(14)
	v_pk_fma_f32 v[24:25], v[24:25], v[202:203], v[152:153]
	v_pk_fma_f32 v[26:27], v[26:27], v[204:205], v[154:155]
	v_fmac_f32_e32 v230, v24, v24
	v_fmac_f32_e32 v230, v25, v25
	v_fmac_f32_e32 v230, v26, v26
	v_fmac_f32_e32 v230, v27, v27
	s_waitcnt vmcnt(13)
	v_pk_fma_f32 v[20:21], v[20:21], v[208:209], v[156:157]
	v_pk_fma_f32 v[22:23], v[22:23], v[210:211], v[158:159]
	v_fmac_f32_e32 v230, v20, v20
	v_fmac_f32_e32 v230, v21, v21
	v_fmac_f32_e32 v230, v22, v22
	v_fmac_f32_e32 v230, v23, v23
	s_waitcnt vmcnt(12)
	v_pk_fma_f32 v[12:13], v[12:13], v[214:215], v[160:161]
	v_pk_fma_f32 v[14:15], v[14:15], v[216:217], v[162:163]
	v_fmac_f32_e32 v230, v12, v12
	v_fmac_f32_e32 v230, v13, v13
	v_fmac_f32_e32 v230, v14, v14
	v_fmac_f32_e32 v230, v15, v15
	global_store_dwordx4 v222, v[32:35], s[10:11]
	global_store_dwordx4 v222, v[24:27], s[10:11] offset:64
	global_store_dwordx4 v222, v[20:23], s[10:11] offset:512
	global_store_dwordx4 v222, v[12:15], s[10:11] offset:576
	s_waitcnt vmcnt(11)
	v_pk_fma_f32 v[16:17], v[16:17], v[198:199], v[164:165]
	v_pk_fma_f32 v[18:19], v[18:19], v[200:201], v[166:167]
	v_mul_f32_e32 v231, v16, v16
	v_fmac_f32_e32 v231, v17, v17
	v_fmac_f32_e32 v231, v18, v18
	v_fmac_f32_e32 v231, v19, v19
	s_waitcnt vmcnt(10)
	v_pk_fma_f32 v[8:9], v[8:9], v[202:203], v[168:169]
	v_pk_fma_f32 v[10:11], v[10:11], v[204:205], v[170:171]
	v_fmac_f32_e32 v231, v8, v8
	v_fmac_f32_e32 v231, v9, v9
	v_fmac_f32_e32 v231, v10, v10
	v_fmac_f32_e32 v231, v11, v11
	s_waitcnt vmcnt(9)
	v_pk_fma_f32 v[4:5], v[4:5], v[208:209], v[172:173]
	v_pk_fma_f32 v[6:7], v[6:7], v[210:211], v[174:175]
	v_fmac_f32_e32 v231, v4, v4
	v_fmac_f32_e32 v231, v5, v5
	v_fmac_f32_e32 v231, v6, v6
	v_fmac_f32_e32 v231, v7, v7
	s_waitcnt vmcnt(8)
	v_pk_fma_f32 v[0:1], v[0:1], v[214:215], v[176:177]
	v_pk_fma_f32 v[2:3], v[2:3], v[216:217], v[178:179]
	v_fmac_f32_e32 v231, v0, v0
	v_fmac_f32_e32 v231, v1, v1
	v_fmac_f32_e32 v231, v2, v2
	v_fmac_f32_e32 v231, v3, v3
	global_store_dwordx4 v223, v[16:19], s[10:11]
	global_store_dwordx4 v223, v[8:11], s[10:11] offset:64
	global_store_dwordx4 v223, v[4:7], s[10:11] offset:512
	global_store_dwordx4 v223, v[0:3], s[10:11] offset:576
	v_mbcnt_lo_u32_b32 v232, -1, 0
	v_mbcnt_hi_u32_b32 v232, -1, v232
	v_xor_b32_e32 v233, 16, v232
	v_xor_b32_e32 v234, 32, v232
	v_lshlrev_b32_e32 v233, 2, v233
	v_lshlrev_b32_e32 v234, 2, v234
	s_waitcnt lgkmcnt(0)
	ds_bpermute_b32 v140, v233, v224
	ds_bpermute_b32 v141, v233, v225
	ds_bpermute_b32 v142, v233, v226
	ds_bpermute_b32 v143, v233, v227
	ds_bpermute_b32 v152, v233, v228
	ds_bpermute_b32 v153, v233, v229
	ds_bpermute_b32 v154, v233, v230
	ds_bpermute_b32 v155, v233, v231
	s_waitcnt lgkmcnt(7)
	v_add_f32_e32 v224, v224, v140
	s_waitcnt lgkmcnt(6)
	v_add_f32_e32 v225, v225, v141
	s_waitcnt lgkmcnt(5)
	v_add_f32_e32 v226, v226, v142
	s_waitcnt lgkmcnt(4)
	v_add_f32_e32 v227, v227, v143
	s_waitcnt lgkmcnt(3)
	v_add_f32_e32 v228, v228, v152
	s_waitcnt lgkmcnt(2)
	v_add_f32_e32 v229, v229, v153
	s_waitcnt lgkmcnt(1)
	v_add_f32_e32 v230, v230, v154
	s_waitcnt lgkmcnt(0)
	v_add_f32_e32 v231, v231, v155
	ds_bpermute_b32 v140, v234, v224
	ds_bpermute_b32 v141, v234, v225
	ds_bpermute_b32 v142, v234, v226
	ds_bpermute_b32 v143, v234, v227
	ds_bpermute_b32 v152, v234, v228
	ds_bpermute_b32 v153, v234, v229
	ds_bpermute_b32 v154, v234, v230
	ds_bpermute_b32 v155, v234, v231
	s_waitcnt lgkmcnt(7)
	v_add_f32_e32 v224, v224, v140
	s_waitcnt lgkmcnt(6)
	v_add_f32_e32 v225, v225, v141
	s_waitcnt lgkmcnt(5)
	v_add_f32_e32 v226, v226, v142
	s_waitcnt lgkmcnt(4)
	v_add_f32_e32 v227, v227, v143
	s_waitcnt lgkmcnt(3)
	v_add_f32_e32 v228, v228, v152
	s_waitcnt lgkmcnt(2)
	v_add_f32_e32 v229, v229, v153
	s_waitcnt lgkmcnt(1)
	v_add_f32_e32 v230, v230, v154
	s_waitcnt lgkmcnt(0)
	v_add_f32_e32 v231, v231, v155
	v_lshlrev_b32_e32 v235, 2, v144
	s_add_u32 s90, s76, 0x6500000
	s_addc_u32 s91, s77, 0
	s_add_u32 s76, s76, 0x3120000
	s_addc_u32 s77, s77, 0
	s_lshl_b32 s83, s65, 6
	s_add_u32 s78, s76, s83
	s_addc_u32 s79, s77, 0
	s_add_u32 s78, s78, 0x20000
	s_addc_u32 s79, s79, 0
	s_mov_b64 s[80:81], exec
	s_mov_b64 exec, 0xffff
	global_atomic_add_f32 v235, v224, s[76:77]
	global_atomic_add_f32 v235, v225, s[76:77] offset:64
	global_atomic_add_f32 v235, v226, s[76:77] offset:128
	global_atomic_add_f32 v235, v227, s[76:77] offset:192
	global_atomic_add_f32 v235, v228, s[76:77] offset:512
	global_atomic_add_f32 v235, v229, s[76:77] offset:576
	global_atomic_add_f32 v235, v230, s[76:77] offset:640
	global_atomic_add_f32 v235, v231, s[76:77] offset:704
	s_mov_b64 exec, s[80:81]
	s_add_u32 s86, s26, 0x1000
	s_addc_u32 s87, s27, 0
	s_add_u32 s88, s86, 0x1000
	s_addc_u32 s89, s87, 0
	s_add_u32 s92, s92, 0x1000
	s_addc_u32 s93, s93, 0
	s_mov_b32 s84, 0xffff0000
	s_mov_b32 s85, 0xffff0000
	s_waitcnt vmcnt(0)
	s_barrier
	v_readfirstlane_b32 s83, v206
	v_mov_b32_e32 v236, 0
	v_mov_b32_e32 v237, 1
	s_cmp_lg_u32 s83, 0
	s_cbranch_scc1 .Lfma_wait_done
	s_mov_b64 exec, 1
	global_atomic_add v236, v237, s[78:79]
	s_mov_b32 s82, 0

; __device__ __forceinline__ unsigned cvtpk_s(float lo, float hi) { f32x2_t v = {lo, hi}; bf16x2_t b = __builtin_convertvector(v, bf16x2_t); return __builtin_bit_cast(unsigned, b); }
; __device__ __forceinline__ void modpass(const float* xs_main, const float* xs_ctx, const float* mod_l, const float* g, int i, bf16_t* H, int nrows, int gw, int NGW, int lane) {
;     ...
;         if (cond != cur) { cur = cond; const float* shift = mod_l + cond * 9216 + 3 * i * 1024; const float* scale = shift + 1024;
; #pragma unroll
;             for (int j = 0; j < 2; ++j)
; #pragma unroll
;                 for (int q = 0; q < 2; ++q) { const int c = 8 * lane + 512 * j + 4 * q; gm[j][q] = *(const f32x4*)(g + c) * (*(const f32x4*)(scale + c) + 1.0f); sh[j][q] = *(const f32x4*)(shift + c); } }
;         float ss = 0.f;
; #pragma unroll
;         for (int j = 0; j < 2; ++j)
; #pragma unroll
;             for (int q = 0; q < 2; ++q) ss += (v[j][q][0] * v[j][q][0] + v[j][q][1] * v[j][q][1]) + (v[j][q][2] * v[j][q][2] + v[j][q][3] * v[j][q][3]);
;         const float rstd = 1.0f / sqrtf(wave_sum(ss) * (1.0f / D) + EPS);
; #pragma unroll
;         for (int j = 0; j < 2; ++j) {
;             const f32x4 o0 = v[j][0] * rstd * gm[j][0] + sh[j][0], o1 = v[j][1] * rstd * gm[j][1] + sh[j][1];
;             u32x4 w; w.x = cvtpk_s(o0[0], o0[1]); w.y = cvtpk_s(o0[2], o0[3]); w.z = cvtpk_s(o1[0], o1[1]); w.w = cvtpk_s(o1[2], o1[3]);
;             *(u32x4*)(H + (size_t)row * D + 8 * lane + 512 * j) = w;
;         }
.Lfma_wait_done:
	s_barrier
	global_load_dword v152, v235, s[76:77] sc1
	global_load_dword v153, v235, s[76:77] offset:64 sc1
	global_load_dword v154, v235, s[76:77] offset:128 sc1
	global_load_dword v155, v235, s[76:77] offset:192 sc1
	global_load_dword v156, v235, s[76:77] offset:512 sc1
	global_load_dword v157, v235, s[76:77] offset:576 sc1
	global_load_dword v158, v235, s[76:77] offset:640 sc1
	global_load_dword v159, v235, s[76:77] offset:704 sc1
	global_load_dwordx4 v[198:201], v184, s[86:87]
	global_load_dwordx4 v[202:205], v184, s[86:87] offset:64
	global_load_dwordx4 v[208:211], v184, s[86:87] offset:512
	global_load_dwordx4 v[214:217], v184, s[86:87] offset:576
	global_load_dwordx4 v[160:163], v184, s[88:89]
	global_load_dwordx4 v[164:167], v184, s[88:89] offset:64
	global_load_dwordx4 v[168:171], v184, s[88:89] offset:512
	global_load_dwordx4 v[172:175], v184, s[88:89] offset:576
	global_load_dwordx4 v[176:179], v184, s[92:93]
	global_load_dwordx4 v[180:183], v184, s[92:93] offset:64
	global_load_dwordx4 v[186:189], v184, s[92:93] offset:512
	global_load_dwordx4 v[190:193], v184, s[92:93] offset:576
	v_mov_b32_e32 v232, 12
	v_cndmask_b32_e64 v232, 0, v232, s[84:85]
	v_add_u32_e32 v232, v232, v145
	v_lshlrev_b32_e32 v232, 1, v232
	v_lshl_add_u32 v239, v144, 11, v232
	v_mov_b32_e32 v232, 0x358637bd
	s_waitcnt vmcnt(0)
	v_fmamk_f32 v152, v152, 0x3a800000, v232
	v_fmamk_f32 v153, v153, 0x3a800000, v232
	v_fmamk_f32 v154, v154, 0x3a800000, v232
	v_fmamk_f32 v155, v155, 0x3a800000, v232
	v_fmamk_f32 v156, v156, 0x3a800000, v232
	v_fmamk_f32 v157, v157, 0x3a800000, v232
	v_fmamk_f32 v158, v158, 0x3a800000, v232
	v_fmamk_f32 v159, v159, 0x3a800000, v232
	v_rsq_f32_e32 v152, v152
	v_rsq_f32_e32 v153, v153
	v_rsq_f32_e32 v154, v154
	v_rsq_f32_e32 v155, v155
	v_rsq_f32_e32 v156, v156
	v_rsq_f32_e32 v157, v157
	v_rsq_f32_e32 v158, v158
	v_rsq_f32_e32 v159, v159
	v_pk_add_f32 v[160:161], v[160:161], 1.0 op_sel_hi:[1,0]
	v_pk_mul_f32 v[160:161], v[176:177], v[160:161]
	v_pk_add_f32 v[162:163], v[162:163], 1.0 op_sel_hi:[1,0]
	v_pk_mul_f32 v[162:163], v[178:179], v[162:163]
	v_pk_add_f32 v[164:165], v[164:165], 1.0 op_sel_hi:[1,0]
	v_pk_mul_f32 v[164:165], v[180:181], v[164:165]
	v_pk_add_f32 v[166:167], v[166:167], 1.0 op_sel_hi:[1,0]
	v_pk_mul_f32 v[166:167], v[182:183], v[166:167]
	v_pk_add_f32 v[168:169], v[168:169], 1.0 op_sel_hi:[1,0]
	v_pk_mul_f32 v[168:169], v[186:187], v[168:169]
	v_pk_add_f32 v[170:171], v[170:171], 1.0 op_sel_hi:[1,0]
	v_pk_mul_f32 v[170:171], v[188:189], v[170:171]
	v_pk_add_f32 v[172:173], v[172:173], 1.0 op_sel_hi:[1,0]
	v_pk_mul_f32 v[172:173], v[190:191], v[172:173]
	v_pk_add_f32 v[174:175], v[174:175], 1.0 op_sel_hi:[1,0]
	v_pk_mul_f32 v[174:175], v[192:193], v[174:175]
	v_mul_f32_e32 v124, v124, v152
	v_mul_f32_e32 v125, v125, v152
	v_pk_fma_f32 v[124:125], v[160:161], v[124:125], v[198:199]
	v_mul_f32_e32 v126, v126, v152
	v_mul_f32_e32 v127, v127, v152
	v_pk_fma_f32 v[126:127], v[162:163], v[126:127], v[200:201]
	v_cvt_pk_bf16_f32 v186, v124, v125
	v_cvt_pk_bf16_f32 v187, v126, v127
	v_mul_f32_e32 v120, v120, v152
	v_mul_f32_e32 v121, v121, v152
	v_pk_fma_f32 v[120:121], v[164:165], v[120:121], v[202:203]
	v_mul_f32_e32 v122, v122, v152
	v_mul_f32_e32 v123, v123, v152
	v_pk_fma_f32 v[122:123], v[166:167], v[122:123], v[204:205]
	v_cvt_pk_bf16_f32 v188, v120, v121
	v_cvt_pk_bf16_f32 v189, v122, v123
	v_mul_f32_e32 v116, v116, v152
	v_mul_f32_e32 v117, v117, v152
	v_pk_fma_f32 v[116:117], v[168:169], v[116:117], v[208:209]
	v_mul_f32_e32 v118, v118, v152
	v_mul_f32_e32 v119, v119, v152
	v_pk_fma_f32 v[118:119], v[170:171], v[118:119], v[210:211]
	v_cvt_pk_bf16_f32 v190, v116, v117
	v_cvt_pk_bf16_f32 v191, v118, v119
	v_mul_f32_e32 v108, v108, v152
	v_mul_f32_e32 v109, v109, v152
	v_pk_fma_f32 v[108:109], v[172:173], v[108:109], v[214:215]
	v_mul_f32_e32 v110, v110, v152
	v_mul_f32_e32 v111, v111, v152
	v_pk_fma_f32 v[110:111], v[174:175], v[110:111], v[216:217]
	v_cvt_pk_bf16_f32 v192, v108, v109
	v_cvt_pk_bf16_f32 v193, v110, v111
	v_mov_b32_e32 v232, v239
	v_cndmask_b32_e64 v194, v188, v186, s[84:85]
	v_cndmask_b32_e64 v195, v189, v187, s[84:85]
	ds_bpermute_b32 v196, v233, v194
	ds_bpermute_b32 v197, v233, v195
	s_waitcnt lgkmcnt(0)
	v_cndmask_b32_e64 v176, v186, v196, s[84:85]
	v_cndmask_b32_e64 v177, v187, v197, s[84:85]
	v_cndmask_b32_e64 v178, v196, v188, s[84:85]
	v_cndmask_b32_e64 v179, v197, v189, s[84:85]
	global_store_dwordx4 v232, v[176:179], s[90:91]
	v_cndmask_b32_e64 v194, v192, v190, s[84:85]
	v_cndmask_b32_e64 v195, v193, v191, s[84:85]
	ds_bpermute_b32 v196, v233, v194
	ds_bpermute_b32 v197, v233, v195
	s_waitcnt lgkmcnt(0)
	v_cndmask_b32_e64 v180, v190, v196, s[84:85]
	v_cndmask_b32_e64 v181, v191, v197, s[84:85]
	v_cndmask_b32_e64 v182, v196, v192, s[84:85]
	v_cndmask_b32_e64 v183, v197, v193, s[84:85]
	global_store_dwordx4 v232, v[180:183], s[90:91] offset:256
	v_mul_f32_e32 v112, v112, v153
	v_mul_f32_e32 v113, v113, v153
	v_pk_fma_f32 v[112:113], v[160:161], v[112:113], v[198:199]
	v_mul_f32_e32 v114, v114, v153
	v_mul_f32_e32 v115, v115, v153
	v_pk_fma_f32 v[114:115], v[162:163], v[114:115], v[200:201]
	v_cvt_pk_bf16_f32 v186, v112, v113
	v_cvt_pk_bf16_f32 v187, v114, v115
	v_mul_f32_e32 v104, v104, v153
	v_mul_f32_e32 v105, v105, v153
	v_pk_fma_f32 v[104:105], v[164:165], v[104:105], v[202:203]
	v_mul_f32_e32 v106, v106, v153
	v_mul_f32_e32 v107, v107, v153
	v_pk_fma_f32 v[106:107], v[166:167], v[106:107], v[204:205]
	v_cvt_pk_bf16_f32 v188, v104, v105
	v_cvt_pk_bf16_f32 v189, v106, v107
	v_mul_f32_e32 v100, v100, v153
	v_mul_f32_e32 v101, v101, v153
	v_pk_fma_f32 v[100:101], v[168:169], v[100:101], v[208:209]
	v_mul_f32_e32 v102, v102, v153
	v_mul_f32_e32 v103, v103, v153
	v_pk_fma_f32 v[102:103], v[170:171], v[102:103], v[210:211]
	v_cvt_pk_bf16_f32 v190, v100, v101
	v_cvt_pk_bf16_f32 v191, v102, v103
	v_mul_f32_e32 v92, v92, v153
	v_mul_f32_e32 v93, v93, v153
	v_pk_fma_f32 v[92:93], v[172:173], v[92:93], v[214:215]
	v_mul_f32_e32 v94, v94, v153
	v_mul_f32_e32 v95, v95, v153
	v_pk_fma_f32 v[94:95], v[174:175], v[94:95], v[216:217]
	v_cvt_pk_bf16_f32 v192, v92, v93
	v_cvt_pk_bf16_f32 v193, v94, v95
	v_add_u32_e32 v232, 0x8000, v239
	v_cndmask_b32_e64 v194, v188, v186, s[84:85]
	v_cndmask_b32_e64 v195, v189, v187, s[84:85]
	ds_bpermute_b32 v196, v233, v194
	ds_bpermute_b32 v197, v233, v195
	s_waitcnt lgkmcnt(0)
; __device__ __forceinline__ unsigned cvtpk_s(float lo, float hi) { f32x2_t v = {lo, hi}; bf16x2_t b = __builtin_convertvector(v, bf16x2_t); return __builtin_bit_cast(unsigned, b); }
; __device__ __forceinline__ void modpass(const float* xs_main, const float* xs_ctx, const float* mod_l, const float* g, int i, bf16_t* H, int nrows, int gw, int NGW, int lane) {
;     ...
; #pragma unroll
;         for (int j = 0; j < 2; ++j) {
;             const f32x4 o0 = v[j][0] * rstd * gm[j][0] + sh[j][0], o1 = v[j][1] * rstd * gm[j][1] + sh[j][1];
;             u32x4 w; w.x = cvtpk_s(o0[0], o0[1]); w.y = cvtpk_s(o0[2], o0[3]); w.z = cvtpk_s(o1[0], o1[1]); w.w = cvtpk_s(o1[2], o1[3]);
;             *(u32x4*)(H + (size_t)row * D + 8 * lane + 512 * j) = w;
;         }
	v_cndmask_b32_e64 v176, v186, v196, s[84:85]
	v_cndmask_b32_e64 v177, v187, v197, s[84:85]
	v_cndmask_b32_e64 v178, v196, v188, s[84:85]
	v_cndmask_b32_e64 v179, v197, v189, s[84:85]
	global_store_dwordx4 v232, v[176:179], s[90:91]
	v_cndmask_b32_e64 v194, v192, v190, s[84:85]
	v_cndmask_b32_e64 v195, v193, v191, s[84:85]
	ds_bpermute_b32 v196, v233, v194
	ds_bpermute_b32 v197, v233, v195
	s_waitcnt lgkmcnt(0)
	v_cndmask_b32_e64 v180, v190, v196, s[84:85]
	v_cndmask_b32_e64 v181, v191, v197, s[84:85]
	v_cndmask_b32_e64 v182, v196, v192, s[84:85]
	v_cndmask_b32_e64 v183, v197, v193, s[84:85]
	global_store_dwordx4 v232, v[180:183], s[90:91] offset:256
	v_mul_f32_e32 v96, v96, v154
	v_mul_f32_e32 v97, v97, v154
	v_pk_fma_f32 v[96:97], v[160:161], v[96:97], v[198:199]
	v_mul_f32_e32 v98, v98, v154
	v_mul_f32_e32 v99, v99, v154
	v_pk_fma_f32 v[98:99], v[162:163], v[98:99], v[200:201]
	v_cvt_pk_bf16_f32 v186, v96, v97
	v_cvt_pk_bf16_f32 v187, v98, v99
	v_mul_f32_e32 v88, v88, v154
	v_mul_f32_e32 v89, v89, v154
	v_pk_fma_f32 v[88:89], v[164:165], v[88:89], v[202:203]
	v_mul_f32_e32 v90, v90, v154
	v_mul_f32_e32 v91, v91, v154
	v_pk_fma_f32 v[90:91], v[166:167], v[90:91], v[204:205]
	v_cvt_pk_bf16_f32 v188, v88, v89
	v_cvt_pk_bf16_f32 v189, v90, v91
	v_mul_f32_e32 v84, v84, v154
	v_mul_f32_e32 v85, v85, v154
	v_pk_fma_f32 v[84:85], v[168:169], v[84:85], v[208:209]
	v_mul_f32_e32 v86, v86, v154
	v_mul_f32_e32 v87, v87, v154
	v_pk_fma_f32 v[86:87], v[170:171], v[86:87], v[210:211]
	v_cvt_pk_bf16_f32 v190, v84, v85
	v_cvt_pk_bf16_f32 v191, v86, v87
	v_mul_f32_e32 v76, v76, v154
	v_mul_f32_e32 v77, v77, v154
	v_pk_fma_f32 v[76:77], v[172:173], v[76:77], v[214:215]
	v_mul_f32_e32 v78, v78, v154
	v_mul_f32_e32 v79, v79, v154
	v_pk_fma_f32 v[78:79], v[174:175], v[78:79], v[216:217]
	v_cvt_pk_bf16_f32 v192, v76, v77
	v_cvt_pk_bf16_f32 v193, v78, v79
	v_add_u32_e32 v232, 0x10000, v239
	v_cndmask_b32_e64 v194, v188, v186, s[84:85]
	v_cndmask_b32_e64 v195, v189, v187, s[84:85]
	ds_bpermute_b32 v196, v233, v194
	ds_bpermute_b32 v197, v233, v195
	s_waitcnt lgkmcnt(0)
	v_cndmask_b32_e64 v176, v186, v196, s[84:85]
	v_cndmask_b32_e64 v177, v187, v197, s[84:85]
	v_cndmask_b32_e64 v178, v196, v188, s[84:85]
	v_cndmask_b32_e64 v179, v197, v189, s[84:85]
	global_store_dwordx4 v232, v[176:179], s[90:91]
	v_cndmask_b32_e64 v194, v192, v190, s[84:85]
	v_cndmask_b32_e64 v195, v193, v191, s[84:85]
	ds_bpermute_b32 v196, v233, v194
	ds_bpermute_b32 v197, v233, v195
	s_waitcnt lgkmcnt(0)
	v_cndmask_b32_e64 v180, v190, v196, s[84:85]
	v_cndmask_b32_e64 v181, v191, v197, s[84:85]
	v_cndmask_b32_e64 v182, v196, v192, s[84:85]
	v_cndmask_b32_e64 v183, v197, v193, s[84:85]
	global_store_dwordx4 v232, v[180:183], s[90:91] offset:256
	v_mul_f32_e32 v80, v80, v155
	v_mul_f32_e32 v81, v81, v155
	v_pk_fma_f32 v[80:81], v[160:161], v[80:81], v[198:199]
	v_mul_f32_e32 v82, v82, v155
	v_mul_f32_e32 v83, v83, v155
	v_pk_fma_f32 v[82:83], v[162:163], v[82:83], v[200:201]
	v_cvt_pk_bf16_f32 v186, v80, v81
	v_cvt_pk_bf16_f32 v187, v82, v83
	v_mul_f32_e32 v72, v72, v155
	v_mul_f32_e32 v73, v73, v155
	v_pk_fma_f32 v[72:73], v[164:165], v[72:73], v[202:203]
	v_mul_f32_e32 v74, v74, v155
	v_mul_f32_e32 v75, v75, v155
	v_pk_fma_f32 v[74:75], v[166:167], v[74:75], v[204:205]
	v_cvt_pk_bf16_f32 v188, v72, v73
	v_cvt_pk_bf16_f32 v189, v74, v75
	v_mul_f32_e32 v68, v68, v155
	v_mul_f32_e32 v69, v69, v155
	v_pk_fma_f32 v[68:69], v[168:169], v[68:69], v[208:209]
	v_mul_f32_e32 v70, v70, v155
	v_mul_f32_e32 v71, v71, v155
	v_pk_fma_f32 v[70:71], v[170:171], v[70:71], v[210:211]
	v_cvt_pk_bf16_f32 v190, v68, v69
	v_cvt_pk_bf16_f32 v191, v70, v71
	v_mul_f32_e32 v64, v64, v155
	v_mul_f32_e32 v65, v65, v155
	v_pk_fma_f32 v[64:65], v[172:173], v[64:65], v[214:215]
	v_mul_f32_e32 v66, v66, v155
	v_mul_f32_e32 v67, v67, v155
	v_pk_fma_f32 v[66:67], v[174:175], v[66:67], v[216:217]
	v_cvt_pk_bf16_f32 v192, v64, v65
	v_cvt_pk_bf16_f32 v193, v66, v67
	v_add_u32_e32 v232, 0x18000, v239
	v_cndmask_b32_e64 v194, v188, v186, s[84:85]
	v_cndmask_b32_e64 v195, v189, v187, s[84:85]
	ds_bpermute_b32 v196, v233, v194
	ds_bpermute_b32 v197, v233, v195
	s_waitcnt lgkmcnt(0)
	v_cndmask_b32_e64 v176, v186, v196, s[84:85]
	v_cndmask_b32_e64 v177, v187, v197, s[84:85]
	v_cndmask_b32_e64 v178, v196, v188, s[84:85]
	v_cndmask_b32_e64 v179, v197, v189, s[84:85]
	global_store_dwordx4 v232, v[176:179], s[90:91]
	v_cndmask_b32_e64 v194, v192, v190, s[84:85]
	v_cndmask_b32_e64 v195, v193, v191, s[84:85]
	ds_bpermute_b32 v196, v233, v194
	ds_bpermute_b32 v197, v233, v195
	s_waitcnt lgkmcnt(0)
	v_cndmask_b32_e64 v180, v190, v196, s[84:85]
	v_cndmask_b32_e64 v181, v191, v197, s[84:85]
	v_cndmask_b32_e64 v182, v196, v192, s[84:85]
	v_cndmask_b32_e64 v183, v197, v193, s[84:85]
	global_store_dwordx4 v232, v[180:183], s[90:91] offset:256
	v_mul_f32_e32 v60, v60, v156
	v_mul_f32_e32 v61, v61, v156
	v_pk_fma_f32 v[60:61], v[160:161], v[60:61], v[198:199]
	v_mul_f32_e32 v62, v62, v156
	v_mul_f32_e32 v63, v63, v156
	v_pk_fma_f32 v[62:63], v[162:163], v[62:63], v[200:201]
	v_cvt_pk_bf16_f32 v186, v60, v61
	v_cvt_pk_bf16_f32 v187, v62, v63
	v_mul_f32_e32 v56, v56, v156
	v_mul_f32_e32 v57, v57, v156
	v_pk_fma_f32 v[56:57], v[164:165], v[56:57], v[202:203]
	v_mul_f32_e32 v58, v58, v156
	v_mul_f32_e32 v59, v59, v156
	v_pk_fma_f32 v[58:59], v[166:167], v[58:59], v[204:205]
	v_cvt_pk_bf16_f32 v188, v56, v57
	v_cvt_pk_bf16_f32 v189, v58, v59
	v_mul_f32_e32 v52, v52, v156
	v_mul_f32_e32 v53, v53, v156
	v_pk_fma_f32 v[52:53], v[168:169], v[52:53], v[208:209]
	v_mul_f32_e32 v54, v54, v156
	v_mul_f32_e32 v55, v55, v156
	v_pk_fma_f32 v[54:55], v[170:171], v[54:55], v[210:211]
	v_cvt_pk_bf16_f32 v190, v52, v53
	v_cvt_pk_bf16_f32 v191, v54, v55
	v_mul_f32_e32 v44, v44, v156
	v_mul_f32_e32 v45, v45, v156
	v_pk_fma_f32 v[44:45], v[172:173], v[44:45], v[214:215]
	v_mul_f32_e32 v46, v46, v156
	v_mul_f32_e32 v47, v47, v156
	v_pk_fma_f32 v[46:47], v[174:175], v[46:47], v[216:217]
	v_cvt_pk_bf16_f32 v192, v44, v45
	v_cvt_pk_bf16_f32 v193, v46, v47
	v_add_u32_e32 v232, 0x40000, v239
	v_cndmask_b32_e64 v194, v188, v186, s[84:85]
	v_cndmask_b32_e64 v195, v189, v187, s[84:85]
	ds_bpermute_b32 v196, v233, v194
	ds_bpermute_b32 v197, v233, v195
	s_waitcnt lgkmcnt(0)
; __device__ __forceinline__ unsigned cvtpk_s(float lo, float hi) { f32x2_t v = {lo, hi}; bf16x2_t b = __builtin_convertvector(v, bf16x2_t); return __builtin_bit_cast(unsigned, b); }
;     ...
;         if constexpr (!Epi::AFTER_DRAIN) { E(acc, cur, wr, wc, fr, fq); S.done(cur); }
;         if (!has_next) break;
; __device__ __forceinline__ void modpass(const float* xs_main, const float* xs_ctx, const float* mod_l, const float* g, int i, bf16_t* H, int nrows, int gw, int NGW, int lane) {
;     ...
; #pragma unroll
;         for (int j = 0; j < 2; ++j) {
;             const f32x4 o0 = v[j][0] * rstd * gm[j][0] + sh[j][0], o1 = v[j][1] * rstd * gm[j][1] + sh[j][1];
;             u32x4 w; w.x = cvtpk_s(o0[0], o0[1]); w.y = cvtpk_s(o0[2], o0[3]); w.z = cvtpk_s(o1[0], o1[1]); w.w = cvtpk_s(o1[2], o1[3]);
;             *(u32x4*)(H + (size_t)row * D + 8 * lane + 512 * j) = w;
;         }
	v_cndmask_b32_e64 v176, v186, v196, s[84:85]
	v_cndmask_b32_e64 v177, v187, v197, s[84:85]
	v_cndmask_b32_e64 v178, v196, v188, s[84:85]
	v_cndmask_b32_e64 v179, v197, v189, s[84:85]
	global_store_dwordx4 v232, v[176:179], s[90:91]
	v_cndmask_b32_e64 v194, v192, v190, s[84:85]
	v_cndmask_b32_e64 v195, v193, v191, s[84:85]
	ds_bpermute_b32 v196, v233, v194
	ds_bpermute_b32 v197, v233, v195
	s_waitcnt lgkmcnt(0)
	v_cndmask_b32_e64 v180, v190, v196, s[84:85]
	v_cndmask_b32_e64 v181, v191, v197, s[84:85]
	v_cndmask_b32_e64 v182, v196, v192, s[84:85]
	v_cndmask_b32_e64 v183, v197, v193, s[84:85]
	global_store_dwordx4 v232, v[180:183], s[90:91] offset:256
	v_mul_f32_e32 v48, v48, v157
	v_mul_f32_e32 v49, v49, v157
	v_pk_fma_f32 v[48:49], v[160:161], v[48:49], v[198:199]
	v_mul_f32_e32 v50, v50, v157
	v_mul_f32_e32 v51, v51, v157
	v_pk_fma_f32 v[50:51], v[162:163], v[50:51], v[200:201]
	v_cvt_pk_bf16_f32 v186, v48, v49
	v_cvt_pk_bf16_f32 v187, v50, v51
	v_mul_f32_e32 v40, v40, v157
	v_mul_f32_e32 v41, v41, v157
	v_pk_fma_f32 v[40:41], v[164:165], v[40:41], v[202:203]
	v_mul_f32_e32 v42, v42, v157
	v_mul_f32_e32 v43, v43, v157
	v_pk_fma_f32 v[42:43], v[166:167], v[42:43], v[204:205]
	v_cvt_pk_bf16_f32 v188, v40, v41
	v_cvt_pk_bf16_f32 v189, v42, v43
	v_mul_f32_e32 v36, v36, v157
	v_mul_f32_e32 v37, v37, v157
	v_pk_fma_f32 v[36:37], v[168:169], v[36:37], v[208:209]
	v_mul_f32_e32 v38, v38, v157
	v_mul_f32_e32 v39, v39, v157
	v_pk_fma_f32 v[38:39], v[170:171], v[38:39], v[210:211]
	v_cvt_pk_bf16_f32 v190, v36, v37
	v_cvt_pk_bf16_f32 v191, v38, v39
	v_mul_f32_e32 v28, v28, v157
	v_mul_f32_e32 v29, v29, v157
	v_pk_fma_f32 v[28:29], v[172:173], v[28:29], v[214:215]
	v_mul_f32_e32 v30, v30, v157
	v_mul_f32_e32 v31, v31, v157
	v_pk_fma_f32 v[30:31], v[174:175], v[30:31], v[216:217]
	v_cvt_pk_bf16_f32 v192, v28, v29
	v_cvt_pk_bf16_f32 v193, v30, v31
	v_add_u32_e32 v232, 0x48000, v239
	v_cndmask_b32_e64 v194, v188, v186, s[84:85]
	v_cndmask_b32_e64 v195, v189, v187, s[84:85]
	ds_bpermute_b32 v196, v233, v194
	ds_bpermute_b32 v197, v233, v195
	s_waitcnt lgkmcnt(0)
	v_cndmask_b32_e64 v176, v186, v196, s[84:85]
	v_cndmask_b32_e64 v177, v187, v197, s[84:85]
	v_cndmask_b32_e64 v178, v196, v188, s[84:85]
	v_cndmask_b32_e64 v179, v197, v189, s[84:85]
	global_store_dwordx4 v232, v[176:179], s[90:91]
	v_cndmask_b32_e64 v194, v192, v190, s[84:85]
	v_cndmask_b32_e64 v195, v193, v191, s[84:85]
	ds_bpermute_b32 v196, v233, v194
	ds_bpermute_b32 v197, v233, v195
	s_waitcnt lgkmcnt(0)
	v_cndmask_b32_e64 v180, v190, v196, s[84:85]
	v_cndmask_b32_e64 v181, v191, v197, s[84:85]
	v_cndmask_b32_e64 v182, v196, v192, s[84:85]
	v_cndmask_b32_e64 v183, v197, v193, s[84:85]
	global_store_dwordx4 v232, v[180:183], s[90:91] offset:256
	v_mul_f32_e32 v32, v32, v158
	v_mul_f32_e32 v33, v33, v158
	v_pk_fma_f32 v[32:33], v[160:161], v[32:33], v[198:199]
	v_mul_f32_e32 v34, v34, v158
	v_mul_f32_e32 v35, v35, v158
	v_pk_fma_f32 v[34:35], v[162:163], v[34:35], v[200:201]
	v_cvt_pk_bf16_f32 v186, v32, v33
	v_cvt_pk_bf16_f32 v187, v34, v35
	v_mul_f32_e32 v24, v24, v158
	v_mul_f32_e32 v25, v25, v158
	v_pk_fma_f32 v[24:25], v[164:165], v[24:25], v[202:203]
	v_mul_f32_e32 v26, v26, v158
	v_mul_f32_e32 v27, v27, v158
	v_pk_fma_f32 v[26:27], v[166:167], v[26:27], v[204:205]
	v_cvt_pk_bf16_f32 v188, v24, v25
	v_cvt_pk_bf16_f32 v189, v26, v27
	v_mul_f32_e32 v20, v20, v158
	v_mul_f32_e32 v21, v21, v158
	v_pk_fma_f32 v[20:21], v[168:169], v[20:21], v[208:209]
	v_mul_f32_e32 v22, v22, v158
	v_mul_f32_e32 v23, v23, v158
	v_pk_fma_f32 v[22:23], v[170:171], v[22:23], v[210:211]
	v_cvt_pk_bf16_f32 v190, v20, v21
	v_cvt_pk_bf16_f32 v191, v22, v23
	v_mul_f32_e32 v12, v12, v158
	v_mul_f32_e32 v13, v13, v158
	v_pk_fma_f32 v[12:13], v[172:173], v[12:13], v[214:215]
	v_mul_f32_e32 v14, v14, v158
	v_mul_f32_e32 v15, v15, v158
	v_pk_fma_f32 v[14:15], v[174:175], v[14:15], v[216:217]
	v_cvt_pk_bf16_f32 v192, v12, v13
	v_cvt_pk_bf16_f32 v193, v14, v15
	v_add_u32_e32 v232, 0x50000, v239
	v_cndmask_b32_e64 v194, v188, v186, s[84:85]
	v_cndmask_b32_e64 v195, v189, v187, s[84:85]
	ds_bpermute_b32 v196, v233, v194
	ds_bpermute_b32 v197, v233, v195
	s_waitcnt lgkmcnt(0)
	v_cndmask_b32_e64 v176, v186, v196, s[84:85]
	v_cndmask_b32_e64 v177, v187, v197, s[84:85]
	v_cndmask_b32_e64 v178, v196, v188, s[84:85]
	v_cndmask_b32_e64 v179, v197, v189, s[84:85]
	global_store_dwordx4 v232, v[176:179], s[90:91]
	v_cndmask_b32_e64 v194, v192, v190, s[84:85]
	v_cndmask_b32_e64 v195, v193, v191, s[84:85]
	ds_bpermute_b32 v196, v233, v194
	ds_bpermute_b32 v197, v233, v195
	s_waitcnt lgkmcnt(0)
	v_cndmask_b32_e64 v180, v190, v196, s[84:85]
	v_cndmask_b32_e64 v181, v191, v197, s[84:85]
	v_cndmask_b32_e64 v182, v196, v192, s[84:85]
	v_cndmask_b32_e64 v183, v197, v193, s[84:85]
	global_store_dwordx4 v232, v[180:183], s[90:91] offset:256
	v_mul_f32_e32 v16, v16, v159
	v_mul_f32_e32 v17, v17, v159
	v_pk_fma_f32 v[16:17], v[160:161], v[16:17], v[198:199]
	v_mul_f32_e32 v18, v18, v159
	v_mul_f32_e32 v19, v19, v159
	v_pk_fma_f32 v[18:19], v[162:163], v[18:19], v[200:201]
	v_cvt_pk_bf16_f32 v186, v16, v17
	v_cvt_pk_bf16_f32 v187, v18, v19
	v_mul_f32_e32 v8, v8, v159
	v_mul_f32_e32 v9, v9, v159
	v_pk_fma_f32 v[8:9], v[164:165], v[8:9], v[202:203]
	v_mul_f32_e32 v10, v10, v159
	v_mul_f32_e32 v11, v11, v159
	v_pk_fma_f32 v[10:11], v[166:167], v[10:11], v[204:205]
	v_cvt_pk_bf16_f32 v188, v8, v9
	v_cvt_pk_bf16_f32 v189, v10, v11
	v_mul_f32_e32 v4, v4, v159
	v_mul_f32_e32 v5, v5, v159
	v_pk_fma_f32 v[4:5], v[168:169], v[4:5], v[208:209]
	v_mul_f32_e32 v6, v6, v159
	v_mul_f32_e32 v7, v7, v159
	v_pk_fma_f32 v[6:7], v[170:171], v[6:7], v[210:211]
	v_cvt_pk_bf16_f32 v190, v4, v5
	v_cvt_pk_bf16_f32 v191, v6, v7
	v_mul_f32_e32 v0, v0, v159
	v_mul_f32_e32 v1, v1, v159
	v_pk_fma_f32 v[0:1], v[172:173], v[0:1], v[214:215]
	v_mul_f32_e32 v2, v2, v159
	v_mul_f32_e32 v3, v3, v159
	v_pk_fma_f32 v[2:3], v[174:175], v[2:3], v[216:217]
	v_cvt_pk_bf16_f32 v192, v0, v1
	v_cvt_pk_bf16_f32 v193, v2, v3
	v_add_u32_e32 v232, 0x58000, v239
	v_cndmask_b32_e64 v194, v188, v186, s[84:85]
	v_cndmask_b32_e64 v195, v189, v187, s[84:85]
	ds_bpermute_b32 v196, v233, v194
	ds_bpermute_b32 v197, v233, v195
	s_waitcnt lgkmcnt(0)
	v_cndmask_b32_e64 v176, v186, v196, s[84:85]
	v_cndmask_b32_e64 v177, v187, v197, s[84:85]
	v_cndmask_b32_e64 v178, v196, v188, s[84:85]
	v_cndmask_b32_e64 v179, v197, v189, s[84:85]
	global_store_dwordx4 v232, v[176:179], s[90:91]
	v_cndmask_b32_e64 v194, v192, v190, s[84:85]
	v_cndmask_b32_e64 v195, v193, v191, s[84:85]
	ds_bpermute_b32 v196, v233, v194
	ds_bpermute_b32 v197, v233, v195
	s_waitcnt lgkmcnt(0)
	v_cndmask_b32_e64 v180, v190, v196, s[84:85]
	v_cndmask_b32_e64 v181, v191, v197, s[84:85]
	v_cndmask_b32_e64 v182, v196, v192, s[84:85]
	v_cndmask_b32_e64 v183, v197, v193, s[84:85]
	global_store_dwordx4 v232, v[180:183], s[90:91] offset:256
	s_and_b64 vcc, exec, s[4:5]
	s_mov_b64 s[4:5], -1
	s_branch .Lfmdone_a
;     __device__ __forceinline__ void operator()(const f32x4 (&acc)[2][2][4][2], const Unit& u, int wr, int wc, int fr, int fq) const {
;         const int cond = u.pm < 64 ? 0 : (u.pm < 128 ? 1 : 2);
;         const float* gate = gate_l + cond * 9216;
;         const int col0 = u.pn * BM + wc * 32 + 4 * fq;
;         f32x4 gv[2][2];
; #pragma unroll
;         for (int bj = 0; bj < 2; ++bj)
; #pragma unroll
;             for (int n = 0; n < 2; ++n) gv[bj][n] = *(const f32x4*)(gate + col0 + bj * HALF + n * 16) * coef;
; #pragma unroll
;         for (int ai = 0; ai < 2; ++ai)
; #pragma unroll
;             for (int m = 0; m < 4; ++m) {
;                 const int row = u.pm * BM + ai * HALF + wr * 64 + m * 16 + fr;
;                 const float* s = row < MX_ ? src_main + (size_t)row * D_ : src_ctx + (size_t)(row - MX_) * D_;
;                 float* d = row < MX_ ? dst_main + (size_t)row * D_ : dst_ctx + (size_t)(row - MX_) * D_;
; #pragma unroll
;                 for (int bj = 0; bj < 2; ++bj)
; #pragma unroll
;                     for (int n = 0; n < 2; ++n) { const int off = col0 + bj * HALF + n * 16; const f32x4 xo = *(const f32x4*)(s + off); *(f32x4*)(d + off) = xo + gv[bj][n] * acc[ai][bj][m][n]; }
.Lfmsel_a:
	s_cmpk_lt_i32 s65, 0x80
	s_cselect_b32 s16, s62, 0x4800
	s_cmp_gt_i32 s65, 63
	s_cselect_b32 s16, s16, 0
	s_lshl_b32 s16, s16, 2
	s_add_u32 s26, s53, s16
	s_addc_u32 s27, s54, 0
	s_load_dwordx2 s[92:93], s[0:1], 0x30
	s_load_dwordx2 s[76:77], s[0:1], 0xb8
	v_lshl_add_u32 v144, s65, 8, v146
	v_lshl_or_b32 v145, s66, 8, v148
	v_lshlrev_b32_e32 v184, 2, v145
	v_lshl_add_u32 v207, v144, 12, v184
	global_load_dwordx4 v[198:201], v184, s[26:27]
	global_load_dwordx4 v[202:205], v184, s[26:27] offset:64
	global_load_dwordx4 v[208:211], v184, s[26:27] offset:512
	global_load_dwordx4 v[214:217], v184, s[26:27] offset:576
	v_add_u32_e32 v213, 0x10000, v207
	v_add_u32_e32 v218, 0x20000, v207
	v_add_u32_e32 v219, 0x30000, v207
	v_add_u32_e32 v250, 0x80000, v207
	v_add_u32_e32 v251, 0x90000, v207
	v_add_u32_e32 v222, 0xa0000, v207
	v_add_u32_e32 v223, 0xb0000, v207
	global_load_dwordx4 v[140:143], v207, s[8:9]
	global_load_dwordx4 v[152:155], v207, s[8:9] offset:64
	global_load_dwordx4 v[156:159], v207, s[8:9] offset:512
	global_load_dwordx4 v[160:163], v207, s[8:9] offset:576
	global_load_dwordx4 v[164:167], v213, s[8:9]
	global_load_dwordx4 v[168:171], v213, s[8:9] offset:64
	global_load_dwordx4 v[172:175], v213, s[8:9] offset:512
	global_load_dwordx4 v[176:179], v213, s[8:9] offset:576
	global_load_dwordx4 v[180:183], v218, s[8:9]
	global_load_dwordx4 v[186:189], v218, s[8:9] offset:64
	global_load_dwordx4 v[190:193], v218, s[8:9] offset:512
	global_load_dwordx4 v[194:197], v218, s[8:9] offset:576
	s_waitcnt vmcnt(12)
	v_pk_mul_f32 v[198:199], v[198:199], 0.5 op_sel_hi:[1,0]
	v_pk_mul_f32 v[200:201], v[200:201], 0.5 op_sel_hi:[1,0]
	v_pk_mul_f32 v[202:203], v[202:203], 0.5 op_sel_hi:[1,0]
	v_pk_mul_f32 v[204:205], v[204:205], 0.5 op_sel_hi:[1,0]
	v_pk_mul_f32 v[208:209], v[208:209], 0.5 op_sel_hi:[1,0]
	v_pk_mul_f32 v[210:211], v[210:211], 0.5 op_sel_hi:[1,0]
	v_pk_mul_f32 v[214:215], v[214:215], 0.5 op_sel_hi:[1,0]
	v_pk_mul_f32 v[216:217], v[216:217], 0.5 op_sel_hi:[1,0]
	s_waitcnt vmcnt(11)
	v_pk_fma_f32 v[124:125], v[124:125], v[198:199], v[140:141]
	v_pk_fma_f32 v[126:127], v[126:127], v[200:201], v[142:143]
	v_mul_f32_e32 v224, v124, v124
	v_fmac_f32_e32 v224, v125, v125
	v_fmac_f32_e32 v224, v126, v126
	v_fmac_f32_e32 v224, v127, v127
	s_waitcnt vmcnt(10)
	v_pk_fma_f32 v[120:121], v[120:121], v[202:203], v[152:153]
	v_pk_fma_f32 v[122:123], v[122:123], v[204:205], v[154:155]
	v_fmac_f32_e32 v224, v120, v120
	v_fmac_f32_e32 v224, v121, v121
	v_fmac_f32_e32 v224, v122, v122
	v_fmac_f32_e32 v224, v123, v123
	s_waitcnt vmcnt(9)
	v_pk_fma_f32 v[116:117], v[116:117], v[208:209], v[156:157]
	v_pk_fma_f32 v[118:119], v[118:119], v[210:211], v[158:159]
	v_fmac_f32_e32 v224, v116, v116
	v_fmac_f32_e32 v224, v117, v117
	v_fmac_f32_e32 v224, v118, v118
	v_fmac_f32_e32 v224, v119, v119
	s_waitcnt vmcnt(8)
	v_pk_fma_f32 v[108:109], v[108:109], v[214:215], v[160:161]
	v_pk_fma_f32 v[110:111], v[110:111], v[216:217], v[162:163]
	v_fmac_f32_e32 v224, v108, v108
	v_fmac_f32_e32 v224, v109, v109
	v_fmac_f32_e32 v224, v110, v110
	v_fmac_f32_e32 v224, v111, v111
	global_store_dwordx4 v207, v[124:127], s[10:11] sc1
	global_store_dwordx4 v207, v[120:123], s[10:11] offset:64 sc1
	global_store_dwordx4 v207, v[116:119], s[10:11] offset:512 sc1
	global_store_dwordx4 v207, v[108:111], s[10:11] offset:576 sc1
	global_load_dwordx4 v[140:143], v219, s[8:9]
	global_load_dwordx4 v[152:155], v219, s[8:9] offset:64
	global_load_dwordx4 v[156:159], v219, s[8:9] offset:512
	global_load_dwordx4 v[160:163], v219, s[8:9] offset:576
	s_waitcnt vmcnt(15)
	v_pk_fma_f32 v[112:113], v[112:113], v[198:199], v[164:165]
	v_pk_fma_f32 v[114:115], v[114:115], v[200:201], v[166:167]
	v_mul_f32_e32 v225, v112, v112
	v_fmac_f32_e32 v225, v113, v113
	v_fmac_f32_e32 v225, v114, v114
	v_fmac_f32_e32 v225, v115, v115
	s_waitcnt vmcnt(14)
	v_pk_fma_f32 v[104:105], v[104:105], v[202:203], v[168:169]
	v_pk_fma_f32 v[106:107], v[106:107], v[204:205], v[170:171]
	v_fmac_f32_e32 v225, v104, v104
	v_fmac_f32_e32 v225, v105, v105
	v_fmac_f32_e32 v225, v106, v106
	v_fmac_f32_e32 v225, v107, v107
	s_waitcnt vmcnt(13)
	v_pk_fma_f32 v[100:101], v[100:101], v[208:209], v[172:173]
	v_pk_fma_f32 v[102:103], v[102:103], v[210:211], v[174:175]
	v_fmac_f32_e32 v225, v100, v100
	v_fmac_f32_e32 v225, v101, v101
	v_fmac_f32_e32 v225, v102, v102
	v_fmac_f32_e32 v225, v103, v103
	s_waitcnt vmcnt(12)
	v_pk_fma_f32 v[92:93], v[92:93], v[214:215], v[176:177]
	v_pk_fma_f32 v[94:95], v[94:95], v[216:217], v[178:179]
	v_fmac_f32_e32 v225, v92, v92
	v_fmac_f32_e32 v225, v93, v93
	v_fmac_f32_e32 v225, v94, v94
	v_fmac_f32_e32 v225, v95, v95
	global_store_dwordx4 v213, v[112:115], s[10:11] sc1
	global_store_dwordx4 v213, v[104:107], s[10:11] offset:64 sc1
	global_store_dwordx4 v213, v[100:103], s[10:11] offset:512 sc1
	global_store_dwordx4 v213, v[92:95], s[10:11] offset:576 sc1
	global_load_dwordx4 v[164:167], v250, s[8:9]
	global_load_dwordx4 v[168:171], v250, s[8:9] offset:64
	global_load_dwordx4 v[172:175], v250, s[8:9] offset:512
	global_load_dwordx4 v[176:179], v250, s[8:9] offset:576
	s_waitcnt vmcnt(19)
	v_pk_fma_f32 v[96:97], v[96:97], v[198:199], v[180:181]
	v_pk_fma_f32 v[98:99], v[98:99], v[200:201], v[182:183]
	v_mul_f32_e32 v226, v96, v96
	v_fmac_f32_e32 v226, v97, v97
	v_fmac_f32_e32 v226, v98, v98
	v_fmac_f32_e32 v226, v99, v99
	s_waitcnt vmcnt(18)
	v_pk_fma_f32 v[88:89], v[88:89], v[202:203], v[186:187]
	v_pk_fma_f32 v[90:91], v[90:91], v[204:205], v[188:189]
	v_fmac_f32_e32 v226, v88, v88
	v_fmac_f32_e32 v226, v89, v89
	v_fmac_f32_e32 v226, v90, v90
	v_fmac_f32_e32 v226, v91, v91
	s_waitcnt vmcnt(17)
;     __device__ __forceinline__ void operator()(const f32x4 (&acc)[2][2][4][2], const Unit& u, int wr, int wc, int fr, int fq) const {
;     ...
;         for (int ai = 0; ai < 2; ++ai)
; #pragma unroll
;             for (int m = 0; m < 4; ++m) {
;                 const int row = u.pm * BM + ai * HALF + wr * 64 + m * 16 + fr;
;                 const float* s = row < MX_ ? src_main + (size_t)row * D_ : src_ctx + (size_t)(row - MX_) * D_;
;                 float* d = row < MX_ ? dst_main + (size_t)row * D_ : dst_ctx + (size_t)(row - MX_) * D_;
; #pragma unroll
;                 for (int bj = 0; bj < 2; ++bj)
; #pragma unroll
;                     for (int n = 0; n < 2; ++n) { const int off = col0 + bj * HALF + n * 16; const f32x4 xo = *(const f32x4*)(s + off); *(f32x4*)(d + off) = xo + gv[bj][n] * acc[ai][bj][m][n]; }
; __device__ __forceinline__ void modpass(const float* xs_main, const float* xs_ctx, const float* mod_l, const float* g, int i, bf16_t* H, int nrows, int gw, int NGW, int lane) {
;     ...
;         float ss = 0.f;
; #pragma unroll
;         for (int j = 0; j < 2; ++j)
; #pragma unroll
;             for (int q = 0; q < 2; ++q) ss += (v[j][q][0] * v[j][q][0] + v[j][q][1] * v[j][q][1]) + (v[j][q][2] * v[j][q][2] + v[j][q][3] * v[j][q][3]);
	v_pk_fma_f32 v[84:85], v[84:85], v[208:209], v[190:191]
	v_pk_fma_f32 v[86:87], v[86:87], v[210:211], v[192:193]
	v_fmac_f32_e32 v226, v84, v84
	v_fmac_f32_e32 v226, v85, v85
	v_fmac_f32_e32 v226, v86, v86
	v_fmac_f32_e32 v226, v87, v87
	s_waitcnt vmcnt(16)
	v_pk_fma_f32 v[76:77], v[76:77], v[214:215], v[194:195]
	v_pk_fma_f32 v[78:79], v[78:79], v[216:217], v[196:197]
	v_fmac_f32_e32 v226, v76, v76
	v_fmac_f32_e32 v226, v77, v77
	v_fmac_f32_e32 v226, v78, v78
	v_fmac_f32_e32 v226, v79, v79
	global_store_dwordx4 v218, v[96:99], s[10:11] sc1
	global_store_dwordx4 v218, v[88:91], s[10:11] offset:64 sc1
	global_store_dwordx4 v218, v[84:87], s[10:11] offset:512 sc1
	global_store_dwordx4 v218, v[76:79], s[10:11] offset:576 sc1
	global_load_dwordx4 v[180:183], v251, s[8:9]
	global_load_dwordx4 v[186:189], v251, s[8:9] offset:64
	global_load_dwordx4 v[190:193], v251, s[8:9] offset:512
	global_load_dwordx4 v[194:197], v251, s[8:9] offset:576
	s_waitcnt vmcnt(19)
	v_pk_fma_f32 v[80:81], v[80:81], v[198:199], v[140:141]
	v_pk_fma_f32 v[82:83], v[82:83], v[200:201], v[142:143]
	v_mul_f32_e32 v227, v80, v80
	v_fmac_f32_e32 v227, v81, v81
	v_fmac_f32_e32 v227, v82, v82
	v_fmac_f32_e32 v227, v83, v83
	s_waitcnt vmcnt(18)
	v_pk_fma_f32 v[72:73], v[72:73], v[202:203], v[152:153]
	v_pk_fma_f32 v[74:75], v[74:75], v[204:205], v[154:155]
	v_fmac_f32_e32 v227, v72, v72
	v_fmac_f32_e32 v227, v73, v73
	v_fmac_f32_e32 v227, v74, v74
	v_fmac_f32_e32 v227, v75, v75
	s_waitcnt vmcnt(17)
	v_pk_fma_f32 v[68:69], v[68:69], v[208:209], v[156:157]
	v_pk_fma_f32 v[70:71], v[70:71], v[210:211], v[158:159]
	v_fmac_f32_e32 v227, v68, v68
	v_fmac_f32_e32 v227, v69, v69
	v_fmac_f32_e32 v227, v70, v70
	v_fmac_f32_e32 v227, v71, v71
	s_waitcnt vmcnt(16)
	v_pk_fma_f32 v[64:65], v[64:65], v[214:215], v[160:161]
	v_pk_fma_f32 v[66:67], v[66:67], v[216:217], v[162:163]
	v_fmac_f32_e32 v227, v64, v64
	v_fmac_f32_e32 v227, v65, v65
	v_fmac_f32_e32 v227, v66, v66
	v_fmac_f32_e32 v227, v67, v67
	global_store_dwordx4 v219, v[80:83], s[10:11] sc1
	global_store_dwordx4 v219, v[72:75], s[10:11] offset:64 sc1
	global_store_dwordx4 v219, v[68:71], s[10:11] offset:512 sc1
	global_store_dwordx4 v219, v[64:67], s[10:11] offset:576 sc1
	global_load_dwordx4 v[140:143], v222, s[8:9]
	global_load_dwordx4 v[152:155], v222, s[8:9] offset:64
	global_load_dwordx4 v[156:159], v222, s[8:9] offset:512
	global_load_dwordx4 v[160:163], v222, s[8:9] offset:576
	s_waitcnt vmcnt(19)
	v_pk_fma_f32 v[60:61], v[60:61], v[198:199], v[164:165]
	v_pk_fma_f32 v[62:63], v[62:63], v[200:201], v[166:167]
	v_mul_f32_e32 v228, v60, v60
	v_fmac_f32_e32 v228, v61, v61
	v_fmac_f32_e32 v228, v62, v62
	v_fmac_f32_e32 v228, v63, v63
	s_waitcnt vmcnt(18)
	v_pk_fma_f32 v[56:57], v[56:57], v[202:203], v[168:169]
	v_pk_fma_f32 v[58:59], v[58:59], v[204:205], v[170:171]
	v_fmac_f32_e32 v228, v56, v56
	v_fmac_f32_e32 v228, v57, v57
	v_fmac_f32_e32 v228, v58, v58
	v_fmac_f32_e32 v228, v59, v59
	s_waitcnt vmcnt(17)
	v_pk_fma_f32 v[52:53], v[52:53], v[208:209], v[172:173]
	v_pk_fma_f32 v[54:55], v[54:55], v[210:211], v[174:175]
	v_fmac_f32_e32 v228, v52, v52
	v_fmac_f32_e32 v228, v53, v53
	v_fmac_f32_e32 v228, v54, v54
	v_fmac_f32_e32 v228, v55, v55
	s_waitcnt vmcnt(16)
	v_pk_fma_f32 v[44:45], v[44:45], v[214:215], v[176:177]
	v_pk_fma_f32 v[46:47], v[46:47], v[216:217], v[178:179]
	v_fmac_f32_e32 v228, v44, v44
	v_fmac_f32_e32 v228, v45, v45
	v_fmac_f32_e32 v228, v46, v46
	v_fmac_f32_e32 v228, v47, v47
	global_store_dwordx4 v250, v[60:63], s[10:11] sc1
	global_store_dwordx4 v250, v[56:59], s[10:11] offset:64 sc1
	global_store_dwordx4 v250, v[52:55], s[10:11] offset:512 sc1
	global_store_dwordx4 v250, v[44:47], s[10:11] offset:576 sc1
	global_load_dwordx4 v[164:167], v223, s[8:9]
	global_load_dwordx4 v[168:171], v223, s[8:9] offset:64
	global_load_dwordx4 v[172:175], v223, s[8:9] offset:512
	global_load_dwordx4 v[176:179], v223, s[8:9] offset:576
	s_waitcnt vmcnt(19)
	v_pk_fma_f32 v[48:49], v[48:49], v[198:199], v[180:181]
	v_pk_fma_f32 v[50:51], v[50:51], v[200:201], v[182:183]
	v_mul_f32_e32 v229, v48, v48
	v_fmac_f32_e32 v229, v49, v49
	v_fmac_f32_e32 v229, v50, v50
	v_fmac_f32_e32 v229, v51, v51
	s_waitcnt vmcnt(18)
	v_pk_fma_f32 v[40:41], v[40:41], v[202:203], v[186:187]
	v_pk_fma_f32 v[42:43], v[42:43], v[204:205], v[188:189]
	v_fmac_f32_e32 v229, v40, v40
	v_fmac_f32_e32 v229, v41, v41
	v_fmac_f32_e32 v229, v42, v42
	v_fmac_f32_e32 v229, v43, v43
	s_waitcnt vmcnt(17)
	v_pk_fma_f32 v[36:37], v[36:37], v[208:209], v[190:191]
	v_pk_fma_f32 v[38:39], v[38:39], v[210:211], v[192:193]
	v_fmac_f32_e32 v229, v36, v36
	v_fmac_f32_e32 v229, v37, v37
	v_fmac_f32_e32 v229, v38, v38
	v_fmac_f32_e32 v229, v39, v39
	s_waitcnt vmcnt(16)
	v_pk_fma_f32 v[28:29], v[28:29], v[214:215], v[194:195]
	v_pk_fma_f32 v[30:31], v[30:31], v[216:217], v[196:197]
	v_fmac_f32_e32 v229, v28, v28
	v_fmac_f32_e32 v229, v29, v29
	v_fmac_f32_e32 v229, v30, v30
	v_fmac_f32_e32 v229, v31, v31
	global_store_dwordx4 v251, v[48:51], s[10:11] sc1
	global_store_dwordx4 v251, v[40:43], s[10:11] offset:64 sc1
	global_store_dwordx4 v251, v[36:39], s[10:11] offset:512 sc1
	global_store_dwordx4 v251, v[28:31], s[10:11] offset:576 sc1
	s_waitcnt vmcnt(15)
;     __device__ __forceinline__ void operator()(const f32x4 (&acc)[2][2][4][2], const Unit& u, int wr, int wc, int fr, int fq) const {
;     ...
;         for (int ai = 0; ai < 2; ++ai)
; #pragma unroll
;             for (int m = 0; m < 4; ++m) {
;                 const int row = u.pm * BM + ai * HALF + wr * 64 + m * 16 + fr;
;                 const float* s = row < MX_ ? src_main + (size_t)row * D_ : src_ctx + (size_t)(row - MX_) * D_;
;                 float* d = row < MX_ ? dst_main + (size_t)row * D_ : dst_ctx + (size_t)(row - MX_) * D_;
; #pragma unroll
;                 for (int bj = 0; bj < 2; ++bj)
; #pragma unroll
;                     for (int n = 0; n < 2; ++n) { const int off = col0 + bj * HALF + n * 16; const f32x4 xo = *(const f32x4*)(s + off); *(f32x4*)(d + off) = xo + gv[bj][n] * acc[ai][bj][m][n]; }
; __device__ __forceinline__ void modpass(const float* xs_main, const float* xs_ctx, const float* mod_l, const float* g, int i, bf16_t* H, int nrows, int gw, int NGW, int lane) {
;     ...
;         const float rstd = 1.0f / sqrtf(wave_sum(ss) * (1.0f / D) + EPS);
	v_pk_fma_f32 v[32:33], v[32:33], v[198:199], v[140:141]
	v_pk_fma_f32 v[34:35], v[34:35], v[200:201], v[142:143]
	v_mul_f32_e32 v230, v32, v32
	v_fmac_f32_e32 v230, v33, v33
	v_fmac_f32_e32 v230, v34, v34
	v_fmac_f32_e32 v230, v35, v35
	s_waitcnt vmcnt(14)
	v_pk_fma_f32 v[24:25], v[24:25], v[202:203], v[152:153]
	v_pk_fma_f32 v[26:27], v[26:27], v[204:205], v[154:155]
	v_fmac_f32_e32 v230, v24, v24
	v_fmac_f32_e32 v230, v25, v25
	v_fmac_f32_e32 v230, v26, v26
	v_fmac_f32_e32 v230, v27, v27
	s_waitcnt vmcnt(13)
	v_pk_fma_f32 v[20:21], v[20:21], v[208:209], v[156:157]
	v_pk_fma_f32 v[22:23], v[22:23], v[210:211], v[158:159]
	v_fmac_f32_e32 v230, v20, v20
	v_fmac_f32_e32 v230, v21, v21
	v_fmac_f32_e32 v230, v22, v22
	v_fmac_f32_e32 v230, v23, v23
	s_waitcnt vmcnt(12)
	v_pk_fma_f32 v[12:13], v[12:13], v[214:215], v[160:161]
	v_pk_fma_f32 v[14:15], v[14:15], v[216:217], v[162:163]
	v_fmac_f32_e32 v230, v12, v12
	v_fmac_f32_e32 v230, v13, v13
	v_fmac_f32_e32 v230, v14, v14
	v_fmac_f32_e32 v230, v15, v15
	global_store_dwordx4 v222, v[32:35], s[10:11] sc1
	global_store_dwordx4 v222, v[24:27], s[10:11] offset:64 sc1
	global_store_dwordx4 v222, v[20:23], s[10:11] offset:512 sc1
	global_store_dwordx4 v222, v[12:15], s[10:11] offset:576 sc1
	s_waitcnt vmcnt(11)
	v_pk_fma_f32 v[16:17], v[16:17], v[198:199], v[164:165]
	v_pk_fma_f32 v[18:19], v[18:19], v[200:201], v[166:167]
	v_mul_f32_e32 v231, v16, v16
	v_fmac_f32_e32 v231, v17, v17
	v_fmac_f32_e32 v231, v18, v18
	v_fmac_f32_e32 v231, v19, v19
	s_waitcnt vmcnt(10)
	v_pk_fma_f32 v[8:9], v[8:9], v[202:203], v[168:169]
	v_pk_fma_f32 v[10:11], v[10:11], v[204:205], v[170:171]
	v_fmac_f32_e32 v231, v8, v8
	v_fmac_f32_e32 v231, v9, v9
	v_fmac_f32_e32 v231, v10, v10
	v_fmac_f32_e32 v231, v11, v11
	s_waitcnt vmcnt(9)
	v_pk_fma_f32 v[4:5], v[4:5], v[208:209], v[172:173]
	v_pk_fma_f32 v[6:7], v[6:7], v[210:211], v[174:175]
	v_fmac_f32_e32 v231, v4, v4
	v_fmac_f32_e32 v231, v5, v5
	v_fmac_f32_e32 v231, v6, v6
	v_fmac_f32_e32 v231, v7, v7
	s_waitcnt vmcnt(8)
	v_pk_fma_f32 v[0:1], v[0:1], v[214:215], v[176:177]
	v_pk_fma_f32 v[2:3], v[2:3], v[216:217], v[178:179]
	v_fmac_f32_e32 v231, v0, v0
	v_fmac_f32_e32 v231, v1, v1
	v_fmac_f32_e32 v231, v2, v2
	v_fmac_f32_e32 v231, v3, v3
	global_store_dwordx4 v223, v[16:19], s[10:11] sc1
	global_store_dwordx4 v223, v[8:11], s[10:11] offset:64 sc1
	global_store_dwordx4 v223, v[4:7], s[10:11] offset:512 sc1
	global_store_dwordx4 v223, v[0:3], s[10:11] offset:576 sc1
	v_mbcnt_lo_u32_b32 v232, -1, 0
	v_mbcnt_hi_u32_b32 v232, -1, v232
	v_xor_b32_e32 v233, 16, v232
	v_xor_b32_e32 v234, 32, v232
	v_lshlrev_b32_e32 v233, 2, v233
	v_lshlrev_b32_e32 v234, 2, v234
	s_waitcnt lgkmcnt(0)
	ds_bpermute_b32 v140, v233, v224
	ds_bpermute_b32 v141, v233, v225
	ds_bpermute_b32 v142, v233, v226
	ds_bpermute_b32 v143, v233, v227
	ds_bpermute_b32 v152, v233, v228
	ds_bpermute_b32 v153, v233, v229
	ds_bpermute_b32 v154, v233, v230
	ds_bpermute_b32 v155, v233, v231
	s_waitcnt lgkmcnt(7)
	v_add_f32_e32 v224, v224, v140
	s_waitcnt lgkmcnt(6)
	v_add_f32_e32 v225, v225, v141
	s_waitcnt lgkmcnt(5)
	v_add_f32_e32 v226, v226, v142
	s_waitcnt lgkmcnt(4)
	v_add_f32_e32 v227, v227, v143
	s_waitcnt lgkmcnt(3)
	v_add_f32_e32 v228, v228, v152
	s_waitcnt lgkmcnt(2)
	v_add_f32_e32 v229, v229, v153
	s_waitcnt lgkmcnt(1)
	v_add_f32_e32 v230, v230, v154
	s_waitcnt lgkmcnt(0)
	v_add_f32_e32 v231, v231, v155
	ds_bpermute_b32 v140, v234, v224
	ds_bpermute_b32 v141, v234, v225
	ds_bpermute_b32 v142, v234, v226
	ds_bpermute_b32 v143, v234, v227
	ds_bpermute_b32 v152, v234, v228
	ds_bpermute_b32 v153, v234, v229
	ds_bpermute_b32 v154, v234, v230
	ds_bpermute_b32 v155, v234, v231
	s_waitcnt lgkmcnt(7)
	v_add_f32_e32 v224, v224, v140
	s_waitcnt lgkmcnt(6)
	v_add_f32_e32 v225, v225, v141
	s_waitcnt lgkmcnt(5)
	v_add_f32_e32 v226, v226, v142
	s_waitcnt lgkmcnt(4)
	v_add_f32_e32 v227, v227, v143
	s_waitcnt lgkmcnt(3)
	v_add_f32_e32 v228, v228, v152
	s_waitcnt lgkmcnt(2)
	v_add_f32_e32 v229, v229, v153
	s_waitcnt lgkmcnt(1)
	v_add_f32_e32 v230, v230, v154
	s_waitcnt lgkmcnt(0)
	v_add_f32_e32 v231, v231, v155
	v_lshlrev_b32_e32 v235, 2, v144
	s_add_u32 s90, s76, 0x6500000
	s_addc_u32 s91, s77, 0
	s_add_u32 s76, s76, 0x3120000
	s_addc_u32 s77, s77, 0
	s_lshl_b32 s83, s65, 6
	s_add_u32 s78, s76, s83
	s_addc_u32 s79, s77, 0
	s_add_u32 s78, s78, 0x20000
	s_addc_u32 s79, s79, 0
	s_mov_b64 s[80:81], exec
	s_mov_b64 exec, 0xffff
	global_atomic_add_f32 v235, v224, s[76:77]
	global_atomic_add_f32 v235, v225, s[76:77] offset:64
	global_atomic_add_f32 v235, v226, s[76:77] offset:128
	global_atomic_add_f32 v235, v227, s[76:77] offset:192
	global_atomic_add_f32 v235, v228, s[76:77] offset:512
	global_atomic_add_f32 v235, v229, s[76:77] offset:576
	global_atomic_add_f32 v235, v230, s[76:77] offset:640
	global_atomic_add_f32 v235, v231, s[76:77] offset:704
	s_mov_b64 exec, s[80:81]
	s_add_u32 s86, s26, 0x1000
	s_addc_u32 s87, s27, 0
	s_add_u32 s88, s86, 0x1000
	s_addc_u32 s89, s87, 0
	s_add_u32 s92, s92, 0x1000
	s_addc_u32 s93, s93, 0
	s_mov_b32 s84, 0xffff0000
	s_mov_b32 s85, 0xffff0000
	s_waitcnt vmcnt(0)
	s_barrier
	v_readfirstlane_b32 s83, v206
	v_mov_b32_e32 v236, 0
	v_mov_b32_e32 v237, 1
	s_cmp_lg_u32 s83, 0
	s_cbranch_scc1 .Lfmas_wait_done
	s_mov_b64 exec, 1
	global_atomic_add v236, v237, s[78:79]
	s_mov_b32 s82, 0

; __device__ __forceinline__ unsigned cvtpk_s(float lo, float hi) { f32x2_t v = {lo, hi}; bf16x2_t b = __builtin_convertvector(v, bf16x2_t); return __builtin_bit_cast(unsigned, b); }
; __device__ __forceinline__ void modpass(const float* xs_main, const float* xs_ctx, const float* mod_l, const float* g, int i, bf16_t* H, int nrows, int gw, int NGW, int lane) {
;     ...
;         if (cond != cur) { cur = cond; const float* shift = mod_l + cond * 9216 + 3 * i * 1024; const float* scale = shift + 1024;
; #pragma unroll
;             for (int j = 0; j < 2; ++j)
; #pragma unroll
;                 for (int q = 0; q < 2; ++q) { const int c = 8 * lane + 512 * j + 4 * q; gm[j][q] = *(const f32x4*)(g + c) * (*(const f32x4*)(scale + c) + 1.0f); sh[j][q] = *(const f32x4*)(shift + c); } }
;         float ss = 0.f;
; #pragma unroll
;         for (int j = 0; j < 2; ++j)
; #pragma unroll
;             for (int q = 0; q < 2; ++q) ss += (v[j][q][0] * v[j][q][0] + v[j][q][1] * v[j][q][1]) + (v[j][q][2] * v[j][q][2] + v[j][q][3] * v[j][q][3]);
;         const float rstd = 1.0f / sqrtf(wave_sum(ss) * (1.0f / D) + EPS);
; #pragma unroll
;         for (int j = 0; j < 2; ++j) {
;             const f32x4 o0 = v[j][0] * rstd * gm[j][0] + sh[j][0], o1 = v[j][1] * rstd * gm[j][1] + sh[j][1];
;             u32x4 w; w.x = cvtpk_s(o0[0], o0[1]); w.y = cvtpk_s(o0[2], o0[3]); w.z = cvtpk_s(o1[0], o1[1]); w.w = cvtpk_s(o1[2], o1[3]);
;             *(u32x4*)(H + (size_t)row * D + 8 * lane + 512 * j) = w;
;         }
.Lfmas_wait_done:
	s_barrier
	global_load_dword v152, v235, s[76:77] sc1
	global_load_dword v153, v235, s[76:77] offset:64 sc1
	global_load_dword v154, v235, s[76:77] offset:128 sc1
	global_load_dword v155, v235, s[76:77] offset:192 sc1
	global_load_dword v156, v235, s[76:77] offset:512 sc1
	global_load_dword v157, v235, s[76:77] offset:576 sc1
	global_load_dword v158, v235, s[76:77] offset:640 sc1
	global_load_dword v159, v235, s[76:77] offset:704 sc1
	global_load_dwordx4 v[198:201], v184, s[86:87]
	global_load_dwordx4 v[202:205], v184, s[86:87] offset:64
	global_load_dwordx4 v[208:211], v184, s[86:87] offset:512
	global_load_dwordx4 v[214:217], v184, s[86:87] offset:576
	global_load_dwordx4 v[160:163], v184, s[88:89]
	global_load_dwordx4 v[164:167], v184, s[88:89] offset:64
	global_load_dwordx4 v[168:171], v184, s[88:89] offset:512
	global_load_dwordx4 v[172:175], v184, s[88:89] offset:576
	global_load_dwordx4 v[176:179], v184, s[92:93]
	global_load_dwordx4 v[180:183], v184, s[92:93] offset:64
	global_load_dwordx4 v[186:189], v184, s[92:93] offset:512
	global_load_dwordx4 v[190:193], v184, s[92:93] offset:576
	v_mov_b32_e32 v232, 12
	v_cndmask_b32_e64 v232, 0, v232, s[84:85]
	v_add_u32_e32 v232, v232, v145
	v_lshlrev_b32_e32 v232, 1, v232
	v_lshl_add_u32 v239, v144, 11, v232
	v_mov_b32_e32 v232, 0x358637bd
	s_waitcnt vmcnt(0)
	v_fmamk_f32 v152, v152, 0x3a800000, v232
	v_fmamk_f32 v153, v153, 0x3a800000, v232
	v_fmamk_f32 v154, v154, 0x3a800000, v232
	v_fmamk_f32 v155, v155, 0x3a800000, v232
	v_fmamk_f32 v156, v156, 0x3a800000, v232
	v_fmamk_f32 v157, v157, 0x3a800000, v232
	v_fmamk_f32 v158, v158, 0x3a800000, v232
	v_fmamk_f32 v159, v159, 0x3a800000, v232
	v_rsq_f32_e32 v152, v152
	v_rsq_f32_e32 v153, v153
	v_rsq_f32_e32 v154, v154
	v_rsq_f32_e32 v155, v155
	v_rsq_f32_e32 v156, v156
	v_rsq_f32_e32 v157, v157
	v_rsq_f32_e32 v158, v158
	v_rsq_f32_e32 v159, v159
	v_pk_add_f32 v[160:161], v[160:161], 1.0 op_sel_hi:[1,0]
	v_pk_mul_f32 v[160:161], v[176:177], v[160:161]
	v_pk_add_f32 v[162:163], v[162:163], 1.0 op_sel_hi:[1,0]
	v_pk_mul_f32 v[162:163], v[178:179], v[162:163]
	v_pk_add_f32 v[164:165], v[164:165], 1.0 op_sel_hi:[1,0]
	v_pk_mul_f32 v[164:165], v[180:181], v[164:165]
	v_pk_add_f32 v[166:167], v[166:167], 1.0 op_sel_hi:[1,0]
	v_pk_mul_f32 v[166:167], v[182:183], v[166:167]
	v_pk_add_f32 v[168:169], v[168:169], 1.0 op_sel_hi:[1,0]
	v_pk_mul_f32 v[168:169], v[186:187], v[168:169]
	v_pk_add_f32 v[170:171], v[170:171], 1.0 op_sel_hi:[1,0]
	v_pk_mul_f32 v[170:171], v[188:189], v[170:171]
	v_pk_add_f32 v[172:173], v[172:173], 1.0 op_sel_hi:[1,0]
	v_pk_mul_f32 v[172:173], v[190:191], v[172:173]
	v_pk_add_f32 v[174:175], v[174:175], 1.0 op_sel_hi:[1,0]
	v_pk_mul_f32 v[174:175], v[192:193], v[174:175]
	v_mul_f32_e32 v124, v124, v152
	v_mul_f32_e32 v125, v125, v152
	v_pk_fma_f32 v[124:125], v[160:161], v[124:125], v[198:199]
	v_mul_f32_e32 v126, v126, v152
	v_mul_f32_e32 v127, v127, v152
	v_pk_fma_f32 v[126:127], v[162:163], v[126:127], v[200:201]
	v_cvt_pk_bf16_f32 v186, v124, v125
	v_cvt_pk_bf16_f32 v187, v126, v127
	v_mul_f32_e32 v120, v120, v152
	v_mul_f32_e32 v121, v121, v152
	v_pk_fma_f32 v[120:121], v[164:165], v[120:121], v[202:203]
	v_mul_f32_e32 v122, v122, v152
	v_mul_f32_e32 v123, v123, v152
	v_pk_fma_f32 v[122:123], v[166:167], v[122:123], v[204:205]
	v_cvt_pk_bf16_f32 v188, v120, v121
	v_cvt_pk_bf16_f32 v189, v122, v123
	v_mul_f32_e32 v116, v116, v152
	v_mul_f32_e32 v117, v117, v152
	v_pk_fma_f32 v[116:117], v[168:169], v[116:117], v[208:209]
	v_mul_f32_e32 v118, v118, v152
	v_mul_f32_e32 v119, v119, v152
	v_pk_fma_f32 v[118:119], v[170:171], v[118:119], v[210:211]
	v_cvt_pk_bf16_f32 v190, v116, v117
	v_cvt_pk_bf16_f32 v191, v118, v119
	v_mul_f32_e32 v108, v108, v152
	v_mul_f32_e32 v109, v109, v152
	v_pk_fma_f32 v[108:109], v[172:173], v[108:109], v[214:215]
	v_mul_f32_e32 v110, v110, v152
	v_mul_f32_e32 v111, v111, v152
	v_pk_fma_f32 v[110:111], v[174:175], v[110:111], v[216:217]
	v_cvt_pk_bf16_f32 v192, v108, v109
	v_cvt_pk_bf16_f32 v193, v110, v111
	v_mov_b32_e32 v232, v239
	v_cndmask_b32_e64 v194, v188, v186, s[84:85]
	v_cndmask_b32_e64 v195, v189, v187, s[84:85]
	ds_bpermute_b32 v196, v233, v194
	ds_bpermute_b32 v197, v233, v195
	s_waitcnt lgkmcnt(0)
	v_cndmask_b32_e64 v176, v186, v196, s[84:85]
	v_cndmask_b32_e64 v177, v187, v197, s[84:85]
	v_cndmask_b32_e64 v178, v196, v188, s[84:85]
	v_cndmask_b32_e64 v179, v197, v189, s[84:85]
	global_store_dwordx4 v232, v[176:179], s[90:91] sc1
	v_cndmask_b32_e64 v194, v192, v190, s[84:85]
	v_cndmask_b32_e64 v195, v193, v191, s[84:85]
	ds_bpermute_b32 v196, v233, v194
	ds_bpermute_b32 v197, v233, v195
	s_waitcnt lgkmcnt(0)
	v_cndmask_b32_e64 v180, v190, v196, s[84:85]
	v_cndmask_b32_e64 v181, v191, v197, s[84:85]
	v_cndmask_b32_e64 v182, v196, v192, s[84:85]
	v_cndmask_b32_e64 v183, v197, v193, s[84:85]
	global_store_dwordx4 v232, v[180:183], s[90:91] offset:256 sc1
	v_mul_f32_e32 v112, v112, v153
	v_mul_f32_e32 v113, v113, v153
	v_pk_fma_f32 v[112:113], v[160:161], v[112:113], v[198:199]
	v_mul_f32_e32 v114, v114, v153
	v_mul_f32_e32 v115, v115, v153
	v_pk_fma_f32 v[114:115], v[162:163], v[114:115], v[200:201]
	v_cvt_pk_bf16_f32 v186, v112, v113
	v_cvt_pk_bf16_f32 v187, v114, v115
	v_mul_f32_e32 v104, v104, v153
	v_mul_f32_e32 v105, v105, v153
	v_pk_fma_f32 v[104:105], v[164:165], v[104:105], v[202:203]
	v_mul_f32_e32 v106, v106, v153
	v_mul_f32_e32 v107, v107, v153
	v_pk_fma_f32 v[106:107], v[166:167], v[106:107], v[204:205]
	v_cvt_pk_bf16_f32 v188, v104, v105
	v_cvt_pk_bf16_f32 v189, v106, v107
	v_mul_f32_e32 v100, v100, v153
	v_mul_f32_e32 v101, v101, v153
	v_pk_fma_f32 v[100:101], v[168:169], v[100:101], v[208:209]
	v_mul_f32_e32 v102, v102, v153
	v_mul_f32_e32 v103, v103, v153
	v_pk_fma_f32 v[102:103], v[170:171], v[102:103], v[210:211]
	v_cvt_pk_bf16_f32 v190, v100, v101
	v_cvt_pk_bf16_f32 v191, v102, v103
	v_mul_f32_e32 v92, v92, v153
	v_mul_f32_e32 v93, v93, v153
	v_pk_fma_f32 v[92:93], v[172:173], v[92:93], v[214:215]
	v_mul_f32_e32 v94, v94, v153
	v_mul_f32_e32 v95, v95, v153
	v_pk_fma_f32 v[94:95], v[174:175], v[94:95], v[216:217]
	v_cvt_pk_bf16_f32 v192, v92, v93
	v_cvt_pk_bf16_f32 v193, v94, v95
	v_add_u32_e32 v232, 0x8000, v239
	v_cndmask_b32_e64 v194, v188, v186, s[84:85]
	v_cndmask_b32_e64 v195, v189, v187, s[84:85]
	ds_bpermute_b32 v196, v233, v194
	ds_bpermute_b32 v197, v233, v195
	s_waitcnt lgkmcnt(0)
; __device__ __forceinline__ unsigned cvtpk_s(float lo, float hi) { f32x2_t v = {lo, hi}; bf16x2_t b = __builtin_convertvector(v, bf16x2_t); return __builtin_bit_cast(unsigned, b); }
; __device__ __forceinline__ void modpass(const float* xs_main, const float* xs_ctx, const float* mod_l, const float* g, int i, bf16_t* H, int nrows, int gw, int NGW, int lane) {
;     ...
; #pragma unroll
;         for (int j = 0; j < 2; ++j) {
;             const f32x4 o0 = v[j][0] * rstd * gm[j][0] + sh[j][0], o1 = v[j][1] * rstd * gm[j][1] + sh[j][1];
;             u32x4 w; w.x = cvtpk_s(o0[0], o0[1]); w.y = cvtpk_s(o0[2], o0[3]); w.z = cvtpk_s(o1[0], o1[1]); w.w = cvtpk_s(o1[2], o1[3]);
;             *(u32x4*)(H + (size_t)row * D + 8 * lane + 512 * j) = w;
;         }
	v_cndmask_b32_e64 v176, v186, v196, s[84:85]
	v_cndmask_b32_e64 v177, v187, v197, s[84:85]
	v_cndmask_b32_e64 v178, v196, v188, s[84:85]
	v_cndmask_b32_e64 v179, v197, v189, s[84:85]
	global_store_dwordx4 v232, v[176:179], s[90:91] sc1
	v_cndmask_b32_e64 v194, v192, v190, s[84:85]
	v_cndmask_b32_e64 v195, v193, v191, s[84:85]
	ds_bpermute_b32 v196, v233, v194
	ds_bpermute_b32 v197, v233, v195
	s_waitcnt lgkmcnt(0)
	v_cndmask_b32_e64 v180, v190, v196, s[84:85]
	v_cndmask_b32_e64 v181, v191, v197, s[84:85]
	v_cndmask_b32_e64 v182, v196, v192, s[84:85]
	v_cndmask_b32_e64 v183, v197, v193, s[84:85]
	global_store_dwordx4 v232, v[180:183], s[90:91] offset:256 sc1
	v_mul_f32_e32 v96, v96, v154
	v_mul_f32_e32 v97, v97, v154
	v_pk_fma_f32 v[96:97], v[160:161], v[96:97], v[198:199]
	v_mul_f32_e32 v98, v98, v154
	v_mul_f32_e32 v99, v99, v154
	v_pk_fma_f32 v[98:99], v[162:163], v[98:99], v[200:201]
	v_cvt_pk_bf16_f32 v186, v96, v97
	v_cvt_pk_bf16_f32 v187, v98, v99
	v_mul_f32_e32 v88, v88, v154
	v_mul_f32_e32 v89, v89, v154
	v_pk_fma_f32 v[88:89], v[164:165], v[88:89], v[202:203]
	v_mul_f32_e32 v90, v90, v154
	v_mul_f32_e32 v91, v91, v154
	v_pk_fma_f32 v[90:91], v[166:167], v[90:91], v[204:205]
	v_cvt_pk_bf16_f32 v188, v88, v89
	v_cvt_pk_bf16_f32 v189, v90, v91
	v_mul_f32_e32 v84, v84, v154
	v_mul_f32_e32 v85, v85, v154
	v_pk_fma_f32 v[84:85], v[168:169], v[84:85], v[208:209]
	v_mul_f32_e32 v86, v86, v154
	v_mul_f32_e32 v87, v87, v154
	v_pk_fma_f32 v[86:87], v[170:171], v[86:87], v[210:211]
	v_cvt_pk_bf16_f32 v190, v84, v85
	v_cvt_pk_bf16_f32 v191, v86, v87
	v_mul_f32_e32 v76, v76, v154
	v_mul_f32_e32 v77, v77, v154
	v_pk_fma_f32 v[76:77], v[172:173], v[76:77], v[214:215]
	v_mul_f32_e32 v78, v78, v154
	v_mul_f32_e32 v79, v79, v154
	v_pk_fma_f32 v[78:79], v[174:175], v[78:79], v[216:217]
	v_cvt_pk_bf16_f32 v192, v76, v77
	v_cvt_pk_bf16_f32 v193, v78, v79
	v_add_u32_e32 v232, 0x10000, v239
	v_cndmask_b32_e64 v194, v188, v186, s[84:85]
	v_cndmask_b32_e64 v195, v189, v187, s[84:85]
	ds_bpermute_b32 v196, v233, v194
	ds_bpermute_b32 v197, v233, v195
	s_waitcnt lgkmcnt(0)
	v_cndmask_b32_e64 v176, v186, v196, s[84:85]
	v_cndmask_b32_e64 v177, v187, v197, s[84:85]
	v_cndmask_b32_e64 v178, v196, v188, s[84:85]
	v_cndmask_b32_e64 v179, v197, v189, s[84:85]
	global_store_dwordx4 v232, v[176:179], s[90:91] sc1
	v_cndmask_b32_e64 v194, v192, v190, s[84:85]
	v_cndmask_b32_e64 v195, v193, v191, s[84:85]
	ds_bpermute_b32 v196, v233, v194
	ds_bpermute_b32 v197, v233, v195
	s_waitcnt lgkmcnt(0)
	v_cndmask_b32_e64 v180, v190, v196, s[84:85]
	v_cndmask_b32_e64 v181, v191, v197, s[84:85]
	v_cndmask_b32_e64 v182, v196, v192, s[84:85]
	v_cndmask_b32_e64 v183, v197, v193, s[84:85]
	global_store_dwordx4 v232, v[180:183], s[90:91] offset:256 sc1
	v_mul_f32_e32 v80, v80, v155
	v_mul_f32_e32 v81, v81, v155
	v_pk_fma_f32 v[80:81], v[160:161], v[80:81], v[198:199]
	v_mul_f32_e32 v82, v82, v155
	v_mul_f32_e32 v83, v83, v155
	v_pk_fma_f32 v[82:83], v[162:163], v[82:83], v[200:201]
	v_cvt_pk_bf16_f32 v186, v80, v81
	v_cvt_pk_bf16_f32 v187, v82, v83
	v_mul_f32_e32 v72, v72, v155
	v_mul_f32_e32 v73, v73, v155
	v_pk_fma_f32 v[72:73], v[164:165], v[72:73], v[202:203]
	v_mul_f32_e32 v74, v74, v155
	v_mul_f32_e32 v75, v75, v155
	v_pk_fma_f32 v[74:75], v[166:167], v[74:75], v[204:205]
	v_cvt_pk_bf16_f32 v188, v72, v73
	v_cvt_pk_bf16_f32 v189, v74, v75
	v_mul_f32_e32 v68, v68, v155
	v_mul_f32_e32 v69, v69, v155
	v_pk_fma_f32 v[68:69], v[168:169], v[68:69], v[208:209]
	v_mul_f32_e32 v70, v70, v155
	v_mul_f32_e32 v71, v71, v155
	v_pk_fma_f32 v[70:71], v[170:171], v[70:71], v[210:211]
	v_cvt_pk_bf16_f32 v190, v68, v69
	v_cvt_pk_bf16_f32 v191, v70, v71
	v_mul_f32_e32 v64, v64, v155
	v_mul_f32_e32 v65, v65, v155
	v_pk_fma_f32 v[64:65], v[172:173], v[64:65], v[214:215]
	v_mul_f32_e32 v66, v66, v155
	v_mul_f32_e32 v67, v67, v155
	v_pk_fma_f32 v[66:67], v[174:175], v[66:67], v[216:217]
	v_cvt_pk_bf16_f32 v192, v64, v65
	v_cvt_pk_bf16_f32 v193, v66, v67
	v_add_u32_e32 v232, 0x18000, v239
	v_cndmask_b32_e64 v194, v188, v186, s[84:85]
	v_cndmask_b32_e64 v195, v189, v187, s[84:85]
	ds_bpermute_b32 v196, v233, v194
	ds_bpermute_b32 v197, v233, v195
	s_waitcnt lgkmcnt(0)
	v_cndmask_b32_e64 v176, v186, v196, s[84:85]
	v_cndmask_b32_e64 v177, v187, v197, s[84:85]
	v_cndmask_b32_e64 v178, v196, v188, s[84:85]
	v_cndmask_b32_e64 v179, v197, v189, s[84:85]
	global_store_dwordx4 v232, v[176:179], s[90:91] sc1
	v_cndmask_b32_e64 v194, v192, v190, s[84:85]
	v_cndmask_b32_e64 v195, v193, v191, s[84:85]
	ds_bpermute_b32 v196, v233, v194
	ds_bpermute_b32 v197, v233, v195
	s_waitcnt lgkmcnt(0)
	v_cndmask_b32_e64 v180, v190, v196, s[84:85]
	v_cndmask_b32_e64 v181, v191, v197, s[84:85]
	v_cndmask_b32_e64 v182, v196, v192, s[84:85]
	v_cndmask_b32_e64 v183, v197, v193, s[84:85]
	global_store_dwordx4 v232, v[180:183], s[90:91] offset:256 sc1
	v_mul_f32_e32 v60, v60, v156
	v_mul_f32_e32 v61, v61, v156
	v_pk_fma_f32 v[60:61], v[160:161], v[60:61], v[198:199]
	v_mul_f32_e32 v62, v62, v156
	v_mul_f32_e32 v63, v63, v156
	v_pk_fma_f32 v[62:63], v[162:163], v[62:63], v[200:201]
	v_cvt_pk_bf16_f32 v186, v60, v61
	v_cvt_pk_bf16_f32 v187, v62, v63
	v_mul_f32_e32 v56, v56, v156
	v_mul_f32_e32 v57, v57, v156
	v_pk_fma_f32 v[56:57], v[164:165], v[56:57], v[202:203]
	v_mul_f32_e32 v58, v58, v156
	v_mul_f32_e32 v59, v59, v156
	v_pk_fma_f32 v[58:59], v[166:167], v[58:59], v[204:205]
	v_cvt_pk_bf16_f32 v188, v56, v57
	v_cvt_pk_bf16_f32 v189, v58, v59
	v_mul_f32_e32 v52, v52, v156
	v_mul_f32_e32 v53, v53, v156
	v_pk_fma_f32 v[52:53], v[168:169], v[52:53], v[208:209]
	v_mul_f32_e32 v54, v54, v156
	v_mul_f32_e32 v55, v55, v156
	v_pk_fma_f32 v[54:55], v[170:171], v[54:55], v[210:211]
	v_cvt_pk_bf16_f32 v190, v52, v53
	v_cvt_pk_bf16_f32 v191, v54, v55
	v_mul_f32_e32 v44, v44, v156
	v_mul_f32_e32 v45, v45, v156
	v_pk_fma_f32 v[44:45], v[172:173], v[44:45], v[214:215]
	v_mul_f32_e32 v46, v46, v156
	v_mul_f32_e32 v47, v47, v156
	v_pk_fma_f32 v[46:47], v[174:175], v[46:47], v[216:217]
	v_cvt_pk_bf16_f32 v192, v44, v45
	v_cvt_pk_bf16_f32 v193, v46, v47
	v_add_u32_e32 v232, 0x40000, v239
	v_cndmask_b32_e64 v194, v188, v186, s[84:85]
	v_cndmask_b32_e64 v195, v189, v187, s[84:85]
	ds_bpermute_b32 v196, v233, v194
	ds_bpermute_b32 v197, v233, v195
	s_waitcnt lgkmcnt(0)
; __device__ __forceinline__ unsigned cvtpk_s(float lo, float hi) { f32x2_t v = {lo, hi}; bf16x2_t b = __builtin_convertvector(v, bf16x2_t); return __builtin_bit_cast(unsigned, b); }
;     ...
;         if constexpr (!Epi::AFTER_DRAIN) { E(acc, cur, wr, wc, fr, fq); S.done(cur); }
;         if (!has_next) break;
; __device__ __forceinline__ void modpass(const float* xs_main, const float* xs_ctx, const float* mod_l, const float* g, int i, bf16_t* H, int nrows, int gw, int NGW, int lane) {
;     ...
; #pragma unroll
;         for (int j = 0; j < 2; ++j) {
;             const f32x4 o0 = v[j][0] * rstd * gm[j][0] + sh[j][0], o1 = v[j][1] * rstd * gm[j][1] + sh[j][1];
;             u32x4 w; w.x = cvtpk_s(o0[0], o0[1]); w.y = cvtpk_s(o0[2], o0[3]); w.z = cvtpk_s(o1[0], o1[1]); w.w = cvtpk_s(o1[2], o1[3]);
;             *(u32x4*)(H + (size_t)row * D + 8 * lane + 512 * j) = w;
;         }
	v_cndmask_b32_e64 v176, v186, v196, s[84:85]
	v_cndmask_b32_e64 v177, v187, v197, s[84:85]
	v_cndmask_b32_e64 v178, v196, v188, s[84:85]
	v_cndmask_b32_e64 v179, v197, v189, s[84:85]
	global_store_dwordx4 v232, v[176:179], s[90:91] sc1
	v_cndmask_b32_e64 v194, v192, v190, s[84:85]
	v_cndmask_b32_e64 v195, v193, v191, s[84:85]
	ds_bpermute_b32 v196, v233, v194
	ds_bpermute_b32 v197, v233, v195
	s_waitcnt lgkmcnt(0)
	v_cndmask_b32_e64 v180, v190, v196, s[84:85]
	v_cndmask_b32_e64 v181, v191, v197, s[84:85]
	v_cndmask_b32_e64 v182, v196, v192, s[84:85]
	v_cndmask_b32_e64 v183, v197, v193, s[84:85]
	global_store_dwordx4 v232, v[180:183], s[90:91] offset:256 sc1
	v_mul_f32_e32 v48, v48, v157
	v_mul_f32_e32 v49, v49, v157
	v_pk_fma_f32 v[48:49], v[160:161], v[48:49], v[198:199]
	v_mul_f32_e32 v50, v50, v157
	v_mul_f32_e32 v51, v51, v157
	v_pk_fma_f32 v[50:51], v[162:163], v[50:51], v[200:201]
	v_cvt_pk_bf16_f32 v186, v48, v49
	v_cvt_pk_bf16_f32 v187, v50, v51
	v_mul_f32_e32 v40, v40, v157
	v_mul_f32_e32 v41, v41, v157
	v_pk_fma_f32 v[40:41], v[164:165], v[40:41], v[202:203]
	v_mul_f32_e32 v42, v42, v157
	v_mul_f32_e32 v43, v43, v157
	v_pk_fma_f32 v[42:43], v[166:167], v[42:43], v[204:205]
	v_cvt_pk_bf16_f32 v188, v40, v41
	v_cvt_pk_bf16_f32 v189, v42, v43
	v_mul_f32_e32 v36, v36, v157
	v_mul_f32_e32 v37, v37, v157
	v_pk_fma_f32 v[36:37], v[168:169], v[36:37], v[208:209]
	v_mul_f32_e32 v38, v38, v157
	v_mul_f32_e32 v39, v39, v157
	v_pk_fma_f32 v[38:39], v[170:171], v[38:39], v[210:211]
	v_cvt_pk_bf16_f32 v190, v36, v37
	v_cvt_pk_bf16_f32 v191, v38, v39
	v_mul_f32_e32 v28, v28, v157
	v_mul_f32_e32 v29, v29, v157
	v_pk_fma_f32 v[28:29], v[172:173], v[28:29], v[214:215]
	v_mul_f32_e32 v30, v30, v157
	v_mul_f32_e32 v31, v31, v157
	v_pk_fma_f32 v[30:31], v[174:175], v[30:31], v[216:217]
	v_cvt_pk_bf16_f32 v192, v28, v29
	v_cvt_pk_bf16_f32 v193, v30, v31
	v_add_u32_e32 v232, 0x48000, v239
	v_cndmask_b32_e64 v194, v188, v186, s[84:85]
	v_cndmask_b32_e64 v195, v189, v187, s[84:85]
	ds_bpermute_b32 v196, v233, v194
	ds_bpermute_b32 v197, v233, v195
	s_waitcnt lgkmcnt(0)
	v_cndmask_b32_e64 v176, v186, v196, s[84:85]
	v_cndmask_b32_e64 v177, v187, v197, s[84:85]
	v_cndmask_b32_e64 v178, v196, v188, s[84:85]
	v_cndmask_b32_e64 v179, v197, v189, s[84:85]
	global_store_dwordx4 v232, v[176:179], s[90:91] sc1
	v_cndmask_b32_e64 v194, v192, v190, s[84:85]
	v_cndmask_b32_e64 v195, v193, v191, s[84:85]
	ds_bpermute_b32 v196, v233, v194
	ds_bpermute_b32 v197, v233, v195
	s_waitcnt lgkmcnt(0)
	v_cndmask_b32_e64 v180, v190, v196, s[84:85]
	v_cndmask_b32_e64 v181, v191, v197, s[84:85]
	v_cndmask_b32_e64 v182, v196, v192, s[84:85]
	v_cndmask_b32_e64 v183, v197, v193, s[84:85]
	global_store_dwordx4 v232, v[180:183], s[90:91] offset:256 sc1
	v_mul_f32_e32 v32, v32, v158
	v_mul_f32_e32 v33, v33, v158
	v_pk_fma_f32 v[32:33], v[160:161], v[32:33], v[198:199]
	v_mul_f32_e32 v34, v34, v158
	v_mul_f32_e32 v35, v35, v158
	v_pk_fma_f32 v[34:35], v[162:163], v[34:35], v[200:201]
	v_cvt_pk_bf16_f32 v186, v32, v33
	v_cvt_pk_bf16_f32 v187, v34, v35
	v_mul_f32_e32 v24, v24, v158
	v_mul_f32_e32 v25, v25, v158
	v_pk_fma_f32 v[24:25], v[164:165], v[24:25], v[202:203]
	v_mul_f32_e32 v26, v26, v158
	v_mul_f32_e32 v27, v27, v158
	v_pk_fma_f32 v[26:27], v[166:167], v[26:27], v[204:205]
	v_cvt_pk_bf16_f32 v188, v24, v25
	v_cvt_pk_bf16_f32 v189, v26, v27
	v_mul_f32_e32 v20, v20, v158
	v_mul_f32_e32 v21, v21, v158
	v_pk_fma_f32 v[20:21], v[168:169], v[20:21], v[208:209]
	v_mul_f32_e32 v22, v22, v158
	v_mul_f32_e32 v23, v23, v158
	v_pk_fma_f32 v[22:23], v[170:171], v[22:23], v[210:211]
	v_cvt_pk_bf16_f32 v190, v20, v21
	v_cvt_pk_bf16_f32 v191, v22, v23
	v_mul_f32_e32 v12, v12, v158
	v_mul_f32_e32 v13, v13, v158
	v_pk_fma_f32 v[12:13], v[172:173], v[12:13], v[214:215]
	v_mul_f32_e32 v14, v14, v158
	v_mul_f32_e32 v15, v15, v158
	v_pk_fma_f32 v[14:15], v[174:175], v[14:15], v[216:217]
	v_cvt_pk_bf16_f32 v192, v12, v13
	v_cvt_pk_bf16_f32 v193, v14, v15
	v_add_u32_e32 v232, 0x50000, v239
	v_cndmask_b32_e64 v194, v188, v186, s[84:85]
	v_cndmask_b32_e64 v195, v189, v187, s[84:85]
	ds_bpermute_b32 v196, v233, v194
	ds_bpermute_b32 v197, v233, v195
	s_waitcnt lgkmcnt(0)
	v_cndmask_b32_e64 v176, v186, v196, s[84:85]
	v_cndmask_b32_e64 v177, v187, v197, s[84:85]
	v_cndmask_b32_e64 v178, v196, v188, s[84:85]
	v_cndmask_b32_e64 v179, v197, v189, s[84:85]
	global_store_dwordx4 v232, v[176:179], s[90:91] sc1
	v_cndmask_b32_e64 v194, v192, v190, s[84:85]
	v_cndmask_b32_e64 v195, v193, v191, s[84:85]
	ds_bpermute_b32 v196, v233, v194
	ds_bpermute_b32 v197, v233, v195
	s_waitcnt lgkmcnt(0)
	v_cndmask_b32_e64 v180, v190, v196, s[84:85]
	v_cndmask_b32_e64 v181, v191, v197, s[84:85]
	v_cndmask_b32_e64 v182, v196, v192, s[84:85]
	v_cndmask_b32_e64 v183, v197, v193, s[84:85]
	global_store_dwordx4 v232, v[180:183], s[90:91] offset:256 sc1
	v_mul_f32_e32 v16, v16, v159
	v_mul_f32_e32 v17, v17, v159
	v_pk_fma_f32 v[16:17], v[160:161], v[16:17], v[198:199]
	v_mul_f32_e32 v18, v18, v159
	v_mul_f32_e32 v19, v19, v159
	v_pk_fma_f32 v[18:19], v[162:163], v[18:19], v[200:201]
	v_cvt_pk_bf16_f32 v186, v16, v17
	v_cvt_pk_bf16_f32 v187, v18, v19
	v_mul_f32_e32 v8, v8, v159
	v_mul_f32_e32 v9, v9, v159
	v_pk_fma_f32 v[8:9], v[164:165], v[8:9], v[202:203]
	v_mul_f32_e32 v10, v10, v159
	v_mul_f32_e32 v11, v11, v159
	v_pk_fma_f32 v[10:11], v[166:167], v[10:11], v[204:205]
	v_cvt_pk_bf16_f32 v188, v8, v9
	v_cvt_pk_bf16_f32 v189, v10, v11
	v_mul_f32_e32 v4, v4, v159
	v_mul_f32_e32 v5, v5, v159
	v_pk_fma_f32 v[4:5], v[168:169], v[4:5], v[208:209]
	v_mul_f32_e32 v6, v6, v159
	v_mul_f32_e32 v7, v7, v159
	v_pk_fma_f32 v[6:7], v[170:171], v[6:7], v[210:211]
	v_cvt_pk_bf16_f32 v190, v4, v5
	v_cvt_pk_bf16_f32 v191, v6, v7
	v_mul_f32_e32 v0, v0, v159
	v_mul_f32_e32 v1, v1, v159
	v_pk_fma_f32 v[0:1], v[172:173], v[0:1], v[214:215]
	v_mul_f32_e32 v2, v2, v159
	v_mul_f32_e32 v3, v3, v159
	v_pk_fma_f32 v[2:3], v[174:175], v[2:3], v[216:217]
	v_cvt_pk_bf16_f32 v192, v0, v1
	v_cvt_pk_bf16_f32 v193, v2, v3
	v_add_u32_e32 v232, 0x58000, v239
	v_cndmask_b32_e64 v194, v188, v186, s[84:85]
	v_cndmask_b32_e64 v195, v189, v187, s[84:85]
	ds_bpermute_b32 v196, v233, v194
	ds_bpermute_b32 v197, v233, v195
	s_waitcnt lgkmcnt(0)
	v_cndmask_b32_e64 v176, v186, v196, s[84:85]
	v_cndmask_b32_e64 v177, v187, v197, s[84:85]
	v_cndmask_b32_e64 v178, v196, v188, s[84:85]
	v_cndmask_b32_e64 v179, v197, v189, s[84:85]
	global_store_dwordx4 v232, v[176:179], s[90:91] sc1
	v_cndmask_b32_e64 v194, v192, v190, s[84:85]
	v_cndmask_b32_e64 v195, v193, v191, s[84:85]
	ds_bpermute_b32 v196, v233, v194
	ds_bpermute_b32 v197, v233, v195
	s_waitcnt lgkmcnt(0)
	v_cndmask_b32_e64 v180, v190, v196, s[84:85]
	v_cndmask_b32_e64 v181, v191, v197, s[84:85]
	v_cndmask_b32_e64 v182, v196, v192, s[84:85]
	v_cndmask_b32_e64 v183, v197, v193, s[84:85]
	global_store_dwordx4 v232, v[180:183], s[90:91] offset:256 sc1
	s_and_b64 vcc, exec, s[4:5]
	s_mov_b64 s[4:5], -1
; #define PG8_BAR __builtin_amdgcn_s_barrier()
;     ...
;         if constexpr (!Epi::AFTER_DRAIN) { E(acc, cur, wr, wc, fr, fq); S.done(cur); }
;         if (!has_next) break;
; #pragma unroll
;         for (int a = 0; a < 2; ++a)
; #pragma unroll
;             for (int b = 0; b < 2; ++b)
; #pragma unroll
;                 for (int m = 0; m < 4; ++m)
; #pragma unroll
;                     for (int n = 0; n < 2; ++n) acc[a][b][m][n] = (f32x4){0.f, 0.f, 0.f, 0.f};
;         cur = nxt; cA = nA; cB = nB; ++ui;
;         if constexpr (ALIGN_EPI) { if (wr == 1) PG8_BAR; }
;     }
.Lfmdone_a:
	s_cbranch_vccnz .LBB0_300
	s_andn2_b64 vcc, exec, s[12:13]
	s_cbranch_vccnz .LBB0_299
	s_barrier
	s_branch .LBB0_299

;     __device__ __forceinline__ void operator()(const f32x4 (&acc)[2][2][4][2], const Unit& u, int wr, int wc, int fr, int fq) const {
;         const int cond = u.pm < 64 ? 0 : (u.pm < 128 ? 1 : 2);
;         const float* gate = gate_l + cond * 9216;
;         const int col0 = u.pn * BM + wc * 32 + 4 * fq;
;         f32x4 gv[2][2];
; #pragma unroll
;         for (int bj = 0; bj < 2; ++bj)
; #pragma unroll
;             for (int n = 0; n < 2; ++n) gv[bj][n] = *(const f32x4*)(gate + col0 + bj * HALF + n * 16) * coef;
; #pragma unroll
;         for (int ai = 0; ai < 2; ++ai)
; #pragma unroll
;             for (int m = 0; m < 4; ++m) {
;                 const int row = u.pm * BM + ai * HALF + wr * 64 + m * 16 + fr;
;                 const float* s = row < MX_ ? src_main + (size_t)row * D_ : src_ctx + (size_t)(row - MX_) * D_;
;                 float* d = row < MX_ ? dst_main + (size_t)row * D_ : dst_ctx + (size_t)(row - MX_) * D_;
; #pragma unroll
;                 for (int bj = 0; bj < 2; ++bj)
; #pragma unroll
;                     for (int n = 0; n < 2; ++n) { const int off = col0 + bj * HALF + n * 16; const f32x4 xo = *(const f32x4*)(s + off); *(f32x4*)(d + off) = xo + gv[bj][n] * acc[ai][bj][m][n]; }
.LBB0_1126:
	s_andn2_b64 vcc, exec, s[10:11]
	s_cbranch_vccnz .Lfmsel_c
	s_cmpk_lt_i32 s40, 0x80
	s_cselect_b32 s7, s69, 0x4800
	s_cmp_gt_i32 s40, 63
	s_cselect_b32 s7, s7, 0
	s_lshl_b32 s7, s7, 2
	s_add_u32 s8, s61, s7
	s_addc_u32 s9, s62, 0
	s_load_dwordx2 s[92:93], s[0:1], 0x30
	s_load_dwordx2 s[76:77], s[0:1], 0xb8
	v_lshl_add_u32 v156, s40, 8, v158
	v_lshl_or_b32 v157, s6, 8, v160
	v_lshlrev_b32_e32 v201, 2, v157
	v_lshl_add_u32 v224, v156, 12, v201
	global_load_dwordx4 v[196:199], v201, s[8:9]
	global_load_dwordx4 v[212:215], v201, s[8:9] offset:64
	global_load_dwordx4 v[216:219], v201, s[8:9] offset:512
	global_load_dwordx4 v[220:223], v201, s[8:9] offset:576
	v_add_u32_e32 v225, 0x10000, v224
	v_add_u32_e32 v226, 0x20000, v224
	v_add_u32_e32 v227, 0x30000, v224
	v_add_u32_e32 v228, 0x80000, v224
	v_add_u32_e32 v229, 0x90000, v224
	v_add_u32_e32 v230, 0xa0000, v224
	v_add_u32_e32 v231, 0xb0000, v224
	global_load_dwordx4 v[128:131], v224, s[12:13]
	global_load_dwordx4 v[132:135], v224, s[12:13] offset:64
	global_load_dwordx4 v[136:139], v224, s[12:13] offset:512
	global_load_dwordx4 v[140:143], v224, s[12:13] offset:576
	global_load_dwordx4 v[164:167], v225, s[12:13]
	global_load_dwordx4 v[168:171], v225, s[12:13] offset:64
	global_load_dwordx4 v[172:175], v225, s[12:13] offset:512
	global_load_dwordx4 v[176:179], v225, s[12:13] offset:576
	global_load_dwordx4 v[180:183], v226, s[12:13]
	global_load_dwordx4 v[184:187], v226, s[12:13] offset:64
	global_load_dwordx4 v[188:191], v226, s[12:13] offset:512
	global_load_dwordx4 v[192:195], v226, s[12:13] offset:576
	s_waitcnt vmcnt(12)
	s_waitcnt vmcnt(11)
	v_pk_fma_f32 v[124:125], v[124:125], v[196:197], v[128:129]
	v_pk_fma_f32 v[126:127], v[126:127], v[198:199], v[130:131]
	v_mul_f32_e32 v232, v124, v124
	v_fmac_f32_e32 v232, v125, v125
	v_fmac_f32_e32 v232, v126, v126
	v_fmac_f32_e32 v232, v127, v127
	s_waitcnt vmcnt(10)
	v_pk_fma_f32 v[120:121], v[120:121], v[212:213], v[132:133]
	v_pk_fma_f32 v[122:123], v[122:123], v[214:215], v[134:135]
	v_fmac_f32_e32 v232, v120, v120
	v_fmac_f32_e32 v232, v121, v121
	v_fmac_f32_e32 v232, v122, v122
	v_fmac_f32_e32 v232, v123, v123
	s_waitcnt vmcnt(9)
	v_pk_fma_f32 v[116:117], v[116:117], v[216:217], v[136:137]
	v_pk_fma_f32 v[118:119], v[118:119], v[218:219], v[138:139]
	v_fmac_f32_e32 v232, v116, v116
	v_fmac_f32_e32 v232, v117, v117
	v_fmac_f32_e32 v232, v118, v118
	v_fmac_f32_e32 v232, v119, v119
	s_waitcnt vmcnt(8)
	v_pk_fma_f32 v[112:113], v[112:113], v[220:221], v[140:141]
	v_pk_fma_f32 v[114:115], v[114:115], v[222:223], v[142:143]
	v_fmac_f32_e32 v232, v112, v112
	v_fmac_f32_e32 v232, v113, v113
	v_fmac_f32_e32 v232, v114, v114
	v_fmac_f32_e32 v232, v115, v115
	global_store_dwordx4 v224, v[124:127], s[12:13]
	global_store_dwordx4 v224, v[120:123], s[12:13] offset:64
	global_store_dwordx4 v224, v[116:119], s[12:13] offset:512
	global_store_dwordx4 v224, v[112:115], s[12:13] offset:576
	global_load_dwordx4 v[128:131], v227, s[12:13]
	global_load_dwordx4 v[132:135], v227, s[12:13] offset:64
	global_load_dwordx4 v[136:139], v227, s[12:13] offset:512
	global_load_dwordx4 v[140:143], v227, s[12:13] offset:576
	s_waitcnt vmcnt(15)
	v_pk_fma_f32 v[108:109], v[108:109], v[196:197], v[164:165]
	v_pk_fma_f32 v[110:111], v[110:111], v[198:199], v[166:167]
	v_mul_f32_e32 v233, v108, v108
	v_fmac_f32_e32 v233, v109, v109
	v_fmac_f32_e32 v233, v110, v110
	v_fmac_f32_e32 v233, v111, v111
	s_waitcnt vmcnt(14)
	v_pk_fma_f32 v[104:105], v[104:105], v[212:213], v[168:169]
	v_pk_fma_f32 v[106:107], v[106:107], v[214:215], v[170:171]
	v_fmac_f32_e32 v233, v104, v104
	v_fmac_f32_e32 v233, v105, v105
	v_fmac_f32_e32 v233, v106, v106
	v_fmac_f32_e32 v233, v107, v107
	s_waitcnt vmcnt(13)
	v_pk_fma_f32 v[100:101], v[100:101], v[216:217], v[172:173]
	v_pk_fma_f32 v[102:103], v[102:103], v[218:219], v[174:175]
	v_fmac_f32_e32 v233, v100, v100
	v_fmac_f32_e32 v233, v101, v101
	v_fmac_f32_e32 v233, v102, v102
	v_fmac_f32_e32 v233, v103, v103
	s_waitcnt vmcnt(12)
	v_pk_fma_f32 v[96:97], v[96:97], v[220:221], v[176:177]
	v_pk_fma_f32 v[98:99], v[98:99], v[222:223], v[178:179]
	v_fmac_f32_e32 v233, v96, v96
	v_fmac_f32_e32 v233, v97, v97
	v_fmac_f32_e32 v233, v98, v98
	v_fmac_f32_e32 v233, v99, v99
	global_store_dwordx4 v225, v[108:111], s[12:13]
	global_store_dwordx4 v225, v[104:107], s[12:13] offset:64
	global_store_dwordx4 v225, v[100:103], s[12:13] offset:512
	global_store_dwordx4 v225, v[96:99], s[12:13] offset:576
	global_load_dwordx4 v[164:167], v228, s[12:13]
	global_load_dwordx4 v[168:171], v228, s[12:13] offset:64
	global_load_dwordx4 v[172:175], v228, s[12:13] offset:512
	global_load_dwordx4 v[176:179], v228, s[12:13] offset:576
	s_waitcnt vmcnt(19)
	v_pk_fma_f32 v[92:93], v[92:93], v[196:197], v[180:181]
	v_pk_fma_f32 v[94:95], v[94:95], v[198:199], v[182:183]
	v_mul_f32_e32 v234, v92, v92
	v_fmac_f32_e32 v234, v93, v93
	v_fmac_f32_e32 v234, v94, v94
	v_fmac_f32_e32 v234, v95, v95
	s_waitcnt vmcnt(18)
	v_pk_fma_f32 v[88:89], v[88:89], v[212:213], v[184:185]
	v_pk_fma_f32 v[90:91], v[90:91], v[214:215], v[186:187]
	v_fmac_f32_e32 v234, v88, v88
	v_fmac_f32_e32 v234, v89, v89
	v_fmac_f32_e32 v234, v90, v90
	v_fmac_f32_e32 v234, v91, v91
	s_waitcnt vmcnt(17)
	v_pk_fma_f32 v[84:85], v[84:85], v[216:217], v[188:189]
	v_pk_fma_f32 v[86:87], v[86:87], v[218:219], v[190:191]
	v_fmac_f32_e32 v234, v84, v84
	v_fmac_f32_e32 v234, v85, v85
	v_fmac_f32_e32 v234, v86, v86
	v_fmac_f32_e32 v234, v87, v87
	s_waitcnt vmcnt(16)
;     __device__ __forceinline__ void operator()(const f32x4 (&acc)[2][2][4][2], const Unit& u, int wr, int wc, int fr, int fq) const {
;     ...
;         for (int ai = 0; ai < 2; ++ai)
; #pragma unroll
;             for (int m = 0; m < 4; ++m) {
;                 const int row = u.pm * BM + ai * HALF + wr * 64 + m * 16 + fr;
;                 const float* s = row < MX_ ? src_main + (size_t)row * D_ : src_ctx + (size_t)(row - MX_) * D_;
;                 float* d = row < MX_ ? dst_main + (size_t)row * D_ : dst_ctx + (size_t)(row - MX_) * D_;
; #pragma unroll
;                 for (int bj = 0; bj < 2; ++bj)
; #pragma unroll
;                     for (int n = 0; n < 2; ++n) { const int off = col0 + bj * HALF + n * 16; const f32x4 xo = *(const f32x4*)(s + off); *(f32x4*)(d + off) = xo + gv[bj][n] * acc[ai][bj][m][n]; }
; __device__ __forceinline__ void modpass(const float* xs_main, const float* xs_ctx, const float* mod_l, const float* g, int i, bf16_t* H, int nrows, int gw, int NGW, int lane) {
;     ...
;         float ss = 0.f;
; #pragma unroll
;         for (int j = 0; j < 2; ++j)
; #pragma unroll
;             for (int q = 0; q < 2; ++q) ss += (v[j][q][0] * v[j][q][0] + v[j][q][1] * v[j][q][1]) + (v[j][q][2] * v[j][q][2] + v[j][q][3] * v[j][q][3]);
	v_pk_fma_f32 v[80:81], v[80:81], v[220:221], v[192:193]
	v_pk_fma_f32 v[82:83], v[82:83], v[222:223], v[194:195]
	v_fmac_f32_e32 v234, v80, v80
	v_fmac_f32_e32 v234, v81, v81
	v_fmac_f32_e32 v234, v82, v82
	v_fmac_f32_e32 v234, v83, v83
	global_store_dwordx4 v226, v[92:95], s[12:13]
	global_store_dwordx4 v226, v[88:91], s[12:13] offset:64
	global_store_dwordx4 v226, v[84:87], s[12:13] offset:512
	global_store_dwordx4 v226, v[80:83], s[12:13] offset:576
	global_load_dwordx4 v[180:183], v229, s[12:13]
	global_load_dwordx4 v[184:187], v229, s[12:13] offset:64
	global_load_dwordx4 v[188:191], v229, s[12:13] offset:512
	global_load_dwordx4 v[192:195], v229, s[12:13] offset:576
	s_waitcnt vmcnt(19)
	v_pk_fma_f32 v[76:77], v[76:77], v[196:197], v[128:129]
	v_pk_fma_f32 v[78:79], v[78:79], v[198:199], v[130:131]
	v_mul_f32_e32 v235, v76, v76
	v_fmac_f32_e32 v235, v77, v77
	v_fmac_f32_e32 v235, v78, v78
	v_fmac_f32_e32 v235, v79, v79
	s_waitcnt vmcnt(18)
	v_pk_fma_f32 v[72:73], v[72:73], v[212:213], v[132:133]
	v_pk_fma_f32 v[74:75], v[74:75], v[214:215], v[134:135]
	v_fmac_f32_e32 v235, v72, v72
	v_fmac_f32_e32 v235, v73, v73
	v_fmac_f32_e32 v235, v74, v74
	v_fmac_f32_e32 v235, v75, v75
	s_waitcnt vmcnt(17)
	v_pk_fma_f32 v[68:69], v[68:69], v[216:217], v[136:137]
	v_pk_fma_f32 v[70:71], v[70:71], v[218:219], v[138:139]
	v_fmac_f32_e32 v235, v68, v68
	v_fmac_f32_e32 v235, v69, v69
	v_fmac_f32_e32 v235, v70, v70
	v_fmac_f32_e32 v235, v71, v71
	s_waitcnt vmcnt(16)
	v_pk_fma_f32 v[64:65], v[64:65], v[220:221], v[140:141]
	v_pk_fma_f32 v[66:67], v[66:67], v[222:223], v[142:143]
	v_fmac_f32_e32 v235, v64, v64
	v_fmac_f32_e32 v235, v65, v65
	v_fmac_f32_e32 v235, v66, v66
	v_fmac_f32_e32 v235, v67, v67
	global_store_dwordx4 v227, v[76:79], s[12:13]
	global_store_dwordx4 v227, v[72:75], s[12:13] offset:64
	global_store_dwordx4 v227, v[68:71], s[12:13] offset:512
	global_store_dwordx4 v227, v[64:67], s[12:13] offset:576
	global_load_dwordx4 v[128:131], v230, s[12:13]
	global_load_dwordx4 v[132:135], v230, s[12:13] offset:64
	global_load_dwordx4 v[136:139], v230, s[12:13] offset:512
	global_load_dwordx4 v[140:143], v230, s[12:13] offset:576
	s_waitcnt vmcnt(19)
	v_pk_fma_f32 v[60:61], v[60:61], v[196:197], v[164:165]
	v_pk_fma_f32 v[62:63], v[62:63], v[198:199], v[166:167]
	v_mul_f32_e32 v236, v60, v60
	v_fmac_f32_e32 v236, v61, v61
	v_fmac_f32_e32 v236, v62, v62
	v_fmac_f32_e32 v236, v63, v63
	s_waitcnt vmcnt(18)
	v_pk_fma_f32 v[56:57], v[56:57], v[212:213], v[168:169]
	v_pk_fma_f32 v[58:59], v[58:59], v[214:215], v[170:171]
	v_fmac_f32_e32 v236, v56, v56
	v_fmac_f32_e32 v236, v57, v57
	v_fmac_f32_e32 v236, v58, v58
	v_fmac_f32_e32 v236, v59, v59
	s_waitcnt vmcnt(17)
	v_pk_fma_f32 v[52:53], v[52:53], v[216:217], v[172:173]
	v_pk_fma_f32 v[54:55], v[54:55], v[218:219], v[174:175]
	v_fmac_f32_e32 v236, v52, v52
	v_fmac_f32_e32 v236, v53, v53
	v_fmac_f32_e32 v236, v54, v54
	v_fmac_f32_e32 v236, v55, v55
	s_waitcnt vmcnt(16)
	v_pk_fma_f32 v[48:49], v[48:49], v[220:221], v[176:177]
	v_pk_fma_f32 v[50:51], v[50:51], v[222:223], v[178:179]
	v_fmac_f32_e32 v236, v48, v48
	v_fmac_f32_e32 v236, v49, v49
	v_fmac_f32_e32 v236, v50, v50
	v_fmac_f32_e32 v236, v51, v51
	global_store_dwordx4 v228, v[60:63], s[12:13]
	global_store_dwordx4 v228, v[56:59], s[12:13] offset:64
	global_store_dwordx4 v228, v[52:55], s[12:13] offset:512
	global_store_dwordx4 v228, v[48:51], s[12:13] offset:576
	global_load_dwordx4 v[164:167], v231, s[12:13]
	global_load_dwordx4 v[168:171], v231, s[12:13] offset:64
	global_load_dwordx4 v[172:175], v231, s[12:13] offset:512
	global_load_dwordx4 v[176:179], v231, s[12:13] offset:576
	s_waitcnt vmcnt(19)
	v_pk_fma_f32 v[44:45], v[44:45], v[196:197], v[180:181]
	v_pk_fma_f32 v[46:47], v[46:47], v[198:199], v[182:183]
	v_mul_f32_e32 v237, v44, v44
	v_fmac_f32_e32 v237, v45, v45
	v_fmac_f32_e32 v237, v46, v46
	v_fmac_f32_e32 v237, v47, v47
	s_waitcnt vmcnt(18)
	v_pk_fma_f32 v[40:41], v[40:41], v[212:213], v[184:185]
	v_pk_fma_f32 v[42:43], v[42:43], v[214:215], v[186:187]
	v_fmac_f32_e32 v237, v40, v40
	v_fmac_f32_e32 v237, v41, v41
	v_fmac_f32_e32 v237, v42, v42
	v_fmac_f32_e32 v237, v43, v43
	s_waitcnt vmcnt(17)
	v_pk_fma_f32 v[36:37], v[36:37], v[216:217], v[188:189]
	v_pk_fma_f32 v[38:39], v[38:39], v[218:219], v[190:191]
	v_fmac_f32_e32 v237, v36, v36
	v_fmac_f32_e32 v237, v37, v37
	v_fmac_f32_e32 v237, v38, v38
	v_fmac_f32_e32 v237, v39, v39
	s_waitcnt vmcnt(16)
	v_pk_fma_f32 v[32:33], v[32:33], v[220:221], v[192:193]
	v_pk_fma_f32 v[34:35], v[34:35], v[222:223], v[194:195]
	v_fmac_f32_e32 v237, v32, v32
	v_fmac_f32_e32 v237, v33, v33
	v_fmac_f32_e32 v237, v34, v34
	v_fmac_f32_e32 v237, v35, v35
	global_store_dwordx4 v229, v[44:47], s[12:13]
	global_store_dwordx4 v229, v[40:43], s[12:13] offset:64
	global_store_dwordx4 v229, v[36:39], s[12:13] offset:512
	global_store_dwordx4 v229, v[32:35], s[12:13] offset:576
	s_waitcnt vmcnt(15)
	v_pk_fma_f32 v[28:29], v[28:29], v[196:197], v[128:129]
	v_pk_fma_f32 v[30:31], v[30:31], v[198:199], v[130:131]
	v_mul_f32_e32 v238, v28, v28
	v_fmac_f32_e32 v238, v29, v29
	v_fmac_f32_e32 v238, v30, v30
	v_fmac_f32_e32 v238, v31, v31
	s_waitcnt vmcnt(14)
;     __device__ __forceinline__ void operator()(const f32x4 (&acc)[2][2][4][2], const Unit& u, int wr, int wc, int fr, int fq) const {
;     ...
;         for (int ai = 0; ai < 2; ++ai)
; #pragma unroll
;             for (int m = 0; m < 4; ++m) {
;                 const int row = u.pm * BM + ai * HALF + wr * 64 + m * 16 + fr;
;                 const float* s = row < MX_ ? src_main + (size_t)row * D_ : src_ctx + (size_t)(row - MX_) * D_;
;                 float* d = row < MX_ ? dst_main + (size_t)row * D_ : dst_ctx + (size_t)(row - MX_) * D_;
; #pragma unroll
;                 for (int bj = 0; bj < 2; ++bj)
; #pragma unroll
;                     for (int n = 0; n < 2; ++n) { const int off = col0 + bj * HALF + n * 16; const f32x4 xo = *(const f32x4*)(s + off); *(f32x4*)(d + off) = xo + gv[bj][n] * acc[ai][bj][m][n]; }
; __device__ __forceinline__ void modpass(const float* xs_main, const float* xs_ctx, const float* mod_l, const float* g, int i, bf16_t* H, int nrows, int gw, int NGW, int lane) {
;     ...
;         const float rstd = 1.0f / sqrtf(wave_sum(ss) * (1.0f / D) + EPS);
	v_pk_fma_f32 v[24:25], v[24:25], v[212:213], v[132:133]
	v_pk_fma_f32 v[26:27], v[26:27], v[214:215], v[134:135]
	v_fmac_f32_e32 v238, v24, v24
	v_fmac_f32_e32 v238, v25, v25
	v_fmac_f32_e32 v238, v26, v26
	v_fmac_f32_e32 v238, v27, v27
	s_waitcnt vmcnt(13)
	v_pk_fma_f32 v[20:21], v[20:21], v[216:217], v[136:137]
	v_pk_fma_f32 v[22:23], v[22:23], v[218:219], v[138:139]
	v_fmac_f32_e32 v238, v20, v20
	v_fmac_f32_e32 v238, v21, v21
	v_fmac_f32_e32 v238, v22, v22
	v_fmac_f32_e32 v238, v23, v23
	s_waitcnt vmcnt(12)
	v_pk_fma_f32 v[16:17], v[16:17], v[220:221], v[140:141]
	v_pk_fma_f32 v[18:19], v[18:19], v[222:223], v[142:143]
	v_fmac_f32_e32 v238, v16, v16
	v_fmac_f32_e32 v238, v17, v17
	v_fmac_f32_e32 v238, v18, v18
	v_fmac_f32_e32 v238, v19, v19
	global_store_dwordx4 v230, v[28:31], s[12:13]
	global_store_dwordx4 v230, v[24:27], s[12:13] offset:64
	global_store_dwordx4 v230, v[20:23], s[12:13] offset:512
	global_store_dwordx4 v230, v[16:19], s[12:13] offset:576
	s_waitcnt vmcnt(11)
	v_pk_fma_f32 v[12:13], v[12:13], v[196:197], v[164:165]
	v_pk_fma_f32 v[14:15], v[14:15], v[198:199], v[166:167]
	v_mul_f32_e32 v239, v12, v12
	v_fmac_f32_e32 v239, v13, v13
	v_fmac_f32_e32 v239, v14, v14
	v_fmac_f32_e32 v239, v15, v15
	s_waitcnt vmcnt(10)
	v_pk_fma_f32 v[8:9], v[8:9], v[212:213], v[168:169]
	v_pk_fma_f32 v[10:11], v[10:11], v[214:215], v[170:171]
	v_fmac_f32_e32 v239, v8, v8
	v_fmac_f32_e32 v239, v9, v9
	v_fmac_f32_e32 v239, v10, v10
	v_fmac_f32_e32 v239, v11, v11
	s_waitcnt vmcnt(9)
	v_pk_fma_f32 v[4:5], v[4:5], v[216:217], v[172:173]
	v_pk_fma_f32 v[6:7], v[6:7], v[218:219], v[174:175]
	v_fmac_f32_e32 v239, v4, v4
	v_fmac_f32_e32 v239, v5, v5
	v_fmac_f32_e32 v239, v6, v6
	v_fmac_f32_e32 v239, v7, v7
	s_waitcnt vmcnt(8)
	v_pk_fma_f32 v[0:1], v[0:1], v[220:221], v[176:177]
	v_pk_fma_f32 v[2:3], v[2:3], v[222:223], v[178:179]
	v_fmac_f32_e32 v239, v0, v0
	v_fmac_f32_e32 v239, v1, v1
	v_fmac_f32_e32 v239, v2, v2
	v_fmac_f32_e32 v239, v3, v3
	global_store_dwordx4 v231, v[12:15], s[12:13]
	global_store_dwordx4 v231, v[8:11], s[12:13] offset:64
	global_store_dwordx4 v231, v[4:7], s[12:13] offset:512
	global_store_dwordx4 v231, v[0:3], s[12:13] offset:576
	v_mbcnt_lo_u32_b32 v240, -1, 0
	v_mbcnt_hi_u32_b32 v240, -1, v240
	v_xor_b32_e32 v241, 16, v240
	v_xor_b32_e32 v242, 32, v240
	v_lshlrev_b32_e32 v241, 2, v241
	v_lshlrev_b32_e32 v242, 2, v242
	s_waitcnt lgkmcnt(0)
	ds_bpermute_b32 v128, v241, v232
	ds_bpermute_b32 v129, v241, v233
	ds_bpermute_b32 v130, v241, v234
	ds_bpermute_b32 v131, v241, v235
	ds_bpermute_b32 v132, v241, v236
	ds_bpermute_b32 v133, v241, v237
	ds_bpermute_b32 v134, v241, v238
	ds_bpermute_b32 v135, v241, v239
	s_waitcnt lgkmcnt(7)
	v_add_f32_e32 v232, v232, v128
	s_waitcnt lgkmcnt(6)
	v_add_f32_e32 v233, v233, v129
	s_waitcnt lgkmcnt(5)
	v_add_f32_e32 v234, v234, v130
	s_waitcnt lgkmcnt(4)
	v_add_f32_e32 v235, v235, v131
	s_waitcnt lgkmcnt(3)
	v_add_f32_e32 v236, v236, v132
	s_waitcnt lgkmcnt(2)
	v_add_f32_e32 v237, v237, v133
	s_waitcnt lgkmcnt(1)
	v_add_f32_e32 v238, v238, v134
	s_waitcnt lgkmcnt(0)
	v_add_f32_e32 v239, v239, v135
	ds_bpermute_b32 v128, v242, v232
	ds_bpermute_b32 v129, v242, v233
	ds_bpermute_b32 v130, v242, v234
	ds_bpermute_b32 v131, v242, v235
	ds_bpermute_b32 v132, v242, v236
	ds_bpermute_b32 v133, v242, v237
	ds_bpermute_b32 v134, v242, v238
	ds_bpermute_b32 v135, v242, v239
	s_waitcnt lgkmcnt(7)
	v_add_f32_e32 v232, v232, v128
	s_waitcnt lgkmcnt(6)
	v_add_f32_e32 v233, v233, v129
	s_waitcnt lgkmcnt(5)
	v_add_f32_e32 v234, v234, v130
	s_waitcnt lgkmcnt(4)
	v_add_f32_e32 v235, v235, v131
	s_waitcnt lgkmcnt(3)
	v_add_f32_e32 v236, v236, v132
	s_waitcnt lgkmcnt(2)
	v_add_f32_e32 v237, v237, v133
	s_waitcnt lgkmcnt(1)
	v_add_f32_e32 v238, v238, v134
	s_waitcnt lgkmcnt(0)
	v_add_f32_e32 v239, v239, v135
	v_lshlrev_b32_e32 v243, 2, v156
	s_add_u32 s90, s76, 0x6500000
	s_addc_u32 s91, s77, 0
	s_add_u32 s76, s76, 0x3142000
	s_addc_u32 s77, s77, 0
	s_lshl_b32 s83, s40, 6
	s_add_u32 s78, s76, s83
	s_addc_u32 s79, s77, 0
	s_add_u32 s78, s78, 0x20000
	s_addc_u32 s79, s79, 0
	s_mov_b64 s[80:81], exec
	s_mov_b64 exec, 0xffff
	global_atomic_add_f32 v243, v232, s[76:77]
	global_atomic_add_f32 v243, v233, s[76:77] offset:64
	global_atomic_add_f32 v243, v234, s[76:77] offset:128
	global_atomic_add_f32 v243, v235, s[76:77] offset:192
	global_atomic_add_f32 v243, v236, s[76:77] offset:512
	global_atomic_add_f32 v243, v237, s[76:77] offset:576
	global_atomic_add_f32 v243, v238, s[76:77] offset:640
	global_atomic_add_f32 v243, v239, s[76:77] offset:704
	s_mov_b64 exec, s[80:81]
	s_add_u32 s86, s8, 0x1000
	s_addc_u32 s87, s9, 0
	s_add_u32 s88, s86, 0x1000
	s_addc_u32 s89, s87, 0
	s_add_u32 s92, s92, 0x2000
	s_addc_u32 s93, s93, 0
	s_mov_b32 s84, 0xffff0000
	s_mov_b32 s85, 0xffff0000
	s_waitcnt vmcnt(0)
	s_barrier
	v_readfirstlane_b32 s83, v206
	v_mov_b32_e32 v244, 0
	v_mov_b32_e32 v245, 1
	s_cmp_lg_u32 s83, 0
	s_cbranch_scc1 .Lfmc_wait_done
	s_mov_b64 exec, 1
	global_atomic_add v244, v245, s[78:79]
	s_mov_b32 s82, 0

; __device__ __forceinline__ unsigned cvtpk_s(float lo, float hi) { f32x2_t v = {lo, hi}; bf16x2_t b = __builtin_convertvector(v, bf16x2_t); return __builtin_bit_cast(unsigned, b); }
; __device__ __forceinline__ u32x4 quad_swap(unsigned lo0, unsigned lo1, unsigned hi0, unsigned hi1, int fq, int& coloff) {
;     const bool odd = fq & 1;
;     const unsigned s0 = odd ? lo0 : hi0, s1 = odd ? lo1 : hi1;
;     const unsigned r0 = (unsigned)__shfl_xor((int)s0, 16), r1 = (unsigned)__shfl_xor((int)s1, 16);
;     coloff = odd ? 16 + 4 * (fq - 1) : 4 * fq;
;     u32x4 o; o.x = odd ? r0 : lo0; o.y = odd ? r1 : lo1; o.z = odd ? hi0 : r0; o.w = odd ? hi1 : r1; return o;
; __device__ __forceinline__ void modpass(const float* xs_main, const float* xs_ctx, const float* mod_l, const float* g, int i, bf16_t* H, int nrows, int gw, int NGW, int lane) {
;     ...
;         if (cond != cur) { cur = cond; const float* shift = mod_l + cond * 9216 + 3 * i * 1024; const float* scale = shift + 1024;
; #pragma unroll
;             for (int j = 0; j < 2; ++j)
; #pragma unroll
;                 for (int q = 0; q < 2; ++q) { const int c = 8 * lane + 512 * j + 4 * q; gm[j][q] = *(const f32x4*)(g + c) * (*(const f32x4*)(scale + c) + 1.0f); sh[j][q] = *(const f32x4*)(shift + c); } }
;         float ss = 0.f;
; #pragma unroll
;         for (int j = 0; j < 2; ++j)
; #pragma unroll
;             for (int q = 0; q < 2; ++q) ss += (v[j][q][0] * v[j][q][0] + v[j][q][1] * v[j][q][1]) + (v[j][q][2] * v[j][q][2] + v[j][q][3] * v[j][q][3]);
;         const float rstd = 1.0f / sqrtf(wave_sum(ss) * (1.0f / D) + EPS);
; #pragma unroll
;         for (int j = 0; j < 2; ++j) {
;             const f32x4 o0 = v[j][0] * rstd * gm[j][0] + sh[j][0], o1 = v[j][1] * rstd * gm[j][1] + sh[j][1];
;             u32x4 w; w.x = cvtpk_s(o0[0], o0[1]); w.y = cvtpk_s(o0[2], o0[3]); w.z = cvtpk_s(o1[0], o1[1]); w.w = cvtpk_s(o1[2], o1[3]);
;             *(u32x4*)(H + (size_t)row * D + 8 * lane + 512 * j) = w;
.Lfmc_wait_done:
	s_barrier
	global_load_dword v132, v243, s[76:77] sc1
	global_load_dword v133, v243, s[76:77] offset:64 sc1
	global_load_dword v134, v243, s[76:77] offset:128 sc1
	global_load_dword v135, v243, s[76:77] offset:192 sc1
	global_load_dword v136, v243, s[76:77] offset:512 sc1
	global_load_dword v137, v243, s[76:77] offset:576 sc1
	global_load_dword v138, v243, s[76:77] offset:640 sc1
	global_load_dword v139, v243, s[76:77] offset:704 sc1
	global_load_dwordx4 v[196:199], v201, s[86:87]
	global_load_dwordx4 v[212:215], v201, s[86:87] offset:64
	global_load_dwordx4 v[216:219], v201, s[86:87] offset:512
	global_load_dwordx4 v[220:223], v201, s[86:87] offset:576
	global_load_dwordx4 v[140:143], v201, s[88:89]
	global_load_dwordx4 v[164:167], v201, s[88:89] offset:64
	global_load_dwordx4 v[168:171], v201, s[88:89] offset:512
	global_load_dwordx4 v[172:175], v201, s[88:89] offset:576
	global_load_dwordx4 v[176:179], v201, s[92:93]
	global_load_dwordx4 v[180:183], v201, s[92:93] offset:64
	global_load_dwordx4 v[184:187], v201, s[92:93] offset:512
	global_load_dwordx4 v[188:191], v201, s[92:93] offset:576
	v_mov_b32_e32 v240, 12
	v_cndmask_b32_e64 v240, 0, v240, s[84:85]
	v_add_u32_e32 v240, v240, v157
	v_lshlrev_b32_e32 v240, 1, v240
	v_lshl_add_u32 v247, v156, 11, v240
	v_mov_b32_e32 v240, 0x358637bd
	s_waitcnt vmcnt(0)
	v_fmamk_f32 v132, v132, 0x3a800000, v240
	v_fmamk_f32 v133, v133, 0x3a800000, v240
	v_fmamk_f32 v134, v134, 0x3a800000, v240
	v_fmamk_f32 v135, v135, 0x3a800000, v240
	v_fmamk_f32 v136, v136, 0x3a800000, v240
	v_fmamk_f32 v137, v137, 0x3a800000, v240
	v_fmamk_f32 v138, v138, 0x3a800000, v240
	v_fmamk_f32 v139, v139, 0x3a800000, v240
	v_rsq_f32_e32 v132, v132
	v_rsq_f32_e32 v133, v133
	v_rsq_f32_e32 v134, v134
	v_rsq_f32_e32 v135, v135
	v_rsq_f32_e32 v136, v136
	v_rsq_f32_e32 v137, v137
	v_rsq_f32_e32 v138, v138
	v_rsq_f32_e32 v139, v139
	v_pk_add_f32 v[140:141], v[140:141], 1.0 op_sel_hi:[1,0]
	v_pk_mul_f32 v[140:141], v[176:177], v[140:141]
	v_pk_add_f32 v[142:143], v[142:143], 1.0 op_sel_hi:[1,0]
	v_pk_mul_f32 v[142:143], v[178:179], v[142:143]
	v_pk_add_f32 v[164:165], v[164:165], 1.0 op_sel_hi:[1,0]
	v_pk_mul_f32 v[164:165], v[180:181], v[164:165]
	v_pk_add_f32 v[166:167], v[166:167], 1.0 op_sel_hi:[1,0]
	v_pk_mul_f32 v[166:167], v[182:183], v[166:167]
	v_pk_add_f32 v[168:169], v[168:169], 1.0 op_sel_hi:[1,0]
	v_pk_mul_f32 v[168:169], v[184:185], v[168:169]
	v_pk_add_f32 v[170:171], v[170:171], 1.0 op_sel_hi:[1,0]
	v_pk_mul_f32 v[170:171], v[186:187], v[170:171]
	v_pk_add_f32 v[172:173], v[172:173], 1.0 op_sel_hi:[1,0]
	v_pk_mul_f32 v[172:173], v[188:189], v[172:173]
	v_pk_add_f32 v[174:175], v[174:175], 1.0 op_sel_hi:[1,0]
	v_pk_mul_f32 v[174:175], v[190:191], v[174:175]
	v_mul_f32_e32 v124, v124, v132
	v_mul_f32_e32 v125, v125, v132
	v_pk_fma_f32 v[124:125], v[140:141], v[124:125], v[196:197]
	v_mul_f32_e32 v126, v126, v132
	v_mul_f32_e32 v127, v127, v132
	v_pk_fma_f32 v[126:127], v[142:143], v[126:127], v[198:199]
	v_cvt_pk_bf16_f32 v184, v124, v125
	v_cvt_pk_bf16_f32 v185, v126, v127
	v_mul_f32_e32 v120, v120, v132
	v_mul_f32_e32 v121, v121, v132
	v_pk_fma_f32 v[120:121], v[164:165], v[120:121], v[212:213]
	v_mul_f32_e32 v122, v122, v132
	v_mul_f32_e32 v123, v123, v132
	v_pk_fma_f32 v[122:123], v[166:167], v[122:123], v[214:215]
	v_cvt_pk_bf16_f32 v186, v120, v121
	v_cvt_pk_bf16_f32 v187, v122, v123
	v_mul_f32_e32 v116, v116, v132
	v_mul_f32_e32 v117, v117, v132
	v_pk_fma_f32 v[116:117], v[168:169], v[116:117], v[216:217]
	v_mul_f32_e32 v118, v118, v132
	v_mul_f32_e32 v119, v119, v132
	v_pk_fma_f32 v[118:119], v[170:171], v[118:119], v[218:219]
	v_cvt_pk_bf16_f32 v188, v116, v117
	v_cvt_pk_bf16_f32 v189, v118, v119
	v_mul_f32_e32 v112, v112, v132
	v_mul_f32_e32 v113, v113, v132
	v_pk_fma_f32 v[112:113], v[172:173], v[112:113], v[220:221]
	v_mul_f32_e32 v114, v114, v132
	v_mul_f32_e32 v115, v115, v132
	v_pk_fma_f32 v[114:115], v[174:175], v[114:115], v[222:223]
	v_cvt_pk_bf16_f32 v190, v112, v113
	v_cvt_pk_bf16_f32 v191, v114, v115
	v_mov_b32_e32 v240, v247
	v_cndmask_b32_e64 v192, v186, v184, s[84:85]
	v_cndmask_b32_e64 v193, v187, v185, s[84:85]
	ds_bpermute_b32 v194, v241, v192
	ds_bpermute_b32 v195, v241, v193
	s_waitcnt lgkmcnt(0)
	v_cndmask_b32_e64 v176, v184, v194, s[84:85]
	v_cndmask_b32_e64 v177, v185, v195, s[84:85]
	v_cndmask_b32_e64 v178, v194, v186, s[84:85]
	v_cndmask_b32_e64 v179, v195, v187, s[84:85]
	global_store_dwordx4 v240, v[176:179], s[90:91]
	v_cndmask_b32_e64 v192, v190, v188, s[84:85]
	v_cndmask_b32_e64 v193, v191, v189, s[84:85]
	ds_bpermute_b32 v194, v241, v192
	ds_bpermute_b32 v195, v241, v193
	s_waitcnt lgkmcnt(0)
	v_cndmask_b32_e64 v180, v188, v194, s[84:85]
	v_cndmask_b32_e64 v181, v189, v195, s[84:85]
	v_cndmask_b32_e64 v182, v194, v190, s[84:85]
	v_cndmask_b32_e64 v183, v195, v191, s[84:85]
	global_store_dwordx4 v240, v[180:183], s[90:91] offset:256
	v_mul_f32_e32 v108, v108, v133
	v_mul_f32_e32 v109, v109, v133
	v_pk_fma_f32 v[108:109], v[140:141], v[108:109], v[196:197]
	v_mul_f32_e32 v110, v110, v133
	v_mul_f32_e32 v111, v111, v133
	v_pk_fma_f32 v[110:111], v[142:143], v[110:111], v[198:199]
	v_cvt_pk_bf16_f32 v184, v108, v109
	v_cvt_pk_bf16_f32 v185, v110, v111
	v_mul_f32_e32 v104, v104, v133
	v_mul_f32_e32 v105, v105, v133
	v_pk_fma_f32 v[104:105], v[164:165], v[104:105], v[212:213]
	v_mul_f32_e32 v106, v106, v133
	v_mul_f32_e32 v107, v107, v133
	v_pk_fma_f32 v[106:107], v[166:167], v[106:107], v[214:215]
	v_cvt_pk_bf16_f32 v186, v104, v105
	v_cvt_pk_bf16_f32 v187, v106, v107
	v_mul_f32_e32 v100, v100, v133
	v_mul_f32_e32 v101, v101, v133
	v_pk_fma_f32 v[100:101], v[168:169], v[100:101], v[216:217]
	v_mul_f32_e32 v102, v102, v133
	v_mul_f32_e32 v103, v103, v133
	v_pk_fma_f32 v[102:103], v[170:171], v[102:103], v[218:219]
	v_cvt_pk_bf16_f32 v188, v100, v101
	v_cvt_pk_bf16_f32 v189, v102, v103
	v_mul_f32_e32 v96, v96, v133
	v_mul_f32_e32 v97, v97, v133
	v_pk_fma_f32 v[96:97], v[172:173], v[96:97], v[220:221]
	v_mul_f32_e32 v98, v98, v133
	v_mul_f32_e32 v99, v99, v133
	v_pk_fma_f32 v[98:99], v[174:175], v[98:99], v[222:223]
	v_cvt_pk_bf16_f32 v190, v96, v97
	v_cvt_pk_bf16_f32 v191, v98, v99
	v_add_u32_e32 v240, 0x8000, v247
	v_cndmask_b32_e64 v192, v186, v184, s[84:85]
	v_cndmask_b32_e64 v193, v187, v185, s[84:85]
	ds_bpermute_b32 v194, v241, v192
	ds_bpermute_b32 v195, v241, v193
	s_waitcnt lgkmcnt(0)
; __device__ __forceinline__ unsigned cvtpk_s(float lo, float hi) { f32x2_t v = {lo, hi}; bf16x2_t b = __builtin_convertvector(v, bf16x2_t); return __builtin_bit_cast(unsigned, b); }
; __device__ __forceinline__ u32x4 quad_swap(unsigned lo0, unsigned lo1, unsigned hi0, unsigned hi1, int fq, int& coloff) {
;     const bool odd = fq & 1;
;     const unsigned s0 = odd ? lo0 : hi0, s1 = odd ? lo1 : hi1;
;     const unsigned r0 = (unsigned)__shfl_xor((int)s0, 16), r1 = (unsigned)__shfl_xor((int)s1, 16);
;     coloff = odd ? 16 + 4 * (fq - 1) : 4 * fq;
;     u32x4 o; o.x = odd ? r0 : lo0; o.y = odd ? r1 : lo1; o.z = odd ? hi0 : r0; o.w = odd ? hi1 : r1; return o;
; __device__ __forceinline__ void modpass(const float* xs_main, const float* xs_ctx, const float* mod_l, const float* g, int i, bf16_t* H, int nrows, int gw, int NGW, int lane) {
;     ...
; #pragma unroll
;                 for (int q = 0; q < 2; ++q) { const int c = 8 * lane + 512 * j + 4 * q; gm[j][q] = *(const f32x4*)(g + c) * (*(const f32x4*)(scale + c) + 1.0f); sh[j][q] = *(const f32x4*)(shift + c); } }
;         float ss = 0.f;
; #pragma unroll
;         for (int j = 0; j < 2; ++j)
; #pragma unroll
;             for (int q = 0; q < 2; ++q) ss += (v[j][q][0] * v[j][q][0] + v[j][q][1] * v[j][q][1]) + (v[j][q][2] * v[j][q][2] + v[j][q][3] * v[j][q][3]);
;         const float rstd = 1.0f / sqrtf(wave_sum(ss) * (1.0f / D) + EPS);
; #pragma unroll
;         for (int j = 0; j < 2; ++j) {
;             const f32x4 o0 = v[j][0] * rstd * gm[j][0] + sh[j][0], o1 = v[j][1] * rstd * gm[j][1] + sh[j][1];
;             u32x4 w; w.x = cvtpk_s(o0[0], o0[1]); w.y = cvtpk_s(o0[2], o0[3]); w.z = cvtpk_s(o1[0], o1[1]); w.w = cvtpk_s(o1[2], o1[3]);
;             *(u32x4*)(H + (size_t)row * D + 8 * lane + 512 * j) = w;
	v_cndmask_b32_e64 v176, v184, v194, s[84:85]
	v_cndmask_b32_e64 v177, v185, v195, s[84:85]
	v_cndmask_b32_e64 v178, v194, v186, s[84:85]
	v_cndmask_b32_e64 v179, v195, v187, s[84:85]
	global_store_dwordx4 v240, v[176:179], s[90:91]
	v_cndmask_b32_e64 v192, v190, v188, s[84:85]
	v_cndmask_b32_e64 v193, v191, v189, s[84:85]
	ds_bpermute_b32 v194, v241, v192
	ds_bpermute_b32 v195, v241, v193
	s_waitcnt lgkmcnt(0)
	v_cndmask_b32_e64 v180, v188, v194, s[84:85]
	v_cndmask_b32_e64 v181, v189, v195, s[84:85]
	v_cndmask_b32_e64 v182, v194, v190, s[84:85]
	v_cndmask_b32_e64 v183, v195, v191, s[84:85]
	global_store_dwordx4 v240, v[180:183], s[90:91] offset:256
	v_mul_f32_e32 v92, v92, v134
	v_mul_f32_e32 v93, v93, v134
	v_pk_fma_f32 v[92:93], v[140:141], v[92:93], v[196:197]
	v_mul_f32_e32 v94, v94, v134
	v_mul_f32_e32 v95, v95, v134
	v_pk_fma_f32 v[94:95], v[142:143], v[94:95], v[198:199]
	v_cvt_pk_bf16_f32 v184, v92, v93
	v_cvt_pk_bf16_f32 v185, v94, v95
	v_mul_f32_e32 v88, v88, v134
	v_mul_f32_e32 v89, v89, v134
	v_pk_fma_f32 v[88:89], v[164:165], v[88:89], v[212:213]
	v_mul_f32_e32 v90, v90, v134
	v_mul_f32_e32 v91, v91, v134
	v_pk_fma_f32 v[90:91], v[166:167], v[90:91], v[214:215]
	v_cvt_pk_bf16_f32 v186, v88, v89
	v_cvt_pk_bf16_f32 v187, v90, v91
	v_mul_f32_e32 v84, v84, v134
	v_mul_f32_e32 v85, v85, v134
	v_pk_fma_f32 v[84:85], v[168:169], v[84:85], v[216:217]
	v_mul_f32_e32 v86, v86, v134
	v_mul_f32_e32 v87, v87, v134
	v_pk_fma_f32 v[86:87], v[170:171], v[86:87], v[218:219]
	v_cvt_pk_bf16_f32 v188, v84, v85
	v_cvt_pk_bf16_f32 v189, v86, v87
	v_mul_f32_e32 v80, v80, v134
	v_mul_f32_e32 v81, v81, v134
	v_pk_fma_f32 v[80:81], v[172:173], v[80:81], v[220:221]
	v_mul_f32_e32 v82, v82, v134
	v_mul_f32_e32 v83, v83, v134
	v_pk_fma_f32 v[82:83], v[174:175], v[82:83], v[222:223]
	v_cvt_pk_bf16_f32 v190, v80, v81
	v_cvt_pk_bf16_f32 v191, v82, v83
	v_add_u32_e32 v240, 0x10000, v247
	v_cndmask_b32_e64 v192, v186, v184, s[84:85]
	v_cndmask_b32_e64 v193, v187, v185, s[84:85]
	ds_bpermute_b32 v194, v241, v192
	ds_bpermute_b32 v195, v241, v193
	s_waitcnt lgkmcnt(0)
	v_cndmask_b32_e64 v176, v184, v194, s[84:85]
	v_cndmask_b32_e64 v177, v185, v195, s[84:85]
	v_cndmask_b32_e64 v178, v194, v186, s[84:85]
	v_cndmask_b32_e64 v179, v195, v187, s[84:85]
	global_store_dwordx4 v240, v[176:179], s[90:91]
	v_cndmask_b32_e64 v192, v190, v188, s[84:85]
	v_cndmask_b32_e64 v193, v191, v189, s[84:85]
	ds_bpermute_b32 v194, v241, v192
	ds_bpermute_b32 v195, v241, v193
	s_waitcnt lgkmcnt(0)
	v_cndmask_b32_e64 v180, v188, v194, s[84:85]
	v_cndmask_b32_e64 v181, v189, v195, s[84:85]
	v_cndmask_b32_e64 v182, v194, v190, s[84:85]
	v_cndmask_b32_e64 v183, v195, v191, s[84:85]
	global_store_dwordx4 v240, v[180:183], s[90:91] offset:256
	v_mul_f32_e32 v76, v76, v135
	v_mul_f32_e32 v77, v77, v135
	v_pk_fma_f32 v[76:77], v[140:141], v[76:77], v[196:197]
	v_mul_f32_e32 v78, v78, v135
	v_mul_f32_e32 v79, v79, v135
	v_pk_fma_f32 v[78:79], v[142:143], v[78:79], v[198:199]
	v_cvt_pk_bf16_f32 v184, v76, v77
	v_cvt_pk_bf16_f32 v185, v78, v79
	v_mul_f32_e32 v72, v72, v135
	v_mul_f32_e32 v73, v73, v135
	v_pk_fma_f32 v[72:73], v[164:165], v[72:73], v[212:213]
	v_mul_f32_e32 v74, v74, v135
	v_mul_f32_e32 v75, v75, v135
	v_pk_fma_f32 v[74:75], v[166:167], v[74:75], v[214:215]
	v_cvt_pk_bf16_f32 v186, v72, v73
	v_cvt_pk_bf16_f32 v187, v74, v75
	v_mul_f32_e32 v68, v68, v135
	v_mul_f32_e32 v69, v69, v135
	v_pk_fma_f32 v[68:69], v[168:169], v[68:69], v[216:217]
	v_mul_f32_e32 v70, v70, v135
	v_mul_f32_e32 v71, v71, v135
	v_pk_fma_f32 v[70:71], v[170:171], v[70:71], v[218:219]
	v_cvt_pk_bf16_f32 v188, v68, v69
	v_cvt_pk_bf16_f32 v189, v70, v71
	v_mul_f32_e32 v64, v64, v135
	v_mul_f32_e32 v65, v65, v135
	v_pk_fma_f32 v[64:65], v[172:173], v[64:65], v[220:221]
	v_mul_f32_e32 v66, v66, v135
	v_mul_f32_e32 v67, v67, v135
	v_pk_fma_f32 v[66:67], v[174:175], v[66:67], v[222:223]
	v_cvt_pk_bf16_f32 v190, v64, v65
	v_cvt_pk_bf16_f32 v191, v66, v67
	v_add_u32_e32 v240, 0x18000, v247
	v_cndmask_b32_e64 v192, v186, v184, s[84:85]
	v_cndmask_b32_e64 v193, v187, v185, s[84:85]
	ds_bpermute_b32 v194, v241, v192
	ds_bpermute_b32 v195, v241, v193
	s_waitcnt lgkmcnt(0)
	v_cndmask_b32_e64 v176, v184, v194, s[84:85]
	v_cndmask_b32_e64 v177, v185, v195, s[84:85]
	v_cndmask_b32_e64 v178, v194, v186, s[84:85]
	v_cndmask_b32_e64 v179, v195, v187, s[84:85]
	global_store_dwordx4 v240, v[176:179], s[90:91]
	v_cndmask_b32_e64 v192, v190, v188, s[84:85]
	v_cndmask_b32_e64 v193, v191, v189, s[84:85]
	ds_bpermute_b32 v194, v241, v192
	ds_bpermute_b32 v195, v241, v193
	s_waitcnt lgkmcnt(0)
	v_cndmask_b32_e64 v180, v188, v194, s[84:85]
	v_cndmask_b32_e64 v181, v189, v195, s[84:85]
	v_cndmask_b32_e64 v182, v194, v190, s[84:85]
	v_cndmask_b32_e64 v183, v195, v191, s[84:85]
	global_store_dwordx4 v240, v[180:183], s[90:91] offset:256
	v_mul_f32_e32 v60, v60, v136
	v_mul_f32_e32 v61, v61, v136
	v_pk_fma_f32 v[60:61], v[140:141], v[60:61], v[196:197]
	v_mul_f32_e32 v62, v62, v136
	v_mul_f32_e32 v63, v63, v136
	v_pk_fma_f32 v[62:63], v[142:143], v[62:63], v[198:199]
	v_cvt_pk_bf16_f32 v184, v60, v61
	v_cvt_pk_bf16_f32 v185, v62, v63
	v_mul_f32_e32 v56, v56, v136
	v_mul_f32_e32 v57, v57, v136
	v_pk_fma_f32 v[56:57], v[164:165], v[56:57], v[212:213]
	v_mul_f32_e32 v58, v58, v136
	v_mul_f32_e32 v59, v59, v136
	v_pk_fma_f32 v[58:59], v[166:167], v[58:59], v[214:215]
	v_cvt_pk_bf16_f32 v186, v56, v57
	v_cvt_pk_bf16_f32 v187, v58, v59
	v_mul_f32_e32 v52, v52, v136
	v_mul_f32_e32 v53, v53, v136
	v_pk_fma_f32 v[52:53], v[168:169], v[52:53], v[216:217]
	v_mul_f32_e32 v54, v54, v136
	v_mul_f32_e32 v55, v55, v136
	v_pk_fma_f32 v[54:55], v[170:171], v[54:55], v[218:219]
	v_cvt_pk_bf16_f32 v188, v52, v53
	v_cvt_pk_bf16_f32 v189, v54, v55
	v_mul_f32_e32 v48, v48, v136
	v_mul_f32_e32 v49, v49, v136
	v_pk_fma_f32 v[48:49], v[172:173], v[48:49], v[220:221]
	v_mul_f32_e32 v50, v50, v136
	v_mul_f32_e32 v51, v51, v136
	v_pk_fma_f32 v[50:51], v[174:175], v[50:51], v[222:223]
	v_cvt_pk_bf16_f32 v190, v48, v49
	v_cvt_pk_bf16_f32 v191, v50, v51
	v_add_u32_e32 v240, 0x40000, v247
	v_cndmask_b32_e64 v192, v186, v184, s[84:85]
	v_cndmask_b32_e64 v193, v187, v185, s[84:85]
	ds_bpermute_b32 v194, v241, v192
	ds_bpermute_b32 v195, v241, v193
	s_waitcnt lgkmcnt(0)
; __device__ __forceinline__ unsigned cvtpk_s(float lo, float hi) { f32x2_t v = {lo, hi}; bf16x2_t b = __builtin_convertvector(v, bf16x2_t); return __builtin_bit_cast(unsigned, b); }
; __device__ __forceinline__ u32x4 quad_swap(unsigned lo0, unsigned lo1, unsigned hi0, unsigned hi1, int fq, int& coloff) {
;     const bool odd = fq & 1;
;     const unsigned s0 = odd ? lo0 : hi0, s1 = odd ? lo1 : hi1;
;     const unsigned r0 = (unsigned)__shfl_xor((int)s0, 16), r1 = (unsigned)__shfl_xor((int)s1, 16);
;     coloff = odd ? 16 + 4 * (fq - 1) : 4 * fq;
;     u32x4 o; o.x = odd ? r0 : lo0; o.y = odd ? r1 : lo1; o.z = odd ? hi0 : r0; o.w = odd ? hi1 : r1; return o;
; __device__ __forceinline__ void modpass(const float* xs_main, const float* xs_ctx, const float* mod_l, const float* g, int i, bf16_t* H, int nrows, int gw, int NGW, int lane) {
;     ...
;         for (int j = 0; j < 2; ++j) {
;             const f32x4 o0 = v[j][0] * rstd * gm[j][0] + sh[j][0], o1 = v[j][1] * rstd * gm[j][1] + sh[j][1];
;             u32x4 w; w.x = cvtpk_s(o0[0], o0[1]); w.y = cvtpk_s(o0[2], o0[3]); w.z = cvtpk_s(o1[0], o1[1]); w.w = cvtpk_s(o1[2], o1[3]);
;             *(u32x4*)(H + (size_t)row * D + 8 * lane + 512 * j) = w;
	v_cndmask_b32_e64 v176, v184, v194, s[84:85]
	v_cndmask_b32_e64 v177, v185, v195, s[84:85]
	v_cndmask_b32_e64 v178, v194, v186, s[84:85]
	v_cndmask_b32_e64 v179, v195, v187, s[84:85]
	global_store_dwordx4 v240, v[176:179], s[90:91]
	v_cndmask_b32_e64 v192, v190, v188, s[84:85]
	v_cndmask_b32_e64 v193, v191, v189, s[84:85]
	ds_bpermute_b32 v194, v241, v192
	ds_bpermute_b32 v195, v241, v193
	s_waitcnt lgkmcnt(0)
	v_cndmask_b32_e64 v180, v188, v194, s[84:85]
	v_cndmask_b32_e64 v181, v189, v195, s[84:85]
	v_cndmask_b32_e64 v182, v194, v190, s[84:85]
	v_cndmask_b32_e64 v183, v195, v191, s[84:85]
	global_store_dwordx4 v240, v[180:183], s[90:91] offset:256
	v_mul_f32_e32 v44, v44, v137
	v_mul_f32_e32 v45, v45, v137
	v_pk_fma_f32 v[44:45], v[140:141], v[44:45], v[196:197]
	v_mul_f32_e32 v46, v46, v137
	v_mul_f32_e32 v47, v47, v137
	v_pk_fma_f32 v[46:47], v[142:143], v[46:47], v[198:199]
	v_cvt_pk_bf16_f32 v184, v44, v45
	v_cvt_pk_bf16_f32 v185, v46, v47
	v_mul_f32_e32 v40, v40, v137
	v_mul_f32_e32 v41, v41, v137
	v_pk_fma_f32 v[40:41], v[164:165], v[40:41], v[212:213]
	v_mul_f32_e32 v42, v42, v137
	v_mul_f32_e32 v43, v43, v137
	v_pk_fma_f32 v[42:43], v[166:167], v[42:43], v[214:215]
	v_cvt_pk_bf16_f32 v186, v40, v41
	v_cvt_pk_bf16_f32 v187, v42, v43
	v_mul_f32_e32 v36, v36, v137
	v_mul_f32_e32 v37, v37, v137
	v_pk_fma_f32 v[36:37], v[168:169], v[36:37], v[216:217]
	v_mul_f32_e32 v38, v38, v137
	v_mul_f32_e32 v39, v39, v137
	v_pk_fma_f32 v[38:39], v[170:171], v[38:39], v[218:219]
	v_cvt_pk_bf16_f32 v188, v36, v37
	v_cvt_pk_bf16_f32 v189, v38, v39
	v_mul_f32_e32 v32, v32, v137
	v_mul_f32_e32 v33, v33, v137
	v_pk_fma_f32 v[32:33], v[172:173], v[32:33], v[220:221]
	v_mul_f32_e32 v34, v34, v137
	v_mul_f32_e32 v35, v35, v137
	v_pk_fma_f32 v[34:35], v[174:175], v[34:35], v[222:223]
	v_cvt_pk_bf16_f32 v190, v32, v33
	v_cvt_pk_bf16_f32 v191, v34, v35
	v_add_u32_e32 v240, 0x48000, v247
	v_cndmask_b32_e64 v192, v186, v184, s[84:85]
	v_cndmask_b32_e64 v193, v187, v185, s[84:85]
	ds_bpermute_b32 v194, v241, v192
	ds_bpermute_b32 v195, v241, v193
	s_waitcnt lgkmcnt(0)
	v_cndmask_b32_e64 v176, v184, v194, s[84:85]
	v_cndmask_b32_e64 v177, v185, v195, s[84:85]
	v_cndmask_b32_e64 v178, v194, v186, s[84:85]
	v_cndmask_b32_e64 v179, v195, v187, s[84:85]
	global_store_dwordx4 v240, v[176:179], s[90:91]
	v_cndmask_b32_e64 v192, v190, v188, s[84:85]
	v_cndmask_b32_e64 v193, v191, v189, s[84:85]
	ds_bpermute_b32 v194, v241, v192
	ds_bpermute_b32 v195, v241, v193
	s_waitcnt lgkmcnt(0)
	v_cndmask_b32_e64 v180, v188, v194, s[84:85]
	v_cndmask_b32_e64 v181, v189, v195, s[84:85]
	v_cndmask_b32_e64 v182, v194, v190, s[84:85]
	v_cndmask_b32_e64 v183, v195, v191, s[84:85]
	global_store_dwordx4 v240, v[180:183], s[90:91] offset:256
	v_mul_f32_e32 v28, v28, v138
	v_mul_f32_e32 v29, v29, v138
	v_pk_fma_f32 v[28:29], v[140:141], v[28:29], v[196:197]
	v_mul_f32_e32 v30, v30, v138
	v_mul_f32_e32 v31, v31, v138
	v_pk_fma_f32 v[30:31], v[142:143], v[30:31], v[198:199]
	v_cvt_pk_bf16_f32 v184, v28, v29
	v_cvt_pk_bf16_f32 v185, v30, v31
	v_mul_f32_e32 v24, v24, v138
	v_mul_f32_e32 v25, v25, v138
	v_pk_fma_f32 v[24:25], v[164:165], v[24:25], v[212:213]
	v_mul_f32_e32 v26, v26, v138
	v_mul_f32_e32 v27, v27, v138
	v_pk_fma_f32 v[26:27], v[166:167], v[26:27], v[214:215]
	v_cvt_pk_bf16_f32 v186, v24, v25
	v_cvt_pk_bf16_f32 v187, v26, v27
	v_mul_f32_e32 v20, v20, v138
	v_mul_f32_e32 v21, v21, v138
	v_pk_fma_f32 v[20:21], v[168:169], v[20:21], v[216:217]
	v_mul_f32_e32 v22, v22, v138
	v_mul_f32_e32 v23, v23, v138
	v_pk_fma_f32 v[22:23], v[170:171], v[22:23], v[218:219]
	v_cvt_pk_bf16_f32 v188, v20, v21
	v_cvt_pk_bf16_f32 v189, v22, v23
	v_mul_f32_e32 v16, v16, v138
	v_mul_f32_e32 v17, v17, v138
	v_pk_fma_f32 v[16:17], v[172:173], v[16:17], v[220:221]
	v_mul_f32_e32 v18, v18, v138
	v_mul_f32_e32 v19, v19, v138
	v_pk_fma_f32 v[18:19], v[174:175], v[18:19], v[222:223]
	v_cvt_pk_bf16_f32 v190, v16, v17
	v_cvt_pk_bf16_f32 v191, v18, v19
	v_add_u32_e32 v240, 0x50000, v247
	v_cndmask_b32_e64 v192, v186, v184, s[84:85]
	v_cndmask_b32_e64 v193, v187, v185, s[84:85]
	ds_bpermute_b32 v194, v241, v192
	ds_bpermute_b32 v195, v241, v193
	s_waitcnt lgkmcnt(0)
	v_cndmask_b32_e64 v176, v184, v194, s[84:85]
	v_cndmask_b32_e64 v177, v185, v195, s[84:85]
	v_cndmask_b32_e64 v178, v194, v186, s[84:85]
	v_cndmask_b32_e64 v179, v195, v187, s[84:85]
	global_store_dwordx4 v240, v[176:179], s[90:91]
	v_cndmask_b32_e64 v192, v190, v188, s[84:85]
	v_cndmask_b32_e64 v193, v191, v189, s[84:85]
	ds_bpermute_b32 v194, v241, v192
	ds_bpermute_b32 v195, v241, v193
	s_waitcnt lgkmcnt(0)
	v_cndmask_b32_e64 v180, v188, v194, s[84:85]
	v_cndmask_b32_e64 v181, v189, v195, s[84:85]
	v_cndmask_b32_e64 v182, v194, v190, s[84:85]
	v_cndmask_b32_e64 v183, v195, v191, s[84:85]
	global_store_dwordx4 v240, v[180:183], s[90:91] offset:256
	v_mul_f32_e32 v12, v12, v139
	v_mul_f32_e32 v13, v13, v139
	v_pk_fma_f32 v[12:13], v[140:141], v[12:13], v[196:197]
	v_mul_f32_e32 v14, v14, v139
	v_mul_f32_e32 v15, v15, v139
	v_pk_fma_f32 v[14:15], v[142:143], v[14:15], v[198:199]
	v_cvt_pk_bf16_f32 v184, v12, v13
	v_cvt_pk_bf16_f32 v185, v14, v15
	v_mul_f32_e32 v8, v8, v139
	v_mul_f32_e32 v9, v9, v139
	v_pk_fma_f32 v[8:9], v[164:165], v[8:9], v[212:213]
	v_mul_f32_e32 v10, v10, v139
	v_mul_f32_e32 v11, v11, v139
	v_pk_fma_f32 v[10:11], v[166:167], v[10:11], v[214:215]
	v_cvt_pk_bf16_f32 v186, v8, v9
	v_cvt_pk_bf16_f32 v187, v10, v11
	v_mul_f32_e32 v4, v4, v139
	v_mul_f32_e32 v5, v5, v139
	v_pk_fma_f32 v[4:5], v[168:169], v[4:5], v[216:217]
	v_mul_f32_e32 v6, v6, v139
	v_mul_f32_e32 v7, v7, v139
	v_pk_fma_f32 v[6:7], v[170:171], v[6:7], v[218:219]
	v_cvt_pk_bf16_f32 v188, v4, v5
	v_cvt_pk_bf16_f32 v189, v6, v7
	v_mul_f32_e32 v0, v0, v139
	v_mul_f32_e32 v1, v1, v139
	v_pk_fma_f32 v[0:1], v[172:173], v[0:1], v[220:221]
	v_mul_f32_e32 v2, v2, v139
	v_mul_f32_e32 v3, v3, v139
	v_pk_fma_f32 v[2:3], v[174:175], v[2:3], v[222:223]
	v_cvt_pk_bf16_f32 v190, v0, v1
	v_cvt_pk_bf16_f32 v191, v2, v3
	v_add_u32_e32 v240, 0x58000, v247
	v_cndmask_b32_e64 v192, v186, v184, s[84:85]
	v_cndmask_b32_e64 v193, v187, v185, s[84:85]
	ds_bpermute_b32 v194, v241, v192
	ds_bpermute_b32 v195, v241, v193
	s_waitcnt lgkmcnt(0)
	v_cndmask_b32_e64 v176, v184, v194, s[84:85]
	v_cndmask_b32_e64 v177, v185, v195, s[84:85]
	v_cndmask_b32_e64 v178, v194, v186, s[84:85]
	v_cndmask_b32_e64 v179, v195, v187, s[84:85]
	global_store_dwordx4 v240, v[176:179], s[90:91]
	v_cndmask_b32_e64 v192, v190, v188, s[84:85]
	v_cndmask_b32_e64 v193, v191, v189, s[84:85]
	ds_bpermute_b32 v194, v241, v192
	ds_bpermute_b32 v195, v241, v193
	s_waitcnt lgkmcnt(0)
	v_cndmask_b32_e64 v180, v188, v194, s[84:85]
	v_cndmask_b32_e64 v181, v189, v195, s[84:85]
	v_cndmask_b32_e64 v182, v194, v190, s[84:85]
	v_cndmask_b32_e64 v183, v195, v191, s[84:85]
	global_store_dwordx4 v240, v[180:183], s[90:91] offset:256
	s_andn2_b64 vcc, exec, s[10:11]
	s_mov_b64 s[10:11], -1
	s_branch .Lfmdone_c
;     __device__ __forceinline__ void operator()(const f32x4 (&acc)[2][2][4][2], const Unit& u, int wr, int wc, int fr, int fq) const {
;         const int cond = u.pm < 64 ? 0 : (u.pm < 128 ? 1 : 2);
;         const float* gate = gate_l + cond * 9216;
;         const int col0 = u.pn * BM + wc * 32 + 4 * fq;
;         f32x4 gv[2][2];
; #pragma unroll
;         for (int bj = 0; bj < 2; ++bj)
; #pragma unroll
;             for (int n = 0; n < 2; ++n) gv[bj][n] = *(const f32x4*)(gate + col0 + bj * HALF + n * 16) * coef;
; #pragma unroll
;         for (int ai = 0; ai < 2; ++ai)
; #pragma unroll
;             for (int m = 0; m < 4; ++m) {
;                 const int row = u.pm * BM + ai * HALF + wr * 64 + m * 16 + fr;
;                 const float* s = row < MX_ ? src_main + (size_t)row * D_ : src_ctx + (size_t)(row - MX_) * D_;
;                 float* d = row < MX_ ? dst_main + (size_t)row * D_ : dst_ctx + (size_t)(row - MX_) * D_;
; #pragma unroll
;                 for (int bj = 0; bj < 2; ++bj)
; #pragma unroll
;                     for (int n = 0; n < 2; ++n) { const int off = col0 + bj * HALF + n * 16; const f32x4 xo = *(const f32x4*)(s + off); *(f32x4*)(d + off) = xo + gv[bj][n] * acc[ai][bj][m][n]; }
.Lfmsel_c:
	s_cmpk_lt_i32 s40, 0x80
	s_cselect_b32 s7, s69, 0x4800
	s_cmp_gt_i32 s40, 63
	s_cselect_b32 s7, s7, 0
	s_lshl_b32 s7, s7, 2
	s_add_u32 s8, s61, s7
	s_addc_u32 s9, s62, 0
	s_load_dwordx2 s[92:93], s[0:1], 0x30
	s_load_dwordx2 s[76:77], s[0:1], 0xb8
	v_lshl_add_u32 v156, s40, 8, v158
	v_lshl_or_b32 v157, s6, 8, v160
	v_lshlrev_b32_e32 v201, 2, v157
	v_lshl_add_u32 v224, v156, 12, v201
	global_load_dwordx4 v[196:199], v201, s[8:9]
	global_load_dwordx4 v[212:215], v201, s[8:9] offset:64
	global_load_dwordx4 v[216:219], v201, s[8:9] offset:512
	global_load_dwordx4 v[220:223], v201, s[8:9] offset:576
	v_add_u32_e32 v225, 0x10000, v224
	v_add_u32_e32 v226, 0x20000, v224
	v_add_u32_e32 v227, 0x30000, v224
	v_add_u32_e32 v228, 0x80000, v224
	v_add_u32_e32 v229, 0x90000, v224
	v_add_u32_e32 v230, 0xa0000, v224
	v_add_u32_e32 v231, 0xb0000, v224
	global_load_dwordx4 v[128:131], v224, s[12:13]
	global_load_dwordx4 v[132:135], v224, s[12:13] offset:64
	global_load_dwordx4 v[136:139], v224, s[12:13] offset:512
	global_load_dwordx4 v[140:143], v224, s[12:13] offset:576
	global_load_dwordx4 v[164:167], v225, s[12:13]
	global_load_dwordx4 v[168:171], v225, s[12:13] offset:64
	global_load_dwordx4 v[172:175], v225, s[12:13] offset:512
	global_load_dwordx4 v[176:179], v225, s[12:13] offset:576
	global_load_dwordx4 v[180:183], v226, s[12:13]
	global_load_dwordx4 v[184:187], v226, s[12:13] offset:64
	global_load_dwordx4 v[188:191], v226, s[12:13] offset:512
	global_load_dwordx4 v[192:195], v226, s[12:13] offset:576
	s_waitcnt vmcnt(12)
	s_waitcnt vmcnt(11)
	v_pk_fma_f32 v[124:125], v[124:125], v[196:197], v[128:129]
	v_pk_fma_f32 v[126:127], v[126:127], v[198:199], v[130:131]
	v_mul_f32_e32 v232, v124, v124
	v_fmac_f32_e32 v232, v125, v125
	v_fmac_f32_e32 v232, v126, v126
	v_fmac_f32_e32 v232, v127, v127
	s_waitcnt vmcnt(10)
	v_pk_fma_f32 v[120:121], v[120:121], v[212:213], v[132:133]
	v_pk_fma_f32 v[122:123], v[122:123], v[214:215], v[134:135]
	v_fmac_f32_e32 v232, v120, v120
	v_fmac_f32_e32 v232, v121, v121
	v_fmac_f32_e32 v232, v122, v122
	v_fmac_f32_e32 v232, v123, v123
	s_waitcnt vmcnt(9)
	v_pk_fma_f32 v[116:117], v[116:117], v[216:217], v[136:137]
	v_pk_fma_f32 v[118:119], v[118:119], v[218:219], v[138:139]
	v_fmac_f32_e32 v232, v116, v116
	v_fmac_f32_e32 v232, v117, v117
	v_fmac_f32_e32 v232, v118, v118
	v_fmac_f32_e32 v232, v119, v119
	s_waitcnt vmcnt(8)
	v_pk_fma_f32 v[112:113], v[112:113], v[220:221], v[140:141]
	v_pk_fma_f32 v[114:115], v[114:115], v[222:223], v[142:143]
	v_fmac_f32_e32 v232, v112, v112
	v_fmac_f32_e32 v232, v113, v113
	v_fmac_f32_e32 v232, v114, v114
	v_fmac_f32_e32 v232, v115, v115
	global_store_dwordx4 v224, v[124:127], s[12:13] sc1
	global_store_dwordx4 v224, v[120:123], s[12:13] offset:64 sc1
	global_store_dwordx4 v224, v[116:119], s[12:13] offset:512 sc1
	global_store_dwordx4 v224, v[112:115], s[12:13] offset:576 sc1
	global_load_dwordx4 v[128:131], v227, s[12:13]
	global_load_dwordx4 v[132:135], v227, s[12:13] offset:64
	global_load_dwordx4 v[136:139], v227, s[12:13] offset:512
	global_load_dwordx4 v[140:143], v227, s[12:13] offset:576
	s_waitcnt vmcnt(15)
	v_pk_fma_f32 v[108:109], v[108:109], v[196:197], v[164:165]
	v_pk_fma_f32 v[110:111], v[110:111], v[198:199], v[166:167]
	v_mul_f32_e32 v233, v108, v108
	v_fmac_f32_e32 v233, v109, v109
	v_fmac_f32_e32 v233, v110, v110
	v_fmac_f32_e32 v233, v111, v111
	s_waitcnt vmcnt(14)
	v_pk_fma_f32 v[104:105], v[104:105], v[212:213], v[168:169]
	v_pk_fma_f32 v[106:107], v[106:107], v[214:215], v[170:171]
	v_fmac_f32_e32 v233, v104, v104
	v_fmac_f32_e32 v233, v105, v105
	v_fmac_f32_e32 v233, v106, v106
	v_fmac_f32_e32 v233, v107, v107
	s_waitcnt vmcnt(13)
	v_pk_fma_f32 v[100:101], v[100:101], v[216:217], v[172:173]
	v_pk_fma_f32 v[102:103], v[102:103], v[218:219], v[174:175]
	v_fmac_f32_e32 v233, v100, v100
	v_fmac_f32_e32 v233, v101, v101
	v_fmac_f32_e32 v233, v102, v102
	v_fmac_f32_e32 v233, v103, v103
	s_waitcnt vmcnt(12)
	v_pk_fma_f32 v[96:97], v[96:97], v[220:221], v[176:177]
	v_pk_fma_f32 v[98:99], v[98:99], v[222:223], v[178:179]
	v_fmac_f32_e32 v233, v96, v96
	v_fmac_f32_e32 v233, v97, v97
	v_fmac_f32_e32 v233, v98, v98
	v_fmac_f32_e32 v233, v99, v99
	global_store_dwordx4 v225, v[108:111], s[12:13] sc1
	global_store_dwordx4 v225, v[104:107], s[12:13] offset:64 sc1
	global_store_dwordx4 v225, v[100:103], s[12:13] offset:512 sc1
	global_store_dwordx4 v225, v[96:99], s[12:13] offset:576 sc1
	global_load_dwordx4 v[164:167], v228, s[12:13]
	global_load_dwordx4 v[168:171], v228, s[12:13] offset:64
	global_load_dwordx4 v[172:175], v228, s[12:13] offset:512
	global_load_dwordx4 v[176:179], v228, s[12:13] offset:576
	s_waitcnt vmcnt(19)
	v_pk_fma_f32 v[92:93], v[92:93], v[196:197], v[180:181]
	v_pk_fma_f32 v[94:95], v[94:95], v[198:199], v[182:183]
	v_mul_f32_e32 v234, v92, v92
	v_fmac_f32_e32 v234, v93, v93
	v_fmac_f32_e32 v234, v94, v94
	v_fmac_f32_e32 v234, v95, v95
	s_waitcnt vmcnt(18)
	v_pk_fma_f32 v[88:89], v[88:89], v[212:213], v[184:185]
	v_pk_fma_f32 v[90:91], v[90:91], v[214:215], v[186:187]
	v_fmac_f32_e32 v234, v88, v88
	v_fmac_f32_e32 v234, v89, v89
	v_fmac_f32_e32 v234, v90, v90
	v_fmac_f32_e32 v234, v91, v91
	s_waitcnt vmcnt(17)
	v_pk_fma_f32 v[84:85], v[84:85], v[216:217], v[188:189]
	v_pk_fma_f32 v[86:87], v[86:87], v[218:219], v[190:191]
	v_fmac_f32_e32 v234, v84, v84
	v_fmac_f32_e32 v234, v85, v85
	v_fmac_f32_e32 v234, v86, v86
	v_fmac_f32_e32 v234, v87, v87
	s_waitcnt vmcnt(16)
;     __device__ __forceinline__ void operator()(const f32x4 (&acc)[2][2][4][2], const Unit& u, int wr, int wc, int fr, int fq) const {
;     ...
;                 const int row = u.pm * BM + ai * HALF + wr * 64 + m * 16 + fr;
;                 const float* s = row < MX_ ? src_main + (size_t)row * D_ : src_ctx + (size_t)(row - MX_) * D_;
;                 float* d = row < MX_ ? dst_main + (size_t)row * D_ : dst_ctx + (size_t)(row - MX_) * D_;
; #pragma unroll
;                 for (int bj = 0; bj < 2; ++bj)
; #pragma unroll
;                     for (int n = 0; n < 2; ++n) { const int off = col0 + bj * HALF + n * 16; const f32x4 xo = *(const f32x4*)(s + off); *(f32x4*)(d + off) = xo + gv[bj][n] * acc[ai][bj][m][n]; }
	v_pk_fma_f32 v[80:81], v[80:81], v[220:221], v[192:193]
	v_pk_fma_f32 v[82:83], v[82:83], v[222:223], v[194:195]
	v_fmac_f32_e32 v234, v80, v80
	v_fmac_f32_e32 v234, v81, v81
	v_fmac_f32_e32 v234, v82, v82
	v_fmac_f32_e32 v234, v83, v83
	global_store_dwordx4 v226, v[92:95], s[12:13] sc1
	global_store_dwordx4 v226, v[88:91], s[12:13] offset:64 sc1
	global_store_dwordx4 v226, v[84:87], s[12:13] offset:512 sc1
	global_store_dwordx4 v226, v[80:83], s[12:13] offset:576 sc1
	global_load_dwordx4 v[180:183], v229, s[12:13]
	global_load_dwordx4 v[184:187], v229, s[12:13] offset:64
	global_load_dwordx4 v[188:191], v229, s[12:13] offset:512
	global_load_dwordx4 v[192:195], v229, s[12:13] offset:576
	s_waitcnt vmcnt(19)
	v_pk_fma_f32 v[76:77], v[76:77], v[196:197], v[128:129]
	v_pk_fma_f32 v[78:79], v[78:79], v[198:199], v[130:131]
	v_mul_f32_e32 v235, v76, v76
	v_fmac_f32_e32 v235, v77, v77
	v_fmac_f32_e32 v235, v78, v78
	v_fmac_f32_e32 v235, v79, v79
	s_waitcnt vmcnt(18)
	v_pk_fma_f32 v[72:73], v[72:73], v[212:213], v[132:133]
	v_pk_fma_f32 v[74:75], v[74:75], v[214:215], v[134:135]
	v_fmac_f32_e32 v235, v72, v72
	v_fmac_f32_e32 v235, v73, v73
	v_fmac_f32_e32 v235, v74, v74
	v_fmac_f32_e32 v235, v75, v75
	s_waitcnt vmcnt(17)
	v_pk_fma_f32 v[68:69], v[68:69], v[216:217], v[136:137]
	v_pk_fma_f32 v[70:71], v[70:71], v[218:219], v[138:139]
	v_fmac_f32_e32 v235, v68, v68
	v_fmac_f32_e32 v235, v69, v69
	v_fmac_f32_e32 v235, v70, v70
	v_fmac_f32_e32 v235, v71, v71
	s_waitcnt vmcnt(16)
	v_pk_fma_f32 v[64:65], v[64:65], v[220:221], v[140:141]
	v_pk_fma_f32 v[66:67], v[66:67], v[222:223], v[142:143]
	v_fmac_f32_e32 v235, v64, v64
	v_fmac_f32_e32 v235, v65, v65
	v_fmac_f32_e32 v235, v66, v66
	v_fmac_f32_e32 v235, v67, v67
	global_store_dwordx4 v227, v[76:79], s[12:13] sc1
	global_store_dwordx4 v227, v[72:75], s[12:13] offset:64 sc1
	global_store_dwordx4 v227, v[68:71], s[12:13] offset:512 sc1
	global_store_dwordx4 v227, v[64:67], s[12:13] offset:576 sc1
	global_load_dwordx4 v[128:131], v230, s[12:13]
	global_load_dwordx4 v[132:135], v230, s[12:13] offset:64
	global_load_dwordx4 v[136:139], v230, s[12:13] offset:512
	global_load_dwordx4 v[140:143], v230, s[12:13] offset:576
	s_waitcnt vmcnt(19)
	v_pk_fma_f32 v[60:61], v[60:61], v[196:197], v[164:165]
	v_pk_fma_f32 v[62:63], v[62:63], v[198:199], v[166:167]
	v_mul_f32_e32 v236, v60, v60
	v_fmac_f32_e32 v236, v61, v61
	v_fmac_f32_e32 v236, v62, v62
	v_fmac_f32_e32 v236, v63, v63
	s_waitcnt vmcnt(18)
	v_pk_fma_f32 v[56:57], v[56:57], v[212:213], v[168:169]
	v_pk_fma_f32 v[58:59], v[58:59], v[214:215], v[170:171]
	v_fmac_f32_e32 v236, v56, v56
	v_fmac_f32_e32 v236, v57, v57
	v_fmac_f32_e32 v236, v58, v58
	v_fmac_f32_e32 v236, v59, v59
	s_waitcnt vmcnt(17)
	v_pk_fma_f32 v[52:53], v[52:53], v[216:217], v[172:173]
	v_pk_fma_f32 v[54:55], v[54:55], v[218:219], v[174:175]
	v_fmac_f32_e32 v236, v52, v52
	v_fmac_f32_e32 v236, v53, v53
	v_fmac_f32_e32 v236, v54, v54
	v_fmac_f32_e32 v236, v55, v55
	s_waitcnt vmcnt(16)
	v_pk_fma_f32 v[48:49], v[48:49], v[220:221], v[176:177]
	v_pk_fma_f32 v[50:51], v[50:51], v[222:223], v[178:179]
	v_fmac_f32_e32 v236, v48, v48
	v_fmac_f32_e32 v236, v49, v49
	v_fmac_f32_e32 v236, v50, v50
	v_fmac_f32_e32 v236, v51, v51
	global_store_dwordx4 v228, v[60:63], s[12:13] sc1
	global_store_dwordx4 v228, v[56:59], s[12:13] offset:64 sc1
	global_store_dwordx4 v228, v[52:55], s[12:13] offset:512 sc1
	global_store_dwordx4 v228, v[48:51], s[12:13] offset:576 sc1
	global_load_dwordx4 v[164:167], v231, s[12:13]
	global_load_dwordx4 v[168:171], v231, s[12:13] offset:64
	global_load_dwordx4 v[172:175], v231, s[12:13] offset:512
	global_load_dwordx4 v[176:179], v231, s[12:13] offset:576
	s_waitcnt vmcnt(19)
	v_pk_fma_f32 v[44:45], v[44:45], v[196:197], v[180:181]
	v_pk_fma_f32 v[46:47], v[46:47], v[198:199], v[182:183]
	v_mul_f32_e32 v237, v44, v44
	v_fmac_f32_e32 v237, v45, v45
	v_fmac_f32_e32 v237, v46, v46
	v_fmac_f32_e32 v237, v47, v47
	s_waitcnt vmcnt(18)
	v_pk_fma_f32 v[40:41], v[40:41], v[212:213], v[184:185]
	v_pk_fma_f32 v[42:43], v[42:43], v[214:215], v[186:187]
	v_fmac_f32_e32 v237, v40, v40
	v_fmac_f32_e32 v237, v41, v41
	v_fmac_f32_e32 v237, v42, v42
	v_fmac_f32_e32 v237, v43, v43
	s_waitcnt vmcnt(17)
	v_pk_fma_f32 v[36:37], v[36:37], v[216:217], v[188:189]
	v_pk_fma_f32 v[38:39], v[38:39], v[218:219], v[190:191]
	v_fmac_f32_e32 v237, v36, v36
	v_fmac_f32_e32 v237, v37, v37
	v_fmac_f32_e32 v237, v38, v38
	v_fmac_f32_e32 v237, v39, v39
	s_waitcnt vmcnt(16)
	v_pk_fma_f32 v[32:33], v[32:33], v[220:221], v[192:193]
	v_pk_fma_f32 v[34:35], v[34:35], v[222:223], v[194:195]
	v_fmac_f32_e32 v237, v32, v32
	v_fmac_f32_e32 v237, v33, v33
	v_fmac_f32_e32 v237, v34, v34
	v_fmac_f32_e32 v237, v35, v35
	global_store_dwordx4 v229, v[44:47], s[12:13] sc1
	global_store_dwordx4 v229, v[40:43], s[12:13] offset:64 sc1
	global_store_dwordx4 v229, v[36:39], s[12:13] offset:512 sc1
	global_store_dwordx4 v229, v[32:35], s[12:13] offset:576 sc1
	s_waitcnt vmcnt(15)
	v_pk_fma_f32 v[28:29], v[28:29], v[196:197], v[128:129]
	v_pk_fma_f32 v[30:31], v[30:31], v[198:199], v[130:131]
	v_mul_f32_e32 v238, v28, v28
	v_fmac_f32_e32 v238, v29, v29
	v_fmac_f32_e32 v238, v30, v30
	v_fmac_f32_e32 v238, v31, v31
	s_waitcnt vmcnt(14)
;     __device__ __forceinline__ void operator()(const f32x4 (&acc)[2][2][4][2], const Unit& u, int wr, int wc, int fr, int fq) const {
;     ...
;                 for (int bj = 0; bj < 2; ++bj)
; #pragma unroll
;                     for (int n = 0; n < 2; ++n) { const int off = col0 + bj * HALF + n * 16; const f32x4 xo = *(const f32x4*)(s + off); *(f32x4*)(d + off) = xo + gv[bj][n] * acc[ai][bj][m][n]; }
; __device__ __forceinline__ void modpass(const float* xs_main, const float* xs_ctx, const float* mod_l, const float* g, int i, bf16_t* H, int nrows, int gw, int NGW, int lane) {
;     ...
;         float ss = 0.f;
; #pragma unroll
;         for (int j = 0; j < 2; ++j)
; #pragma unroll
;             for (int q = 0; q < 2; ++q) ss += (v[j][q][0] * v[j][q][0] + v[j][q][1] * v[j][q][1]) + (v[j][q][2] * v[j][q][2] + v[j][q][3] * v[j][q][3]);
;         const float rstd = 1.0f / sqrtf(wave_sum(ss) * (1.0f / D) + EPS);
	v_pk_fma_f32 v[24:25], v[24:25], v[212:213], v[132:133]
	v_pk_fma_f32 v[26:27], v[26:27], v[214:215], v[134:135]
	v_fmac_f32_e32 v238, v24, v24
	v_fmac_f32_e32 v238, v25, v25
	v_fmac_f32_e32 v238, v26, v26
	v_fmac_f32_e32 v238, v27, v27
	s_waitcnt vmcnt(13)
	v_pk_fma_f32 v[20:21], v[20:21], v[216:217], v[136:137]
	v_pk_fma_f32 v[22:23], v[22:23], v[218:219], v[138:139]
	v_fmac_f32_e32 v238, v20, v20
	v_fmac_f32_e32 v238, v21, v21
	v_fmac_f32_e32 v238, v22, v22
	v_fmac_f32_e32 v238, v23, v23
	s_waitcnt vmcnt(12)
	v_pk_fma_f32 v[16:17], v[16:17], v[220:221], v[140:141]
	v_pk_fma_f32 v[18:19], v[18:19], v[222:223], v[142:143]
	v_fmac_f32_e32 v238, v16, v16
	v_fmac_f32_e32 v238, v17, v17
	v_fmac_f32_e32 v238, v18, v18
	v_fmac_f32_e32 v238, v19, v19
	global_store_dwordx4 v230, v[28:31], s[12:13] sc1
	global_store_dwordx4 v230, v[24:27], s[12:13] offset:64 sc1
	global_store_dwordx4 v230, v[20:23], s[12:13] offset:512 sc1
	global_store_dwordx4 v230, v[16:19], s[12:13] offset:576 sc1
	s_waitcnt vmcnt(11)
	v_pk_fma_f32 v[12:13], v[12:13], v[196:197], v[164:165]
	v_pk_fma_f32 v[14:15], v[14:15], v[198:199], v[166:167]
	v_mul_f32_e32 v239, v12, v12
	v_fmac_f32_e32 v239, v13, v13
	v_fmac_f32_e32 v239, v14, v14
	v_fmac_f32_e32 v239, v15, v15
	s_waitcnt vmcnt(10)
	v_pk_fma_f32 v[8:9], v[8:9], v[212:213], v[168:169]
	v_pk_fma_f32 v[10:11], v[10:11], v[214:215], v[170:171]
	v_fmac_f32_e32 v239, v8, v8
	v_fmac_f32_e32 v239, v9, v9
	v_fmac_f32_e32 v239, v10, v10
	v_fmac_f32_e32 v239, v11, v11
	s_waitcnt vmcnt(9)
	v_pk_fma_f32 v[4:5], v[4:5], v[216:217], v[172:173]
	v_pk_fma_f32 v[6:7], v[6:7], v[218:219], v[174:175]
	v_fmac_f32_e32 v239, v4, v4
	v_fmac_f32_e32 v239, v5, v5
	v_fmac_f32_e32 v239, v6, v6
	v_fmac_f32_e32 v239, v7, v7
	s_waitcnt vmcnt(8)
	v_pk_fma_f32 v[0:1], v[0:1], v[220:221], v[176:177]
	v_pk_fma_f32 v[2:3], v[2:3], v[222:223], v[178:179]
	v_fmac_f32_e32 v239, v0, v0
	v_fmac_f32_e32 v239, v1, v1
	v_fmac_f32_e32 v239, v2, v2
	v_fmac_f32_e32 v239, v3, v3
	global_store_dwordx4 v231, v[12:15], s[12:13] sc1
	global_store_dwordx4 v231, v[8:11], s[12:13] offset:64 sc1
	global_store_dwordx4 v231, v[4:7], s[12:13] offset:512 sc1
	global_store_dwordx4 v231, v[0:3], s[12:13] offset:576 sc1
	v_mbcnt_lo_u32_b32 v240, -1, 0
	v_mbcnt_hi_u32_b32 v240, -1, v240
	v_xor_b32_e32 v241, 16, v240
	v_xor_b32_e32 v242, 32, v240
	v_lshlrev_b32_e32 v241, 2, v241
	v_lshlrev_b32_e32 v242, 2, v242
	s_waitcnt lgkmcnt(0)
	ds_bpermute_b32 v128, v241, v232
	ds_bpermute_b32 v129, v241, v233
	ds_bpermute_b32 v130, v241, v234
	ds_bpermute_b32 v131, v241, v235
	ds_bpermute_b32 v132, v241, v236
	ds_bpermute_b32 v133, v241, v237
	ds_bpermute_b32 v134, v241, v238
	ds_bpermute_b32 v135, v241, v239
	s_waitcnt lgkmcnt(7)
	v_add_f32_e32 v232, v232, v128
	s_waitcnt lgkmcnt(6)
	v_add_f32_e32 v233, v233, v129
	s_waitcnt lgkmcnt(5)
	v_add_f32_e32 v234, v234, v130
	s_waitcnt lgkmcnt(4)
	v_add_f32_e32 v235, v235, v131
	s_waitcnt lgkmcnt(3)
	v_add_f32_e32 v236, v236, v132
	s_waitcnt lgkmcnt(2)
	v_add_f32_e32 v237, v237, v133
	s_waitcnt lgkmcnt(1)
	v_add_f32_e32 v238, v238, v134
	s_waitcnt lgkmcnt(0)
	v_add_f32_e32 v239, v239, v135
	ds_bpermute_b32 v128, v242, v232
	ds_bpermute_b32 v129, v242, v233
	ds_bpermute_b32 v130, v242, v234
	ds_bpermute_b32 v131, v242, v235
	ds_bpermute_b32 v132, v242, v236
	ds_bpermute_b32 v133, v242, v237
	ds_bpermute_b32 v134, v242, v238
	ds_bpermute_b32 v135, v242, v239
	s_waitcnt lgkmcnt(7)
	v_add_f32_e32 v232, v232, v128
	s_waitcnt lgkmcnt(6)
	v_add_f32_e32 v233, v233, v129
	s_waitcnt lgkmcnt(5)
	v_add_f32_e32 v234, v234, v130
	s_waitcnt lgkmcnt(4)
	v_add_f32_e32 v235, v235, v131
	s_waitcnt lgkmcnt(3)
	v_add_f32_e32 v236, v236, v132
	s_waitcnt lgkmcnt(2)
	v_add_f32_e32 v237, v237, v133
	s_waitcnt lgkmcnt(1)
	v_add_f32_e32 v238, v238, v134
	s_waitcnt lgkmcnt(0)
	v_add_f32_e32 v239, v239, v135
	v_lshlrev_b32_e32 v243, 2, v156
	s_add_u32 s90, s76, 0x6500000
	s_addc_u32 s91, s77, 0
	s_add_u32 s76, s76, 0x3142000
	s_addc_u32 s77, s77, 0
	s_lshl_b32 s83, s40, 6
	s_add_u32 s78, s76, s83
	s_addc_u32 s79, s77, 0
	s_add_u32 s78, s78, 0x20000
	s_addc_u32 s79, s79, 0
	s_mov_b64 s[80:81], exec
	s_mov_b64 exec, 0xffff
	global_atomic_add_f32 v243, v232, s[76:77]
	global_atomic_add_f32 v243, v233, s[76:77] offset:64
	global_atomic_add_f32 v243, v234, s[76:77] offset:128
	global_atomic_add_f32 v243, v235, s[76:77] offset:192
	global_atomic_add_f32 v243, v236, s[76:77] offset:512
	global_atomic_add_f32 v243, v237, s[76:77] offset:576
	global_atomic_add_f32 v243, v238, s[76:77] offset:640
	global_atomic_add_f32 v243, v239, s[76:77] offset:704
	s_mov_b64 exec, s[80:81]
	s_add_u32 s86, s8, 0x1000
	s_addc_u32 s87, s9, 0
	s_add_u32 s88, s86, 0x1000
	s_addc_u32 s89, s87, 0
	s_add_u32 s92, s92, 0x2000
	s_addc_u32 s93, s93, 0
	s_mov_b32 s84, 0xffff0000
	s_mov_b32 s85, 0xffff0000
	s_waitcnt vmcnt(0)
	s_barrier
	v_readfirstlane_b32 s83, v206
	v_mov_b32_e32 v244, 0
	v_mov_b32_e32 v245, 1
	s_cmp_lg_u32 s83, 0
	s_cbranch_scc1 .Lfmcs_wait_done
	s_mov_b64 exec, 1
	global_atomic_add v244, v245, s[78:79]
	s_mov_b32 s82, 0

; __device__ __forceinline__ unsigned cvtpk_s(float lo, float hi) { f32x2_t v = {lo, hi}; bf16x2_t b = __builtin_convertvector(v, bf16x2_t); return __builtin_bit_cast(unsigned, b); }
; __device__ __forceinline__ u32x4 quad_swap(unsigned lo0, unsigned lo1, unsigned hi0, unsigned hi1, int fq, int& coloff) {
;     const bool odd = fq & 1;
;     const unsigned s0 = odd ? lo0 : hi0, s1 = odd ? lo1 : hi1;
;     const unsigned r0 = (unsigned)__shfl_xor((int)s0, 16), r1 = (unsigned)__shfl_xor((int)s1, 16);
;     coloff = odd ? 16 + 4 * (fq - 1) : 4 * fq;
;     u32x4 o; o.x = odd ? r0 : lo0; o.y = odd ? r1 : lo1; o.z = odd ? hi0 : r0; o.w = odd ? hi1 : r1; return o;
; __device__ __forceinline__ void modpass(const float* xs_main, const float* xs_ctx, const float* mod_l, const float* g, int i, bf16_t* H, int nrows, int gw, int NGW, int lane) {
;     ...
;         if (cond != cur) { cur = cond; const float* shift = mod_l + cond * 9216 + 3 * i * 1024; const float* scale = shift + 1024;
; #pragma unroll
;             for (int j = 0; j < 2; ++j)
; #pragma unroll
;                 for (int q = 0; q < 2; ++q) { const int c = 8 * lane + 512 * j + 4 * q; gm[j][q] = *(const f32x4*)(g + c) * (*(const f32x4*)(scale + c) + 1.0f); sh[j][q] = *(const f32x4*)(shift + c); } }
;         float ss = 0.f;
; #pragma unroll
;         for (int j = 0; j < 2; ++j)
; #pragma unroll
;             for (int q = 0; q < 2; ++q) ss += (v[j][q][0] * v[j][q][0] + v[j][q][1] * v[j][q][1]) + (v[j][q][2] * v[j][q][2] + v[j][q][3] * v[j][q][3]);
;         const float rstd = 1.0f / sqrtf(wave_sum(ss) * (1.0f / D) + EPS);
; #pragma unroll
;         for (int j = 0; j < 2; ++j) {
;             const f32x4 o0 = v[j][0] * rstd * gm[j][0] + sh[j][0], o1 = v[j][1] * rstd * gm[j][1] + sh[j][1];
;             u32x4 w; w.x = cvtpk_s(o0[0], o0[1]); w.y = cvtpk_s(o0[2], o0[3]); w.z = cvtpk_s(o1[0], o1[1]); w.w = cvtpk_s(o1[2], o1[3]);
;             *(u32x4*)(H + (size_t)row * D + 8 * lane + 512 * j) = w;
.Lfmcs_wait_done:
	s_barrier
	global_load_dword v132, v243, s[76:77] sc1
	global_load_dword v133, v243, s[76:77] offset:64 sc1
	global_load_dword v134, v243, s[76:77] offset:128 sc1
	global_load_dword v135, v243, s[76:77] offset:192 sc1
	global_load_dword v136, v243, s[76:77] offset:512 sc1
	global_load_dword v137, v243, s[76:77] offset:576 sc1
	global_load_dword v138, v243, s[76:77] offset:640 sc1
	global_load_dword v139, v243, s[76:77] offset:704 sc1
	global_load_dwordx4 v[196:199], v201, s[86:87]
	global_load_dwordx4 v[212:215], v201, s[86:87] offset:64
	global_load_dwordx4 v[216:219], v201, s[86:87] offset:512
	global_load_dwordx4 v[220:223], v201, s[86:87] offset:576
	global_load_dwordx4 v[140:143], v201, s[88:89]
	global_load_dwordx4 v[164:167], v201, s[88:89] offset:64
	global_load_dwordx4 v[168:171], v201, s[88:89] offset:512
	global_load_dwordx4 v[172:175], v201, s[88:89] offset:576
	global_load_dwordx4 v[176:179], v201, s[92:93]
	global_load_dwordx4 v[180:183], v201, s[92:93] offset:64
	global_load_dwordx4 v[184:187], v201, s[92:93] offset:512
	global_load_dwordx4 v[188:191], v201, s[92:93] offset:576
	v_mov_b32_e32 v240, 12
	v_cndmask_b32_e64 v240, 0, v240, s[84:85]
	v_add_u32_e32 v240, v240, v157
	v_lshlrev_b32_e32 v240, 1, v240
	v_lshl_add_u32 v247, v156, 11, v240
	v_mov_b32_e32 v240, 0x358637bd
	s_waitcnt vmcnt(0)
	v_fmamk_f32 v132, v132, 0x3a800000, v240
	v_fmamk_f32 v133, v133, 0x3a800000, v240
	v_fmamk_f32 v134, v134, 0x3a800000, v240
	v_fmamk_f32 v135, v135, 0x3a800000, v240
	v_fmamk_f32 v136, v136, 0x3a800000, v240
	v_fmamk_f32 v137, v137, 0x3a800000, v240
	v_fmamk_f32 v138, v138, 0x3a800000, v240
	v_fmamk_f32 v139, v139, 0x3a800000, v240
	v_rsq_f32_e32 v132, v132
	v_rsq_f32_e32 v133, v133
	v_rsq_f32_e32 v134, v134
	v_rsq_f32_e32 v135, v135
	v_rsq_f32_e32 v136, v136
	v_rsq_f32_e32 v137, v137
	v_rsq_f32_e32 v138, v138
	v_rsq_f32_e32 v139, v139
	v_pk_add_f32 v[140:141], v[140:141], 1.0 op_sel_hi:[1,0]
	v_pk_mul_f32 v[140:141], v[176:177], v[140:141]
	v_pk_add_f32 v[142:143], v[142:143], 1.0 op_sel_hi:[1,0]
	v_pk_mul_f32 v[142:143], v[178:179], v[142:143]
	v_pk_add_f32 v[164:165], v[164:165], 1.0 op_sel_hi:[1,0]
	v_pk_mul_f32 v[164:165], v[180:181], v[164:165]
	v_pk_add_f32 v[166:167], v[166:167], 1.0 op_sel_hi:[1,0]
	v_pk_mul_f32 v[166:167], v[182:183], v[166:167]
	v_pk_add_f32 v[168:169], v[168:169], 1.0 op_sel_hi:[1,0]
	v_pk_mul_f32 v[168:169], v[184:185], v[168:169]
	v_pk_add_f32 v[170:171], v[170:171], 1.0 op_sel_hi:[1,0]
	v_pk_mul_f32 v[170:171], v[186:187], v[170:171]
	v_pk_add_f32 v[172:173], v[172:173], 1.0 op_sel_hi:[1,0]
	v_pk_mul_f32 v[172:173], v[188:189], v[172:173]
	v_pk_add_f32 v[174:175], v[174:175], 1.0 op_sel_hi:[1,0]
	v_pk_mul_f32 v[174:175], v[190:191], v[174:175]
	v_mul_f32_e32 v124, v124, v132
	v_mul_f32_e32 v125, v125, v132
	v_pk_fma_f32 v[124:125], v[140:141], v[124:125], v[196:197]
	v_mul_f32_e32 v126, v126, v132
	v_mul_f32_e32 v127, v127, v132
	v_pk_fma_f32 v[126:127], v[142:143], v[126:127], v[198:199]
	v_cvt_pk_bf16_f32 v184, v124, v125
	v_cvt_pk_bf16_f32 v185, v126, v127
	v_mul_f32_e32 v120, v120, v132
	v_mul_f32_e32 v121, v121, v132
	v_pk_fma_f32 v[120:121], v[164:165], v[120:121], v[212:213]
	v_mul_f32_e32 v122, v122, v132
	v_mul_f32_e32 v123, v123, v132
	v_pk_fma_f32 v[122:123], v[166:167], v[122:123], v[214:215]
	v_cvt_pk_bf16_f32 v186, v120, v121
	v_cvt_pk_bf16_f32 v187, v122, v123
	v_mul_f32_e32 v116, v116, v132
	v_mul_f32_e32 v117, v117, v132
	v_pk_fma_f32 v[116:117], v[168:169], v[116:117], v[216:217]
	v_mul_f32_e32 v118, v118, v132
	v_mul_f32_e32 v119, v119, v132
	v_pk_fma_f32 v[118:119], v[170:171], v[118:119], v[218:219]
	v_cvt_pk_bf16_f32 v188, v116, v117
	v_cvt_pk_bf16_f32 v189, v118, v119
	v_mul_f32_e32 v112, v112, v132
	v_mul_f32_e32 v113, v113, v132
	v_pk_fma_f32 v[112:113], v[172:173], v[112:113], v[220:221]
	v_mul_f32_e32 v114, v114, v132
	v_mul_f32_e32 v115, v115, v132
	v_pk_fma_f32 v[114:115], v[174:175], v[114:115], v[222:223]
	v_cvt_pk_bf16_f32 v190, v112, v113
	v_cvt_pk_bf16_f32 v191, v114, v115
	v_mov_b32_e32 v240, v247
	v_cndmask_b32_e64 v192, v186, v184, s[84:85]
	v_cndmask_b32_e64 v193, v187, v185, s[84:85]
	ds_bpermute_b32 v194, v241, v192
	ds_bpermute_b32 v195, v241, v193
	s_waitcnt lgkmcnt(0)
	v_cndmask_b32_e64 v176, v184, v194, s[84:85]
	v_cndmask_b32_e64 v177, v185, v195, s[84:85]
	v_cndmask_b32_e64 v178, v194, v186, s[84:85]
	v_cndmask_b32_e64 v179, v195, v187, s[84:85]
	global_store_dwordx4 v240, v[176:179], s[90:91] sc1
	v_cndmask_b32_e64 v192, v190, v188, s[84:85]
	v_cndmask_b32_e64 v193, v191, v189, s[84:85]
	ds_bpermute_b32 v194, v241, v192
	ds_bpermute_b32 v195, v241, v193
	s_waitcnt lgkmcnt(0)
	v_cndmask_b32_e64 v180, v188, v194, s[84:85]
	v_cndmask_b32_e64 v181, v189, v195, s[84:85]
	v_cndmask_b32_e64 v182, v194, v190, s[84:85]
	v_cndmask_b32_e64 v183, v195, v191, s[84:85]
	global_store_dwordx4 v240, v[180:183], s[90:91] offset:256 sc1
	v_mul_f32_e32 v108, v108, v133
	v_mul_f32_e32 v109, v109, v133
	v_pk_fma_f32 v[108:109], v[140:141], v[108:109], v[196:197]
	v_mul_f32_e32 v110, v110, v133
	v_mul_f32_e32 v111, v111, v133
	v_pk_fma_f32 v[110:111], v[142:143], v[110:111], v[198:199]
	v_cvt_pk_bf16_f32 v184, v108, v109
	v_cvt_pk_bf16_f32 v185, v110, v111
	v_mul_f32_e32 v104, v104, v133
	v_mul_f32_e32 v105, v105, v133
	v_pk_fma_f32 v[104:105], v[164:165], v[104:105], v[212:213]
	v_mul_f32_e32 v106, v106, v133
	v_mul_f32_e32 v107, v107, v133
	v_pk_fma_f32 v[106:107], v[166:167], v[106:107], v[214:215]
	v_cvt_pk_bf16_f32 v186, v104, v105
	v_cvt_pk_bf16_f32 v187, v106, v107
	v_mul_f32_e32 v100, v100, v133
	v_mul_f32_e32 v101, v101, v133
	v_pk_fma_f32 v[100:101], v[168:169], v[100:101], v[216:217]
	v_mul_f32_e32 v102, v102, v133
	v_mul_f32_e32 v103, v103, v133
	v_pk_fma_f32 v[102:103], v[170:171], v[102:103], v[218:219]
	v_cvt_pk_bf16_f32 v188, v100, v101
	v_cvt_pk_bf16_f32 v189, v102, v103
	v_mul_f32_e32 v96, v96, v133
	v_mul_f32_e32 v97, v97, v133
	v_pk_fma_f32 v[96:97], v[172:173], v[96:97], v[220:221]
	v_mul_f32_e32 v98, v98, v133
	v_mul_f32_e32 v99, v99, v133
	v_pk_fma_f32 v[98:99], v[174:175], v[98:99], v[222:223]
	v_cvt_pk_bf16_f32 v190, v96, v97
	v_cvt_pk_bf16_f32 v191, v98, v99
	v_add_u32_e32 v240, 0x8000, v247
	v_cndmask_b32_e64 v192, v186, v184, s[84:85]
	v_cndmask_b32_e64 v193, v187, v185, s[84:85]
	ds_bpermute_b32 v194, v241, v192
	ds_bpermute_b32 v195, v241, v193
	s_waitcnt lgkmcnt(0)
; __device__ __forceinline__ unsigned cvtpk_s(float lo, float hi) { f32x2_t v = {lo, hi}; bf16x2_t b = __builtin_convertvector(v, bf16x2_t); return __builtin_bit_cast(unsigned, b); }
; __device__ __forceinline__ u32x4 quad_swap(unsigned lo0, unsigned lo1, unsigned hi0, unsigned hi1, int fq, int& coloff) {
;     const bool odd = fq & 1;
;     const unsigned s0 = odd ? lo0 : hi0, s1 = odd ? lo1 : hi1;
;     const unsigned r0 = (unsigned)__shfl_xor((int)s0, 16), r1 = (unsigned)__shfl_xor((int)s1, 16);
;     coloff = odd ? 16 + 4 * (fq - 1) : 4 * fq;
;     u32x4 o; o.x = odd ? r0 : lo0; o.y = odd ? r1 : lo1; o.z = odd ? hi0 : r0; o.w = odd ? hi1 : r1; return o;
; __device__ __forceinline__ void modpass(const float* xs_main, const float* xs_ctx, const float* mod_l, const float* g, int i, bf16_t* H, int nrows, int gw, int NGW, int lane) {
;     ...
;         for (int j = 0; j < 2; ++j) {
;             const f32x4 o0 = v[j][0] * rstd * gm[j][0] + sh[j][0], o1 = v[j][1] * rstd * gm[j][1] + sh[j][1];
;             u32x4 w; w.x = cvtpk_s(o0[0], o0[1]); w.y = cvtpk_s(o0[2], o0[3]); w.z = cvtpk_s(o1[0], o1[1]); w.w = cvtpk_s(o1[2], o1[3]);
;             *(u32x4*)(H + (size_t)row * D + 8 * lane + 512 * j) = w;
	v_cndmask_b32_e64 v176, v184, v194, s[84:85]
	v_cndmask_b32_e64 v177, v185, v195, s[84:85]
	v_cndmask_b32_e64 v178, v194, v186, s[84:85]
	v_cndmask_b32_e64 v179, v195, v187, s[84:85]
	global_store_dwordx4 v240, v[176:179], s[90:91] sc1
	v_cndmask_b32_e64 v192, v190, v188, s[84:85]
	v_cndmask_b32_e64 v193, v191, v189, s[84:85]
	ds_bpermute_b32 v194, v241, v192
	ds_bpermute_b32 v195, v241, v193
	s_waitcnt lgkmcnt(0)
	v_cndmask_b32_e64 v180, v188, v194, s[84:85]
	v_cndmask_b32_e64 v181, v189, v195, s[84:85]
	v_cndmask_b32_e64 v182, v194, v190, s[84:85]
	v_cndmask_b32_e64 v183, v195, v191, s[84:85]
	global_store_dwordx4 v240, v[180:183], s[90:91] offset:256 sc1
	v_mul_f32_e32 v92, v92, v134
	v_mul_f32_e32 v93, v93, v134
	v_pk_fma_f32 v[92:93], v[140:141], v[92:93], v[196:197]
	v_mul_f32_e32 v94, v94, v134
	v_mul_f32_e32 v95, v95, v134
	v_pk_fma_f32 v[94:95], v[142:143], v[94:95], v[198:199]
	v_cvt_pk_bf16_f32 v184, v92, v93
	v_cvt_pk_bf16_f32 v185, v94, v95
	v_mul_f32_e32 v88, v88, v134
	v_mul_f32_e32 v89, v89, v134
	v_pk_fma_f32 v[88:89], v[164:165], v[88:89], v[212:213]
	v_mul_f32_e32 v90, v90, v134
	v_mul_f32_e32 v91, v91, v134
	v_pk_fma_f32 v[90:91], v[166:167], v[90:91], v[214:215]
	v_cvt_pk_bf16_f32 v186, v88, v89
	v_cvt_pk_bf16_f32 v187, v90, v91
	v_mul_f32_e32 v84, v84, v134
	v_mul_f32_e32 v85, v85, v134
	v_pk_fma_f32 v[84:85], v[168:169], v[84:85], v[216:217]
	v_mul_f32_e32 v86, v86, v134
	v_mul_f32_e32 v87, v87, v134
	v_pk_fma_f32 v[86:87], v[170:171], v[86:87], v[218:219]
	v_cvt_pk_bf16_f32 v188, v84, v85
	v_cvt_pk_bf16_f32 v189, v86, v87
	v_mul_f32_e32 v80, v80, v134
	v_mul_f32_e32 v81, v81, v134
	v_pk_fma_f32 v[80:81], v[172:173], v[80:81], v[220:221]
	v_mul_f32_e32 v82, v82, v134
	v_mul_f32_e32 v83, v83, v134
	v_pk_fma_f32 v[82:83], v[174:175], v[82:83], v[222:223]
	v_cvt_pk_bf16_f32 v190, v80, v81
	v_cvt_pk_bf16_f32 v191, v82, v83
	v_add_u32_e32 v240, 0x10000, v247
	v_cndmask_b32_e64 v192, v186, v184, s[84:85]
	v_cndmask_b32_e64 v193, v187, v185, s[84:85]
	ds_bpermute_b32 v194, v241, v192
	ds_bpermute_b32 v195, v241, v193
	s_waitcnt lgkmcnt(0)
	v_cndmask_b32_e64 v176, v184, v194, s[84:85]
	v_cndmask_b32_e64 v177, v185, v195, s[84:85]
	v_cndmask_b32_e64 v178, v194, v186, s[84:85]
	v_cndmask_b32_e64 v179, v195, v187, s[84:85]
	global_store_dwordx4 v240, v[176:179], s[90:91] sc1
	v_cndmask_b32_e64 v192, v190, v188, s[84:85]
	v_cndmask_b32_e64 v193, v191, v189, s[84:85]
	ds_bpermute_b32 v194, v241, v192
	ds_bpermute_b32 v195, v241, v193
	s_waitcnt lgkmcnt(0)
	v_cndmask_b32_e64 v180, v188, v194, s[84:85]
	v_cndmask_b32_e64 v181, v189, v195, s[84:85]
	v_cndmask_b32_e64 v182, v194, v190, s[84:85]
	v_cndmask_b32_e64 v183, v195, v191, s[84:85]
	global_store_dwordx4 v240, v[180:183], s[90:91] offset:256 sc1
	v_mul_f32_e32 v76, v76, v135
	v_mul_f32_e32 v77, v77, v135
	v_pk_fma_f32 v[76:77], v[140:141], v[76:77], v[196:197]
	v_mul_f32_e32 v78, v78, v135
	v_mul_f32_e32 v79, v79, v135
	v_pk_fma_f32 v[78:79], v[142:143], v[78:79], v[198:199]
	v_cvt_pk_bf16_f32 v184, v76, v77
	v_cvt_pk_bf16_f32 v185, v78, v79
	v_mul_f32_e32 v72, v72, v135
	v_mul_f32_e32 v73, v73, v135
	v_pk_fma_f32 v[72:73], v[164:165], v[72:73], v[212:213]
	v_mul_f32_e32 v74, v74, v135
	v_mul_f32_e32 v75, v75, v135
	v_pk_fma_f32 v[74:75], v[166:167], v[74:75], v[214:215]
	v_cvt_pk_bf16_f32 v186, v72, v73
	v_cvt_pk_bf16_f32 v187, v74, v75
	v_mul_f32_e32 v68, v68, v135
	v_mul_f32_e32 v69, v69, v135
	v_pk_fma_f32 v[68:69], v[168:169], v[68:69], v[216:217]
	v_mul_f32_e32 v70, v70, v135
	v_mul_f32_e32 v71, v71, v135
	v_pk_fma_f32 v[70:71], v[170:171], v[70:71], v[218:219]
	v_cvt_pk_bf16_f32 v188, v68, v69
	v_cvt_pk_bf16_f32 v189, v70, v71
	v_mul_f32_e32 v64, v64, v135
	v_mul_f32_e32 v65, v65, v135
	v_pk_fma_f32 v[64:65], v[172:173], v[64:65], v[220:221]
	v_mul_f32_e32 v66, v66, v135
	v_mul_f32_e32 v67, v67, v135
	v_pk_fma_f32 v[66:67], v[174:175], v[66:67], v[222:223]
	v_cvt_pk_bf16_f32 v190, v64, v65
	v_cvt_pk_bf16_f32 v191, v66, v67
	v_add_u32_e32 v240, 0x18000, v247
	v_cndmask_b32_e64 v192, v186, v184, s[84:85]
	v_cndmask_b32_e64 v193, v187, v185, s[84:85]
	ds_bpermute_b32 v194, v241, v192
	ds_bpermute_b32 v195, v241, v193
	s_waitcnt lgkmcnt(0)
	v_cndmask_b32_e64 v176, v184, v194, s[84:85]
	v_cndmask_b32_e64 v177, v185, v195, s[84:85]
	v_cndmask_b32_e64 v178, v194, v186, s[84:85]
	v_cndmask_b32_e64 v179, v195, v187, s[84:85]
	global_store_dwordx4 v240, v[176:179], s[90:91] sc1
	v_cndmask_b32_e64 v192, v190, v188, s[84:85]
	v_cndmask_b32_e64 v193, v191, v189, s[84:85]
	ds_bpermute_b32 v194, v241, v192
	ds_bpermute_b32 v195, v241, v193
	s_waitcnt lgkmcnt(0)
	v_cndmask_b32_e64 v180, v188, v194, s[84:85]
	v_cndmask_b32_e64 v181, v189, v195, s[84:85]
	v_cndmask_b32_e64 v182, v194, v190, s[84:85]
	v_cndmask_b32_e64 v183, v195, v191, s[84:85]
	global_store_dwordx4 v240, v[180:183], s[90:91] offset:256 sc1
	v_mul_f32_e32 v60, v60, v136
	v_mul_f32_e32 v61, v61, v136
	v_pk_fma_f32 v[60:61], v[140:141], v[60:61], v[196:197]
	v_mul_f32_e32 v62, v62, v136
	v_mul_f32_e32 v63, v63, v136
	v_pk_fma_f32 v[62:63], v[142:143], v[62:63], v[198:199]
	v_cvt_pk_bf16_f32 v184, v60, v61
	v_cvt_pk_bf16_f32 v185, v62, v63
	v_mul_f32_e32 v56, v56, v136
	v_mul_f32_e32 v57, v57, v136
	v_pk_fma_f32 v[56:57], v[164:165], v[56:57], v[212:213]
	v_mul_f32_e32 v58, v58, v136
	v_mul_f32_e32 v59, v59, v136
	v_pk_fma_f32 v[58:59], v[166:167], v[58:59], v[214:215]
	v_cvt_pk_bf16_f32 v186, v56, v57
	v_cvt_pk_bf16_f32 v187, v58, v59
	v_mul_f32_e32 v52, v52, v136
	v_mul_f32_e32 v53, v53, v136
	v_pk_fma_f32 v[52:53], v[168:169], v[52:53], v[216:217]
	v_mul_f32_e32 v54, v54, v136
	v_mul_f32_e32 v55, v55, v136
	v_pk_fma_f32 v[54:55], v[170:171], v[54:55], v[218:219]
	v_cvt_pk_bf16_f32 v188, v52, v53
	v_cvt_pk_bf16_f32 v189, v54, v55
	v_mul_f32_e32 v48, v48, v136
	v_mul_f32_e32 v49, v49, v136
	v_pk_fma_f32 v[48:49], v[172:173], v[48:49], v[220:221]
	v_mul_f32_e32 v50, v50, v136
	v_mul_f32_e32 v51, v51, v136
	v_pk_fma_f32 v[50:51], v[174:175], v[50:51], v[222:223]
	v_cvt_pk_bf16_f32 v190, v48, v49
	v_cvt_pk_bf16_f32 v191, v50, v51
	v_add_u32_e32 v240, 0x40000, v247
	v_cndmask_b32_e64 v192, v186, v184, s[84:85]
	v_cndmask_b32_e64 v193, v187, v185, s[84:85]
	ds_bpermute_b32 v194, v241, v192
	ds_bpermute_b32 v195, v241, v193
	s_waitcnt lgkmcnt(0)
; __device__ __forceinline__ unsigned cvtpk_s(float lo, float hi) { f32x2_t v = {lo, hi}; bf16x2_t b = __builtin_convertvector(v, bf16x2_t); return __builtin_bit_cast(unsigned, b); }
; __device__ __forceinline__ u32x4 quad_swap(unsigned lo0, unsigned lo1, unsigned hi0, unsigned hi1, int fq, int& coloff) {
;     const bool odd = fq & 1;
;     const unsigned s0 = odd ? lo0 : hi0, s1 = odd ? lo1 : hi1;
;     const unsigned r0 = (unsigned)__shfl_xor((int)s0, 16), r1 = (unsigned)__shfl_xor((int)s1, 16);
;     coloff = odd ? 16 + 4 * (fq - 1) : 4 * fq;
;     u32x4 o; o.x = odd ? r0 : lo0; o.y = odd ? r1 : lo1; o.z = odd ? hi0 : r0; o.w = odd ? hi1 : r1; return o;
; __device__ __forceinline__ void modpass(const float* xs_main, const float* xs_ctx, const float* mod_l, const float* g, int i, bf16_t* H, int nrows, int gw, int NGW, int lane) {
;     ...
;         for (int j = 0; j < 2; ++j) {
;             const f32x4 o0 = v[j][0] * rstd * gm[j][0] + sh[j][0], o1 = v[j][1] * rstd * gm[j][1] + sh[j][1];
;             u32x4 w; w.x = cvtpk_s(o0[0], o0[1]); w.y = cvtpk_s(o0[2], o0[3]); w.z = cvtpk_s(o1[0], o1[1]); w.w = cvtpk_s(o1[2], o1[3]);
;             *(u32x4*)(H + (size_t)row * D + 8 * lane + 512 * j) = w;
	v_cndmask_b32_e64 v176, v184, v194, s[84:85]
	v_cndmask_b32_e64 v177, v185, v195, s[84:85]
	v_cndmask_b32_e64 v178, v194, v186, s[84:85]
	v_cndmask_b32_e64 v179, v195, v187, s[84:85]
	global_store_dwordx4 v240, v[176:179], s[90:91] sc1
	v_cndmask_b32_e64 v192, v190, v188, s[84:85]
	v_cndmask_b32_e64 v193, v191, v189, s[84:85]
	ds_bpermute_b32 v194, v241, v192
	ds_bpermute_b32 v195, v241, v193
	s_waitcnt lgkmcnt(0)
	v_cndmask_b32_e64 v180, v188, v194, s[84:85]
	v_cndmask_b32_e64 v181, v189, v195, s[84:85]
	v_cndmask_b32_e64 v182, v194, v190, s[84:85]
	v_cndmask_b32_e64 v183, v195, v191, s[84:85]
	global_store_dwordx4 v240, v[180:183], s[90:91] offset:256 sc1
	v_mul_f32_e32 v44, v44, v137
	v_mul_f32_e32 v45, v45, v137
	v_pk_fma_f32 v[44:45], v[140:141], v[44:45], v[196:197]
	v_mul_f32_e32 v46, v46, v137
	v_mul_f32_e32 v47, v47, v137
	v_pk_fma_f32 v[46:47], v[142:143], v[46:47], v[198:199]
	v_cvt_pk_bf16_f32 v184, v44, v45
	v_cvt_pk_bf16_f32 v185, v46, v47
	v_mul_f32_e32 v40, v40, v137
	v_mul_f32_e32 v41, v41, v137
	v_pk_fma_f32 v[40:41], v[164:165], v[40:41], v[212:213]
	v_mul_f32_e32 v42, v42, v137
	v_mul_f32_e32 v43, v43, v137
	v_pk_fma_f32 v[42:43], v[166:167], v[42:43], v[214:215]
	v_cvt_pk_bf16_f32 v186, v40, v41
	v_cvt_pk_bf16_f32 v187, v42, v43
	v_mul_f32_e32 v36, v36, v137
	v_mul_f32_e32 v37, v37, v137
	v_pk_fma_f32 v[36:37], v[168:169], v[36:37], v[216:217]
	v_mul_f32_e32 v38, v38, v137
	v_mul_f32_e32 v39, v39, v137
	v_pk_fma_f32 v[38:39], v[170:171], v[38:39], v[218:219]
	v_cvt_pk_bf16_f32 v188, v36, v37
	v_cvt_pk_bf16_f32 v189, v38, v39
	v_mul_f32_e32 v32, v32, v137
	v_mul_f32_e32 v33, v33, v137
	v_pk_fma_f32 v[32:33], v[172:173], v[32:33], v[220:221]
	v_mul_f32_e32 v34, v34, v137
	v_mul_f32_e32 v35, v35, v137
	v_pk_fma_f32 v[34:35], v[174:175], v[34:35], v[222:223]
	v_cvt_pk_bf16_f32 v190, v32, v33
	v_cvt_pk_bf16_f32 v191, v34, v35
	v_add_u32_e32 v240, 0x48000, v247
	v_cndmask_b32_e64 v192, v186, v184, s[84:85]
	v_cndmask_b32_e64 v193, v187, v185, s[84:85]
	ds_bpermute_b32 v194, v241, v192
	ds_bpermute_b32 v195, v241, v193
	s_waitcnt lgkmcnt(0)
	v_cndmask_b32_e64 v176, v184, v194, s[84:85]
	v_cndmask_b32_e64 v177, v185, v195, s[84:85]
	v_cndmask_b32_e64 v178, v194, v186, s[84:85]
	v_cndmask_b32_e64 v179, v195, v187, s[84:85]
	global_store_dwordx4 v240, v[176:179], s[90:91] sc1
	v_cndmask_b32_e64 v192, v190, v188, s[84:85]
	v_cndmask_b32_e64 v193, v191, v189, s[84:85]
	ds_bpermute_b32 v194, v241, v192
	ds_bpermute_b32 v195, v241, v193
	s_waitcnt lgkmcnt(0)
	v_cndmask_b32_e64 v180, v188, v194, s[84:85]
	v_cndmask_b32_e64 v181, v189, v195, s[84:85]
	v_cndmask_b32_e64 v182, v194, v190, s[84:85]
	v_cndmask_b32_e64 v183, v195, v191, s[84:85]
	global_store_dwordx4 v240, v[180:183], s[90:91] offset:256 sc1
	v_mul_f32_e32 v28, v28, v138
	v_mul_f32_e32 v29, v29, v138
	v_pk_fma_f32 v[28:29], v[140:141], v[28:29], v[196:197]
	v_mul_f32_e32 v30, v30, v138
	v_mul_f32_e32 v31, v31, v138
	v_pk_fma_f32 v[30:31], v[142:143], v[30:31], v[198:199]
	v_cvt_pk_bf16_f32 v184, v28, v29
	v_cvt_pk_bf16_f32 v185, v30, v31
	v_mul_f32_e32 v24, v24, v138
	v_mul_f32_e32 v25, v25, v138
	v_pk_fma_f32 v[24:25], v[164:165], v[24:25], v[212:213]
	v_mul_f32_e32 v26, v26, v138
	v_mul_f32_e32 v27, v27, v138
	v_pk_fma_f32 v[26:27], v[166:167], v[26:27], v[214:215]
	v_cvt_pk_bf16_f32 v186, v24, v25
	v_cvt_pk_bf16_f32 v187, v26, v27
	v_mul_f32_e32 v20, v20, v138
	v_mul_f32_e32 v21, v21, v138
	v_pk_fma_f32 v[20:21], v[168:169], v[20:21], v[216:217]
	v_mul_f32_e32 v22, v22, v138
	v_mul_f32_e32 v23, v23, v138
	v_pk_fma_f32 v[22:23], v[170:171], v[22:23], v[218:219]
	v_cvt_pk_bf16_f32 v188, v20, v21
	v_cvt_pk_bf16_f32 v189, v22, v23
	v_mul_f32_e32 v16, v16, v138
	v_mul_f32_e32 v17, v17, v138
	v_pk_fma_f32 v[16:17], v[172:173], v[16:17], v[220:221]
	v_mul_f32_e32 v18, v18, v138
	v_mul_f32_e32 v19, v19, v138
	v_pk_fma_f32 v[18:19], v[174:175], v[18:19], v[222:223]
	v_cvt_pk_bf16_f32 v190, v16, v17
	v_cvt_pk_bf16_f32 v191, v18, v19
	v_add_u32_e32 v240, 0x50000, v247
	v_cndmask_b32_e64 v192, v186, v184, s[84:85]
	v_cndmask_b32_e64 v193, v187, v185, s[84:85]
	ds_bpermute_b32 v194, v241, v192
	ds_bpermute_b32 v195, v241, v193
	s_waitcnt lgkmcnt(0)
	v_cndmask_b32_e64 v176, v184, v194, s[84:85]
	v_cndmask_b32_e64 v177, v185, v195, s[84:85]
	v_cndmask_b32_e64 v178, v194, v186, s[84:85]
	v_cndmask_b32_e64 v179, v195, v187, s[84:85]
	global_store_dwordx4 v240, v[176:179], s[90:91] sc1
	v_cndmask_b32_e64 v192, v190, v188, s[84:85]
	v_cndmask_b32_e64 v193, v191, v189, s[84:85]
	ds_bpermute_b32 v194, v241, v192
	ds_bpermute_b32 v195, v241, v193
	s_waitcnt lgkmcnt(0)
	v_cndmask_b32_e64 v180, v188, v194, s[84:85]
	v_cndmask_b32_e64 v181, v189, v195, s[84:85]
	v_cndmask_b32_e64 v182, v194, v190, s[84:85]
	v_cndmask_b32_e64 v183, v195, v191, s[84:85]
	global_store_dwordx4 v240, v[180:183], s[90:91] offset:256 sc1
	v_mul_f32_e32 v12, v12, v139
	v_mul_f32_e32 v13, v13, v139
	v_pk_fma_f32 v[12:13], v[140:141], v[12:13], v[196:197]
	v_mul_f32_e32 v14, v14, v139
	v_mul_f32_e32 v15, v15, v139
	v_pk_fma_f32 v[14:15], v[142:143], v[14:15], v[198:199]
	v_cvt_pk_bf16_f32 v184, v12, v13
	v_cvt_pk_bf16_f32 v185, v14, v15
	v_mul_f32_e32 v8, v8, v139
	v_mul_f32_e32 v9, v9, v139
	v_pk_fma_f32 v[8:9], v[164:165], v[8:9], v[212:213]
	v_mul_f32_e32 v10, v10, v139
	v_mul_f32_e32 v11, v11, v139
	v_pk_fma_f32 v[10:11], v[166:167], v[10:11], v[214:215]
	v_cvt_pk_bf16_f32 v186, v8, v9
	v_cvt_pk_bf16_f32 v187, v10, v11
	v_mul_f32_e32 v4, v4, v139
	v_mul_f32_e32 v5, v5, v139
	v_pk_fma_f32 v[4:5], v[168:169], v[4:5], v[216:217]
	v_mul_f32_e32 v6, v6, v139
	v_mul_f32_e32 v7, v7, v139
	v_pk_fma_f32 v[6:7], v[170:171], v[6:7], v[218:219]
	v_cvt_pk_bf16_f32 v188, v4, v5
	v_cvt_pk_bf16_f32 v189, v6, v7
	v_mul_f32_e32 v0, v0, v139
	v_mul_f32_e32 v1, v1, v139
	v_pk_fma_f32 v[0:1], v[172:173], v[0:1], v[220:221]
	v_mul_f32_e32 v2, v2, v139
	v_mul_f32_e32 v3, v3, v139
	v_pk_fma_f32 v[2:3], v[174:175], v[2:3], v[222:223]
	v_cvt_pk_bf16_f32 v190, v0, v1
	v_cvt_pk_bf16_f32 v191, v2, v3
	v_add_u32_e32 v240, 0x58000, v247
	v_cndmask_b32_e64 v192, v186, v184, s[84:85]
	v_cndmask_b32_e64 v193, v187, v185, s[84:85]
	ds_bpermute_b32 v194, v241, v192
	ds_bpermute_b32 v195, v241, v193
	s_waitcnt lgkmcnt(0)
	v_cndmask_b32_e64 v176, v184, v194, s[84:85]
	v_cndmask_b32_e64 v177, v185, v195, s[84:85]
	v_cndmask_b32_e64 v178, v194, v186, s[84:85]
	v_cndmask_b32_e64 v179, v195, v187, s[84:85]
	global_store_dwordx4 v240, v[176:179], s[90:91] sc1
	v_cndmask_b32_e64 v192, v190, v188, s[84:85]
	v_cndmask_b32_e64 v193, v191, v189, s[84:85]
	ds_bpermute_b32 v194, v241, v192
	ds_bpermute_b32 v195, v241, v193
	s_waitcnt lgkmcnt(0)
	v_cndmask_b32_e64 v180, v188, v194, s[84:85]
	v_cndmask_b32_e64 v181, v189, v195, s[84:85]
	v_cndmask_b32_e64 v182, v194, v190, s[84:85]
	v_cndmask_b32_e64 v183, v195, v191, s[84:85]
	global_store_dwordx4 v240, v[180:183], s[90:91] offset:256 sc1
	s_andn2_b64 vcc, exec, s[10:11]
	s_mov_b64 s[10:11], -1
;     ...
;         if constexpr (!Epi::AFTER_DRAIN) { E(acc, cur, wr, wc, fr, fq); S.done(cur); }
;         if (!has_next) break;
.Lfmdone_c:
	s_cbranch_vccnz .LBB0_1115
	s_andn2_b64 vcc, exec, s[14:15]
	s_cbranch_vccnz .LBB0_1114
	s_barrier
	s_branch .LBB0_1114

;     __device__ __forceinline__ void operator()(const f32x4 (&acc)[2][2][4][2], const Unit& u, int wr, int wc, int fr, int fq) const {
;         const int cond = u.pm < 64 ? 0 : (u.pm < 128 ? 1 : 2);
;         const float* gate = gate_l + cond * 9216;
;         const int col0 = u.pn * BM + wc * 32 + 4 * fq;
;         f32x4 gv[2][2];
; #pragma unroll
;         for (int bj = 0; bj < 2; ++bj)
; #pragma unroll
;             for (int n = 0; n < 2; ++n) gv[bj][n] = *(const f32x4*)(gate + col0 + bj * HALF + n * 16) * coef;
; #pragma unroll
;         for (int ai = 0; ai < 2; ++ai)
; #pragma unroll
;             for (int m = 0; m < 4; ++m) {
;                 const int row = u.pm * BM + ai * HALF + wr * 64 + m * 16 + fr;
;                 const float* s = row < MX_ ? src_main + (size_t)row * D_ : src_ctx + (size_t)(row - MX_) * D_;
;                 float* d = row < MX_ ? dst_main + (size_t)row * D_ : dst_ctx + (size_t)(row - MX_) * D_;
; #pragma unroll
;                 for (int bj = 0; bj < 2; ++bj)
; #pragma unroll
;                     for (int n = 0; n < 2; ++n) { const int off = col0 + bj * HALF + n * 16; const f32x4 xo = *(const f32x4*)(s + off); *(f32x4*)(d + off) = xo + gv[bj][n] * acc[ai][bj][m][n]; }
.LBB0_1346:
	s_and_b64 vcc, exec, s[12:13]
	s_cbranch_vccnz .Lfmsel_d
	s_cmpk_lt_i32 s6, 0x80
	s_cselect_b32 s8, s64, 0x4800
	s_cmp_gt_i32 s6, 63
	s_cselect_b32 s8, s8, 0
	s_lshl_b32 s8, s8, 2
	s_add_u32 s8, s56, s8
	s_addc_u32 s9, s57, 0
	s_load_dwordx2 s[92:93], s[0:1], 0x30
	s_load_dwordx2 s[76:77], s[0:1], 0xb8
	v_lshl_add_u32 v156, s6, 8, v158
	v_lshl_or_b32 v157, s7, 8, v160
	v_lshlrev_b32_e32 v201, 2, v157
	v_lshl_add_u32 v224, v156, 12, v201
	global_load_dwordx4 v[196:199], v201, s[8:9]
	global_load_dwordx4 v[212:215], v201, s[8:9] offset:64
	global_load_dwordx4 v[216:219], v201, s[8:9] offset:512
	global_load_dwordx4 v[220:223], v201, s[8:9] offset:576
	v_add_u32_e32 v225, 0x10000, v224
	v_add_u32_e32 v226, 0x20000, v224
	v_add_u32_e32 v227, 0x30000, v224
	v_add_u32_e32 v228, 0x80000, v224
	v_add_u32_e32 v229, 0x90000, v224
	v_add_u32_e32 v230, 0xa0000, v224
	v_add_u32_e32 v231, 0xb0000, v224
	global_load_dwordx4 v[140:143], v224, s[16:17]
	global_load_dwordx4 v[144:147], v224, s[16:17] offset:64
	global_load_dwordx4 v[148:151], v224, s[16:17] offset:512
	global_load_dwordx4 v[152:155], v224, s[16:17] offset:576
	global_load_dwordx4 v[164:167], v225, s[16:17]
	global_load_dwordx4 v[168:171], v225, s[16:17] offset:64
	global_load_dwordx4 v[172:175], v225, s[16:17] offset:512
	global_load_dwordx4 v[176:179], v225, s[16:17] offset:576
	global_load_dwordx4 v[180:183], v226, s[16:17]
	global_load_dwordx4 v[184:187], v226, s[16:17] offset:64
	global_load_dwordx4 v[188:191], v226, s[16:17] offset:512
	global_load_dwordx4 v[192:195], v226, s[16:17] offset:576
	s_waitcnt vmcnt(12)
	v_pk_mul_f32 v[196:197], v[196:197], 0.5 op_sel_hi:[1,0]
	v_pk_mul_f32 v[198:199], v[198:199], 0.5 op_sel_hi:[1,0]
	v_pk_mul_f32 v[212:213], v[212:213], 0.5 op_sel_hi:[1,0]
	v_pk_mul_f32 v[214:215], v[214:215], 0.5 op_sel_hi:[1,0]
	v_pk_mul_f32 v[216:217], v[216:217], 0.5 op_sel_hi:[1,0]
	v_pk_mul_f32 v[218:219], v[218:219], 0.5 op_sel_hi:[1,0]
	v_pk_mul_f32 v[220:221], v[220:221], 0.5 op_sel_hi:[1,0]
	v_pk_mul_f32 v[222:223], v[222:223], 0.5 op_sel_hi:[1,0]
	s_waitcnt vmcnt(11)
	v_pk_fma_f32 v[124:125], v[124:125], v[196:197], v[140:141]
	v_pk_fma_f32 v[126:127], v[126:127], v[198:199], v[142:143]
	v_mul_f32_e32 v232, v124, v124
	v_fmac_f32_e32 v232, v125, v125
	v_fmac_f32_e32 v232, v126, v126
	v_fmac_f32_e32 v232, v127, v127
	s_waitcnt vmcnt(10)
	v_pk_fma_f32 v[120:121], v[120:121], v[212:213], v[144:145]
	v_pk_fma_f32 v[122:123], v[122:123], v[214:215], v[146:147]
	v_fmac_f32_e32 v232, v120, v120
	v_fmac_f32_e32 v232, v121, v121
	v_fmac_f32_e32 v232, v122, v122
	v_fmac_f32_e32 v232, v123, v123
	s_waitcnt vmcnt(9)
	v_pk_fma_f32 v[116:117], v[116:117], v[216:217], v[148:149]
	v_pk_fma_f32 v[118:119], v[118:119], v[218:219], v[150:151]
	v_fmac_f32_e32 v232, v116, v116
	v_fmac_f32_e32 v232, v117, v117
	v_fmac_f32_e32 v232, v118, v118
	v_fmac_f32_e32 v232, v119, v119
	s_waitcnt vmcnt(8)
	v_pk_fma_f32 v[112:113], v[112:113], v[220:221], v[152:153]
	v_pk_fma_f32 v[114:115], v[114:115], v[222:223], v[154:155]
	v_fmac_f32_e32 v232, v112, v112
	v_fmac_f32_e32 v232, v113, v113
	v_fmac_f32_e32 v232, v114, v114
	v_fmac_f32_e32 v232, v115, v115
	global_store_dwordx4 v224, v[124:127], s[16:17]
	global_store_dwordx4 v224, v[120:123], s[16:17] offset:64
	global_store_dwordx4 v224, v[116:119], s[16:17] offset:512
	global_store_dwordx4 v224, v[112:115], s[16:17] offset:576
	global_load_dwordx4 v[140:143], v227, s[16:17]
	global_load_dwordx4 v[144:147], v227, s[16:17] offset:64
	global_load_dwordx4 v[148:151], v227, s[16:17] offset:512
	global_load_dwordx4 v[152:155], v227, s[16:17] offset:576
	s_waitcnt vmcnt(15)
	v_pk_fma_f32 v[108:109], v[108:109], v[196:197], v[164:165]
	v_pk_fma_f32 v[110:111], v[110:111], v[198:199], v[166:167]
	v_mul_f32_e32 v233, v108, v108
	v_fmac_f32_e32 v233, v109, v109
	v_fmac_f32_e32 v233, v110, v110
	v_fmac_f32_e32 v233, v111, v111
	s_waitcnt vmcnt(14)
	v_pk_fma_f32 v[104:105], v[104:105], v[212:213], v[168:169]
	v_pk_fma_f32 v[106:107], v[106:107], v[214:215], v[170:171]
	v_fmac_f32_e32 v233, v104, v104
	v_fmac_f32_e32 v233, v105, v105
	v_fmac_f32_e32 v233, v106, v106
	v_fmac_f32_e32 v233, v107, v107
	s_waitcnt vmcnt(13)
	v_pk_fma_f32 v[100:101], v[100:101], v[216:217], v[172:173]
	v_pk_fma_f32 v[102:103], v[102:103], v[218:219], v[174:175]
	v_fmac_f32_e32 v233, v100, v100
	v_fmac_f32_e32 v233, v101, v101
	v_fmac_f32_e32 v233, v102, v102
	v_fmac_f32_e32 v233, v103, v103
	s_waitcnt vmcnt(12)
	v_pk_fma_f32 v[96:97], v[96:97], v[220:221], v[176:177]
	v_pk_fma_f32 v[98:99], v[98:99], v[222:223], v[178:179]
	v_fmac_f32_e32 v233, v96, v96
	v_fmac_f32_e32 v233, v97, v97
	v_fmac_f32_e32 v233, v98, v98
	v_fmac_f32_e32 v233, v99, v99
	global_store_dwordx4 v225, v[108:111], s[16:17]
	global_store_dwordx4 v225, v[104:107], s[16:17] offset:64
	global_store_dwordx4 v225, v[100:103], s[16:17] offset:512
	global_store_dwordx4 v225, v[96:99], s[16:17] offset:576
	global_load_dwordx4 v[164:167], v228, s[16:17]
	global_load_dwordx4 v[168:171], v228, s[16:17] offset:64
	global_load_dwordx4 v[172:175], v228, s[16:17] offset:512
	global_load_dwordx4 v[176:179], v228, s[16:17] offset:576
	s_waitcnt vmcnt(19)
	v_pk_fma_f32 v[92:93], v[92:93], v[196:197], v[180:181]
	v_pk_fma_f32 v[94:95], v[94:95], v[198:199], v[182:183]
	v_mul_f32_e32 v234, v92, v92
	v_fmac_f32_e32 v234, v93, v93
	v_fmac_f32_e32 v234, v94, v94
	v_fmac_f32_e32 v234, v95, v95
	s_waitcnt vmcnt(18)
	v_pk_fma_f32 v[88:89], v[88:89], v[212:213], v[184:185]
	v_pk_fma_f32 v[90:91], v[90:91], v[214:215], v[186:187]
	v_fmac_f32_e32 v234, v88, v88
	v_fmac_f32_e32 v234, v89, v89
	v_fmac_f32_e32 v234, v90, v90
	v_fmac_f32_e32 v234, v91, v91
	s_waitcnt vmcnt(17)
;     __device__ __forceinline__ void operator()(const f32x4 (&acc)[2][2][4][2], const Unit& u, int wr, int wc, int fr, int fq) const {
;     ...
;                 const int row = u.pm * BM + ai * HALF + wr * 64 + m * 16 + fr;
;                 const float* s = row < MX_ ? src_main + (size_t)row * D_ : src_ctx + (size_t)(row - MX_) * D_;
;                 float* d = row < MX_ ? dst_main + (size_t)row * D_ : dst_ctx + (size_t)(row - MX_) * D_;
; #pragma unroll
;                 for (int bj = 0; bj < 2; ++bj)
; #pragma unroll
;                     for (int n = 0; n < 2; ++n) { const int off = col0 + bj * HALF + n * 16; const f32x4 xo = *(const f32x4*)(s + off); *(f32x4*)(d + off) = xo + gv[bj][n] * acc[ai][bj][m][n]; }
	v_pk_fma_f32 v[84:85], v[84:85], v[216:217], v[188:189]
	v_pk_fma_f32 v[86:87], v[86:87], v[218:219], v[190:191]
	v_fmac_f32_e32 v234, v84, v84
	v_fmac_f32_e32 v234, v85, v85
	v_fmac_f32_e32 v234, v86, v86
	v_fmac_f32_e32 v234, v87, v87
	s_waitcnt vmcnt(16)
	v_pk_fma_f32 v[80:81], v[80:81], v[220:221], v[192:193]
	v_pk_fma_f32 v[82:83], v[82:83], v[222:223], v[194:195]
	v_fmac_f32_e32 v234, v80, v80
	v_fmac_f32_e32 v234, v81, v81
	v_fmac_f32_e32 v234, v82, v82
	v_fmac_f32_e32 v234, v83, v83
	global_store_dwordx4 v226, v[92:95], s[16:17]
	global_store_dwordx4 v226, v[88:91], s[16:17] offset:64
	global_store_dwordx4 v226, v[84:87], s[16:17] offset:512
	global_store_dwordx4 v226, v[80:83], s[16:17] offset:576
	global_load_dwordx4 v[180:183], v229, s[16:17]
	global_load_dwordx4 v[184:187], v229, s[16:17] offset:64
	global_load_dwordx4 v[188:191], v229, s[16:17] offset:512
	global_load_dwordx4 v[192:195], v229, s[16:17] offset:576
	s_waitcnt vmcnt(19)
	v_pk_fma_f32 v[76:77], v[76:77], v[196:197], v[140:141]
	v_pk_fma_f32 v[78:79], v[78:79], v[198:199], v[142:143]
	v_mul_f32_e32 v235, v76, v76
	v_fmac_f32_e32 v235, v77, v77
	v_fmac_f32_e32 v235, v78, v78
	v_fmac_f32_e32 v235, v79, v79
	s_waitcnt vmcnt(18)
	v_pk_fma_f32 v[72:73], v[72:73], v[212:213], v[144:145]
	v_pk_fma_f32 v[74:75], v[74:75], v[214:215], v[146:147]
	v_fmac_f32_e32 v235, v72, v72
	v_fmac_f32_e32 v235, v73, v73
	v_fmac_f32_e32 v235, v74, v74
	v_fmac_f32_e32 v235, v75, v75
	s_waitcnt vmcnt(17)
	v_pk_fma_f32 v[68:69], v[68:69], v[216:217], v[148:149]
	v_pk_fma_f32 v[70:71], v[70:71], v[218:219], v[150:151]
	v_fmac_f32_e32 v235, v68, v68
	v_fmac_f32_e32 v235, v69, v69
	v_fmac_f32_e32 v235, v70, v70
	v_fmac_f32_e32 v235, v71, v71
	s_waitcnt vmcnt(16)
	v_pk_fma_f32 v[64:65], v[64:65], v[220:221], v[152:153]
	v_pk_fma_f32 v[66:67], v[66:67], v[222:223], v[154:155]
	v_fmac_f32_e32 v235, v64, v64
	v_fmac_f32_e32 v235, v65, v65
	v_fmac_f32_e32 v235, v66, v66
	v_fmac_f32_e32 v235, v67, v67
	global_store_dwordx4 v227, v[76:79], s[16:17]
	global_store_dwordx4 v227, v[72:75], s[16:17] offset:64
	global_store_dwordx4 v227, v[68:71], s[16:17] offset:512
	global_store_dwordx4 v227, v[64:67], s[16:17] offset:576
	global_load_dwordx4 v[140:143], v230, s[16:17]
	global_load_dwordx4 v[144:147], v230, s[16:17] offset:64
	global_load_dwordx4 v[148:151], v230, s[16:17] offset:512
	global_load_dwordx4 v[152:155], v230, s[16:17] offset:576
	s_waitcnt vmcnt(19)
	v_pk_fma_f32 v[60:61], v[60:61], v[196:197], v[164:165]
	v_pk_fma_f32 v[62:63], v[62:63], v[198:199], v[166:167]
	v_mul_f32_e32 v236, v60, v60
	v_fmac_f32_e32 v236, v61, v61
	v_fmac_f32_e32 v236, v62, v62
	v_fmac_f32_e32 v236, v63, v63
	s_waitcnt vmcnt(18)
	v_pk_fma_f32 v[56:57], v[56:57], v[212:213], v[168:169]
	v_pk_fma_f32 v[58:59], v[58:59], v[214:215], v[170:171]
	v_fmac_f32_e32 v236, v56, v56
	v_fmac_f32_e32 v236, v57, v57
	v_fmac_f32_e32 v236, v58, v58
	v_fmac_f32_e32 v236, v59, v59
	s_waitcnt vmcnt(17)
	v_pk_fma_f32 v[52:53], v[52:53], v[216:217], v[172:173]
	v_pk_fma_f32 v[54:55], v[54:55], v[218:219], v[174:175]
	v_fmac_f32_e32 v236, v52, v52
	v_fmac_f32_e32 v236, v53, v53
	v_fmac_f32_e32 v236, v54, v54
	v_fmac_f32_e32 v236, v55, v55
	s_waitcnt vmcnt(16)
	v_pk_fma_f32 v[48:49], v[48:49], v[220:221], v[176:177]
	v_pk_fma_f32 v[50:51], v[50:51], v[222:223], v[178:179]
	v_fmac_f32_e32 v236, v48, v48
	v_fmac_f32_e32 v236, v49, v49
	v_fmac_f32_e32 v236, v50, v50
	v_fmac_f32_e32 v236, v51, v51
	global_store_dwordx4 v228, v[60:63], s[16:17]
	global_store_dwordx4 v228, v[56:59], s[16:17] offset:64
	global_store_dwordx4 v228, v[52:55], s[16:17] offset:512
	global_store_dwordx4 v228, v[48:51], s[16:17] offset:576
	global_load_dwordx4 v[164:167], v231, s[16:17]
	global_load_dwordx4 v[168:171], v231, s[16:17] offset:64
	global_load_dwordx4 v[172:175], v231, s[16:17] offset:512
	global_load_dwordx4 v[176:179], v231, s[16:17] offset:576
	s_waitcnt vmcnt(19)
	v_pk_fma_f32 v[44:45], v[44:45], v[196:197], v[180:181]
	v_pk_fma_f32 v[46:47], v[46:47], v[198:199], v[182:183]
	v_mul_f32_e32 v237, v44, v44
	v_fmac_f32_e32 v237, v45, v45
	v_fmac_f32_e32 v237, v46, v46
	v_fmac_f32_e32 v237, v47, v47
	s_waitcnt vmcnt(18)
	v_pk_fma_f32 v[40:41], v[40:41], v[212:213], v[184:185]
	v_pk_fma_f32 v[42:43], v[42:43], v[214:215], v[186:187]
	v_fmac_f32_e32 v237, v40, v40
	v_fmac_f32_e32 v237, v41, v41
	v_fmac_f32_e32 v237, v42, v42
	v_fmac_f32_e32 v237, v43, v43
	s_waitcnt vmcnt(17)
	v_pk_fma_f32 v[36:37], v[36:37], v[216:217], v[188:189]
	v_pk_fma_f32 v[38:39], v[38:39], v[218:219], v[190:191]
	v_fmac_f32_e32 v237, v36, v36
	v_fmac_f32_e32 v237, v37, v37
	v_fmac_f32_e32 v237, v38, v38
	v_fmac_f32_e32 v237, v39, v39
	s_waitcnt vmcnt(16)
	v_pk_fma_f32 v[32:33], v[32:33], v[220:221], v[192:193]
	v_pk_fma_f32 v[34:35], v[34:35], v[222:223], v[194:195]
	v_fmac_f32_e32 v237, v32, v32
	v_fmac_f32_e32 v237, v33, v33
	v_fmac_f32_e32 v237, v34, v34
	v_fmac_f32_e32 v237, v35, v35
	global_store_dwordx4 v229, v[44:47], s[16:17]
	global_store_dwordx4 v229, v[40:43], s[16:17] offset:64
	global_store_dwordx4 v229, v[36:39], s[16:17] offset:512
	global_store_dwordx4 v229, v[32:35], s[16:17] offset:576
	s_waitcnt vmcnt(15)
;     __device__ __forceinline__ void operator()(const f32x4 (&acc)[2][2][4][2], const Unit& u, int wr, int wc, int fr, int fq) const {
;     ...
;                 for (int bj = 0; bj < 2; ++bj)
; #pragma unroll
;                     for (int n = 0; n < 2; ++n) { const int off = col0 + bj * HALF + n * 16; const f32x4 xo = *(const f32x4*)(s + off); *(f32x4*)(d + off) = xo + gv[bj][n] * acc[ai][bj][m][n]; }
; __device__ __forceinline__ void modpass(const float* xs_main, const float* xs_ctx, const float* mod_l, const float* g, int i, bf16_t* H, int nrows, int gw, int NGW, int lane) {
;     ...
;         float ss = 0.f;
; #pragma unroll
;         for (int j = 0; j < 2; ++j)
; #pragma unroll
;             for (int q = 0; q < 2; ++q) ss += (v[j][q][0] * v[j][q][0] + v[j][q][1] * v[j][q][1]) + (v[j][q][2] * v[j][q][2] + v[j][q][3] * v[j][q][3]);
;         const float rstd = 1.0f / sqrtf(wave_sum(ss) * (1.0f / D) + EPS);
	v_pk_fma_f32 v[28:29], v[28:29], v[196:197], v[140:141]
	v_pk_fma_f32 v[30:31], v[30:31], v[198:199], v[142:143]
	v_mul_f32_e32 v238, v28, v28
	v_fmac_f32_e32 v238, v29, v29
	v_fmac_f32_e32 v238, v30, v30
	v_fmac_f32_e32 v238, v31, v31
	s_waitcnt vmcnt(14)
	v_pk_fma_f32 v[24:25], v[24:25], v[212:213], v[144:145]
	v_pk_fma_f32 v[26:27], v[26:27], v[214:215], v[146:147]
	v_fmac_f32_e32 v238, v24, v24
	v_fmac_f32_e32 v238, v25, v25
	v_fmac_f32_e32 v238, v26, v26
	v_fmac_f32_e32 v238, v27, v27
	s_waitcnt vmcnt(13)
	v_pk_fma_f32 v[20:21], v[20:21], v[216:217], v[148:149]
	v_pk_fma_f32 v[22:23], v[22:23], v[218:219], v[150:151]
	v_fmac_f32_e32 v238, v20, v20
	v_fmac_f32_e32 v238, v21, v21
	v_fmac_f32_e32 v238, v22, v22
	v_fmac_f32_e32 v238, v23, v23
	s_waitcnt vmcnt(12)
	v_pk_fma_f32 v[16:17], v[16:17], v[220:221], v[152:153]
	v_pk_fma_f32 v[18:19], v[18:19], v[222:223], v[154:155]
	v_fmac_f32_e32 v238, v16, v16
	v_fmac_f32_e32 v238, v17, v17
	v_fmac_f32_e32 v238, v18, v18
	v_fmac_f32_e32 v238, v19, v19
	global_store_dwordx4 v230, v[28:31], s[16:17]
	global_store_dwordx4 v230, v[24:27], s[16:17] offset:64
	global_store_dwordx4 v230, v[20:23], s[16:17] offset:512
	global_store_dwordx4 v230, v[16:19], s[16:17] offset:576
	s_waitcnt vmcnt(11)
	v_pk_fma_f32 v[12:13], v[12:13], v[196:197], v[164:165]
	v_pk_fma_f32 v[14:15], v[14:15], v[198:199], v[166:167]
	v_mul_f32_e32 v239, v12, v12
	v_fmac_f32_e32 v239, v13, v13
	v_fmac_f32_e32 v239, v14, v14
	v_fmac_f32_e32 v239, v15, v15
	s_waitcnt vmcnt(10)
	v_pk_fma_f32 v[8:9], v[8:9], v[212:213], v[168:169]
	v_pk_fma_f32 v[10:11], v[10:11], v[214:215], v[170:171]
	v_fmac_f32_e32 v239, v8, v8
	v_fmac_f32_e32 v239, v9, v9
	v_fmac_f32_e32 v239, v10, v10
	v_fmac_f32_e32 v239, v11, v11
	s_waitcnt vmcnt(9)
	v_pk_fma_f32 v[4:5], v[4:5], v[216:217], v[172:173]
	v_pk_fma_f32 v[6:7], v[6:7], v[218:219], v[174:175]
	v_fmac_f32_e32 v239, v4, v4
	v_fmac_f32_e32 v239, v5, v5
	v_fmac_f32_e32 v239, v6, v6
	v_fmac_f32_e32 v239, v7, v7
	s_waitcnt vmcnt(8)
	v_pk_fma_f32 v[0:1], v[0:1], v[220:221], v[176:177]
	v_pk_fma_f32 v[2:3], v[2:3], v[222:223], v[178:179]
	v_fmac_f32_e32 v239, v0, v0
	v_fmac_f32_e32 v239, v1, v1
	v_fmac_f32_e32 v239, v2, v2
	v_fmac_f32_e32 v239, v3, v3
	global_store_dwordx4 v231, v[12:15], s[16:17]
	global_store_dwordx4 v231, v[8:11], s[16:17] offset:64
	global_store_dwordx4 v231, v[4:7], s[16:17] offset:512
	global_store_dwordx4 v231, v[0:3], s[16:17] offset:576
	v_mbcnt_lo_u32_b32 v240, -1, 0
	v_mbcnt_hi_u32_b32 v240, -1, v240
	v_xor_b32_e32 v241, 16, v240
	v_xor_b32_e32 v242, 32, v240
	v_lshlrev_b32_e32 v241, 2, v241
	v_lshlrev_b32_e32 v242, 2, v242
	s_waitcnt lgkmcnt(0)
	ds_bpermute_b32 v140, v241, v232
	ds_bpermute_b32 v141, v241, v233
	ds_bpermute_b32 v142, v241, v234
	ds_bpermute_b32 v143, v241, v235
	ds_bpermute_b32 v144, v241, v236
	ds_bpermute_b32 v145, v241, v237
	ds_bpermute_b32 v146, v241, v238
	ds_bpermute_b32 v147, v241, v239
	s_waitcnt lgkmcnt(7)
	v_add_f32_e32 v232, v232, v140
	s_waitcnt lgkmcnt(6)
	v_add_f32_e32 v233, v233, v141
	s_waitcnt lgkmcnt(5)
	v_add_f32_e32 v234, v234, v142
	s_waitcnt lgkmcnt(4)
	v_add_f32_e32 v235, v235, v143
	s_waitcnt lgkmcnt(3)
	v_add_f32_e32 v236, v236, v144
	s_waitcnt lgkmcnt(2)
	v_add_f32_e32 v237, v237, v145
	s_waitcnt lgkmcnt(1)
	v_add_f32_e32 v238, v238, v146
	s_waitcnt lgkmcnt(0)
	v_add_f32_e32 v239, v239, v147
	ds_bpermute_b32 v140, v242, v232
	ds_bpermute_b32 v141, v242, v233
	ds_bpermute_b32 v142, v242, v234
	ds_bpermute_b32 v143, v242, v235
	ds_bpermute_b32 v144, v242, v236
	ds_bpermute_b32 v145, v242, v237
	ds_bpermute_b32 v146, v242, v238
	ds_bpermute_b32 v147, v242, v239
	s_waitcnt lgkmcnt(7)
	v_add_f32_e32 v232, v232, v140
	s_waitcnt lgkmcnt(6)
	v_add_f32_e32 v233, v233, v141
	s_waitcnt lgkmcnt(5)
	v_add_f32_e32 v234, v234, v142
	s_waitcnt lgkmcnt(4)
	v_add_f32_e32 v235, v235, v143
	s_waitcnt lgkmcnt(3)
	v_add_f32_e32 v236, v236, v144
	s_waitcnt lgkmcnt(2)
	v_add_f32_e32 v237, v237, v145
	s_waitcnt lgkmcnt(1)
	v_add_f32_e32 v238, v238, v146
	s_waitcnt lgkmcnt(0)
	v_add_f32_e32 v239, v239, v147
	v_lshlrev_b32_e32 v243, 2, v156
	s_add_u32 s90, s76, 0x6500000
	s_addc_u32 s91, s77, 0
	s_add_u32 s76, s76, 0x3164000
	s_addc_u32 s77, s77, 0
	s_lshl_b32 s83, s6, 6
	s_add_u32 s78, s76, s83
	s_addc_u32 s79, s77, 0
	s_add_u32 s78, s78, 0x20000
	s_addc_u32 s79, s79, 0
	s_mov_b64 s[80:81], exec
	s_mov_b64 exec, 0xffff
	global_atomic_add_f32 v243, v232, s[76:77]
	global_atomic_add_f32 v243, v233, s[76:77] offset:64
	global_atomic_add_f32 v243, v234, s[76:77] offset:128
	global_atomic_add_f32 v243, v235, s[76:77] offset:192
	global_atomic_add_f32 v243, v236, s[76:77] offset:512
	global_atomic_add_f32 v243, v237, s[76:77] offset:576
	global_atomic_add_f32 v243, v238, s[76:77] offset:640
	global_atomic_add_f32 v243, v239, s[76:77] offset:704
	s_mov_b64 exec, s[80:81]
	s_add_u32 s86, s8, 0x13000
	s_addc_u32 s87, s9, 0
	s_add_u32 s88, s86, 0x1000
	s_addc_u32 s89, s87, 0
	s_add_u32 s92, s92, 0x3000
	s_addc_u32 s93, s93, 0
	s_mov_b32 s84, 0xffff0000
	s_mov_b32 s85, 0xffff0000
	s_waitcnt vmcnt(0)
	s_barrier
	v_readfirstlane_b32 s83, v206
	v_mov_b32_e32 v244, 0
	v_mov_b32_e32 v245, 1
	s_cmp_lg_u32 s83, 0
	s_cbranch_scc1 .Lfmd_wait_done
	s_mov_b64 exec, 1
	global_atomic_add v244, v245, s[78:79]
	s_mov_b32 s82, 0

; __device__ __forceinline__ unsigned cvtpk_s(float lo, float hi) { f32x2_t v = {lo, hi}; bf16x2_t b = __builtin_convertvector(v, bf16x2_t); return __builtin_bit_cast(unsigned, b); }
; __device__ __forceinline__ u32x4 quad_swap(unsigned lo0, unsigned lo1, unsigned hi0, unsigned hi1, int fq, int& coloff) {
;     const bool odd = fq & 1;
;     const unsigned s0 = odd ? lo0 : hi0, s1 = odd ? lo1 : hi1;
;     const unsigned r0 = (unsigned)__shfl_xor((int)s0, 16), r1 = (unsigned)__shfl_xor((int)s1, 16);
;     coloff = odd ? 16 + 4 * (fq - 1) : 4 * fq;
;     u32x4 o; o.x = odd ? r0 : lo0; o.y = odd ? r1 : lo1; o.z = odd ? hi0 : r0; o.w = odd ? hi1 : r1; return o;
; __device__ __forceinline__ void modpass(const float* xs_main, const float* xs_ctx, const float* mod_l, const float* g, int i, bf16_t* H, int nrows, int gw, int NGW, int lane) {
;     ...
;         if (cond != cur) { cur = cond; const float* shift = mod_l + cond * 9216 + 3 * i * 1024; const float* scale = shift + 1024;
; #pragma unroll
;             for (int j = 0; j < 2; ++j)
; #pragma unroll
;                 for (int q = 0; q < 2; ++q) { const int c = 8 * lane + 512 * j + 4 * q; gm[j][q] = *(const f32x4*)(g + c) * (*(const f32x4*)(scale + c) + 1.0f); sh[j][q] = *(const f32x4*)(shift + c); } }
;         float ss = 0.f;
; #pragma unroll
;         for (int j = 0; j < 2; ++j)
; #pragma unroll
;             for (int q = 0; q < 2; ++q) ss += (v[j][q][0] * v[j][q][0] + v[j][q][1] * v[j][q][1]) + (v[j][q][2] * v[j][q][2] + v[j][q][3] * v[j][q][3]);
;         const float rstd = 1.0f / sqrtf(wave_sum(ss) * (1.0f / D) + EPS);
; #pragma unroll
;         for (int j = 0; j < 2; ++j) {
;             const f32x4 o0 = v[j][0] * rstd * gm[j][0] + sh[j][0], o1 = v[j][1] * rstd * gm[j][1] + sh[j][1];
;             u32x4 w; w.x = cvtpk_s(o0[0], o0[1]); w.y = cvtpk_s(o0[2], o0[3]); w.z = cvtpk_s(o1[0], o1[1]); w.w = cvtpk_s(o1[2], o1[3]);
;             *(u32x4*)(H + (size_t)row * D + 8 * lane + 512 * j) = w;
.Lfmd_wait_done:
	s_barrier
	global_load_dword v144, v243, s[76:77] sc1
	global_load_dword v145, v243, s[76:77] offset:64 sc1
	global_load_dword v146, v243, s[76:77] offset:128 sc1
	global_load_dword v147, v243, s[76:77] offset:192 sc1
	global_load_dword v148, v243, s[76:77] offset:512 sc1
	global_load_dword v149, v243, s[76:77] offset:576 sc1
	global_load_dword v150, v243, s[76:77] offset:640 sc1
	global_load_dword v151, v243, s[76:77] offset:704 sc1
	global_load_dwordx4 v[196:199], v201, s[86:87]
	global_load_dwordx4 v[212:215], v201, s[86:87] offset:64
	global_load_dwordx4 v[216:219], v201, s[86:87] offset:512
	global_load_dwordx4 v[220:223], v201, s[86:87] offset:576
	global_load_dwordx4 v[152:155], v201, s[88:89]
	global_load_dwordx4 v[164:167], v201, s[88:89] offset:64
	global_load_dwordx4 v[168:171], v201, s[88:89] offset:512
	global_load_dwordx4 v[172:175], v201, s[88:89] offset:576
	global_load_dwordx4 v[176:179], v201, s[92:93]
	global_load_dwordx4 v[180:183], v201, s[92:93] offset:64
	global_load_dwordx4 v[184:187], v201, s[92:93] offset:512
	global_load_dwordx4 v[188:191], v201, s[92:93] offset:576
	v_mov_b32_e32 v240, 12
	v_cndmask_b32_e64 v240, 0, v240, s[84:85]
	v_add_u32_e32 v240, v240, v157
	v_lshlrev_b32_e32 v240, 1, v240
	v_lshl_add_u32 v247, v156, 11, v240
	v_mov_b32_e32 v240, 0x358637bd
	s_waitcnt vmcnt(0)
	v_fmamk_f32 v144, v144, 0x3a800000, v240
	v_fmamk_f32 v145, v145, 0x3a800000, v240
	v_fmamk_f32 v146, v146, 0x3a800000, v240
	v_fmamk_f32 v147, v147, 0x3a800000, v240
	v_fmamk_f32 v148, v148, 0x3a800000, v240
	v_fmamk_f32 v149, v149, 0x3a800000, v240
	v_fmamk_f32 v150, v150, 0x3a800000, v240
	v_fmamk_f32 v151, v151, 0x3a800000, v240
	v_rsq_f32_e32 v144, v144
	v_rsq_f32_e32 v145, v145
	v_rsq_f32_e32 v146, v146
	v_rsq_f32_e32 v147, v147
	v_rsq_f32_e32 v148, v148
	v_rsq_f32_e32 v149, v149
	v_rsq_f32_e32 v150, v150
	v_rsq_f32_e32 v151, v151
	v_pk_add_f32 v[152:153], v[152:153], 1.0 op_sel_hi:[1,0]
	v_pk_mul_f32 v[152:153], v[176:177], v[152:153]
	v_pk_add_f32 v[154:155], v[154:155], 1.0 op_sel_hi:[1,0]
	v_pk_mul_f32 v[154:155], v[178:179], v[154:155]
	v_pk_add_f32 v[164:165], v[164:165], 1.0 op_sel_hi:[1,0]
	v_pk_mul_f32 v[164:165], v[180:181], v[164:165]
	v_pk_add_f32 v[166:167], v[166:167], 1.0 op_sel_hi:[1,0]
	v_pk_mul_f32 v[166:167], v[182:183], v[166:167]
	v_pk_add_f32 v[168:169], v[168:169], 1.0 op_sel_hi:[1,0]
	v_pk_mul_f32 v[168:169], v[184:185], v[168:169]
	v_pk_add_f32 v[170:171], v[170:171], 1.0 op_sel_hi:[1,0]
	v_pk_mul_f32 v[170:171], v[186:187], v[170:171]
	v_pk_add_f32 v[172:173], v[172:173], 1.0 op_sel_hi:[1,0]
	v_pk_mul_f32 v[172:173], v[188:189], v[172:173]
	v_pk_add_f32 v[174:175], v[174:175], 1.0 op_sel_hi:[1,0]
	v_pk_mul_f32 v[174:175], v[190:191], v[174:175]
	v_mul_f32_e32 v124, v124, v144
	v_mul_f32_e32 v125, v125, v144
	v_pk_fma_f32 v[124:125], v[152:153], v[124:125], v[196:197]
	v_mul_f32_e32 v126, v126, v144
	v_mul_f32_e32 v127, v127, v144
	v_pk_fma_f32 v[126:127], v[154:155], v[126:127], v[198:199]
	v_cvt_pk_bf16_f32 v184, v124, v125
	v_cvt_pk_bf16_f32 v185, v126, v127
	v_mul_f32_e32 v120, v120, v144
	v_mul_f32_e32 v121, v121, v144
	v_pk_fma_f32 v[120:121], v[164:165], v[120:121], v[212:213]
	v_mul_f32_e32 v122, v122, v144
	v_mul_f32_e32 v123, v123, v144
	v_pk_fma_f32 v[122:123], v[166:167], v[122:123], v[214:215]
	v_cvt_pk_bf16_f32 v186, v120, v121
	v_cvt_pk_bf16_f32 v187, v122, v123
	v_mul_f32_e32 v116, v116, v144
	v_mul_f32_e32 v117, v117, v144
	v_pk_fma_f32 v[116:117], v[168:169], v[116:117], v[216:217]
	v_mul_f32_e32 v118, v118, v144
	v_mul_f32_e32 v119, v119, v144
	v_pk_fma_f32 v[118:119], v[170:171], v[118:119], v[218:219]
	v_cvt_pk_bf16_f32 v188, v116, v117
	v_cvt_pk_bf16_f32 v189, v118, v119
	v_mul_f32_e32 v112, v112, v144
	v_mul_f32_e32 v113, v113, v144
	v_pk_fma_f32 v[112:113], v[172:173], v[112:113], v[220:221]
	v_mul_f32_e32 v114, v114, v144
	v_mul_f32_e32 v115, v115, v144
	v_pk_fma_f32 v[114:115], v[174:175], v[114:115], v[222:223]
	v_cvt_pk_bf16_f32 v190, v112, v113
	v_cvt_pk_bf16_f32 v191, v114, v115
	v_mov_b32_e32 v240, v247
	v_cndmask_b32_e64 v192, v186, v184, s[84:85]
	v_cndmask_b32_e64 v193, v187, v185, s[84:85]
	ds_bpermute_b32 v194, v241, v192
	ds_bpermute_b32 v195, v241, v193
	s_waitcnt lgkmcnt(0)
	v_cndmask_b32_e64 v176, v184, v194, s[84:85]
	v_cndmask_b32_e64 v177, v185, v195, s[84:85]
	v_cndmask_b32_e64 v178, v194, v186, s[84:85]
	v_cndmask_b32_e64 v179, v195, v187, s[84:85]
	global_store_dwordx4 v240, v[176:179], s[90:91]
	v_cndmask_b32_e64 v192, v190, v188, s[84:85]
	v_cndmask_b32_e64 v193, v191, v189, s[84:85]
	ds_bpermute_b32 v194, v241, v192
	ds_bpermute_b32 v195, v241, v193
	s_waitcnt lgkmcnt(0)
	v_cndmask_b32_e64 v180, v188, v194, s[84:85]
	v_cndmask_b32_e64 v181, v189, v195, s[84:85]
	v_cndmask_b32_e64 v182, v194, v190, s[84:85]
	v_cndmask_b32_e64 v183, v195, v191, s[84:85]
	global_store_dwordx4 v240, v[180:183], s[90:91] offset:256
	v_mul_f32_e32 v108, v108, v145
	v_mul_f32_e32 v109, v109, v145
	v_pk_fma_f32 v[108:109], v[152:153], v[108:109], v[196:197]
	v_mul_f32_e32 v110, v110, v145
	v_mul_f32_e32 v111, v111, v145
	v_pk_fma_f32 v[110:111], v[154:155], v[110:111], v[198:199]
	v_cvt_pk_bf16_f32 v184, v108, v109
	v_cvt_pk_bf16_f32 v185, v110, v111
	v_mul_f32_e32 v104, v104, v145
	v_mul_f32_e32 v105, v105, v145
	v_pk_fma_f32 v[104:105], v[164:165], v[104:105], v[212:213]
	v_mul_f32_e32 v106, v106, v145
	v_mul_f32_e32 v107, v107, v145
	v_pk_fma_f32 v[106:107], v[166:167], v[106:107], v[214:215]
	v_cvt_pk_bf16_f32 v186, v104, v105
	v_cvt_pk_bf16_f32 v187, v106, v107
	v_mul_f32_e32 v100, v100, v145
	v_mul_f32_e32 v101, v101, v145
	v_pk_fma_f32 v[100:101], v[168:169], v[100:101], v[216:217]
	v_mul_f32_e32 v102, v102, v145
	v_mul_f32_e32 v103, v103, v145
	v_pk_fma_f32 v[102:103], v[170:171], v[102:103], v[218:219]
	v_cvt_pk_bf16_f32 v188, v100, v101
	v_cvt_pk_bf16_f32 v189, v102, v103
	v_mul_f32_e32 v96, v96, v145
	v_mul_f32_e32 v97, v97, v145
	v_pk_fma_f32 v[96:97], v[172:173], v[96:97], v[220:221]
	v_mul_f32_e32 v98, v98, v145
	v_mul_f32_e32 v99, v99, v145
	v_pk_fma_f32 v[98:99], v[174:175], v[98:99], v[222:223]
	v_cvt_pk_bf16_f32 v190, v96, v97
	v_cvt_pk_bf16_f32 v191, v98, v99
	v_add_u32_e32 v240, 0x8000, v247
	v_cndmask_b32_e64 v192, v186, v184, s[84:85]
	v_cndmask_b32_e64 v193, v187, v185, s[84:85]
	ds_bpermute_b32 v194, v241, v192
	ds_bpermute_b32 v195, v241, v193
	s_waitcnt lgkmcnt(0)
; __device__ __forceinline__ unsigned cvtpk_s(float lo, float hi) { f32x2_t v = {lo, hi}; bf16x2_t b = __builtin_convertvector(v, bf16x2_t); return __builtin_bit_cast(unsigned, b); }
; __device__ __forceinline__ u32x4 quad_swap(unsigned lo0, unsigned lo1, unsigned hi0, unsigned hi1, int fq, int& coloff) {
;     const bool odd = fq & 1;
;     const unsigned s0 = odd ? lo0 : hi0, s1 = odd ? lo1 : hi1;
;     const unsigned r0 = (unsigned)__shfl_xor((int)s0, 16), r1 = (unsigned)__shfl_xor((int)s1, 16);
;     coloff = odd ? 16 + 4 * (fq - 1) : 4 * fq;
;     u32x4 o; o.x = odd ? r0 : lo0; o.y = odd ? r1 : lo1; o.z = odd ? hi0 : r0; o.w = odd ? hi1 : r1; return o;
; __device__ __forceinline__ void modpass(const float* xs_main, const float* xs_ctx, const float* mod_l, const float* g, int i, bf16_t* H, int nrows, int gw, int NGW, int lane) {
;     ...
;         for (int j = 0; j < 2; ++j) {
;             const f32x4 o0 = v[j][0] * rstd * gm[j][0] + sh[j][0], o1 = v[j][1] * rstd * gm[j][1] + sh[j][1];
;             u32x4 w; w.x = cvtpk_s(o0[0], o0[1]); w.y = cvtpk_s(o0[2], o0[3]); w.z = cvtpk_s(o1[0], o1[1]); w.w = cvtpk_s(o1[2], o1[3]);
;             *(u32x4*)(H + (size_t)row * D + 8 * lane + 512 * j) = w;
	v_cndmask_b32_e64 v176, v184, v194, s[84:85]
	v_cndmask_b32_e64 v177, v185, v195, s[84:85]
	v_cndmask_b32_e64 v178, v194, v186, s[84:85]
	v_cndmask_b32_e64 v179, v195, v187, s[84:85]
	global_store_dwordx4 v240, v[176:179], s[90:91]
	v_cndmask_b32_e64 v192, v190, v188, s[84:85]
	v_cndmask_b32_e64 v193, v191, v189, s[84:85]
	ds_bpermute_b32 v194, v241, v192
	ds_bpermute_b32 v195, v241, v193
	s_waitcnt lgkmcnt(0)
	v_cndmask_b32_e64 v180, v188, v194, s[84:85]
	v_cndmask_b32_e64 v181, v189, v195, s[84:85]
	v_cndmask_b32_e64 v182, v194, v190, s[84:85]
	v_cndmask_b32_e64 v183, v195, v191, s[84:85]
	global_store_dwordx4 v240, v[180:183], s[90:91] offset:256
	v_mul_f32_e32 v92, v92, v146
	v_mul_f32_e32 v93, v93, v146
	v_pk_fma_f32 v[92:93], v[152:153], v[92:93], v[196:197]
	v_mul_f32_e32 v94, v94, v146
	v_mul_f32_e32 v95, v95, v146
	v_pk_fma_f32 v[94:95], v[154:155], v[94:95], v[198:199]
	v_cvt_pk_bf16_f32 v184, v92, v93
	v_cvt_pk_bf16_f32 v185, v94, v95
	v_mul_f32_e32 v88, v88, v146
	v_mul_f32_e32 v89, v89, v146
	v_pk_fma_f32 v[88:89], v[164:165], v[88:89], v[212:213]
	v_mul_f32_e32 v90, v90, v146
	v_mul_f32_e32 v91, v91, v146
	v_pk_fma_f32 v[90:91], v[166:167], v[90:91], v[214:215]
	v_cvt_pk_bf16_f32 v186, v88, v89
	v_cvt_pk_bf16_f32 v187, v90, v91
	v_mul_f32_e32 v84, v84, v146
	v_mul_f32_e32 v85, v85, v146
	v_pk_fma_f32 v[84:85], v[168:169], v[84:85], v[216:217]
	v_mul_f32_e32 v86, v86, v146
	v_mul_f32_e32 v87, v87, v146
	v_pk_fma_f32 v[86:87], v[170:171], v[86:87], v[218:219]
	v_cvt_pk_bf16_f32 v188, v84, v85
	v_cvt_pk_bf16_f32 v189, v86, v87
	v_mul_f32_e32 v80, v80, v146
	v_mul_f32_e32 v81, v81, v146
	v_pk_fma_f32 v[80:81], v[172:173], v[80:81], v[220:221]
	v_mul_f32_e32 v82, v82, v146
	v_mul_f32_e32 v83, v83, v146
	v_pk_fma_f32 v[82:83], v[174:175], v[82:83], v[222:223]
	v_cvt_pk_bf16_f32 v190, v80, v81
	v_cvt_pk_bf16_f32 v191, v82, v83
	v_add_u32_e32 v240, 0x10000, v247
	v_cndmask_b32_e64 v192, v186, v184, s[84:85]
	v_cndmask_b32_e64 v193, v187, v185, s[84:85]
	ds_bpermute_b32 v194, v241, v192
	ds_bpermute_b32 v195, v241, v193
	s_waitcnt lgkmcnt(0)
	v_cndmask_b32_e64 v176, v184, v194, s[84:85]
	v_cndmask_b32_e64 v177, v185, v195, s[84:85]
	v_cndmask_b32_e64 v178, v194, v186, s[84:85]
	v_cndmask_b32_e64 v179, v195, v187, s[84:85]
	global_store_dwordx4 v240, v[176:179], s[90:91]
	v_cndmask_b32_e64 v192, v190, v188, s[84:85]
	v_cndmask_b32_e64 v193, v191, v189, s[84:85]
	ds_bpermute_b32 v194, v241, v192
	ds_bpermute_b32 v195, v241, v193
	s_waitcnt lgkmcnt(0)
	v_cndmask_b32_e64 v180, v188, v194, s[84:85]
	v_cndmask_b32_e64 v181, v189, v195, s[84:85]
	v_cndmask_b32_e64 v182, v194, v190, s[84:85]
	v_cndmask_b32_e64 v183, v195, v191, s[84:85]
	global_store_dwordx4 v240, v[180:183], s[90:91] offset:256
	v_mul_f32_e32 v76, v76, v147
	v_mul_f32_e32 v77, v77, v147
	v_pk_fma_f32 v[76:77], v[152:153], v[76:77], v[196:197]
	v_mul_f32_e32 v78, v78, v147
	v_mul_f32_e32 v79, v79, v147
	v_pk_fma_f32 v[78:79], v[154:155], v[78:79], v[198:199]
	v_cvt_pk_bf16_f32 v184, v76, v77
	v_cvt_pk_bf16_f32 v185, v78, v79
	v_mul_f32_e32 v72, v72, v147
	v_mul_f32_e32 v73, v73, v147
	v_pk_fma_f32 v[72:73], v[164:165], v[72:73], v[212:213]
	v_mul_f32_e32 v74, v74, v147
	v_mul_f32_e32 v75, v75, v147
	v_pk_fma_f32 v[74:75], v[166:167], v[74:75], v[214:215]
	v_cvt_pk_bf16_f32 v186, v72, v73
	v_cvt_pk_bf16_f32 v187, v74, v75
	v_mul_f32_e32 v68, v68, v147
	v_mul_f32_e32 v69, v69, v147
	v_pk_fma_f32 v[68:69], v[168:169], v[68:69], v[216:217]
	v_mul_f32_e32 v70, v70, v147
	v_mul_f32_e32 v71, v71, v147
	v_pk_fma_f32 v[70:71], v[170:171], v[70:71], v[218:219]
	v_cvt_pk_bf16_f32 v188, v68, v69
	v_cvt_pk_bf16_f32 v189, v70, v71
	v_mul_f32_e32 v64, v64, v147
	v_mul_f32_e32 v65, v65, v147
	v_pk_fma_f32 v[64:65], v[172:173], v[64:65], v[220:221]
	v_mul_f32_e32 v66, v66, v147
	v_mul_f32_e32 v67, v67, v147
	v_pk_fma_f32 v[66:67], v[174:175], v[66:67], v[222:223]
	v_cvt_pk_bf16_f32 v190, v64, v65
	v_cvt_pk_bf16_f32 v191, v66, v67
	v_add_u32_e32 v240, 0x18000, v247
	v_cndmask_b32_e64 v192, v186, v184, s[84:85]
	v_cndmask_b32_e64 v193, v187, v185, s[84:85]
	ds_bpermute_b32 v194, v241, v192
	ds_bpermute_b32 v195, v241, v193
	s_waitcnt lgkmcnt(0)
	v_cndmask_b32_e64 v176, v184, v194, s[84:85]
	v_cndmask_b32_e64 v177, v185, v195, s[84:85]
	v_cndmask_b32_e64 v178, v194, v186, s[84:85]
	v_cndmask_b32_e64 v179, v195, v187, s[84:85]
	global_store_dwordx4 v240, v[176:179], s[90:91]
	v_cndmask_b32_e64 v192, v190, v188, s[84:85]
	v_cndmask_b32_e64 v193, v191, v189, s[84:85]
	ds_bpermute_b32 v194, v241, v192
	ds_bpermute_b32 v195, v241, v193
	s_waitcnt lgkmcnt(0)
	v_cndmask_b32_e64 v180, v188, v194, s[84:85]
	v_cndmask_b32_e64 v181, v189, v195, s[84:85]
	v_cndmask_b32_e64 v182, v194, v190, s[84:85]
	v_cndmask_b32_e64 v183, v195, v191, s[84:85]
	global_store_dwordx4 v240, v[180:183], s[90:91] offset:256
	v_mul_f32_e32 v60, v60, v148
	v_mul_f32_e32 v61, v61, v148
	v_pk_fma_f32 v[60:61], v[152:153], v[60:61], v[196:197]
	v_mul_f32_e32 v62, v62, v148
	v_mul_f32_e32 v63, v63, v148
	v_pk_fma_f32 v[62:63], v[154:155], v[62:63], v[198:199]
	v_cvt_pk_bf16_f32 v184, v60, v61
	v_cvt_pk_bf16_f32 v185, v62, v63
	v_mul_f32_e32 v56, v56, v148
	v_mul_f32_e32 v57, v57, v148
	v_pk_fma_f32 v[56:57], v[164:165], v[56:57], v[212:213]
	v_mul_f32_e32 v58, v58, v148
	v_mul_f32_e32 v59, v59, v148
	v_pk_fma_f32 v[58:59], v[166:167], v[58:59], v[214:215]
	v_cvt_pk_bf16_f32 v186, v56, v57
	v_cvt_pk_bf16_f32 v187, v58, v59
	v_mul_f32_e32 v52, v52, v148
	v_mul_f32_e32 v53, v53, v148
	v_pk_fma_f32 v[52:53], v[168:169], v[52:53], v[216:217]
	v_mul_f32_e32 v54, v54, v148
	v_mul_f32_e32 v55, v55, v148
	v_pk_fma_f32 v[54:55], v[170:171], v[54:55], v[218:219]
	v_cvt_pk_bf16_f32 v188, v52, v53
	v_cvt_pk_bf16_f32 v189, v54, v55
	v_mul_f32_e32 v48, v48, v148
	v_mul_f32_e32 v49, v49, v148
	v_pk_fma_f32 v[48:49], v[172:173], v[48:49], v[220:221]
	v_mul_f32_e32 v50, v50, v148
	v_mul_f32_e32 v51, v51, v148
	v_pk_fma_f32 v[50:51], v[174:175], v[50:51], v[222:223]
	v_cvt_pk_bf16_f32 v190, v48, v49
	v_cvt_pk_bf16_f32 v191, v50, v51
	v_add_u32_e32 v240, 0x40000, v247
	v_cndmask_b32_e64 v192, v186, v184, s[84:85]
	v_cndmask_b32_e64 v193, v187, v185, s[84:85]
	ds_bpermute_b32 v194, v241, v192
	ds_bpermute_b32 v195, v241, v193
	s_waitcnt lgkmcnt(0)
; __device__ __forceinline__ unsigned cvtpk_s(float lo, float hi) { f32x2_t v = {lo, hi}; bf16x2_t b = __builtin_convertvector(v, bf16x2_t); return __builtin_bit_cast(unsigned, b); }
; __device__ __forceinline__ u32x4 quad_swap(unsigned lo0, unsigned lo1, unsigned hi0, unsigned hi1, int fq, int& coloff) {
;     const bool odd = fq & 1;
;     const unsigned s0 = odd ? lo0 : hi0, s1 = odd ? lo1 : hi1;
;     const unsigned r0 = (unsigned)__shfl_xor((int)s0, 16), r1 = (unsigned)__shfl_xor((int)s1, 16);
;     coloff = odd ? 16 + 4 * (fq - 1) : 4 * fq;
;     u32x4 o; o.x = odd ? r0 : lo0; o.y = odd ? r1 : lo1; o.z = odd ? hi0 : r0; o.w = odd ? hi1 : r1; return o;
; __device__ __forceinline__ void modpass(const float* xs_main, const float* xs_ctx, const float* mod_l, const float* g, int i, bf16_t* H, int nrows, int gw, int NGW, int lane) {
;     ...
;         for (int j = 0; j < 2; ++j) {
;             const f32x4 o0 = v[j][0] * rstd * gm[j][0] + sh[j][0], o1 = v[j][1] * rstd * gm[j][1] + sh[j][1];
;             u32x4 w; w.x = cvtpk_s(o0[0], o0[1]); w.y = cvtpk_s(o0[2], o0[3]); w.z = cvtpk_s(o1[0], o1[1]); w.w = cvtpk_s(o1[2], o1[3]);
;             *(u32x4*)(H + (size_t)row * D + 8 * lane + 512 * j) = w;
	v_cndmask_b32_e64 v176, v184, v194, s[84:85]
	v_cndmask_b32_e64 v177, v185, v195, s[84:85]
	v_cndmask_b32_e64 v178, v194, v186, s[84:85]
	v_cndmask_b32_e64 v179, v195, v187, s[84:85]
	global_store_dwordx4 v240, v[176:179], s[90:91]
	v_cndmask_b32_e64 v192, v190, v188, s[84:85]
	v_cndmask_b32_e64 v193, v191, v189, s[84:85]
	ds_bpermute_b32 v194, v241, v192
	ds_bpermute_b32 v195, v241, v193
	s_waitcnt lgkmcnt(0)
	v_cndmask_b32_e64 v180, v188, v194, s[84:85]
	v_cndmask_b32_e64 v181, v189, v195, s[84:85]
	v_cndmask_b32_e64 v182, v194, v190, s[84:85]
	v_cndmask_b32_e64 v183, v195, v191, s[84:85]
	global_store_dwordx4 v240, v[180:183], s[90:91] offset:256
	v_mul_f32_e32 v44, v44, v149
	v_mul_f32_e32 v45, v45, v149
	v_pk_fma_f32 v[44:45], v[152:153], v[44:45], v[196:197]
	v_mul_f32_e32 v46, v46, v149
	v_mul_f32_e32 v47, v47, v149
	v_pk_fma_f32 v[46:47], v[154:155], v[46:47], v[198:199]
	v_cvt_pk_bf16_f32 v184, v44, v45
	v_cvt_pk_bf16_f32 v185, v46, v47
	v_mul_f32_e32 v40, v40, v149
	v_mul_f32_e32 v41, v41, v149
	v_pk_fma_f32 v[40:41], v[164:165], v[40:41], v[212:213]
	v_mul_f32_e32 v42, v42, v149
	v_mul_f32_e32 v43, v43, v149
	v_pk_fma_f32 v[42:43], v[166:167], v[42:43], v[214:215]
	v_cvt_pk_bf16_f32 v186, v40, v41
	v_cvt_pk_bf16_f32 v187, v42, v43
	v_mul_f32_e32 v36, v36, v149
	v_mul_f32_e32 v37, v37, v149
	v_pk_fma_f32 v[36:37], v[168:169], v[36:37], v[216:217]
	v_mul_f32_e32 v38, v38, v149
	v_mul_f32_e32 v39, v39, v149
	v_pk_fma_f32 v[38:39], v[170:171], v[38:39], v[218:219]
	v_cvt_pk_bf16_f32 v188, v36, v37
	v_cvt_pk_bf16_f32 v189, v38, v39
	v_mul_f32_e32 v32, v32, v149
	v_mul_f32_e32 v33, v33, v149
	v_pk_fma_f32 v[32:33], v[172:173], v[32:33], v[220:221]
	v_mul_f32_e32 v34, v34, v149
	v_mul_f32_e32 v35, v35, v149
	v_pk_fma_f32 v[34:35], v[174:175], v[34:35], v[222:223]
	v_cvt_pk_bf16_f32 v190, v32, v33
	v_cvt_pk_bf16_f32 v191, v34, v35
	v_add_u32_e32 v240, 0x48000, v247
	v_cndmask_b32_e64 v192, v186, v184, s[84:85]
	v_cndmask_b32_e64 v193, v187, v185, s[84:85]
	ds_bpermute_b32 v194, v241, v192
	ds_bpermute_b32 v195, v241, v193
	s_waitcnt lgkmcnt(0)
	v_cndmask_b32_e64 v176, v184, v194, s[84:85]
	v_cndmask_b32_e64 v177, v185, v195, s[84:85]
	v_cndmask_b32_e64 v178, v194, v186, s[84:85]
	v_cndmask_b32_e64 v179, v195, v187, s[84:85]
	global_store_dwordx4 v240, v[176:179], s[90:91]
	v_cndmask_b32_e64 v192, v190, v188, s[84:85]
	v_cndmask_b32_e64 v193, v191, v189, s[84:85]
	ds_bpermute_b32 v194, v241, v192
	ds_bpermute_b32 v195, v241, v193
	s_waitcnt lgkmcnt(0)
	v_cndmask_b32_e64 v180, v188, v194, s[84:85]
	v_cndmask_b32_e64 v181, v189, v195, s[84:85]
	v_cndmask_b32_e64 v182, v194, v190, s[84:85]
	v_cndmask_b32_e64 v183, v195, v191, s[84:85]
	global_store_dwordx4 v240, v[180:183], s[90:91] offset:256
	v_mul_f32_e32 v28, v28, v150
	v_mul_f32_e32 v29, v29, v150
	v_pk_fma_f32 v[28:29], v[152:153], v[28:29], v[196:197]
	v_mul_f32_e32 v30, v30, v150
	v_mul_f32_e32 v31, v31, v150
	v_pk_fma_f32 v[30:31], v[154:155], v[30:31], v[198:199]
	v_cvt_pk_bf16_f32 v184, v28, v29
	v_cvt_pk_bf16_f32 v185, v30, v31
	v_mul_f32_e32 v24, v24, v150
	v_mul_f32_e32 v25, v25, v150
	v_pk_fma_f32 v[24:25], v[164:165], v[24:25], v[212:213]
	v_mul_f32_e32 v26, v26, v150
	v_mul_f32_e32 v27, v27, v150
	v_pk_fma_f32 v[26:27], v[166:167], v[26:27], v[214:215]
	v_cvt_pk_bf16_f32 v186, v24, v25
	v_cvt_pk_bf16_f32 v187, v26, v27
	v_mul_f32_e32 v20, v20, v150
	v_mul_f32_e32 v21, v21, v150
	v_pk_fma_f32 v[20:21], v[168:169], v[20:21], v[216:217]
	v_mul_f32_e32 v22, v22, v150
	v_mul_f32_e32 v23, v23, v150
	v_pk_fma_f32 v[22:23], v[170:171], v[22:23], v[218:219]
	v_cvt_pk_bf16_f32 v188, v20, v21
	v_cvt_pk_bf16_f32 v189, v22, v23
	v_mul_f32_e32 v16, v16, v150
	v_mul_f32_e32 v17, v17, v150
	v_pk_fma_f32 v[16:17], v[172:173], v[16:17], v[220:221]
	v_mul_f32_e32 v18, v18, v150
	v_mul_f32_e32 v19, v19, v150
	v_pk_fma_f32 v[18:19], v[174:175], v[18:19], v[222:223]
	v_cvt_pk_bf16_f32 v190, v16, v17
	v_cvt_pk_bf16_f32 v191, v18, v19
	v_add_u32_e32 v240, 0x50000, v247
	v_cndmask_b32_e64 v192, v186, v184, s[84:85]
	v_cndmask_b32_e64 v193, v187, v185, s[84:85]
	ds_bpermute_b32 v194, v241, v192
	ds_bpermute_b32 v195, v241, v193
	s_waitcnt lgkmcnt(0)
	v_cndmask_b32_e64 v176, v184, v194, s[84:85]
	v_cndmask_b32_e64 v177, v185, v195, s[84:85]
	v_cndmask_b32_e64 v178, v194, v186, s[84:85]
	v_cndmask_b32_e64 v179, v195, v187, s[84:85]
	global_store_dwordx4 v240, v[176:179], s[90:91]
	v_cndmask_b32_e64 v192, v190, v188, s[84:85]
	v_cndmask_b32_e64 v193, v191, v189, s[84:85]
	ds_bpermute_b32 v194, v241, v192
	ds_bpermute_b32 v195, v241, v193
	s_waitcnt lgkmcnt(0)
	v_cndmask_b32_e64 v180, v188, v194, s[84:85]
	v_cndmask_b32_e64 v181, v189, v195, s[84:85]
	v_cndmask_b32_e64 v182, v194, v190, s[84:85]
	v_cndmask_b32_e64 v183, v195, v191, s[84:85]
	global_store_dwordx4 v240, v[180:183], s[90:91] offset:256
	v_mul_f32_e32 v12, v12, v151
	v_mul_f32_e32 v13, v13, v151
	v_pk_fma_f32 v[12:13], v[152:153], v[12:13], v[196:197]
	v_mul_f32_e32 v14, v14, v151
	v_mul_f32_e32 v15, v15, v151
	v_pk_fma_f32 v[14:15], v[154:155], v[14:15], v[198:199]
	v_cvt_pk_bf16_f32 v184, v12, v13
	v_cvt_pk_bf16_f32 v185, v14, v15
	v_mul_f32_e32 v8, v8, v151
	v_mul_f32_e32 v9, v9, v151
	v_pk_fma_f32 v[8:9], v[164:165], v[8:9], v[212:213]
	v_mul_f32_e32 v10, v10, v151
	v_mul_f32_e32 v11, v11, v151
	v_pk_fma_f32 v[10:11], v[166:167], v[10:11], v[214:215]
	v_cvt_pk_bf16_f32 v186, v8, v9
	v_cvt_pk_bf16_f32 v187, v10, v11
	v_mul_f32_e32 v4, v4, v151
	v_mul_f32_e32 v5, v5, v151
	v_pk_fma_f32 v[4:5], v[168:169], v[4:5], v[216:217]
	v_mul_f32_e32 v6, v6, v151
	v_mul_f32_e32 v7, v7, v151
	v_pk_fma_f32 v[6:7], v[170:171], v[6:7], v[218:219]
	v_cvt_pk_bf16_f32 v188, v4, v5
	v_cvt_pk_bf16_f32 v189, v6, v7
	v_mul_f32_e32 v0, v0, v151
	v_mul_f32_e32 v1, v1, v151
	v_pk_fma_f32 v[0:1], v[172:173], v[0:1], v[220:221]
	v_mul_f32_e32 v2, v2, v151
	v_mul_f32_e32 v3, v3, v151
	v_pk_fma_f32 v[2:3], v[174:175], v[2:3], v[222:223]
	v_cvt_pk_bf16_f32 v190, v0, v1
	v_cvt_pk_bf16_f32 v191, v2, v3
	v_add_u32_e32 v240, 0x58000, v247
	v_cndmask_b32_e64 v192, v186, v184, s[84:85]
	v_cndmask_b32_e64 v193, v187, v185, s[84:85]
	ds_bpermute_b32 v194, v241, v192
	ds_bpermute_b32 v195, v241, v193
	s_waitcnt lgkmcnt(0)
	v_cndmask_b32_e64 v176, v184, v194, s[84:85]
	v_cndmask_b32_e64 v177, v185, v195, s[84:85]
	v_cndmask_b32_e64 v178, v194, v186, s[84:85]
	v_cndmask_b32_e64 v179, v195, v187, s[84:85]
	global_store_dwordx4 v240, v[176:179], s[90:91]
	v_cndmask_b32_e64 v192, v190, v188, s[84:85]
	v_cndmask_b32_e64 v193, v191, v189, s[84:85]
	ds_bpermute_b32 v194, v241, v192
	ds_bpermute_b32 v195, v241, v193
	s_waitcnt lgkmcnt(0)
	v_cndmask_b32_e64 v180, v188, v194, s[84:85]
	v_cndmask_b32_e64 v181, v189, v195, s[84:85]
	v_cndmask_b32_e64 v182, v194, v190, s[84:85]
	v_cndmask_b32_e64 v183, v195, v191, s[84:85]
	global_store_dwordx4 v240, v[180:183], s[90:91] offset:256
	s_and_b64 vcc, exec, s[12:13]
	s_mov_b64 s[12:13], -1
	s_branch .Lfmdone_d
;     __device__ __forceinline__ void operator()(const f32x4 (&acc)[2][2][4][2], const Unit& u, int wr, int wc, int fr, int fq) const {
;         const int cond = u.pm < 64 ? 0 : (u.pm < 128 ? 1 : 2);
;         const float* gate = gate_l + cond * 9216;
;         const int col0 = u.pn * BM + wc * 32 + 4 * fq;
;         f32x4 gv[2][2];
; #pragma unroll
;         for (int bj = 0; bj < 2; ++bj)
; #pragma unroll
;             for (int n = 0; n < 2; ++n) gv[bj][n] = *(const f32x4*)(gate + col0 + bj * HALF + n * 16) * coef;
; #pragma unroll
;         for (int ai = 0; ai < 2; ++ai)
; #pragma unroll
;             for (int m = 0; m < 4; ++m) {
;                 const int row = u.pm * BM + ai * HALF + wr * 64 + m * 16 + fr;
;                 const float* s = row < MX_ ? src_main + (size_t)row * D_ : src_ctx + (size_t)(row - MX_) * D_;
;                 float* d = row < MX_ ? dst_main + (size_t)row * D_ : dst_ctx + (size_t)(row - MX_) * D_;
; #pragma unroll
;                 for (int bj = 0; bj < 2; ++bj)
; #pragma unroll
;                     for (int n = 0; n < 2; ++n) { const int off = col0 + bj * HALF + n * 16; const f32x4 xo = *(const f32x4*)(s + off); *(f32x4*)(d + off) = xo + gv[bj][n] * acc[ai][bj][m][n]; }
.Lfmsel_d:
	s_cmpk_lt_i32 s6, 0x80
	s_cselect_b32 s8, s64, 0x4800
	s_cmp_gt_i32 s6, 63
	s_cselect_b32 s8, s8, 0
	s_lshl_b32 s8, s8, 2
	s_add_u32 s8, s56, s8
	s_addc_u32 s9, s57, 0
	s_load_dwordx2 s[92:93], s[0:1], 0x30
	s_load_dwordx2 s[76:77], s[0:1], 0xb8
	v_lshl_add_u32 v156, s6, 8, v158
	v_lshl_or_b32 v157, s7, 8, v160
	v_lshlrev_b32_e32 v201, 2, v157
	v_lshl_add_u32 v224, v156, 12, v201
	global_load_dwordx4 v[196:199], v201, s[8:9]
	global_load_dwordx4 v[212:215], v201, s[8:9] offset:64
	global_load_dwordx4 v[216:219], v201, s[8:9] offset:512
	global_load_dwordx4 v[220:223], v201, s[8:9] offset:576
	v_add_u32_e32 v225, 0x10000, v224
	v_add_u32_e32 v226, 0x20000, v224
	v_add_u32_e32 v227, 0x30000, v224
	v_add_u32_e32 v228, 0x80000, v224
	v_add_u32_e32 v229, 0x90000, v224
	v_add_u32_e32 v230, 0xa0000, v224
	v_add_u32_e32 v231, 0xb0000, v224
	global_load_dwordx4 v[140:143], v224, s[16:17]
	global_load_dwordx4 v[144:147], v224, s[16:17] offset:64
	global_load_dwordx4 v[148:151], v224, s[16:17] offset:512
	global_load_dwordx4 v[152:155], v224, s[16:17] offset:576
	global_load_dwordx4 v[164:167], v225, s[16:17]
	global_load_dwordx4 v[168:171], v225, s[16:17] offset:64
	global_load_dwordx4 v[172:175], v225, s[16:17] offset:512
	global_load_dwordx4 v[176:179], v225, s[16:17] offset:576
	global_load_dwordx4 v[180:183], v226, s[16:17]
	global_load_dwordx4 v[184:187], v226, s[16:17] offset:64
	global_load_dwordx4 v[188:191], v226, s[16:17] offset:512
	global_load_dwordx4 v[192:195], v226, s[16:17] offset:576
	s_waitcnt vmcnt(12)
	v_pk_mul_f32 v[196:197], v[196:197], 0.5 op_sel_hi:[1,0]
	v_pk_mul_f32 v[198:199], v[198:199], 0.5 op_sel_hi:[1,0]
	v_pk_mul_f32 v[212:213], v[212:213], 0.5 op_sel_hi:[1,0]
	v_pk_mul_f32 v[214:215], v[214:215], 0.5 op_sel_hi:[1,0]
	v_pk_mul_f32 v[216:217], v[216:217], 0.5 op_sel_hi:[1,0]
	v_pk_mul_f32 v[218:219], v[218:219], 0.5 op_sel_hi:[1,0]
	v_pk_mul_f32 v[220:221], v[220:221], 0.5 op_sel_hi:[1,0]
	v_pk_mul_f32 v[222:223], v[222:223], 0.5 op_sel_hi:[1,0]
	s_waitcnt vmcnt(11)
	v_pk_fma_f32 v[124:125], v[124:125], v[196:197], v[140:141]
	v_pk_fma_f32 v[126:127], v[126:127], v[198:199], v[142:143]
	v_mul_f32_e32 v232, v124, v124
	v_fmac_f32_e32 v232, v125, v125
	v_fmac_f32_e32 v232, v126, v126
	v_fmac_f32_e32 v232, v127, v127
	s_waitcnt vmcnt(10)
	v_pk_fma_f32 v[120:121], v[120:121], v[212:213], v[144:145]
	v_pk_fma_f32 v[122:123], v[122:123], v[214:215], v[146:147]
	v_fmac_f32_e32 v232, v120, v120
	v_fmac_f32_e32 v232, v121, v121
	v_fmac_f32_e32 v232, v122, v122
	v_fmac_f32_e32 v232, v123, v123
	s_waitcnt vmcnt(9)
	v_pk_fma_f32 v[116:117], v[116:117], v[216:217], v[148:149]
	v_pk_fma_f32 v[118:119], v[118:119], v[218:219], v[150:151]
	v_fmac_f32_e32 v232, v116, v116
	v_fmac_f32_e32 v232, v117, v117
	v_fmac_f32_e32 v232, v118, v118
	v_fmac_f32_e32 v232, v119, v119
	s_waitcnt vmcnt(8)
	v_pk_fma_f32 v[112:113], v[112:113], v[220:221], v[152:153]
	v_pk_fma_f32 v[114:115], v[114:115], v[222:223], v[154:155]
	v_fmac_f32_e32 v232, v112, v112
	v_fmac_f32_e32 v232, v113, v113
	v_fmac_f32_e32 v232, v114, v114
	v_fmac_f32_e32 v232, v115, v115
	global_store_dwordx4 v224, v[124:127], s[16:17] sc1
	global_store_dwordx4 v224, v[120:123], s[16:17] offset:64 sc1
	global_store_dwordx4 v224, v[116:119], s[16:17] offset:512 sc1
	global_store_dwordx4 v224, v[112:115], s[16:17] offset:576 sc1
	global_load_dwordx4 v[140:143], v227, s[16:17]
	global_load_dwordx4 v[144:147], v227, s[16:17] offset:64
	global_load_dwordx4 v[148:151], v227, s[16:17] offset:512
	global_load_dwordx4 v[152:155], v227, s[16:17] offset:576
	s_waitcnt vmcnt(15)
	v_pk_fma_f32 v[108:109], v[108:109], v[196:197], v[164:165]
	v_pk_fma_f32 v[110:111], v[110:111], v[198:199], v[166:167]
	v_mul_f32_e32 v233, v108, v108
	v_fmac_f32_e32 v233, v109, v109
	v_fmac_f32_e32 v233, v110, v110
	v_fmac_f32_e32 v233, v111, v111
	s_waitcnt vmcnt(14)
	v_pk_fma_f32 v[104:105], v[104:105], v[212:213], v[168:169]
	v_pk_fma_f32 v[106:107], v[106:107], v[214:215], v[170:171]
	v_fmac_f32_e32 v233, v104, v104
	v_fmac_f32_e32 v233, v105, v105
	v_fmac_f32_e32 v233, v106, v106
	v_fmac_f32_e32 v233, v107, v107
	s_waitcnt vmcnt(13)
	v_pk_fma_f32 v[100:101], v[100:101], v[216:217], v[172:173]
	v_pk_fma_f32 v[102:103], v[102:103], v[218:219], v[174:175]
	v_fmac_f32_e32 v233, v100, v100
	v_fmac_f32_e32 v233, v101, v101
	v_fmac_f32_e32 v233, v102, v102
	v_fmac_f32_e32 v233, v103, v103
	s_waitcnt vmcnt(12)
	v_pk_fma_f32 v[96:97], v[96:97], v[220:221], v[176:177]
	v_pk_fma_f32 v[98:99], v[98:99], v[222:223], v[178:179]
	v_fmac_f32_e32 v233, v96, v96
	v_fmac_f32_e32 v233, v97, v97
	v_fmac_f32_e32 v233, v98, v98
	v_fmac_f32_e32 v233, v99, v99
	global_store_dwordx4 v225, v[108:111], s[16:17] sc1
	global_store_dwordx4 v225, v[104:107], s[16:17] offset:64 sc1
	global_store_dwordx4 v225, v[100:103], s[16:17] offset:512 sc1
	global_store_dwordx4 v225, v[96:99], s[16:17] offset:576 sc1
	global_load_dwordx4 v[164:167], v228, s[16:17]
	global_load_dwordx4 v[168:171], v228, s[16:17] offset:64
	global_load_dwordx4 v[172:175], v228, s[16:17] offset:512
	global_load_dwordx4 v[176:179], v228, s[16:17] offset:576
	s_waitcnt vmcnt(19)
	v_pk_fma_f32 v[92:93], v[92:93], v[196:197], v[180:181]
	v_pk_fma_f32 v[94:95], v[94:95], v[198:199], v[182:183]
	v_mul_f32_e32 v234, v92, v92
	v_fmac_f32_e32 v234, v93, v93
	v_fmac_f32_e32 v234, v94, v94
	v_fmac_f32_e32 v234, v95, v95
	s_waitcnt vmcnt(18)
	v_pk_fma_f32 v[88:89], v[88:89], v[212:213], v[184:185]
	v_pk_fma_f32 v[90:91], v[90:91], v[214:215], v[186:187]
	v_fmac_f32_e32 v234, v88, v88
	v_fmac_f32_e32 v234, v89, v89
	v_fmac_f32_e32 v234, v90, v90
	v_fmac_f32_e32 v234, v91, v91
	s_waitcnt vmcnt(17)
;     __device__ __forceinline__ void operator()(const f32x4 (&acc)[2][2][4][2], const Unit& u, int wr, int wc, int fr, int fq) const {
;     ...
;                 const int row = u.pm * BM + ai * HALF + wr * 64 + m * 16 + fr;
;                 const float* s = row < MX_ ? src_main + (size_t)row * D_ : src_ctx + (size_t)(row - MX_) * D_;
;                 float* d = row < MX_ ? dst_main + (size_t)row * D_ : dst_ctx + (size_t)(row - MX_) * D_;
; #pragma unroll
;                 for (int bj = 0; bj < 2; ++bj)
; #pragma unroll
;                     for (int n = 0; n < 2; ++n) { const int off = col0 + bj * HALF + n * 16; const f32x4 xo = *(const f32x4*)(s + off); *(f32x4*)(d + off) = xo + gv[bj][n] * acc[ai][bj][m][n]; }
	v_pk_fma_f32 v[84:85], v[84:85], v[216:217], v[188:189]
	v_pk_fma_f32 v[86:87], v[86:87], v[218:219], v[190:191]
	v_fmac_f32_e32 v234, v84, v84
	v_fmac_f32_e32 v234, v85, v85
	v_fmac_f32_e32 v234, v86, v86
	v_fmac_f32_e32 v234, v87, v87
	s_waitcnt vmcnt(16)
	v_pk_fma_f32 v[80:81], v[80:81], v[220:221], v[192:193]
	v_pk_fma_f32 v[82:83], v[82:83], v[222:223], v[194:195]
	v_fmac_f32_e32 v234, v80, v80
	v_fmac_f32_e32 v234, v81, v81
	v_fmac_f32_e32 v234, v82, v82
	v_fmac_f32_e32 v234, v83, v83
	global_store_dwordx4 v226, v[92:95], s[16:17] sc1
	global_store_dwordx4 v226, v[88:91], s[16:17] offset:64 sc1
	global_store_dwordx4 v226, v[84:87], s[16:17] offset:512 sc1
	global_store_dwordx4 v226, v[80:83], s[16:17] offset:576 sc1
	global_load_dwordx4 v[180:183], v229, s[16:17]
	global_load_dwordx4 v[184:187], v229, s[16:17] offset:64
	global_load_dwordx4 v[188:191], v229, s[16:17] offset:512
	global_load_dwordx4 v[192:195], v229, s[16:17] offset:576
	s_waitcnt vmcnt(19)
	v_pk_fma_f32 v[76:77], v[76:77], v[196:197], v[140:141]
	v_pk_fma_f32 v[78:79], v[78:79], v[198:199], v[142:143]
	v_mul_f32_e32 v235, v76, v76
	v_fmac_f32_e32 v235, v77, v77
	v_fmac_f32_e32 v235, v78, v78
	v_fmac_f32_e32 v235, v79, v79
	s_waitcnt vmcnt(18)
	v_pk_fma_f32 v[72:73], v[72:73], v[212:213], v[144:145]
	v_pk_fma_f32 v[74:75], v[74:75], v[214:215], v[146:147]
	v_fmac_f32_e32 v235, v72, v72
	v_fmac_f32_e32 v235, v73, v73
	v_fmac_f32_e32 v235, v74, v74
	v_fmac_f32_e32 v235, v75, v75
	s_waitcnt vmcnt(17)
	v_pk_fma_f32 v[68:69], v[68:69], v[216:217], v[148:149]
	v_pk_fma_f32 v[70:71], v[70:71], v[218:219], v[150:151]
	v_fmac_f32_e32 v235, v68, v68
	v_fmac_f32_e32 v235, v69, v69
	v_fmac_f32_e32 v235, v70, v70
	v_fmac_f32_e32 v235, v71, v71
	s_waitcnt vmcnt(16)
	v_pk_fma_f32 v[64:65], v[64:65], v[220:221], v[152:153]
	v_pk_fma_f32 v[66:67], v[66:67], v[222:223], v[154:155]
	v_fmac_f32_e32 v235, v64, v64
	v_fmac_f32_e32 v235, v65, v65
	v_fmac_f32_e32 v235, v66, v66
	v_fmac_f32_e32 v235, v67, v67
	global_store_dwordx4 v227, v[76:79], s[16:17] sc1
	global_store_dwordx4 v227, v[72:75], s[16:17] offset:64 sc1
	global_store_dwordx4 v227, v[68:71], s[16:17] offset:512 sc1
	global_store_dwordx4 v227, v[64:67], s[16:17] offset:576 sc1
	global_load_dwordx4 v[140:143], v230, s[16:17]
	global_load_dwordx4 v[144:147], v230, s[16:17] offset:64
	global_load_dwordx4 v[148:151], v230, s[16:17] offset:512
	global_load_dwordx4 v[152:155], v230, s[16:17] offset:576
	s_waitcnt vmcnt(19)
	v_pk_fma_f32 v[60:61], v[60:61], v[196:197], v[164:165]
	v_pk_fma_f32 v[62:63], v[62:63], v[198:199], v[166:167]
	v_mul_f32_e32 v236, v60, v60
	v_fmac_f32_e32 v236, v61, v61
	v_fmac_f32_e32 v236, v62, v62
	v_fmac_f32_e32 v236, v63, v63
	s_waitcnt vmcnt(18)
	v_pk_fma_f32 v[56:57], v[56:57], v[212:213], v[168:169]
	v_pk_fma_f32 v[58:59], v[58:59], v[214:215], v[170:171]
	v_fmac_f32_e32 v236, v56, v56
	v_fmac_f32_e32 v236, v57, v57
	v_fmac_f32_e32 v236, v58, v58
	v_fmac_f32_e32 v236, v59, v59
	s_waitcnt vmcnt(17)
	v_pk_fma_f32 v[52:53], v[52:53], v[216:217], v[172:173]
	v_pk_fma_f32 v[54:55], v[54:55], v[218:219], v[174:175]
	v_fmac_f32_e32 v236, v52, v52
	v_fmac_f32_e32 v236, v53, v53
	v_fmac_f32_e32 v236, v54, v54
	v_fmac_f32_e32 v236, v55, v55
	s_waitcnt vmcnt(16)
	v_pk_fma_f32 v[48:49], v[48:49], v[220:221], v[176:177]
	v_pk_fma_f32 v[50:51], v[50:51], v[222:223], v[178:179]
	v_fmac_f32_e32 v236, v48, v48
	v_fmac_f32_e32 v236, v49, v49
	v_fmac_f32_e32 v236, v50, v50
	v_fmac_f32_e32 v236, v51, v51
	global_store_dwordx4 v228, v[60:63], s[16:17] sc1
	global_store_dwordx4 v228, v[56:59], s[16:17] offset:64 sc1
	global_store_dwordx4 v228, v[52:55], s[16:17] offset:512 sc1
	global_store_dwordx4 v228, v[48:51], s[16:17] offset:576 sc1
	global_load_dwordx4 v[164:167], v231, s[16:17]
	global_load_dwordx4 v[168:171], v231, s[16:17] offset:64
	global_load_dwordx4 v[172:175], v231, s[16:17] offset:512
	global_load_dwordx4 v[176:179], v231, s[16:17] offset:576
	s_waitcnt vmcnt(19)
	v_pk_fma_f32 v[44:45], v[44:45], v[196:197], v[180:181]
	v_pk_fma_f32 v[46:47], v[46:47], v[198:199], v[182:183]
	v_mul_f32_e32 v237, v44, v44
	v_fmac_f32_e32 v237, v45, v45
	v_fmac_f32_e32 v237, v46, v46
	v_fmac_f32_e32 v237, v47, v47
	s_waitcnt vmcnt(18)
	v_pk_fma_f32 v[40:41], v[40:41], v[212:213], v[184:185]
	v_pk_fma_f32 v[42:43], v[42:43], v[214:215], v[186:187]
	v_fmac_f32_e32 v237, v40, v40
	v_fmac_f32_e32 v237, v41, v41
	v_fmac_f32_e32 v237, v42, v42
	v_fmac_f32_e32 v237, v43, v43
	s_waitcnt vmcnt(17)
	v_pk_fma_f32 v[36:37], v[36:37], v[216:217], v[188:189]
	v_pk_fma_f32 v[38:39], v[38:39], v[218:219], v[190:191]
	v_fmac_f32_e32 v237, v36, v36
	v_fmac_f32_e32 v237, v37, v37
	v_fmac_f32_e32 v237, v38, v38
	v_fmac_f32_e32 v237, v39, v39
	s_waitcnt vmcnt(16)
	v_pk_fma_f32 v[32:33], v[32:33], v[220:221], v[192:193]
	v_pk_fma_f32 v[34:35], v[34:35], v[222:223], v[194:195]
	v_fmac_f32_e32 v237, v32, v32
	v_fmac_f32_e32 v237, v33, v33
	v_fmac_f32_e32 v237, v34, v34
	v_fmac_f32_e32 v237, v35, v35
	global_store_dwordx4 v229, v[44:47], s[16:17] sc1
	global_store_dwordx4 v229, v[40:43], s[16:17] offset:64 sc1
	global_store_dwordx4 v229, v[36:39], s[16:17] offset:512 sc1
	global_store_dwordx4 v229, v[32:35], s[16:17] offset:576 sc1
	s_waitcnt vmcnt(15)
;     __device__ __forceinline__ void operator()(const f32x4 (&acc)[2][2][4][2], const Unit& u, int wr, int wc, int fr, int fq) const {
;     ...
;                 for (int bj = 0; bj < 2; ++bj)
; #pragma unroll
;                     for (int n = 0; n < 2; ++n) { const int off = col0 + bj * HALF + n * 16; const f32x4 xo = *(const f32x4*)(s + off); *(f32x4*)(d + off) = xo + gv[bj][n] * acc[ai][bj][m][n]; }
; __device__ __forceinline__ void modpass(const float* xs_main, const float* xs_ctx, const float* mod_l, const float* g, int i, bf16_t* H, int nrows, int gw, int NGW, int lane) {
;     ...
;         float ss = 0.f;
; #pragma unroll
;         for (int j = 0; j < 2; ++j)
; #pragma unroll
;             for (int q = 0; q < 2; ++q) ss += (v[j][q][0] * v[j][q][0] + v[j][q][1] * v[j][q][1]) + (v[j][q][2] * v[j][q][2] + v[j][q][3] * v[j][q][3]);
;         const float rstd = 1.0f / sqrtf(wave_sum(ss) * (1.0f / D) + EPS);
	v_pk_fma_f32 v[28:29], v[28:29], v[196:197], v[140:141]
	v_pk_fma_f32 v[30:31], v[30:31], v[198:199], v[142:143]
	v_mul_f32_e32 v238, v28, v28
	v_fmac_f32_e32 v238, v29, v29
	v_fmac_f32_e32 v238, v30, v30
	v_fmac_f32_e32 v238, v31, v31
	s_waitcnt vmcnt(14)
	v_pk_fma_f32 v[24:25], v[24:25], v[212:213], v[144:145]
	v_pk_fma_f32 v[26:27], v[26:27], v[214:215], v[146:147]
	v_fmac_f32_e32 v238, v24, v24
	v_fmac_f32_e32 v238, v25, v25
	v_fmac_f32_e32 v238, v26, v26
	v_fmac_f32_e32 v238, v27, v27
	s_waitcnt vmcnt(13)
	v_pk_fma_f32 v[20:21], v[20:21], v[216:217], v[148:149]
	v_pk_fma_f32 v[22:23], v[22:23], v[218:219], v[150:151]
	v_fmac_f32_e32 v238, v20, v20
	v_fmac_f32_e32 v238, v21, v21
	v_fmac_f32_e32 v238, v22, v22
	v_fmac_f32_e32 v238, v23, v23
	s_waitcnt vmcnt(12)
	v_pk_fma_f32 v[16:17], v[16:17], v[220:221], v[152:153]
	v_pk_fma_f32 v[18:19], v[18:19], v[222:223], v[154:155]
	v_fmac_f32_e32 v238, v16, v16
	v_fmac_f32_e32 v238, v17, v17
	v_fmac_f32_e32 v238, v18, v18
	v_fmac_f32_e32 v238, v19, v19
	global_store_dwordx4 v230, v[28:31], s[16:17] sc1
	global_store_dwordx4 v230, v[24:27], s[16:17] offset:64 sc1
	global_store_dwordx4 v230, v[20:23], s[16:17] offset:512 sc1
	global_store_dwordx4 v230, v[16:19], s[16:17] offset:576 sc1
	s_waitcnt vmcnt(11)
	v_pk_fma_f32 v[12:13], v[12:13], v[196:197], v[164:165]
	v_pk_fma_f32 v[14:15], v[14:15], v[198:199], v[166:167]
	v_mul_f32_e32 v239, v12, v12
	v_fmac_f32_e32 v239, v13, v13
	v_fmac_f32_e32 v239, v14, v14
	v_fmac_f32_e32 v239, v15, v15
	s_waitcnt vmcnt(10)
	v_pk_fma_f32 v[8:9], v[8:9], v[212:213], v[168:169]
	v_pk_fma_f32 v[10:11], v[10:11], v[214:215], v[170:171]
	v_fmac_f32_e32 v239, v8, v8
	v_fmac_f32_e32 v239, v9, v9
	v_fmac_f32_e32 v239, v10, v10
	v_fmac_f32_e32 v239, v11, v11
	s_waitcnt vmcnt(9)
	v_pk_fma_f32 v[4:5], v[4:5], v[216:217], v[172:173]
	v_pk_fma_f32 v[6:7], v[6:7], v[218:219], v[174:175]
	v_fmac_f32_e32 v239, v4, v4
	v_fmac_f32_e32 v239, v5, v5
	v_fmac_f32_e32 v239, v6, v6
	v_fmac_f32_e32 v239, v7, v7
	s_waitcnt vmcnt(8)
	v_pk_fma_f32 v[0:1], v[0:1], v[220:221], v[176:177]
	v_pk_fma_f32 v[2:3], v[2:3], v[222:223], v[178:179]
	v_fmac_f32_e32 v239, v0, v0
	v_fmac_f32_e32 v239, v1, v1
	v_fmac_f32_e32 v239, v2, v2
	v_fmac_f32_e32 v239, v3, v3
	global_store_dwordx4 v231, v[12:15], s[16:17] sc1
	global_store_dwordx4 v231, v[8:11], s[16:17] offset:64 sc1
	global_store_dwordx4 v231, v[4:7], s[16:17] offset:512 sc1
	global_store_dwordx4 v231, v[0:3], s[16:17] offset:576 sc1
	v_mbcnt_lo_u32_b32 v240, -1, 0
	v_mbcnt_hi_u32_b32 v240, -1, v240
	v_xor_b32_e32 v241, 16, v240
	v_xor_b32_e32 v242, 32, v240
	v_lshlrev_b32_e32 v241, 2, v241
	v_lshlrev_b32_e32 v242, 2, v242
	s_waitcnt lgkmcnt(0)
	ds_bpermute_b32 v140, v241, v232
	ds_bpermute_b32 v141, v241, v233
	ds_bpermute_b32 v142, v241, v234
	ds_bpermute_b32 v143, v241, v235
	ds_bpermute_b32 v144, v241, v236
	ds_bpermute_b32 v145, v241, v237
	ds_bpermute_b32 v146, v241, v238
	ds_bpermute_b32 v147, v241, v239
	s_waitcnt lgkmcnt(7)
	v_add_f32_e32 v232, v232, v140
	s_waitcnt lgkmcnt(6)
	v_add_f32_e32 v233, v233, v141
	s_waitcnt lgkmcnt(5)
	v_add_f32_e32 v234, v234, v142
	s_waitcnt lgkmcnt(4)
	v_add_f32_e32 v235, v235, v143
	s_waitcnt lgkmcnt(3)
	v_add_f32_e32 v236, v236, v144
	s_waitcnt lgkmcnt(2)
	v_add_f32_e32 v237, v237, v145
	s_waitcnt lgkmcnt(1)
	v_add_f32_e32 v238, v238, v146
	s_waitcnt lgkmcnt(0)
	v_add_f32_e32 v239, v239, v147
	ds_bpermute_b32 v140, v242, v232
	ds_bpermute_b32 v141, v242, v233
	ds_bpermute_b32 v142, v242, v234
	ds_bpermute_b32 v143, v242, v235
	ds_bpermute_b32 v144, v242, v236
	ds_bpermute_b32 v145, v242, v237
	ds_bpermute_b32 v146, v242, v238
	ds_bpermute_b32 v147, v242, v239
	s_waitcnt lgkmcnt(7)
	v_add_f32_e32 v232, v232, v140
	s_waitcnt lgkmcnt(6)
	v_add_f32_e32 v233, v233, v141
	s_waitcnt lgkmcnt(5)
	v_add_f32_e32 v234, v234, v142
	s_waitcnt lgkmcnt(4)
	v_add_f32_e32 v235, v235, v143
	s_waitcnt lgkmcnt(3)
	v_add_f32_e32 v236, v236, v144
	s_waitcnt lgkmcnt(2)
	v_add_f32_e32 v237, v237, v145
	s_waitcnt lgkmcnt(1)
	v_add_f32_e32 v238, v238, v146
	s_waitcnt lgkmcnt(0)
	v_add_f32_e32 v239, v239, v147
	v_lshlrev_b32_e32 v243, 2, v156
	s_add_u32 s90, s76, 0x6500000
	s_addc_u32 s91, s77, 0
	s_add_u32 s76, s76, 0x3164000
	s_addc_u32 s77, s77, 0
	s_lshl_b32 s83, s6, 6
	s_add_u32 s78, s76, s83
	s_addc_u32 s79, s77, 0
	s_add_u32 s78, s78, 0x20000
	s_addc_u32 s79, s79, 0
	s_mov_b64 s[80:81], exec
	s_mov_b64 exec, 0xffff
	global_atomic_add_f32 v243, v232, s[76:77]
	global_atomic_add_f32 v243, v233, s[76:77] offset:64
	global_atomic_add_f32 v243, v234, s[76:77] offset:128
	global_atomic_add_f32 v243, v235, s[76:77] offset:192
	global_atomic_add_f32 v243, v236, s[76:77] offset:512
	global_atomic_add_f32 v243, v237, s[76:77] offset:576
	global_atomic_add_f32 v243, v238, s[76:77] offset:640
	global_atomic_add_f32 v243, v239, s[76:77] offset:704
	s_mov_b64 exec, s[80:81]
	s_add_u32 s86, s8, 0x13000
	s_addc_u32 s87, s9, 0
	s_add_u32 s88, s86, 0x1000
	s_addc_u32 s89, s87, 0
	s_add_u32 s92, s92, 0x3000
	s_addc_u32 s93, s93, 0
	s_mov_b32 s84, 0xffff0000
	s_mov_b32 s85, 0xffff0000
	s_waitcnt vmcnt(0)
	s_barrier
	v_readfirstlane_b32 s83, v206
	v_mov_b32_e32 v244, 0
	v_mov_b32_e32 v245, 1
	s_cmp_lg_u32 s83, 0
	s_cbranch_scc1 .Lfmds_wait_done
	s_mov_b64 exec, 1
	global_atomic_add v244, v245, s[78:79]
	s_mov_b32 s82, 0

; __device__ __forceinline__ unsigned cvtpk_s(float lo, float hi) { f32x2_t v = {lo, hi}; bf16x2_t b = __builtin_convertvector(v, bf16x2_t); return __builtin_bit_cast(unsigned, b); }
; __device__ __forceinline__ u32x4 quad_swap(unsigned lo0, unsigned lo1, unsigned hi0, unsigned hi1, int fq, int& coloff) {
;     const bool odd = fq & 1;
;     const unsigned s0 = odd ? lo0 : hi0, s1 = odd ? lo1 : hi1;
;     const unsigned r0 = (unsigned)__shfl_xor((int)s0, 16), r1 = (unsigned)__shfl_xor((int)s1, 16);
;     coloff = odd ? 16 + 4 * (fq - 1) : 4 * fq;
;     u32x4 o; o.x = odd ? r0 : lo0; o.y = odd ? r1 : lo1; o.z = odd ? hi0 : r0; o.w = odd ? hi1 : r1; return o;
; __device__ __forceinline__ void modpass(const float* xs_main, const float* xs_ctx, const float* mod_l, const float* g, int i, bf16_t* H, int nrows, int gw, int NGW, int lane) {
;     ...
;         if (cond != cur) { cur = cond; const float* shift = mod_l + cond * 9216 + 3 * i * 1024; const float* scale = shift + 1024;
; #pragma unroll
;             for (int j = 0; j < 2; ++j)
; #pragma unroll
;                 for (int q = 0; q < 2; ++q) { const int c = 8 * lane + 512 * j + 4 * q; gm[j][q] = *(const f32x4*)(g + c) * (*(const f32x4*)(scale + c) + 1.0f); sh[j][q] = *(const f32x4*)(shift + c); } }
;         float ss = 0.f;
; #pragma unroll
;         for (int j = 0; j < 2; ++j)
; #pragma unroll
;             for (int q = 0; q < 2; ++q) ss += (v[j][q][0] * v[j][q][0] + v[j][q][1] * v[j][q][1]) + (v[j][q][2] * v[j][q][2] + v[j][q][3] * v[j][q][3]);
;         const float rstd = 1.0f / sqrtf(wave_sum(ss) * (1.0f / D) + EPS);
; #pragma unroll
;         for (int j = 0; j < 2; ++j) {
;             const f32x4 o0 = v[j][0] * rstd * gm[j][0] + sh[j][0], o1 = v[j][1] * rstd * gm[j][1] + sh[j][1];
;             u32x4 w; w.x = cvtpk_s(o0[0], o0[1]); w.y = cvtpk_s(o0[2], o0[3]); w.z = cvtpk_s(o1[0], o1[1]); w.w = cvtpk_s(o1[2], o1[3]);
;             *(u32x4*)(H + (size_t)row * D + 8 * lane + 512 * j) = w;
.Lfmds_wait_done:
	s_barrier
	global_load_dword v144, v243, s[76:77] sc1
	global_load_dword v145, v243, s[76:77] offset:64 sc1
	global_load_dword v146, v243, s[76:77] offset:128 sc1
	global_load_dword v147, v243, s[76:77] offset:192 sc1
	global_load_dword v148, v243, s[76:77] offset:512 sc1
	global_load_dword v149, v243, s[76:77] offset:576 sc1
	global_load_dword v150, v243, s[76:77] offset:640 sc1
	global_load_dword v151, v243, s[76:77] offset:704 sc1
	global_load_dwordx4 v[196:199], v201, s[86:87]
	global_load_dwordx4 v[212:215], v201, s[86:87] offset:64
	global_load_dwordx4 v[216:219], v201, s[86:87] offset:512
	global_load_dwordx4 v[220:223], v201, s[86:87] offset:576
	global_load_dwordx4 v[152:155], v201, s[88:89]
	global_load_dwordx4 v[164:167], v201, s[88:89] offset:64
	global_load_dwordx4 v[168:171], v201, s[88:89] offset:512
	global_load_dwordx4 v[172:175], v201, s[88:89] offset:576
	global_load_dwordx4 v[176:179], v201, s[92:93]
	global_load_dwordx4 v[180:183], v201, s[92:93] offset:64
	global_load_dwordx4 v[184:187], v201, s[92:93] offset:512
	global_load_dwordx4 v[188:191], v201, s[92:93] offset:576
	v_mov_b32_e32 v240, 12
	v_cndmask_b32_e64 v240, 0, v240, s[84:85]
	v_add_u32_e32 v240, v240, v157
	v_lshlrev_b32_e32 v240, 1, v240
	v_lshl_add_u32 v247, v156, 11, v240
	v_mov_b32_e32 v240, 0x358637bd
	s_waitcnt vmcnt(0)
	v_fmamk_f32 v144, v144, 0x3a800000, v240
	v_fmamk_f32 v145, v145, 0x3a800000, v240
	v_fmamk_f32 v146, v146, 0x3a800000, v240
	v_fmamk_f32 v147, v147, 0x3a800000, v240
	v_fmamk_f32 v148, v148, 0x3a800000, v240
	v_fmamk_f32 v149, v149, 0x3a800000, v240
	v_fmamk_f32 v150, v150, 0x3a800000, v240
	v_fmamk_f32 v151, v151, 0x3a800000, v240
	v_rsq_f32_e32 v144, v144
	v_rsq_f32_e32 v145, v145
	v_rsq_f32_e32 v146, v146
	v_rsq_f32_e32 v147, v147
	v_rsq_f32_e32 v148, v148
	v_rsq_f32_e32 v149, v149
	v_rsq_f32_e32 v150, v150
	v_rsq_f32_e32 v151, v151
	v_pk_add_f32 v[152:153], v[152:153], 1.0 op_sel_hi:[1,0]
	v_pk_mul_f32 v[152:153], v[176:177], v[152:153]
	v_pk_add_f32 v[154:155], v[154:155], 1.0 op_sel_hi:[1,0]
	v_pk_mul_f32 v[154:155], v[178:179], v[154:155]
	v_pk_add_f32 v[164:165], v[164:165], 1.0 op_sel_hi:[1,0]
	v_pk_mul_f32 v[164:165], v[180:181], v[164:165]
	v_pk_add_f32 v[166:167], v[166:167], 1.0 op_sel_hi:[1,0]
	v_pk_mul_f32 v[166:167], v[182:183], v[166:167]
	v_pk_add_f32 v[168:169], v[168:169], 1.0 op_sel_hi:[1,0]
	v_pk_mul_f32 v[168:169], v[184:185], v[168:169]
	v_pk_add_f32 v[170:171], v[170:171], 1.0 op_sel_hi:[1,0]
	v_pk_mul_f32 v[170:171], v[186:187], v[170:171]
	v_pk_add_f32 v[172:173], v[172:173], 1.0 op_sel_hi:[1,0]
	v_pk_mul_f32 v[172:173], v[188:189], v[172:173]
	v_pk_add_f32 v[174:175], v[174:175], 1.0 op_sel_hi:[1,0]
	v_pk_mul_f32 v[174:175], v[190:191], v[174:175]
	v_mul_f32_e32 v124, v124, v144
	v_mul_f32_e32 v125, v125, v144
	v_pk_fma_f32 v[124:125], v[152:153], v[124:125], v[196:197]
	v_mul_f32_e32 v126, v126, v144
	v_mul_f32_e32 v127, v127, v144
	v_pk_fma_f32 v[126:127], v[154:155], v[126:127], v[198:199]
	v_cvt_pk_bf16_f32 v184, v124, v125
	v_cvt_pk_bf16_f32 v185, v126, v127
	v_mul_f32_e32 v120, v120, v144
	v_mul_f32_e32 v121, v121, v144
	v_pk_fma_f32 v[120:121], v[164:165], v[120:121], v[212:213]
	v_mul_f32_e32 v122, v122, v144
	v_mul_f32_e32 v123, v123, v144
	v_pk_fma_f32 v[122:123], v[166:167], v[122:123], v[214:215]
	v_cvt_pk_bf16_f32 v186, v120, v121
	v_cvt_pk_bf16_f32 v187, v122, v123
	v_mul_f32_e32 v116, v116, v144
	v_mul_f32_e32 v117, v117, v144
	v_pk_fma_f32 v[116:117], v[168:169], v[116:117], v[216:217]
	v_mul_f32_e32 v118, v118, v144
	v_mul_f32_e32 v119, v119, v144
	v_pk_fma_f32 v[118:119], v[170:171], v[118:119], v[218:219]
	v_cvt_pk_bf16_f32 v188, v116, v117
	v_cvt_pk_bf16_f32 v189, v118, v119
	v_mul_f32_e32 v112, v112, v144
	v_mul_f32_e32 v113, v113, v144
	v_pk_fma_f32 v[112:113], v[172:173], v[112:113], v[220:221]
	v_mul_f32_e32 v114, v114, v144
	v_mul_f32_e32 v115, v115, v144
	v_pk_fma_f32 v[114:115], v[174:175], v[114:115], v[222:223]
	v_cvt_pk_bf16_f32 v190, v112, v113
	v_cvt_pk_bf16_f32 v191, v114, v115
	v_mov_b32_e32 v240, v247
	v_cndmask_b32_e64 v192, v186, v184, s[84:85]
	v_cndmask_b32_e64 v193, v187, v185, s[84:85]
	ds_bpermute_b32 v194, v241, v192
	ds_bpermute_b32 v195, v241, v193
	s_waitcnt lgkmcnt(0)
	v_cndmask_b32_e64 v176, v184, v194, s[84:85]
	v_cndmask_b32_e64 v177, v185, v195, s[84:85]
	v_cndmask_b32_e64 v178, v194, v186, s[84:85]
	v_cndmask_b32_e64 v179, v195, v187, s[84:85]
	global_store_dwordx4 v240, v[176:179], s[90:91] sc1
	v_cndmask_b32_e64 v192, v190, v188, s[84:85]
	v_cndmask_b32_e64 v193, v191, v189, s[84:85]
	ds_bpermute_b32 v194, v241, v192
	ds_bpermute_b32 v195, v241, v193
	s_waitcnt lgkmcnt(0)
	v_cndmask_b32_e64 v180, v188, v194, s[84:85]
	v_cndmask_b32_e64 v181, v189, v195, s[84:85]
	v_cndmask_b32_e64 v182, v194, v190, s[84:85]
	v_cndmask_b32_e64 v183, v195, v191, s[84:85]
	global_store_dwordx4 v240, v[180:183], s[90:91] offset:256 sc1
	v_mul_f32_e32 v108, v108, v145
	v_mul_f32_e32 v109, v109, v145
	v_pk_fma_f32 v[108:109], v[152:153], v[108:109], v[196:197]
	v_mul_f32_e32 v110, v110, v145
	v_mul_f32_e32 v111, v111, v145
	v_pk_fma_f32 v[110:111], v[154:155], v[110:111], v[198:199]
	v_cvt_pk_bf16_f32 v184, v108, v109
	v_cvt_pk_bf16_f32 v185, v110, v111
	v_mul_f32_e32 v104, v104, v145
	v_mul_f32_e32 v105, v105, v145
	v_pk_fma_f32 v[104:105], v[164:165], v[104:105], v[212:213]
	v_mul_f32_e32 v106, v106, v145
	v_mul_f32_e32 v107, v107, v145
	v_pk_fma_f32 v[106:107], v[166:167], v[106:107], v[214:215]
	v_cvt_pk_bf16_f32 v186, v104, v105
	v_cvt_pk_bf16_f32 v187, v106, v107
	v_mul_f32_e32 v100, v100, v145
	v_mul_f32_e32 v101, v101, v145
	v_pk_fma_f32 v[100:101], v[168:169], v[100:101], v[216:217]
	v_mul_f32_e32 v102, v102, v145
	v_mul_f32_e32 v103, v103, v145
	v_pk_fma_f32 v[102:103], v[170:171], v[102:103], v[218:219]
	v_cvt_pk_bf16_f32 v188, v100, v101
	v_cvt_pk_bf16_f32 v189, v102, v103
	v_mul_f32_e32 v96, v96, v145
	v_mul_f32_e32 v97, v97, v145
	v_pk_fma_f32 v[96:97], v[172:173], v[96:97], v[220:221]
	v_mul_f32_e32 v98, v98, v145
	v_mul_f32_e32 v99, v99, v145
	v_pk_fma_f32 v[98:99], v[174:175], v[98:99], v[222:223]
	v_cvt_pk_bf16_f32 v190, v96, v97
	v_cvt_pk_bf16_f32 v191, v98, v99
	v_add_u32_e32 v240, 0x8000, v247
	v_cndmask_b32_e64 v192, v186, v184, s[84:85]
	v_cndmask_b32_e64 v193, v187, v185, s[84:85]
	ds_bpermute_b32 v194, v241, v192
	ds_bpermute_b32 v195, v241, v193
	s_waitcnt lgkmcnt(0)
; __device__ __forceinline__ unsigned cvtpk_s(float lo, float hi) { f32x2_t v = {lo, hi}; bf16x2_t b = __builtin_convertvector(v, bf16x2_t); return __builtin_bit_cast(unsigned, b); }
; __device__ __forceinline__ u32x4 quad_swap(unsigned lo0, unsigned lo1, unsigned hi0, unsigned hi1, int fq, int& coloff) {
;     const bool odd = fq & 1;
;     const unsigned s0 = odd ? lo0 : hi0, s1 = odd ? lo1 : hi1;
;     const unsigned r0 = (unsigned)__shfl_xor((int)s0, 16), r1 = (unsigned)__shfl_xor((int)s1, 16);
;     coloff = odd ? 16 + 4 * (fq - 1) : 4 * fq;
;     u32x4 o; o.x = odd ? r0 : lo0; o.y = odd ? r1 : lo1; o.z = odd ? hi0 : r0; o.w = odd ? hi1 : r1; return o;
; __device__ __forceinline__ void modpass(const float* xs_main, const float* xs_ctx, const float* mod_l, const float* g, int i, bf16_t* H, int nrows, int gw, int NGW, int lane) {
;     ...
;         for (int j = 0; j < 2; ++j) {
;             const f32x4 o0 = v[j][0] * rstd * gm[j][0] + sh[j][0], o1 = v[j][1] * rstd * gm[j][1] + sh[j][1];
;             u32x4 w; w.x = cvtpk_s(o0[0], o0[1]); w.y = cvtpk_s(o0[2], o0[3]); w.z = cvtpk_s(o1[0], o1[1]); w.w = cvtpk_s(o1[2], o1[3]);
;             *(u32x4*)(H + (size_t)row * D + 8 * lane + 512 * j) = w;
	v_cndmask_b32_e64 v176, v184, v194, s[84:85]
	v_cndmask_b32_e64 v177, v185, v195, s[84:85]
	v_cndmask_b32_e64 v178, v194, v186, s[84:85]
	v_cndmask_b32_e64 v179, v195, v187, s[84:85]
	global_store_dwordx4 v240, v[176:179], s[90:91] sc1
	v_cndmask_b32_e64 v192, v190, v188, s[84:85]
	v_cndmask_b32_e64 v193, v191, v189, s[84:85]
	ds_bpermute_b32 v194, v241, v192
	ds_bpermute_b32 v195, v241, v193
	s_waitcnt lgkmcnt(0)
	v_cndmask_b32_e64 v180, v188, v194, s[84:85]
	v_cndmask_b32_e64 v181, v189, v195, s[84:85]
	v_cndmask_b32_e64 v182, v194, v190, s[84:85]
	v_cndmask_b32_e64 v183, v195, v191, s[84:85]
	global_store_dwordx4 v240, v[180:183], s[90:91] offset:256 sc1
	v_mul_f32_e32 v92, v92, v146
	v_mul_f32_e32 v93, v93, v146
	v_pk_fma_f32 v[92:93], v[152:153], v[92:93], v[196:197]
	v_mul_f32_e32 v94, v94, v146
	v_mul_f32_e32 v95, v95, v146
	v_pk_fma_f32 v[94:95], v[154:155], v[94:95], v[198:199]
	v_cvt_pk_bf16_f32 v184, v92, v93
	v_cvt_pk_bf16_f32 v185, v94, v95
	v_mul_f32_e32 v88, v88, v146
	v_mul_f32_e32 v89, v89, v146
	v_pk_fma_f32 v[88:89], v[164:165], v[88:89], v[212:213]
	v_mul_f32_e32 v90, v90, v146
	v_mul_f32_e32 v91, v91, v146
	v_pk_fma_f32 v[90:91], v[166:167], v[90:91], v[214:215]
	v_cvt_pk_bf16_f32 v186, v88, v89
	v_cvt_pk_bf16_f32 v187, v90, v91
	v_mul_f32_e32 v84, v84, v146
	v_mul_f32_e32 v85, v85, v146
	v_pk_fma_f32 v[84:85], v[168:169], v[84:85], v[216:217]
	v_mul_f32_e32 v86, v86, v146
	v_mul_f32_e32 v87, v87, v146
	v_pk_fma_f32 v[86:87], v[170:171], v[86:87], v[218:219]
	v_cvt_pk_bf16_f32 v188, v84, v85
	v_cvt_pk_bf16_f32 v189, v86, v87
	v_mul_f32_e32 v80, v80, v146
	v_mul_f32_e32 v81, v81, v146
	v_pk_fma_f32 v[80:81], v[172:173], v[80:81], v[220:221]
	v_mul_f32_e32 v82, v82, v146
	v_mul_f32_e32 v83, v83, v146
	v_pk_fma_f32 v[82:83], v[174:175], v[82:83], v[222:223]
	v_cvt_pk_bf16_f32 v190, v80, v81
	v_cvt_pk_bf16_f32 v191, v82, v83
	v_add_u32_e32 v240, 0x10000, v247
	v_cndmask_b32_e64 v192, v186, v184, s[84:85]
	v_cndmask_b32_e64 v193, v187, v185, s[84:85]
	ds_bpermute_b32 v194, v241, v192
	ds_bpermute_b32 v195, v241, v193
	s_waitcnt lgkmcnt(0)
	v_cndmask_b32_e64 v176, v184, v194, s[84:85]
	v_cndmask_b32_e64 v177, v185, v195, s[84:85]
	v_cndmask_b32_e64 v178, v194, v186, s[84:85]
	v_cndmask_b32_e64 v179, v195, v187, s[84:85]
	global_store_dwordx4 v240, v[176:179], s[90:91] sc1
	v_cndmask_b32_e64 v192, v190, v188, s[84:85]
	v_cndmask_b32_e64 v193, v191, v189, s[84:85]
	ds_bpermute_b32 v194, v241, v192
	ds_bpermute_b32 v195, v241, v193
	s_waitcnt lgkmcnt(0)
	v_cndmask_b32_e64 v180, v188, v194, s[84:85]
	v_cndmask_b32_e64 v181, v189, v195, s[84:85]
	v_cndmask_b32_e64 v182, v194, v190, s[84:85]
	v_cndmask_b32_e64 v183, v195, v191, s[84:85]
	global_store_dwordx4 v240, v[180:183], s[90:91] offset:256 sc1
	v_mul_f32_e32 v76, v76, v147
	v_mul_f32_e32 v77, v77, v147
	v_pk_fma_f32 v[76:77], v[152:153], v[76:77], v[196:197]
	v_mul_f32_e32 v78, v78, v147
	v_mul_f32_e32 v79, v79, v147
	v_pk_fma_f32 v[78:79], v[154:155], v[78:79], v[198:199]
	v_cvt_pk_bf16_f32 v184, v76, v77
	v_cvt_pk_bf16_f32 v185, v78, v79
	v_mul_f32_e32 v72, v72, v147
	v_mul_f32_e32 v73, v73, v147
	v_pk_fma_f32 v[72:73], v[164:165], v[72:73], v[212:213]
	v_mul_f32_e32 v74, v74, v147
	v_mul_f32_e32 v75, v75, v147
	v_pk_fma_f32 v[74:75], v[166:167], v[74:75], v[214:215]
	v_cvt_pk_bf16_f32 v186, v72, v73
	v_cvt_pk_bf16_f32 v187, v74, v75
	v_mul_f32_e32 v68, v68, v147
	v_mul_f32_e32 v69, v69, v147
	v_pk_fma_f32 v[68:69], v[168:169], v[68:69], v[216:217]
	v_mul_f32_e32 v70, v70, v147
	v_mul_f32_e32 v71, v71, v147
	v_pk_fma_f32 v[70:71], v[170:171], v[70:71], v[218:219]
	v_cvt_pk_bf16_f32 v188, v68, v69
	v_cvt_pk_bf16_f32 v189, v70, v71
	v_mul_f32_e32 v64, v64, v147
	v_mul_f32_e32 v65, v65, v147
	v_pk_fma_f32 v[64:65], v[172:173], v[64:65], v[220:221]
	v_mul_f32_e32 v66, v66, v147
	v_mul_f32_e32 v67, v67, v147
	v_pk_fma_f32 v[66:67], v[174:175], v[66:67], v[222:223]
	v_cvt_pk_bf16_f32 v190, v64, v65
	v_cvt_pk_bf16_f32 v191, v66, v67
	v_add_u32_e32 v240, 0x18000, v247
	v_cndmask_b32_e64 v192, v186, v184, s[84:85]
	v_cndmask_b32_e64 v193, v187, v185, s[84:85]
	ds_bpermute_b32 v194, v241, v192
	ds_bpermute_b32 v195, v241, v193
	s_waitcnt lgkmcnt(0)
	v_cndmask_b32_e64 v176, v184, v194, s[84:85]
	v_cndmask_b32_e64 v177, v185, v195, s[84:85]
	v_cndmask_b32_e64 v178, v194, v186, s[84:85]
	v_cndmask_b32_e64 v179, v195, v187, s[84:85]
	global_store_dwordx4 v240, v[176:179], s[90:91] sc1
	v_cndmask_b32_e64 v192, v190, v188, s[84:85]
	v_cndmask_b32_e64 v193, v191, v189, s[84:85]
	ds_bpermute_b32 v194, v241, v192
	ds_bpermute_b32 v195, v241, v193
	s_waitcnt lgkmcnt(0)
	v_cndmask_b32_e64 v180, v188, v194, s[84:85]
	v_cndmask_b32_e64 v181, v189, v195, s[84:85]
	v_cndmask_b32_e64 v182, v194, v190, s[84:85]
	v_cndmask_b32_e64 v183, v195, v191, s[84:85]
	global_store_dwordx4 v240, v[180:183], s[90:91] offset:256 sc1
	v_mul_f32_e32 v60, v60, v148
	v_mul_f32_e32 v61, v61, v148
	v_pk_fma_f32 v[60:61], v[152:153], v[60:61], v[196:197]
	v_mul_f32_e32 v62, v62, v148
	v_mul_f32_e32 v63, v63, v148
	v_pk_fma_f32 v[62:63], v[154:155], v[62:63], v[198:199]
	v_cvt_pk_bf16_f32 v184, v60, v61
	v_cvt_pk_bf16_f32 v185, v62, v63
	v_mul_f32_e32 v56, v56, v148
	v_mul_f32_e32 v57, v57, v148
	v_pk_fma_f32 v[56:57], v[164:165], v[56:57], v[212:213]
	v_mul_f32_e32 v58, v58, v148
	v_mul_f32_e32 v59, v59, v148
	v_pk_fma_f32 v[58:59], v[166:167], v[58:59], v[214:215]
	v_cvt_pk_bf16_f32 v186, v56, v57
	v_cvt_pk_bf16_f32 v187, v58, v59
	v_mul_f32_e32 v52, v52, v148
	v_mul_f32_e32 v53, v53, v148
	v_pk_fma_f32 v[52:53], v[168:169], v[52:53], v[216:217]
	v_mul_f32_e32 v54, v54, v148
	v_mul_f32_e32 v55, v55, v148
	v_pk_fma_f32 v[54:55], v[170:171], v[54:55], v[218:219]
	v_cvt_pk_bf16_f32 v188, v52, v53
	v_cvt_pk_bf16_f32 v189, v54, v55
	v_mul_f32_e32 v48, v48, v148
	v_mul_f32_e32 v49, v49, v148
	v_pk_fma_f32 v[48:49], v[172:173], v[48:49], v[220:221]
	v_mul_f32_e32 v50, v50, v148
	v_mul_f32_e32 v51, v51, v148
	v_pk_fma_f32 v[50:51], v[174:175], v[50:51], v[222:223]
	v_cvt_pk_bf16_f32 v190, v48, v49
	v_cvt_pk_bf16_f32 v191, v50, v51
	v_add_u32_e32 v240, 0x40000, v247
	v_cndmask_b32_e64 v192, v186, v184, s[84:85]
	v_cndmask_b32_e64 v193, v187, v185, s[84:85]
	ds_bpermute_b32 v194, v241, v192
	ds_bpermute_b32 v195, v241, v193
	s_waitcnt lgkmcnt(0)
; __device__ __forceinline__ unsigned cvtpk_s(float lo, float hi) { f32x2_t v = {lo, hi}; bf16x2_t b = __builtin_convertvector(v, bf16x2_t); return __builtin_bit_cast(unsigned, b); }
; __device__ __forceinline__ u32x4 quad_swap(unsigned lo0, unsigned lo1, unsigned hi0, unsigned hi1, int fq, int& coloff) {
;     const bool odd = fq & 1;
;     const unsigned s0 = odd ? lo0 : hi0, s1 = odd ? lo1 : hi1;
;     const unsigned r0 = (unsigned)__shfl_xor((int)s0, 16), r1 = (unsigned)__shfl_xor((int)s1, 16);
;     coloff = odd ? 16 + 4 * (fq - 1) : 4 * fq;
;     u32x4 o; o.x = odd ? r0 : lo0; o.y = odd ? r1 : lo1; o.z = odd ? hi0 : r0; o.w = odd ? hi1 : r1; return o;
; __device__ __forceinline__ void modpass(const float* xs_main, const float* xs_ctx, const float* mod_l, const float* g, int i, bf16_t* H, int nrows, int gw, int NGW, int lane) {
;     ...
;             const f32x4 o0 = v[j][0] * rstd * gm[j][0] + sh[j][0], o1 = v[j][1] * rstd * gm[j][1] + sh[j][1];
;             u32x4 w; w.x = cvtpk_s(o0[0], o0[1]); w.y = cvtpk_s(o0[2], o0[3]); w.z = cvtpk_s(o1[0], o1[1]); w.w = cvtpk_s(o1[2], o1[3]);
;             *(u32x4*)(H + (size_t)row * D + 8 * lane + 512 * j) = w;
	v_cndmask_b32_e64 v176, v184, v194, s[84:85]
	v_cndmask_b32_e64 v177, v185, v195, s[84:85]
	v_cndmask_b32_e64 v178, v194, v186, s[84:85]
	v_cndmask_b32_e64 v179, v195, v187, s[84:85]
	global_store_dwordx4 v240, v[176:179], s[90:91] sc1
	v_cndmask_b32_e64 v192, v190, v188, s[84:85]
	v_cndmask_b32_e64 v193, v191, v189, s[84:85]
	ds_bpermute_b32 v194, v241, v192
	ds_bpermute_b32 v195, v241, v193
	s_waitcnt lgkmcnt(0)
	v_cndmask_b32_e64 v180, v188, v194, s[84:85]
	v_cndmask_b32_e64 v181, v189, v195, s[84:85]
	v_cndmask_b32_e64 v182, v194, v190, s[84:85]
	v_cndmask_b32_e64 v183, v195, v191, s[84:85]
	global_store_dwordx4 v240, v[180:183], s[90:91] offset:256 sc1
	v_mul_f32_e32 v44, v44, v149
	v_mul_f32_e32 v45, v45, v149
	v_pk_fma_f32 v[44:45], v[152:153], v[44:45], v[196:197]
	v_mul_f32_e32 v46, v46, v149
	v_mul_f32_e32 v47, v47, v149
	v_pk_fma_f32 v[46:47], v[154:155], v[46:47], v[198:199]
	v_cvt_pk_bf16_f32 v184, v44, v45
	v_cvt_pk_bf16_f32 v185, v46, v47
	v_mul_f32_e32 v40, v40, v149
	v_mul_f32_e32 v41, v41, v149
	v_pk_fma_f32 v[40:41], v[164:165], v[40:41], v[212:213]
	v_mul_f32_e32 v42, v42, v149
	v_mul_f32_e32 v43, v43, v149
	v_pk_fma_f32 v[42:43], v[166:167], v[42:43], v[214:215]
	v_cvt_pk_bf16_f32 v186, v40, v41
	v_cvt_pk_bf16_f32 v187, v42, v43
	v_mul_f32_e32 v36, v36, v149
	v_mul_f32_e32 v37, v37, v149
	v_pk_fma_f32 v[36:37], v[168:169], v[36:37], v[216:217]
	v_mul_f32_e32 v38, v38, v149
	v_mul_f32_e32 v39, v39, v149
	v_pk_fma_f32 v[38:39], v[170:171], v[38:39], v[218:219]
	v_cvt_pk_bf16_f32 v188, v36, v37
	v_cvt_pk_bf16_f32 v189, v38, v39
	v_mul_f32_e32 v32, v32, v149
	v_mul_f32_e32 v33, v33, v149
	v_pk_fma_f32 v[32:33], v[172:173], v[32:33], v[220:221]
	v_mul_f32_e32 v34, v34, v149
	v_mul_f32_e32 v35, v35, v149
	v_pk_fma_f32 v[34:35], v[174:175], v[34:35], v[222:223]
	v_cvt_pk_bf16_f32 v190, v32, v33
	v_cvt_pk_bf16_f32 v191, v34, v35
	v_add_u32_e32 v240, 0x48000, v247
	v_cndmask_b32_e64 v192, v186, v184, s[84:85]
	v_cndmask_b32_e64 v193, v187, v185, s[84:85]
	ds_bpermute_b32 v194, v241, v192
	ds_bpermute_b32 v195, v241, v193
	s_waitcnt lgkmcnt(0)
	v_cndmask_b32_e64 v176, v184, v194, s[84:85]
	v_cndmask_b32_e64 v177, v185, v195, s[84:85]
	v_cndmask_b32_e64 v178, v194, v186, s[84:85]
	v_cndmask_b32_e64 v179, v195, v187, s[84:85]
	global_store_dwordx4 v240, v[176:179], s[90:91] sc1
	v_cndmask_b32_e64 v192, v190, v188, s[84:85]
	v_cndmask_b32_e64 v193, v191, v189, s[84:85]
	ds_bpermute_b32 v194, v241, v192
	ds_bpermute_b32 v195, v241, v193
	s_waitcnt lgkmcnt(0)
	v_cndmask_b32_e64 v180, v188, v194, s[84:85]
	v_cndmask_b32_e64 v181, v189, v195, s[84:85]
	v_cndmask_b32_e64 v182, v194, v190, s[84:85]
	v_cndmask_b32_e64 v183, v195, v191, s[84:85]
	global_store_dwordx4 v240, v[180:183], s[90:91] offset:256 sc1
	v_mul_f32_e32 v28, v28, v150
	v_mul_f32_e32 v29, v29, v150
	v_pk_fma_f32 v[28:29], v[152:153], v[28:29], v[196:197]
	v_mul_f32_e32 v30, v30, v150
	v_mul_f32_e32 v31, v31, v150
	v_pk_fma_f32 v[30:31], v[154:155], v[30:31], v[198:199]
	v_cvt_pk_bf16_f32 v184, v28, v29
	v_cvt_pk_bf16_f32 v185, v30, v31
	v_mul_f32_e32 v24, v24, v150
	v_mul_f32_e32 v25, v25, v150
	v_pk_fma_f32 v[24:25], v[164:165], v[24:25], v[212:213]
	v_mul_f32_e32 v26, v26, v150
	v_mul_f32_e32 v27, v27, v150
	v_pk_fma_f32 v[26:27], v[166:167], v[26:27], v[214:215]
	v_cvt_pk_bf16_f32 v186, v24, v25
	v_cvt_pk_bf16_f32 v187, v26, v27
	v_mul_f32_e32 v20, v20, v150
	v_mul_f32_e32 v21, v21, v150
	v_pk_fma_f32 v[20:21], v[168:169], v[20:21], v[216:217]
	v_mul_f32_e32 v22, v22, v150
	v_mul_f32_e32 v23, v23, v150
	v_pk_fma_f32 v[22:23], v[170:171], v[22:23], v[218:219]
	v_cvt_pk_bf16_f32 v188, v20, v21
	v_cvt_pk_bf16_f32 v189, v22, v23
	v_mul_f32_e32 v16, v16, v150
	v_mul_f32_e32 v17, v17, v150
	v_pk_fma_f32 v[16:17], v[172:173], v[16:17], v[220:221]
	v_mul_f32_e32 v18, v18, v150
	v_mul_f32_e32 v19, v19, v150
	v_pk_fma_f32 v[18:19], v[174:175], v[18:19], v[222:223]
	v_cvt_pk_bf16_f32 v190, v16, v17
	v_cvt_pk_bf16_f32 v191, v18, v19
	v_add_u32_e32 v240, 0x50000, v247
	v_cndmask_b32_e64 v192, v186, v184, s[84:85]
	v_cndmask_b32_e64 v193, v187, v185, s[84:85]
	ds_bpermute_b32 v194, v241, v192
	ds_bpermute_b32 v195, v241, v193
	s_waitcnt lgkmcnt(0)
	v_cndmask_b32_e64 v176, v184, v194, s[84:85]
	v_cndmask_b32_e64 v177, v185, v195, s[84:85]
	v_cndmask_b32_e64 v178, v194, v186, s[84:85]
	v_cndmask_b32_e64 v179, v195, v187, s[84:85]
	global_store_dwordx4 v240, v[176:179], s[90:91] sc1
	v_cndmask_b32_e64 v192, v190, v188, s[84:85]
	v_cndmask_b32_e64 v193, v191, v189, s[84:85]
	ds_bpermute_b32 v194, v241, v192
	ds_bpermute_b32 v195, v241, v193
	s_waitcnt lgkmcnt(0)
	v_cndmask_b32_e64 v180, v188, v194, s[84:85]
	v_cndmask_b32_e64 v181, v189, v195, s[84:85]
	v_cndmask_b32_e64 v182, v194, v190, s[84:85]
	v_cndmask_b32_e64 v183, v195, v191, s[84:85]
	global_store_dwordx4 v240, v[180:183], s[90:91] offset:256 sc1
	v_mul_f32_e32 v12, v12, v151
	v_mul_f32_e32 v13, v13, v151
	v_pk_fma_f32 v[12:13], v[152:153], v[12:13], v[196:197]
	v_mul_f32_e32 v14, v14, v151
	v_mul_f32_e32 v15, v15, v151
	v_pk_fma_f32 v[14:15], v[154:155], v[14:15], v[198:199]
	v_cvt_pk_bf16_f32 v184, v12, v13
	v_cvt_pk_bf16_f32 v185, v14, v15
	v_mul_f32_e32 v8, v8, v151
	v_mul_f32_e32 v9, v9, v151
	v_pk_fma_f32 v[8:9], v[164:165], v[8:9], v[212:213]
	v_mul_f32_e32 v10, v10, v151
	v_mul_f32_e32 v11, v11, v151
	v_pk_fma_f32 v[10:11], v[166:167], v[10:11], v[214:215]
	v_cvt_pk_bf16_f32 v186, v8, v9
	v_cvt_pk_bf16_f32 v187, v10, v11
	v_mul_f32_e32 v4, v4, v151
	v_mul_f32_e32 v5, v5, v151
	v_pk_fma_f32 v[4:5], v[168:169], v[4:5], v[216:217]
	v_mul_f32_e32 v6, v6, v151
	v_mul_f32_e32 v7, v7, v151
	v_pk_fma_f32 v[6:7], v[170:171], v[6:7], v[218:219]
	v_cvt_pk_bf16_f32 v188, v4, v5
	v_cvt_pk_bf16_f32 v189, v6, v7
	v_mul_f32_e32 v0, v0, v151
	v_mul_f32_e32 v1, v1, v151
	v_pk_fma_f32 v[0:1], v[172:173], v[0:1], v[220:221]
	v_mul_f32_e32 v2, v2, v151
	v_mul_f32_e32 v3, v3, v151
	v_pk_fma_f32 v[2:3], v[174:175], v[2:3], v[222:223]
	v_cvt_pk_bf16_f32 v190, v0, v1
	v_cvt_pk_bf16_f32 v191, v2, v3
	v_add_u32_e32 v240, 0x58000, v247
	v_cndmask_b32_e64 v192, v186, v184, s[84:85]
	v_cndmask_b32_e64 v193, v187, v185, s[84:85]
	ds_bpermute_b32 v194, v241, v192
	ds_bpermute_b32 v195, v241, v193
	s_waitcnt lgkmcnt(0)
	v_cndmask_b32_e64 v176, v184, v194, s[84:85]
	v_cndmask_b32_e64 v177, v185, v195, s[84:85]
	v_cndmask_b32_e64 v178, v194, v186, s[84:85]
	v_cndmask_b32_e64 v179, v195, v187, s[84:85]
	global_store_dwordx4 v240, v[176:179], s[90:91] sc1
	v_cndmask_b32_e64 v192, v190, v188, s[84:85]
	v_cndmask_b32_e64 v193, v191, v189, s[84:85]
	ds_bpermute_b32 v194, v241, v192
	ds_bpermute_b32 v195, v241, v193
	s_waitcnt lgkmcnt(0)
	v_cndmask_b32_e64 v180, v188, v194, s[84:85]
	v_cndmask_b32_e64 v181, v189, v195, s[84:85]
	v_cndmask_b32_e64 v182, v194, v190, s[84:85]
	v_cndmask_b32_e64 v183, v195, v191, s[84:85]
	global_store_dwordx4 v240, v[180:183], s[90:91] offset:256 sc1
	s_and_b64 vcc, exec, s[12:13]
	s_mov_b64 s[12:13], -1
; #define PG8_BAR __builtin_amdgcn_s_barrier()
;     ...
;         if constexpr (ALIGN_EPI) { if (wr == 0) PG8_BAR; }
;         if constexpr (!Epi::AFTER_DRAIN) { E(acc, cur, wr, wc, fr, fq); S.done(cur); }
;         if (!has_next) break;
; #pragma unroll
;         for (int a = 0; a < 2; ++a)
; #pragma unroll
;             for (int b = 0; b < 2; ++b)
; #pragma unroll
;                 for (int m = 0; m < 4; ++m)
; #pragma unroll
;                     for (int n = 0; n < 2; ++n) acc[a][b][m][n] = (f32x4){0.f, 0.f, 0.f, 0.f};
;         cur = nxt; cA = nA; cB = nB; ++ui;
;         if constexpr (ALIGN_EPI) { if (wr == 1) PG8_BAR; }
.Lfmdone_d:
	s_cbranch_vccnz .LBB0_1331
	s_andn2_b64 vcc, exec, s[18:19]
	s_cbranch_vccnz .LBB0_1330
	s_barrier
	s_branch .LBB0_1330

;     __device__ __forceinline__ void operator()(const f32x4 (&acc)[2][2][4][2], const Unit& u, int wr, int wc, int fr, int fq) const {
;         const int cond = u.pm < 64 ? 0 : (u.pm < 128 ? 1 : 2);
;         const float* gate = gate_l + cond * 9216;
;         const int col0 = u.pn * BM + wc * 32 + 4 * fq;
;         f32x4 gv[2][2];
; #pragma unroll
;         for (int bj = 0; bj < 2; ++bj)
; #pragma unroll
;             for (int n = 0; n < 2; ++n) gv[bj][n] = *(const f32x4*)(gate + col0 + bj * HALF + n * 16) * coef;
; #pragma unroll
;         for (int ai = 0; ai < 2; ++ai)
; #pragma unroll
;             for (int m = 0; m < 4; ++m) {
;                 const int row = u.pm * BM + ai * HALF + wr * 64 + m * 16 + fr;
;                 const float* s = row < MX_ ? src_main + (size_t)row * D_ : src_ctx + (size_t)(row - MX_) * D_;
;                 float* d = row < MX_ ? dst_main + (size_t)row * D_ : dst_ctx + (size_t)(row - MX_) * D_;
; #pragma unroll
;                 for (int bj = 0; bj < 2; ++bj)
; #pragma unroll
;                     for (int n = 0; n < 2; ++n) { const int off = col0 + bj * HALF + n * 16; const f32x4 xo = *(const f32x4*)(s + off); *(f32x4*)(d + off) = xo + gv[bj][n] * acc[ai][bj][m][n]; }
.LBB0_1566:
	s_and_b64 vcc, exec, s[10:11]
	s_cbranch_vccnz .Lfmsel_e
	s_cmpk_lt_i32 s6, 0x80
	s_cselect_b32 s8, s62, 0x4800
	s_cmp_gt_i32 s6, 63
	s_cselect_b32 s8, s8, 0
	s_lshl_b32 s8, s8, 2
	s_add_u32 s8, s54, s8
	s_addc_u32 s9, s55, 0
	s_load_dwordx2 s[92:93], s[0:1], 0x30
	s_load_dwordx2 s[76:77], s[0:1], 0xb8
	v_lshl_add_u32 v156, s6, 8, v158
	v_lshl_or_b32 v157, s7, 8, v160
	v_lshlrev_b32_e32 v201, 2, v157
	v_lshl_add_u32 v224, v156, 12, v201
	global_load_dwordx4 v[196:199], v201, s[8:9]
	global_load_dwordx4 v[212:215], v201, s[8:9] offset:64
	global_load_dwordx4 v[216:219], v201, s[8:9] offset:512
	global_load_dwordx4 v[220:223], v201, s[8:9] offset:576
	v_add_u32_e32 v225, 0x10000, v224
	v_add_u32_e32 v226, 0x20000, v224
	v_add_u32_e32 v227, 0x30000, v224
	v_add_u32_e32 v228, 0x80000, v224
	v_add_u32_e32 v229, 0x90000, v224
	v_add_u32_e32 v230, 0xa0000, v224
	v_add_u32_e32 v231, 0xb0000, v224
	global_load_dwordx4 v[140:143], v224, s[14:15]
	global_load_dwordx4 v[144:147], v224, s[14:15] offset:64
	global_load_dwordx4 v[148:151], v224, s[14:15] offset:512
	global_load_dwordx4 v[152:155], v224, s[14:15] offset:576
	global_load_dwordx4 v[164:167], v225, s[14:15]
	global_load_dwordx4 v[168:171], v225, s[14:15] offset:64
	global_load_dwordx4 v[172:175], v225, s[14:15] offset:512
	global_load_dwordx4 v[176:179], v225, s[14:15] offset:576
	global_load_dwordx4 v[180:183], v226, s[14:15]
	global_load_dwordx4 v[184:187], v226, s[14:15] offset:64
	global_load_dwordx4 v[188:191], v226, s[14:15] offset:512
	global_load_dwordx4 v[192:195], v226, s[14:15] offset:576
	s_waitcnt vmcnt(12)
	v_pk_mul_f32 v[196:197], v[196:197], 0.5 op_sel_hi:[1,0]
	v_pk_mul_f32 v[198:199], v[198:199], 0.5 op_sel_hi:[1,0]
	v_pk_mul_f32 v[212:213], v[212:213], 0.5 op_sel_hi:[1,0]
	v_pk_mul_f32 v[214:215], v[214:215], 0.5 op_sel_hi:[1,0]
	v_pk_mul_f32 v[216:217], v[216:217], 0.5 op_sel_hi:[1,0]
	v_pk_mul_f32 v[218:219], v[218:219], 0.5 op_sel_hi:[1,0]
	v_pk_mul_f32 v[220:221], v[220:221], 0.5 op_sel_hi:[1,0]
	v_pk_mul_f32 v[222:223], v[222:223], 0.5 op_sel_hi:[1,0]
	s_waitcnt vmcnt(11)
	v_pk_fma_f32 v[124:125], v[124:125], v[196:197], v[140:141]
	v_pk_fma_f32 v[126:127], v[126:127], v[198:199], v[142:143]
	v_mul_f32_e32 v232, v124, v124
	v_fmac_f32_e32 v232, v125, v125
	v_fmac_f32_e32 v232, v126, v126
	v_fmac_f32_e32 v232, v127, v127
	s_waitcnt vmcnt(10)
	v_pk_fma_f32 v[120:121], v[120:121], v[212:213], v[144:145]
	v_pk_fma_f32 v[122:123], v[122:123], v[214:215], v[146:147]
	v_fmac_f32_e32 v232, v120, v120
	v_fmac_f32_e32 v232, v121, v121
	v_fmac_f32_e32 v232, v122, v122
	v_fmac_f32_e32 v232, v123, v123
	s_waitcnt vmcnt(9)
	v_pk_fma_f32 v[116:117], v[116:117], v[216:217], v[148:149]
	v_pk_fma_f32 v[118:119], v[118:119], v[218:219], v[150:151]
	v_fmac_f32_e32 v232, v116, v116
	v_fmac_f32_e32 v232, v117, v117
	v_fmac_f32_e32 v232, v118, v118
	v_fmac_f32_e32 v232, v119, v119
	s_waitcnt vmcnt(8)
	v_pk_fma_f32 v[112:113], v[112:113], v[220:221], v[152:153]
	v_pk_fma_f32 v[114:115], v[114:115], v[222:223], v[154:155]
	v_fmac_f32_e32 v232, v112, v112
	v_fmac_f32_e32 v232, v113, v113
	v_fmac_f32_e32 v232, v114, v114
	v_fmac_f32_e32 v232, v115, v115
	global_store_dwordx4 v224, v[124:127], s[14:15]
	global_store_dwordx4 v224, v[120:123], s[14:15] offset:64
	global_store_dwordx4 v224, v[116:119], s[14:15] offset:512
	global_store_dwordx4 v224, v[112:115], s[14:15] offset:576
	global_load_dwordx4 v[140:143], v227, s[14:15]
	global_load_dwordx4 v[144:147], v227, s[14:15] offset:64
	global_load_dwordx4 v[148:151], v227, s[14:15] offset:512
	global_load_dwordx4 v[152:155], v227, s[14:15] offset:576
	s_waitcnt vmcnt(15)
	v_pk_fma_f32 v[108:109], v[108:109], v[196:197], v[164:165]
	v_pk_fma_f32 v[110:111], v[110:111], v[198:199], v[166:167]
	v_mul_f32_e32 v233, v108, v108
	v_fmac_f32_e32 v233, v109, v109
	v_fmac_f32_e32 v233, v110, v110
	v_fmac_f32_e32 v233, v111, v111
	s_waitcnt vmcnt(14)
	v_pk_fma_f32 v[104:105], v[104:105], v[212:213], v[168:169]
	v_pk_fma_f32 v[106:107], v[106:107], v[214:215], v[170:171]
	v_fmac_f32_e32 v233, v104, v104
	v_fmac_f32_e32 v233, v105, v105
	v_fmac_f32_e32 v233, v106, v106
	v_fmac_f32_e32 v233, v107, v107
	s_waitcnt vmcnt(13)
	v_pk_fma_f32 v[100:101], v[100:101], v[216:217], v[172:173]
	v_pk_fma_f32 v[102:103], v[102:103], v[218:219], v[174:175]
	v_fmac_f32_e32 v233, v100, v100
	v_fmac_f32_e32 v233, v101, v101
	v_fmac_f32_e32 v233, v102, v102
	v_fmac_f32_e32 v233, v103, v103
	s_waitcnt vmcnt(12)
	v_pk_fma_f32 v[96:97], v[96:97], v[220:221], v[176:177]
	v_pk_fma_f32 v[98:99], v[98:99], v[222:223], v[178:179]
	v_fmac_f32_e32 v233, v96, v96
	v_fmac_f32_e32 v233, v97, v97
	v_fmac_f32_e32 v233, v98, v98
	v_fmac_f32_e32 v233, v99, v99
	global_store_dwordx4 v225, v[108:111], s[14:15]
	global_store_dwordx4 v225, v[104:107], s[14:15] offset:64
	global_store_dwordx4 v225, v[100:103], s[14:15] offset:512
	global_store_dwordx4 v225, v[96:99], s[14:15] offset:576
	global_load_dwordx4 v[164:167], v228, s[14:15]
	global_load_dwordx4 v[168:171], v228, s[14:15] offset:64
	global_load_dwordx4 v[172:175], v228, s[14:15] offset:512
	global_load_dwordx4 v[176:179], v228, s[14:15] offset:576
	s_waitcnt vmcnt(19)
	v_pk_fma_f32 v[92:93], v[92:93], v[196:197], v[180:181]
	v_pk_fma_f32 v[94:95], v[94:95], v[198:199], v[182:183]
	v_mul_f32_e32 v234, v92, v92
	v_fmac_f32_e32 v234, v93, v93
	v_fmac_f32_e32 v234, v94, v94
	v_fmac_f32_e32 v234, v95, v95
	s_waitcnt vmcnt(18)
	v_pk_fma_f32 v[88:89], v[88:89], v[212:213], v[184:185]
	v_pk_fma_f32 v[90:91], v[90:91], v[214:215], v[186:187]
	v_fmac_f32_e32 v234, v88, v88
	v_fmac_f32_e32 v234, v89, v89
	v_fmac_f32_e32 v234, v90, v90
	v_fmac_f32_e32 v234, v91, v91
	s_waitcnt vmcnt(17)
;     __device__ __forceinline__ void operator()(const f32x4 (&acc)[2][2][4][2], const Unit& u, int wr, int wc, int fr, int fq) const {
;     ...
;         for (int ai = 0; ai < 2; ++ai)
; #pragma unroll
;             for (int m = 0; m < 4; ++m) {
;                 const int row = u.pm * BM + ai * HALF + wr * 64 + m * 16 + fr;
;                 const float* s = row < MX_ ? src_main + (size_t)row * D_ : src_ctx + (size_t)(row - MX_) * D_;
;                 float* d = row < MX_ ? dst_main + (size_t)row * D_ : dst_ctx + (size_t)(row - MX_) * D_;
; #pragma unroll
;                 for (int bj = 0; bj < 2; ++bj)
; #pragma unroll
;                     for (int n = 0; n < 2; ++n) { const int off = col0 + bj * HALF + n * 16; const f32x4 xo = *(const f32x4*)(s + off); *(f32x4*)(d + off) = xo + gv[bj][n] * acc[ai][bj][m][n]; }
	v_pk_fma_f32 v[84:85], v[84:85], v[216:217], v[188:189]
	v_pk_fma_f32 v[86:87], v[86:87], v[218:219], v[190:191]
	v_fmac_f32_e32 v234, v84, v84
	v_fmac_f32_e32 v234, v85, v85
	v_fmac_f32_e32 v234, v86, v86
	v_fmac_f32_e32 v234, v87, v87
	s_waitcnt vmcnt(16)
	v_pk_fma_f32 v[80:81], v[80:81], v[220:221], v[192:193]
	v_pk_fma_f32 v[82:83], v[82:83], v[222:223], v[194:195]
	v_fmac_f32_e32 v234, v80, v80
	v_fmac_f32_e32 v234, v81, v81
	v_fmac_f32_e32 v234, v82, v82
	v_fmac_f32_e32 v234, v83, v83
	global_store_dwordx4 v226, v[92:95], s[14:15]
	global_store_dwordx4 v226, v[88:91], s[14:15] offset:64
	global_store_dwordx4 v226, v[84:87], s[14:15] offset:512
	global_store_dwordx4 v226, v[80:83], s[14:15] offset:576
	global_load_dwordx4 v[180:183], v229, s[14:15]
	global_load_dwordx4 v[184:187], v229, s[14:15] offset:64
	global_load_dwordx4 v[188:191], v229, s[14:15] offset:512
	global_load_dwordx4 v[192:195], v229, s[14:15] offset:576
	s_waitcnt vmcnt(19)
	v_pk_fma_f32 v[76:77], v[76:77], v[196:197], v[140:141]
	v_pk_fma_f32 v[78:79], v[78:79], v[198:199], v[142:143]
	v_mul_f32_e32 v235, v76, v76
	v_fmac_f32_e32 v235, v77, v77
	v_fmac_f32_e32 v235, v78, v78
	v_fmac_f32_e32 v235, v79, v79
	s_waitcnt vmcnt(18)
	v_pk_fma_f32 v[72:73], v[72:73], v[212:213], v[144:145]
	v_pk_fma_f32 v[74:75], v[74:75], v[214:215], v[146:147]
	v_fmac_f32_e32 v235, v72, v72
	v_fmac_f32_e32 v235, v73, v73
	v_fmac_f32_e32 v235, v74, v74
	v_fmac_f32_e32 v235, v75, v75
	s_waitcnt vmcnt(17)
	v_pk_fma_f32 v[68:69], v[68:69], v[216:217], v[148:149]
	v_pk_fma_f32 v[70:71], v[70:71], v[218:219], v[150:151]
	v_fmac_f32_e32 v235, v68, v68
	v_fmac_f32_e32 v235, v69, v69
	v_fmac_f32_e32 v235, v70, v70
	v_fmac_f32_e32 v235, v71, v71
	s_waitcnt vmcnt(16)
	v_pk_fma_f32 v[64:65], v[64:65], v[220:221], v[152:153]
	v_pk_fma_f32 v[66:67], v[66:67], v[222:223], v[154:155]
	v_fmac_f32_e32 v235, v64, v64
	v_fmac_f32_e32 v235, v65, v65
	v_fmac_f32_e32 v235, v66, v66
	v_fmac_f32_e32 v235, v67, v67
	global_store_dwordx4 v227, v[76:79], s[14:15]
	global_store_dwordx4 v227, v[72:75], s[14:15] offset:64
	global_store_dwordx4 v227, v[68:71], s[14:15] offset:512
	global_store_dwordx4 v227, v[64:67], s[14:15] offset:576
	global_load_dwordx4 v[140:143], v230, s[14:15]
	global_load_dwordx4 v[144:147], v230, s[14:15] offset:64
	global_load_dwordx4 v[148:151], v230, s[14:15] offset:512
	global_load_dwordx4 v[152:155], v230, s[14:15] offset:576
	s_waitcnt vmcnt(19)
	v_pk_fma_f32 v[60:61], v[60:61], v[196:197], v[164:165]
	v_pk_fma_f32 v[62:63], v[62:63], v[198:199], v[166:167]
	v_mul_f32_e32 v236, v60, v60
	v_fmac_f32_e32 v236, v61, v61
	v_fmac_f32_e32 v236, v62, v62
	v_fmac_f32_e32 v236, v63, v63
	s_waitcnt vmcnt(18)
	v_pk_fma_f32 v[56:57], v[56:57], v[212:213], v[168:169]
	v_pk_fma_f32 v[58:59], v[58:59], v[214:215], v[170:171]
	v_fmac_f32_e32 v236, v56, v56
	v_fmac_f32_e32 v236, v57, v57
	v_fmac_f32_e32 v236, v58, v58
	v_fmac_f32_e32 v236, v59, v59
	s_waitcnt vmcnt(17)
	v_pk_fma_f32 v[52:53], v[52:53], v[216:217], v[172:173]
	v_pk_fma_f32 v[54:55], v[54:55], v[218:219], v[174:175]
	v_fmac_f32_e32 v236, v52, v52
	v_fmac_f32_e32 v236, v53, v53
	v_fmac_f32_e32 v236, v54, v54
	v_fmac_f32_e32 v236, v55, v55
	s_waitcnt vmcnt(16)
	v_pk_fma_f32 v[48:49], v[48:49], v[220:221], v[176:177]
	v_pk_fma_f32 v[50:51], v[50:51], v[222:223], v[178:179]
	v_fmac_f32_e32 v236, v48, v48
	v_fmac_f32_e32 v236, v49, v49
	v_fmac_f32_e32 v236, v50, v50
	v_fmac_f32_e32 v236, v51, v51
	global_store_dwordx4 v228, v[60:63], s[14:15]
	global_store_dwordx4 v228, v[56:59], s[14:15] offset:64
	global_store_dwordx4 v228, v[52:55], s[14:15] offset:512
	global_store_dwordx4 v228, v[48:51], s[14:15] offset:576
	global_load_dwordx4 v[164:167], v231, s[14:15]
	global_load_dwordx4 v[168:171], v231, s[14:15] offset:64
	global_load_dwordx4 v[172:175], v231, s[14:15] offset:512
	global_load_dwordx4 v[176:179], v231, s[14:15] offset:576
	s_waitcnt vmcnt(19)
	v_pk_fma_f32 v[44:45], v[44:45], v[196:197], v[180:181]
	v_pk_fma_f32 v[46:47], v[46:47], v[198:199], v[182:183]
	v_mul_f32_e32 v237, v44, v44
	v_fmac_f32_e32 v237, v45, v45
	v_fmac_f32_e32 v237, v46, v46
	v_fmac_f32_e32 v237, v47, v47
	s_waitcnt vmcnt(18)
	v_pk_fma_f32 v[40:41], v[40:41], v[212:213], v[184:185]
	v_pk_fma_f32 v[42:43], v[42:43], v[214:215], v[186:187]
	v_fmac_f32_e32 v237, v40, v40
	v_fmac_f32_e32 v237, v41, v41
	v_fmac_f32_e32 v237, v42, v42
	v_fmac_f32_e32 v237, v43, v43
	s_waitcnt vmcnt(17)
	v_pk_fma_f32 v[36:37], v[36:37], v[216:217], v[188:189]
	v_pk_fma_f32 v[38:39], v[38:39], v[218:219], v[190:191]
	v_fmac_f32_e32 v237, v36, v36
	v_fmac_f32_e32 v237, v37, v37
	v_fmac_f32_e32 v237, v38, v38
	v_fmac_f32_e32 v237, v39, v39
	s_waitcnt vmcnt(16)
	v_pk_fma_f32 v[32:33], v[32:33], v[220:221], v[192:193]
	v_pk_fma_f32 v[34:35], v[34:35], v[222:223], v[194:195]
	v_fmac_f32_e32 v237, v32, v32
	v_fmac_f32_e32 v237, v33, v33
	v_fmac_f32_e32 v237, v34, v34
	v_fmac_f32_e32 v237, v35, v35
	global_store_dwordx4 v229, v[44:47], s[14:15]
	global_store_dwordx4 v229, v[40:43], s[14:15] offset:64
	global_store_dwordx4 v229, v[36:39], s[14:15] offset:512
	global_store_dwordx4 v229, v[32:35], s[14:15] offset:576
	s_waitcnt vmcnt(15)
;     __device__ __forceinline__ void operator()(const f32x4 (&acc)[2][2][4][2], const Unit& u, int wr, int wc, int fr, int fq) const {
;     ...
;         for (int ai = 0; ai < 2; ++ai)
; #pragma unroll
;             for (int m = 0; m < 4; ++m) {
;                 const int row = u.pm * BM + ai * HALF + wr * 64 + m * 16 + fr;
;                 const float* s = row < MX_ ? src_main + (size_t)row * D_ : src_ctx + (size_t)(row - MX_) * D_;
;                 float* d = row < MX_ ? dst_main + (size_t)row * D_ : dst_ctx + (size_t)(row - MX_) * D_;
; #pragma unroll
;                 for (int bj = 0; bj < 2; ++bj)
; #pragma unroll
;                     for (int n = 0; n < 2; ++n) { const int off = col0 + bj * HALF + n * 16; const f32x4 xo = *(const f32x4*)(s + off); *(f32x4*)(d + off) = xo + gv[bj][n] * acc[ai][bj][m][n]; }
; __device__ __forceinline__ void modpass(const float* xs_main, const float* xs_ctx, const float* mod_l, const float* g, int i, bf16_t* H, int nrows, int gw, int NGW, int lane) {
;     ...
;         float ss = 0.f;
; #pragma unroll
;         for (int j = 0; j < 2; ++j)
; #pragma unroll
;             for (int q = 0; q < 2; ++q) ss += (v[j][q][0] * v[j][q][0] + v[j][q][1] * v[j][q][1]) + (v[j][q][2] * v[j][q][2] + v[j][q][3] * v[j][q][3]);
;         const float rstd = 1.0f / sqrtf(wave_sum(ss) * (1.0f / D) + EPS);
	v_pk_fma_f32 v[28:29], v[28:29], v[196:197], v[140:141]
	v_pk_fma_f32 v[30:31], v[30:31], v[198:199], v[142:143]
	v_mul_f32_e32 v238, v28, v28
	v_fmac_f32_e32 v238, v29, v29
	v_fmac_f32_e32 v238, v30, v30
	v_fmac_f32_e32 v238, v31, v31
	s_waitcnt vmcnt(14)
	v_pk_fma_f32 v[24:25], v[24:25], v[212:213], v[144:145]
	v_pk_fma_f32 v[26:27], v[26:27], v[214:215], v[146:147]
	v_fmac_f32_e32 v238, v24, v24
	v_fmac_f32_e32 v238, v25, v25
	v_fmac_f32_e32 v238, v26, v26
	v_fmac_f32_e32 v238, v27, v27
	s_waitcnt vmcnt(13)
	v_pk_fma_f32 v[20:21], v[20:21], v[216:217], v[148:149]
	v_pk_fma_f32 v[22:23], v[22:23], v[218:219], v[150:151]
	v_fmac_f32_e32 v238, v20, v20
	v_fmac_f32_e32 v238, v21, v21
	v_fmac_f32_e32 v238, v22, v22
	v_fmac_f32_e32 v238, v23, v23
	s_waitcnt vmcnt(12)
	v_pk_fma_f32 v[16:17], v[16:17], v[220:221], v[152:153]
	v_pk_fma_f32 v[18:19], v[18:19], v[222:223], v[154:155]
	v_fmac_f32_e32 v238, v16, v16
	v_fmac_f32_e32 v238, v17, v17
	v_fmac_f32_e32 v238, v18, v18
	v_fmac_f32_e32 v238, v19, v19
	global_store_dwordx4 v230, v[28:31], s[14:15]
	global_store_dwordx4 v230, v[24:27], s[14:15] offset:64
	global_store_dwordx4 v230, v[20:23], s[14:15] offset:512
	global_store_dwordx4 v230, v[16:19], s[14:15] offset:576
	s_waitcnt vmcnt(11)
	v_pk_fma_f32 v[12:13], v[12:13], v[196:197], v[164:165]
	v_pk_fma_f32 v[14:15], v[14:15], v[198:199], v[166:167]
	v_mul_f32_e32 v239, v12, v12
	v_fmac_f32_e32 v239, v13, v13
	v_fmac_f32_e32 v239, v14, v14
	v_fmac_f32_e32 v239, v15, v15
	s_waitcnt vmcnt(10)
	v_pk_fma_f32 v[8:9], v[8:9], v[212:213], v[168:169]
	v_pk_fma_f32 v[10:11], v[10:11], v[214:215], v[170:171]
	v_fmac_f32_e32 v239, v8, v8
	v_fmac_f32_e32 v239, v9, v9
	v_fmac_f32_e32 v239, v10, v10
	v_fmac_f32_e32 v239, v11, v11
	s_waitcnt vmcnt(9)
	v_pk_fma_f32 v[4:5], v[4:5], v[216:217], v[172:173]
	v_pk_fma_f32 v[6:7], v[6:7], v[218:219], v[174:175]
	v_fmac_f32_e32 v239, v4, v4
	v_fmac_f32_e32 v239, v5, v5
	v_fmac_f32_e32 v239, v6, v6
	v_fmac_f32_e32 v239, v7, v7
	s_waitcnt vmcnt(8)
	v_pk_fma_f32 v[0:1], v[0:1], v[220:221], v[176:177]
	v_pk_fma_f32 v[2:3], v[2:3], v[222:223], v[178:179]
	v_fmac_f32_e32 v239, v0, v0
	v_fmac_f32_e32 v239, v1, v1
	v_fmac_f32_e32 v239, v2, v2
	v_fmac_f32_e32 v239, v3, v3
	global_store_dwordx4 v231, v[12:15], s[14:15]
	global_store_dwordx4 v231, v[8:11], s[14:15] offset:64
	global_store_dwordx4 v231, v[4:7], s[14:15] offset:512
	global_store_dwordx4 v231, v[0:3], s[14:15] offset:576
	v_mbcnt_lo_u32_b32 v240, -1, 0
	v_mbcnt_hi_u32_b32 v240, -1, v240
	v_xor_b32_e32 v241, 16, v240
	v_xor_b32_e32 v242, 32, v240
	v_lshlrev_b32_e32 v241, 2, v241
	v_lshlrev_b32_e32 v242, 2, v242
	s_waitcnt lgkmcnt(0)
	ds_bpermute_b32 v140, v241, v232
	ds_bpermute_b32 v141, v241, v233
	ds_bpermute_b32 v142, v241, v234
	ds_bpermute_b32 v143, v241, v235
	ds_bpermute_b32 v144, v241, v236
	ds_bpermute_b32 v145, v241, v237
	ds_bpermute_b32 v146, v241, v238
	ds_bpermute_b32 v147, v241, v239
	s_waitcnt lgkmcnt(7)
	v_add_f32_e32 v232, v232, v140
	s_waitcnt lgkmcnt(6)
	v_add_f32_e32 v233, v233, v141
	s_waitcnt lgkmcnt(5)
	v_add_f32_e32 v234, v234, v142
	s_waitcnt lgkmcnt(4)
	v_add_f32_e32 v235, v235, v143
	s_waitcnt lgkmcnt(3)
	v_add_f32_e32 v236, v236, v144
	s_waitcnt lgkmcnt(2)
	v_add_f32_e32 v237, v237, v145
	s_waitcnt lgkmcnt(1)
	v_add_f32_e32 v238, v238, v146
	s_waitcnt lgkmcnt(0)
	v_add_f32_e32 v239, v239, v147
	ds_bpermute_b32 v140, v242, v232
	ds_bpermute_b32 v141, v242, v233
	ds_bpermute_b32 v142, v242, v234
	ds_bpermute_b32 v143, v242, v235
	ds_bpermute_b32 v144, v242, v236
	ds_bpermute_b32 v145, v242, v237
	ds_bpermute_b32 v146, v242, v238
	ds_bpermute_b32 v147, v242, v239
	s_waitcnt lgkmcnt(7)
	v_add_f32_e32 v232, v232, v140
	s_waitcnt lgkmcnt(6)
	v_add_f32_e32 v233, v233, v141
	s_waitcnt lgkmcnt(5)
	v_add_f32_e32 v234, v234, v142
	s_waitcnt lgkmcnt(4)
	v_add_f32_e32 v235, v235, v143
	s_waitcnt lgkmcnt(3)
	v_add_f32_e32 v236, v236, v144
	s_waitcnt lgkmcnt(2)
	v_add_f32_e32 v237, v237, v145
	s_waitcnt lgkmcnt(1)
	v_add_f32_e32 v238, v238, v146
	s_waitcnt lgkmcnt(0)
	v_add_f32_e32 v239, v239, v147
	v_lshlrev_b32_e32 v243, 2, v156
	s_add_u32 s90, s76, 0x6500000
	s_addc_u32 s91, s77, 0
	s_add_u32 s76, s76, 0x3186000
	s_addc_u32 s77, s77, 0
	s_lshl_b32 s83, s6, 6
	s_add_u32 s78, s76, s83
	s_addc_u32 s79, s77, 0
	s_add_u32 s78, s78, 0x20000
	s_addc_u32 s79, s79, 0
	s_mov_b64 s[80:81], exec
	s_mov_b64 exec, 0xffff
	global_atomic_add_f32 v243, v232, s[76:77]
	global_atomic_add_f32 v243, v233, s[76:77] offset:64
	global_atomic_add_f32 v243, v234, s[76:77] offset:128
	global_atomic_add_f32 v243, v235, s[76:77] offset:192
	global_atomic_add_f32 v243, v236, s[76:77] offset:512
	global_atomic_add_f32 v243, v237, s[76:77] offset:576
	global_atomic_add_f32 v243, v238, s[76:77] offset:640
	global_atomic_add_f32 v243, v239, s[76:77] offset:704
	s_mov_b64 exec, s[80:81]
	s_add_u32 s86, s8, 0x1000
	s_addc_u32 s87, s9, 0
	s_add_u32 s88, s86, 0x1000
	s_addc_u32 s89, s87, 0
	s_add_u32 s92, s92, 0x4000
	s_addc_u32 s93, s93, 0
	s_mov_b32 s84, 0xffff0000
	s_mov_b32 s85, 0xffff0000
	s_waitcnt vmcnt(0)
	s_barrier
	v_readfirstlane_b32 s83, v206
	v_mov_b32_e32 v244, 0
	v_mov_b32_e32 v245, 1
	s_cmp_lg_u32 s83, 0
	s_cbranch_scc1 .Lfme_wait_done
	s_mov_b64 exec, 1
	global_atomic_add v244, v245, s[78:79]
	s_mov_b32 s82, 0

; __device__ __forceinline__ unsigned cvtpk_s(float lo, float hi) { f32x2_t v = {lo, hi}; bf16x2_t b = __builtin_convertvector(v, bf16x2_t); return __builtin_bit_cast(unsigned, b); }
; __device__ __forceinline__ void modpass(const float* xs_main, const float* xs_ctx, const float* mod_l, const float* g, int i, bf16_t* H, int nrows, int gw, int NGW, int lane) {
;     ...
;         if (cond != cur) { cur = cond; const float* shift = mod_l + cond * 9216 + 3 * i * 1024; const float* scale = shift + 1024;
; #pragma unroll
;             for (int j = 0; j < 2; ++j)
; #pragma unroll
;                 for (int q = 0; q < 2; ++q) { const int c = 8 * lane + 512 * j + 4 * q; gm[j][q] = *(const f32x4*)(g + c) * (*(const f32x4*)(scale + c) + 1.0f); sh[j][q] = *(const f32x4*)(shift + c); } }
;         float ss = 0.f;
; #pragma unroll
;         for (int j = 0; j < 2; ++j)
; #pragma unroll
;             for (int q = 0; q < 2; ++q) ss += (v[j][q][0] * v[j][q][0] + v[j][q][1] * v[j][q][1]) + (v[j][q][2] * v[j][q][2] + v[j][q][3] * v[j][q][3]);
;         const float rstd = 1.0f / sqrtf(wave_sum(ss) * (1.0f / D) + EPS);
; #pragma unroll
;         for (int j = 0; j < 2; ++j) {
;             const f32x4 o0 = v[j][0] * rstd * gm[j][0] + sh[j][0], o1 = v[j][1] * rstd * gm[j][1] + sh[j][1];
;             u32x4 w; w.x = cvtpk_s(o0[0], o0[1]); w.y = cvtpk_s(o0[2], o0[3]); w.z = cvtpk_s(o1[0], o1[1]); w.w = cvtpk_s(o1[2], o1[3]);
;             *(u32x4*)(H + (size_t)row * D + 8 * lane + 512 * j) = w;
.Lfme_wait_done:
	s_barrier
	global_load_dword v144, v243, s[76:77] sc1
	global_load_dword v145, v243, s[76:77] offset:64 sc1
	global_load_dword v146, v243, s[76:77] offset:128 sc1
	global_load_dword v147, v243, s[76:77] offset:192 sc1
	global_load_dword v148, v243, s[76:77] offset:512 sc1
	global_load_dword v149, v243, s[76:77] offset:576 sc1
	global_load_dword v150, v243, s[76:77] offset:640 sc1
	global_load_dword v151, v243, s[76:77] offset:704 sc1
	global_load_dwordx4 v[196:199], v201, s[86:87]
	global_load_dwordx4 v[212:215], v201, s[86:87] offset:64
	global_load_dwordx4 v[216:219], v201, s[86:87] offset:512
	global_load_dwordx4 v[220:223], v201, s[86:87] offset:576
	global_load_dwordx4 v[152:155], v201, s[88:89]
	global_load_dwordx4 v[164:167], v201, s[88:89] offset:64
	global_load_dwordx4 v[168:171], v201, s[88:89] offset:512
	global_load_dwordx4 v[172:175], v201, s[88:89] offset:576
	global_load_dwordx4 v[176:179], v201, s[92:93]
	global_load_dwordx4 v[180:183], v201, s[92:93] offset:64
	global_load_dwordx4 v[184:187], v201, s[92:93] offset:512
	global_load_dwordx4 v[188:191], v201, s[92:93] offset:576
	v_mov_b32_e32 v240, 12
	v_cndmask_b32_e64 v240, 0, v240, s[84:85]
	v_add_u32_e32 v240, v240, v157
	v_lshlrev_b32_e32 v240, 1, v240
	v_lshl_add_u32 v247, v156, 11, v240
	v_mov_b32_e32 v240, 0x358637bd
	s_waitcnt vmcnt(0)
	v_fmamk_f32 v144, v144, 0x3a800000, v240
	v_fmamk_f32 v145, v145, 0x3a800000, v240
	v_fmamk_f32 v146, v146, 0x3a800000, v240
	v_fmamk_f32 v147, v147, 0x3a800000, v240
	v_fmamk_f32 v148, v148, 0x3a800000, v240
	v_fmamk_f32 v149, v149, 0x3a800000, v240
	v_fmamk_f32 v150, v150, 0x3a800000, v240
	v_fmamk_f32 v151, v151, 0x3a800000, v240
	v_rsq_f32_e32 v144, v144
	v_rsq_f32_e32 v145, v145
	v_rsq_f32_e32 v146, v146
	v_rsq_f32_e32 v147, v147
	v_rsq_f32_e32 v148, v148
	v_rsq_f32_e32 v149, v149
	v_rsq_f32_e32 v150, v150
	v_rsq_f32_e32 v151, v151
	v_pk_add_f32 v[152:153], v[152:153], 1.0 op_sel_hi:[1,0]
	v_pk_mul_f32 v[152:153], v[176:177], v[152:153]
	v_pk_add_f32 v[154:155], v[154:155], 1.0 op_sel_hi:[1,0]
	v_pk_mul_f32 v[154:155], v[178:179], v[154:155]
	v_pk_add_f32 v[164:165], v[164:165], 1.0 op_sel_hi:[1,0]
	v_pk_mul_f32 v[164:165], v[180:181], v[164:165]
	v_pk_add_f32 v[166:167], v[166:167], 1.0 op_sel_hi:[1,0]
	v_pk_mul_f32 v[166:167], v[182:183], v[166:167]
	v_pk_add_f32 v[168:169], v[168:169], 1.0 op_sel_hi:[1,0]
	v_pk_mul_f32 v[168:169], v[184:185], v[168:169]
	v_pk_add_f32 v[170:171], v[170:171], 1.0 op_sel_hi:[1,0]
	v_pk_mul_f32 v[170:171], v[186:187], v[170:171]
	v_pk_add_f32 v[172:173], v[172:173], 1.0 op_sel_hi:[1,0]
	v_pk_mul_f32 v[172:173], v[188:189], v[172:173]
	v_pk_add_f32 v[174:175], v[174:175], 1.0 op_sel_hi:[1,0]
	v_pk_mul_f32 v[174:175], v[190:191], v[174:175]
	v_mul_f32_e32 v124, v124, v144
	v_mul_f32_e32 v125, v125, v144
	v_pk_fma_f32 v[124:125], v[152:153], v[124:125], v[196:197]
	v_mul_f32_e32 v126, v126, v144
	v_mul_f32_e32 v127, v127, v144
	v_pk_fma_f32 v[126:127], v[154:155], v[126:127], v[198:199]
	v_cvt_pk_bf16_f32 v184, v124, v125
	v_cvt_pk_bf16_f32 v185, v126, v127
	v_mul_f32_e32 v120, v120, v144
	v_mul_f32_e32 v121, v121, v144
	v_pk_fma_f32 v[120:121], v[164:165], v[120:121], v[212:213]
	v_mul_f32_e32 v122, v122, v144
	v_mul_f32_e32 v123, v123, v144
	v_pk_fma_f32 v[122:123], v[166:167], v[122:123], v[214:215]
	v_cvt_pk_bf16_f32 v186, v120, v121
	v_cvt_pk_bf16_f32 v187, v122, v123
	v_mul_f32_e32 v116, v116, v144
	v_mul_f32_e32 v117, v117, v144
	v_pk_fma_f32 v[116:117], v[168:169], v[116:117], v[216:217]
	v_mul_f32_e32 v118, v118, v144
	v_mul_f32_e32 v119, v119, v144
	v_pk_fma_f32 v[118:119], v[170:171], v[118:119], v[218:219]
	v_cvt_pk_bf16_f32 v188, v116, v117
	v_cvt_pk_bf16_f32 v189, v118, v119
	v_mul_f32_e32 v112, v112, v144
	v_mul_f32_e32 v113, v113, v144
	v_pk_fma_f32 v[112:113], v[172:173], v[112:113], v[220:221]
	v_mul_f32_e32 v114, v114, v144
	v_mul_f32_e32 v115, v115, v144
	v_pk_fma_f32 v[114:115], v[174:175], v[114:115], v[222:223]
	v_cvt_pk_bf16_f32 v190, v112, v113
	v_cvt_pk_bf16_f32 v191, v114, v115
	v_mov_b32_e32 v240, v247
	v_cndmask_b32_e64 v192, v186, v184, s[84:85]
	v_cndmask_b32_e64 v193, v187, v185, s[84:85]
	ds_bpermute_b32 v194, v241, v192
	ds_bpermute_b32 v195, v241, v193
	s_waitcnt lgkmcnt(0)
	v_cndmask_b32_e64 v176, v184, v194, s[84:85]
	v_cndmask_b32_e64 v177, v185, v195, s[84:85]
	v_cndmask_b32_e64 v178, v194, v186, s[84:85]
	v_cndmask_b32_e64 v179, v195, v187, s[84:85]
	global_store_dwordx4 v240, v[176:179], s[90:91]
	v_cndmask_b32_e64 v192, v190, v188, s[84:85]
	v_cndmask_b32_e64 v193, v191, v189, s[84:85]
	ds_bpermute_b32 v194, v241, v192
	ds_bpermute_b32 v195, v241, v193
	s_waitcnt lgkmcnt(0)
	v_cndmask_b32_e64 v180, v188, v194, s[84:85]
	v_cndmask_b32_e64 v181, v189, v195, s[84:85]
	v_cndmask_b32_e64 v182, v194, v190, s[84:85]
	v_cndmask_b32_e64 v183, v195, v191, s[84:85]
	global_store_dwordx4 v240, v[180:183], s[90:91] offset:256
	v_mul_f32_e32 v108, v108, v145
	v_mul_f32_e32 v109, v109, v145
	v_pk_fma_f32 v[108:109], v[152:153], v[108:109], v[196:197]
	v_mul_f32_e32 v110, v110, v145
	v_mul_f32_e32 v111, v111, v145
	v_pk_fma_f32 v[110:111], v[154:155], v[110:111], v[198:199]
	v_cvt_pk_bf16_f32 v184, v108, v109
	v_cvt_pk_bf16_f32 v185, v110, v111
	v_mul_f32_e32 v104, v104, v145
	v_mul_f32_e32 v105, v105, v145
	v_pk_fma_f32 v[104:105], v[164:165], v[104:105], v[212:213]
	v_mul_f32_e32 v106, v106, v145
	v_mul_f32_e32 v107, v107, v145
	v_pk_fma_f32 v[106:107], v[166:167], v[106:107], v[214:215]
	v_cvt_pk_bf16_f32 v186, v104, v105
	v_cvt_pk_bf16_f32 v187, v106, v107
	v_mul_f32_e32 v100, v100, v145
	v_mul_f32_e32 v101, v101, v145
	v_pk_fma_f32 v[100:101], v[168:169], v[100:101], v[216:217]
	v_mul_f32_e32 v102, v102, v145
	v_mul_f32_e32 v103, v103, v145
	v_pk_fma_f32 v[102:103], v[170:171], v[102:103], v[218:219]
	v_cvt_pk_bf16_f32 v188, v100, v101
	v_cvt_pk_bf16_f32 v189, v102, v103
	v_mul_f32_e32 v96, v96, v145
	v_mul_f32_e32 v97, v97, v145
	v_pk_fma_f32 v[96:97], v[172:173], v[96:97], v[220:221]
	v_mul_f32_e32 v98, v98, v145
	v_mul_f32_e32 v99, v99, v145
	v_pk_fma_f32 v[98:99], v[174:175], v[98:99], v[222:223]
	v_cvt_pk_bf16_f32 v190, v96, v97
	v_cvt_pk_bf16_f32 v191, v98, v99
	v_add_u32_e32 v240, 0x8000, v247
	v_cndmask_b32_e64 v192, v186, v184, s[84:85]
	v_cndmask_b32_e64 v193, v187, v185, s[84:85]
	ds_bpermute_b32 v194, v241, v192
	ds_bpermute_b32 v195, v241, v193
	s_waitcnt lgkmcnt(0)
; __device__ __forceinline__ unsigned cvtpk_s(float lo, float hi) { f32x2_t v = {lo, hi}; bf16x2_t b = __builtin_convertvector(v, bf16x2_t); return __builtin_bit_cast(unsigned, b); }
; __device__ __forceinline__ u32x4 quad_swap(unsigned lo0, unsigned lo1, unsigned hi0, unsigned hi1, int fq, int& coloff) {
;     const bool odd = fq & 1;
;     const unsigned s0 = odd ? lo0 : hi0, s1 = odd ? lo1 : hi1;
;     const unsigned r0 = (unsigned)__shfl_xor((int)s0, 16), r1 = (unsigned)__shfl_xor((int)s1, 16);
;     coloff = odd ? 16 + 4 * (fq - 1) : 4 * fq;
;     u32x4 o; o.x = odd ? r0 : lo0; o.y = odd ? r1 : lo1; o.z = odd ? hi0 : r0; o.w = odd ? hi1 : r1; return o;
; __device__ __forceinline__ void modpass(const float* xs_main, const float* xs_ctx, const float* mod_l, const float* g, int i, bf16_t* H, int nrows, int gw, int NGW, int lane) {
;     ...
; #pragma unroll
;         for (int j = 0; j < 2; ++j) {
;             const f32x4 o0 = v[j][0] * rstd * gm[j][0] + sh[j][0], o1 = v[j][1] * rstd * gm[j][1] + sh[j][1];
;             u32x4 w; w.x = cvtpk_s(o0[0], o0[1]); w.y = cvtpk_s(o0[2], o0[3]); w.z = cvtpk_s(o1[0], o1[1]); w.w = cvtpk_s(o1[2], o1[3]);
;             *(u32x4*)(H + (size_t)row * D + 8 * lane + 512 * j) = w;
	v_cndmask_b32_e64 v176, v184, v194, s[84:85]
	v_cndmask_b32_e64 v177, v185, v195, s[84:85]
	v_cndmask_b32_e64 v178, v194, v186, s[84:85]
	v_cndmask_b32_e64 v179, v195, v187, s[84:85]
	global_store_dwordx4 v240, v[176:179], s[90:91]
	v_cndmask_b32_e64 v192, v190, v188, s[84:85]
	v_cndmask_b32_e64 v193, v191, v189, s[84:85]
	ds_bpermute_b32 v194, v241, v192
	ds_bpermute_b32 v195, v241, v193
	s_waitcnt lgkmcnt(0)
	v_cndmask_b32_e64 v180, v188, v194, s[84:85]
	v_cndmask_b32_e64 v181, v189, v195, s[84:85]
	v_cndmask_b32_e64 v182, v194, v190, s[84:85]
	v_cndmask_b32_e64 v183, v195, v191, s[84:85]
	global_store_dwordx4 v240, v[180:183], s[90:91] offset:256
	v_mul_f32_e32 v92, v92, v146
	v_mul_f32_e32 v93, v93, v146
	v_pk_fma_f32 v[92:93], v[152:153], v[92:93], v[196:197]
	v_mul_f32_e32 v94, v94, v146
	v_mul_f32_e32 v95, v95, v146
	v_pk_fma_f32 v[94:95], v[154:155], v[94:95], v[198:199]
	v_cvt_pk_bf16_f32 v184, v92, v93
	v_cvt_pk_bf16_f32 v185, v94, v95
	v_mul_f32_e32 v88, v88, v146
	v_mul_f32_e32 v89, v89, v146
	v_pk_fma_f32 v[88:89], v[164:165], v[88:89], v[212:213]
	v_mul_f32_e32 v90, v90, v146
	v_mul_f32_e32 v91, v91, v146
	v_pk_fma_f32 v[90:91], v[166:167], v[90:91], v[214:215]
	v_cvt_pk_bf16_f32 v186, v88, v89
	v_cvt_pk_bf16_f32 v187, v90, v91
	v_mul_f32_e32 v84, v84, v146
	v_mul_f32_e32 v85, v85, v146
	v_pk_fma_f32 v[84:85], v[168:169], v[84:85], v[216:217]
	v_mul_f32_e32 v86, v86, v146
	v_mul_f32_e32 v87, v87, v146
	v_pk_fma_f32 v[86:87], v[170:171], v[86:87], v[218:219]
	v_cvt_pk_bf16_f32 v188, v84, v85
	v_cvt_pk_bf16_f32 v189, v86, v87
	v_mul_f32_e32 v80, v80, v146
	v_mul_f32_e32 v81, v81, v146
	v_pk_fma_f32 v[80:81], v[172:173], v[80:81], v[220:221]
	v_mul_f32_e32 v82, v82, v146
	v_mul_f32_e32 v83, v83, v146
	v_pk_fma_f32 v[82:83], v[174:175], v[82:83], v[222:223]
	v_cvt_pk_bf16_f32 v190, v80, v81
	v_cvt_pk_bf16_f32 v191, v82, v83
	v_add_u32_e32 v240, 0x10000, v247
	v_cndmask_b32_e64 v192, v186, v184, s[84:85]
	v_cndmask_b32_e64 v193, v187, v185, s[84:85]
	ds_bpermute_b32 v194, v241, v192
	ds_bpermute_b32 v195, v241, v193
	s_waitcnt lgkmcnt(0)
	v_cndmask_b32_e64 v176, v184, v194, s[84:85]
	v_cndmask_b32_e64 v177, v185, v195, s[84:85]
	v_cndmask_b32_e64 v178, v194, v186, s[84:85]
	v_cndmask_b32_e64 v179, v195, v187, s[84:85]
	global_store_dwordx4 v240, v[176:179], s[90:91]
	v_cndmask_b32_e64 v192, v190, v188, s[84:85]
	v_cndmask_b32_e64 v193, v191, v189, s[84:85]
	ds_bpermute_b32 v194, v241, v192
	ds_bpermute_b32 v195, v241, v193
	s_waitcnt lgkmcnt(0)
	v_cndmask_b32_e64 v180, v188, v194, s[84:85]
	v_cndmask_b32_e64 v181, v189, v195, s[84:85]
	v_cndmask_b32_e64 v182, v194, v190, s[84:85]
	v_cndmask_b32_e64 v183, v195, v191, s[84:85]
	global_store_dwordx4 v240, v[180:183], s[90:91] offset:256
	v_mul_f32_e32 v76, v76, v147
	v_mul_f32_e32 v77, v77, v147
	v_pk_fma_f32 v[76:77], v[152:153], v[76:77], v[196:197]
	v_mul_f32_e32 v78, v78, v147
	v_mul_f32_e32 v79, v79, v147
	v_pk_fma_f32 v[78:79], v[154:155], v[78:79], v[198:199]
	v_cvt_pk_bf16_f32 v184, v76, v77
	v_cvt_pk_bf16_f32 v185, v78, v79
	v_mul_f32_e32 v72, v72, v147
	v_mul_f32_e32 v73, v73, v147
	v_pk_fma_f32 v[72:73], v[164:165], v[72:73], v[212:213]
	v_mul_f32_e32 v74, v74, v147
	v_mul_f32_e32 v75, v75, v147
	v_pk_fma_f32 v[74:75], v[166:167], v[74:75], v[214:215]
	v_cvt_pk_bf16_f32 v186, v72, v73
	v_cvt_pk_bf16_f32 v187, v74, v75
	v_mul_f32_e32 v68, v68, v147
	v_mul_f32_e32 v69, v69, v147
	v_pk_fma_f32 v[68:69], v[168:169], v[68:69], v[216:217]
	v_mul_f32_e32 v70, v70, v147
	v_mul_f32_e32 v71, v71, v147
	v_pk_fma_f32 v[70:71], v[170:171], v[70:71], v[218:219]
	v_cvt_pk_bf16_f32 v188, v68, v69
	v_cvt_pk_bf16_f32 v189, v70, v71
	v_mul_f32_e32 v64, v64, v147
	v_mul_f32_e32 v65, v65, v147
	v_pk_fma_f32 v[64:65], v[172:173], v[64:65], v[220:221]
	v_mul_f32_e32 v66, v66, v147
	v_mul_f32_e32 v67, v67, v147
	v_pk_fma_f32 v[66:67], v[174:175], v[66:67], v[222:223]
	v_cvt_pk_bf16_f32 v190, v64, v65
	v_cvt_pk_bf16_f32 v191, v66, v67
	v_add_u32_e32 v240, 0x18000, v247
	v_cndmask_b32_e64 v192, v186, v184, s[84:85]
	v_cndmask_b32_e64 v193, v187, v185, s[84:85]
	ds_bpermute_b32 v194, v241, v192
	ds_bpermute_b32 v195, v241, v193
	s_waitcnt lgkmcnt(0)
	v_cndmask_b32_e64 v176, v184, v194, s[84:85]
	v_cndmask_b32_e64 v177, v185, v195, s[84:85]
	v_cndmask_b32_e64 v178, v194, v186, s[84:85]
	v_cndmask_b32_e64 v179, v195, v187, s[84:85]
	global_store_dwordx4 v240, v[176:179], s[90:91]
	v_cndmask_b32_e64 v192, v190, v188, s[84:85]
	v_cndmask_b32_e64 v193, v191, v189, s[84:85]
	ds_bpermute_b32 v194, v241, v192
	ds_bpermute_b32 v195, v241, v193
	s_waitcnt lgkmcnt(0)
	v_cndmask_b32_e64 v180, v188, v194, s[84:85]
	v_cndmask_b32_e64 v181, v189, v195, s[84:85]
	v_cndmask_b32_e64 v182, v194, v190, s[84:85]
	v_cndmask_b32_e64 v183, v195, v191, s[84:85]
	global_store_dwordx4 v240, v[180:183], s[90:91] offset:256
	v_mul_f32_e32 v60, v60, v148
	v_mul_f32_e32 v61, v61, v148
	v_pk_fma_f32 v[60:61], v[152:153], v[60:61], v[196:197]
	v_mul_f32_e32 v62, v62, v148
	v_mul_f32_e32 v63, v63, v148
	v_pk_fma_f32 v[62:63], v[154:155], v[62:63], v[198:199]
	v_cvt_pk_bf16_f32 v184, v60, v61
	v_cvt_pk_bf16_f32 v185, v62, v63
	v_mul_f32_e32 v56, v56, v148
	v_mul_f32_e32 v57, v57, v148
	v_pk_fma_f32 v[56:57], v[164:165], v[56:57], v[212:213]
	v_mul_f32_e32 v58, v58, v148
	v_mul_f32_e32 v59, v59, v148
	v_pk_fma_f32 v[58:59], v[166:167], v[58:59], v[214:215]
	v_cvt_pk_bf16_f32 v186, v56, v57
	v_cvt_pk_bf16_f32 v187, v58, v59
	v_mul_f32_e32 v52, v52, v148
	v_mul_f32_e32 v53, v53, v148
	v_pk_fma_f32 v[52:53], v[168:169], v[52:53], v[216:217]
	v_mul_f32_e32 v54, v54, v148
	v_mul_f32_e32 v55, v55, v148
	v_pk_fma_f32 v[54:55], v[170:171], v[54:55], v[218:219]
	v_cvt_pk_bf16_f32 v188, v52, v53
	v_cvt_pk_bf16_f32 v189, v54, v55
	v_mul_f32_e32 v48, v48, v148
	v_mul_f32_e32 v49, v49, v148
	v_pk_fma_f32 v[48:49], v[172:173], v[48:49], v[220:221]
	v_mul_f32_e32 v50, v50, v148
	v_mul_f32_e32 v51, v51, v148
	v_pk_fma_f32 v[50:51], v[174:175], v[50:51], v[222:223]
	v_cvt_pk_bf16_f32 v190, v48, v49
	v_cvt_pk_bf16_f32 v191, v50, v51
	v_add_u32_e32 v240, 0x40000, v247
	v_cndmask_b32_e64 v192, v186, v184, s[84:85]
	v_cndmask_b32_e64 v193, v187, v185, s[84:85]
	ds_bpermute_b32 v194, v241, v192
	ds_bpermute_b32 v195, v241, v193
	s_waitcnt lgkmcnt(0)
; __device__ __forceinline__ unsigned cvtpk_s(float lo, float hi) { f32x2_t v = {lo, hi}; bf16x2_t b = __builtin_convertvector(v, bf16x2_t); return __builtin_bit_cast(unsigned, b); }
; __device__ __forceinline__ u32x4 quad_swap(unsigned lo0, unsigned lo1, unsigned hi0, unsigned hi1, int fq, int& coloff) {
;     const bool odd = fq & 1;
;     const unsigned s0 = odd ? lo0 : hi0, s1 = odd ? lo1 : hi1;
;     const unsigned r0 = (unsigned)__shfl_xor((int)s0, 16), r1 = (unsigned)__shfl_xor((int)s1, 16);
;     coloff = odd ? 16 + 4 * (fq - 1) : 4 * fq;
;     u32x4 o; o.x = odd ? r0 : lo0; o.y = odd ? r1 : lo1; o.z = odd ? hi0 : r0; o.w = odd ? hi1 : r1; return o;
; __device__ __forceinline__ void modpass(const float* xs_main, const float* xs_ctx, const float* mod_l, const float* g, int i, bf16_t* H, int nrows, int gw, int NGW, int lane) {
;     ...
; #pragma unroll
;         for (int j = 0; j < 2; ++j) {
;             const f32x4 o0 = v[j][0] * rstd * gm[j][0] + sh[j][0], o1 = v[j][1] * rstd * gm[j][1] + sh[j][1];
;             u32x4 w; w.x = cvtpk_s(o0[0], o0[1]); w.y = cvtpk_s(o0[2], o0[3]); w.z = cvtpk_s(o1[0], o1[1]); w.w = cvtpk_s(o1[2], o1[3]);
;             *(u32x4*)(H + (size_t)row * D + 8 * lane + 512 * j) = w;
	v_cndmask_b32_e64 v176, v184, v194, s[84:85]
	v_cndmask_b32_e64 v177, v185, v195, s[84:85]
	v_cndmask_b32_e64 v178, v194, v186, s[84:85]
	v_cndmask_b32_e64 v179, v195, v187, s[84:85]
	global_store_dwordx4 v240, v[176:179], s[90:91]
	v_cndmask_b32_e64 v192, v190, v188, s[84:85]
	v_cndmask_b32_e64 v193, v191, v189, s[84:85]
	ds_bpermute_b32 v194, v241, v192
	ds_bpermute_b32 v195, v241, v193
	s_waitcnt lgkmcnt(0)
	v_cndmask_b32_e64 v180, v188, v194, s[84:85]
	v_cndmask_b32_e64 v181, v189, v195, s[84:85]
	v_cndmask_b32_e64 v182, v194, v190, s[84:85]
	v_cndmask_b32_e64 v183, v195, v191, s[84:85]
	global_store_dwordx4 v240, v[180:183], s[90:91] offset:256
	v_mul_f32_e32 v44, v44, v149
	v_mul_f32_e32 v45, v45, v149
	v_pk_fma_f32 v[44:45], v[152:153], v[44:45], v[196:197]
	v_mul_f32_e32 v46, v46, v149
	v_mul_f32_e32 v47, v47, v149
	v_pk_fma_f32 v[46:47], v[154:155], v[46:47], v[198:199]
	v_cvt_pk_bf16_f32 v184, v44, v45
	v_cvt_pk_bf16_f32 v185, v46, v47
	v_mul_f32_e32 v40, v40, v149
	v_mul_f32_e32 v41, v41, v149
	v_pk_fma_f32 v[40:41], v[164:165], v[40:41], v[212:213]
	v_mul_f32_e32 v42, v42, v149
	v_mul_f32_e32 v43, v43, v149
	v_pk_fma_f32 v[42:43], v[166:167], v[42:43], v[214:215]
	v_cvt_pk_bf16_f32 v186, v40, v41
	v_cvt_pk_bf16_f32 v187, v42, v43
	v_mul_f32_e32 v36, v36, v149
	v_mul_f32_e32 v37, v37, v149
	v_pk_fma_f32 v[36:37], v[168:169], v[36:37], v[216:217]
	v_mul_f32_e32 v38, v38, v149
	v_mul_f32_e32 v39, v39, v149
	v_pk_fma_f32 v[38:39], v[170:171], v[38:39], v[218:219]
	v_cvt_pk_bf16_f32 v188, v36, v37
	v_cvt_pk_bf16_f32 v189, v38, v39
	v_mul_f32_e32 v32, v32, v149
	v_mul_f32_e32 v33, v33, v149
	v_pk_fma_f32 v[32:33], v[172:173], v[32:33], v[220:221]
	v_mul_f32_e32 v34, v34, v149
	v_mul_f32_e32 v35, v35, v149
	v_pk_fma_f32 v[34:35], v[174:175], v[34:35], v[222:223]
	v_cvt_pk_bf16_f32 v190, v32, v33
	v_cvt_pk_bf16_f32 v191, v34, v35
	v_add_u32_e32 v240, 0x48000, v247
	v_cndmask_b32_e64 v192, v186, v184, s[84:85]
	v_cndmask_b32_e64 v193, v187, v185, s[84:85]
	ds_bpermute_b32 v194, v241, v192
	ds_bpermute_b32 v195, v241, v193
	s_waitcnt lgkmcnt(0)
	v_cndmask_b32_e64 v176, v184, v194, s[84:85]
	v_cndmask_b32_e64 v177, v185, v195, s[84:85]
	v_cndmask_b32_e64 v178, v194, v186, s[84:85]
	v_cndmask_b32_e64 v179, v195, v187, s[84:85]
	global_store_dwordx4 v240, v[176:179], s[90:91]
	v_cndmask_b32_e64 v192, v190, v188, s[84:85]
	v_cndmask_b32_e64 v193, v191, v189, s[84:85]
	ds_bpermute_b32 v194, v241, v192
	ds_bpermute_b32 v195, v241, v193
	s_waitcnt lgkmcnt(0)
	v_cndmask_b32_e64 v180, v188, v194, s[84:85]
	v_cndmask_b32_e64 v181, v189, v195, s[84:85]
	v_cndmask_b32_e64 v182, v194, v190, s[84:85]
	v_cndmask_b32_e64 v183, v195, v191, s[84:85]
	global_store_dwordx4 v240, v[180:183], s[90:91] offset:256
	v_mul_f32_e32 v28, v28, v150
	v_mul_f32_e32 v29, v29, v150
	v_pk_fma_f32 v[28:29], v[152:153], v[28:29], v[196:197]
	v_mul_f32_e32 v30, v30, v150
	v_mul_f32_e32 v31, v31, v150
	v_pk_fma_f32 v[30:31], v[154:155], v[30:31], v[198:199]
	v_cvt_pk_bf16_f32 v184, v28, v29
	v_cvt_pk_bf16_f32 v185, v30, v31
	v_mul_f32_e32 v24, v24, v150
	v_mul_f32_e32 v25, v25, v150
	v_pk_fma_f32 v[24:25], v[164:165], v[24:25], v[212:213]
	v_mul_f32_e32 v26, v26, v150
	v_mul_f32_e32 v27, v27, v150
	v_pk_fma_f32 v[26:27], v[166:167], v[26:27], v[214:215]
	v_cvt_pk_bf16_f32 v186, v24, v25
	v_cvt_pk_bf16_f32 v187, v26, v27
	v_mul_f32_e32 v20, v20, v150
	v_mul_f32_e32 v21, v21, v150
	v_pk_fma_f32 v[20:21], v[168:169], v[20:21], v[216:217]
	v_mul_f32_e32 v22, v22, v150
	v_mul_f32_e32 v23, v23, v150
	v_pk_fma_f32 v[22:23], v[170:171], v[22:23], v[218:219]
	v_cvt_pk_bf16_f32 v188, v20, v21
	v_cvt_pk_bf16_f32 v189, v22, v23
	v_mul_f32_e32 v16, v16, v150
	v_mul_f32_e32 v17, v17, v150
	v_pk_fma_f32 v[16:17], v[172:173], v[16:17], v[220:221]
	v_mul_f32_e32 v18, v18, v150
	v_mul_f32_e32 v19, v19, v150
	v_pk_fma_f32 v[18:19], v[174:175], v[18:19], v[222:223]
	v_cvt_pk_bf16_f32 v190, v16, v17
	v_cvt_pk_bf16_f32 v191, v18, v19
	v_add_u32_e32 v240, 0x50000, v247
	v_cndmask_b32_e64 v192, v186, v184, s[84:85]
	v_cndmask_b32_e64 v193, v187, v185, s[84:85]
	ds_bpermute_b32 v194, v241, v192
	ds_bpermute_b32 v195, v241, v193
	s_waitcnt lgkmcnt(0)
	v_cndmask_b32_e64 v176, v184, v194, s[84:85]
	v_cndmask_b32_e64 v177, v185, v195, s[84:85]
	v_cndmask_b32_e64 v178, v194, v186, s[84:85]
	v_cndmask_b32_e64 v179, v195, v187, s[84:85]
	global_store_dwordx4 v240, v[176:179], s[90:91]
	v_cndmask_b32_e64 v192, v190, v188, s[84:85]
	v_cndmask_b32_e64 v193, v191, v189, s[84:85]
	ds_bpermute_b32 v194, v241, v192
	ds_bpermute_b32 v195, v241, v193
	s_waitcnt lgkmcnt(0)
	v_cndmask_b32_e64 v180, v188, v194, s[84:85]
	v_cndmask_b32_e64 v181, v189, v195, s[84:85]
	v_cndmask_b32_e64 v182, v194, v190, s[84:85]
	v_cndmask_b32_e64 v183, v195, v191, s[84:85]
	global_store_dwordx4 v240, v[180:183], s[90:91] offset:256
	v_mul_f32_e32 v12, v12, v151
	v_mul_f32_e32 v13, v13, v151
	v_pk_fma_f32 v[12:13], v[152:153], v[12:13], v[196:197]
	v_mul_f32_e32 v14, v14, v151
	v_mul_f32_e32 v15, v15, v151
	v_pk_fma_f32 v[14:15], v[154:155], v[14:15], v[198:199]
	v_cvt_pk_bf16_f32 v184, v12, v13
	v_cvt_pk_bf16_f32 v185, v14, v15
	v_mul_f32_e32 v8, v8, v151
	v_mul_f32_e32 v9, v9, v151
	v_pk_fma_f32 v[8:9], v[164:165], v[8:9], v[212:213]
	v_mul_f32_e32 v10, v10, v151
	v_mul_f32_e32 v11, v11, v151
	v_pk_fma_f32 v[10:11], v[166:167], v[10:11], v[214:215]
	v_cvt_pk_bf16_f32 v186, v8, v9
	v_cvt_pk_bf16_f32 v187, v10, v11
	v_mul_f32_e32 v4, v4, v151
	v_mul_f32_e32 v5, v5, v151
	v_pk_fma_f32 v[4:5], v[168:169], v[4:5], v[216:217]
	v_mul_f32_e32 v6, v6, v151
	v_mul_f32_e32 v7, v7, v151
	v_pk_fma_f32 v[6:7], v[170:171], v[6:7], v[218:219]
	v_cvt_pk_bf16_f32 v188, v4, v5
	v_cvt_pk_bf16_f32 v189, v6, v7
	v_mul_f32_e32 v0, v0, v151
	v_mul_f32_e32 v1, v1, v151
	v_pk_fma_f32 v[0:1], v[172:173], v[0:1], v[220:221]
	v_mul_f32_e32 v2, v2, v151
	v_mul_f32_e32 v3, v3, v151
	v_pk_fma_f32 v[2:3], v[174:175], v[2:3], v[222:223]
	v_cvt_pk_bf16_f32 v190, v0, v1
	v_cvt_pk_bf16_f32 v191, v2, v3
	v_add_u32_e32 v240, 0x58000, v247
	v_cndmask_b32_e64 v192, v186, v184, s[84:85]
	v_cndmask_b32_e64 v193, v187, v185, s[84:85]
	ds_bpermute_b32 v194, v241, v192
	ds_bpermute_b32 v195, v241, v193
	s_waitcnt lgkmcnt(0)
	v_cndmask_b32_e64 v176, v184, v194, s[84:85]
	v_cndmask_b32_e64 v177, v185, v195, s[84:85]
	v_cndmask_b32_e64 v178, v194, v186, s[84:85]
	v_cndmask_b32_e64 v179, v195, v187, s[84:85]
	global_store_dwordx4 v240, v[176:179], s[90:91]
	v_cndmask_b32_e64 v192, v190, v188, s[84:85]
	v_cndmask_b32_e64 v193, v191, v189, s[84:85]
	ds_bpermute_b32 v194, v241, v192
	ds_bpermute_b32 v195, v241, v193
	s_waitcnt lgkmcnt(0)
	v_cndmask_b32_e64 v180, v188, v194, s[84:85]
	v_cndmask_b32_e64 v181, v189, v195, s[84:85]
	v_cndmask_b32_e64 v182, v194, v190, s[84:85]
	v_cndmask_b32_e64 v183, v195, v191, s[84:85]
	global_store_dwordx4 v240, v[180:183], s[90:91] offset:256
	s_and_b64 vcc, exec, s[10:11]
	s_mov_b64 s[10:11], -1
	s_branch .Lfmdone_e
;     __device__ __forceinline__ void operator()(const f32x4 (&acc)[2][2][4][2], const Unit& u, int wr, int wc, int fr, int fq) const {
;         const int cond = u.pm < 64 ? 0 : (u.pm < 128 ? 1 : 2);
;         const float* gate = gate_l + cond * 9216;
;         const int col0 = u.pn * BM + wc * 32 + 4 * fq;
;         f32x4 gv[2][2];
; #pragma unroll
;         for (int bj = 0; bj < 2; ++bj)
; #pragma unroll
;             for (int n = 0; n < 2; ++n) gv[bj][n] = *(const f32x4*)(gate + col0 + bj * HALF + n * 16) * coef;
; #pragma unroll
;         for (int ai = 0; ai < 2; ++ai)
; #pragma unroll
;             for (int m = 0; m < 4; ++m) {
;                 const int row = u.pm * BM + ai * HALF + wr * 64 + m * 16 + fr;
;                 const float* s = row < MX_ ? src_main + (size_t)row * D_ : src_ctx + (size_t)(row - MX_) * D_;
;                 float* d = row < MX_ ? dst_main + (size_t)row * D_ : dst_ctx + (size_t)(row - MX_) * D_;
; #pragma unroll
;                 for (int bj = 0; bj < 2; ++bj)
; #pragma unroll
;                     for (int n = 0; n < 2; ++n) { const int off = col0 + bj * HALF + n * 16; const f32x4 xo = *(const f32x4*)(s + off); *(f32x4*)(d + off) = xo + gv[bj][n] * acc[ai][bj][m][n]; }
.Lfmsel_e:
	s_cmpk_lt_i32 s6, 0x80
	s_cselect_b32 s8, s62, 0x4800
	s_cmp_gt_i32 s6, 63
	s_cselect_b32 s8, s8, 0
	s_lshl_b32 s8, s8, 2
	s_add_u32 s8, s54, s8
	s_addc_u32 s9, s55, 0
	s_load_dwordx2 s[92:93], s[0:1], 0x30
	s_load_dwordx2 s[76:77], s[0:1], 0xb8
	v_lshl_add_u32 v156, s6, 8, v158
	v_lshl_or_b32 v157, s7, 8, v160
	v_lshlrev_b32_e32 v201, 2, v157
	v_lshl_add_u32 v224, v156, 12, v201
	global_load_dwordx4 v[196:199], v201, s[8:9]
	global_load_dwordx4 v[212:215], v201, s[8:9] offset:64
	global_load_dwordx4 v[216:219], v201, s[8:9] offset:512
	global_load_dwordx4 v[220:223], v201, s[8:9] offset:576
	v_add_u32_e32 v225, 0x10000, v224
	v_add_u32_e32 v226, 0x20000, v224
	v_add_u32_e32 v227, 0x30000, v224
	v_add_u32_e32 v228, 0x80000, v224
	v_add_u32_e32 v229, 0x90000, v224
	v_add_u32_e32 v230, 0xa0000, v224
	v_add_u32_e32 v231, 0xb0000, v224
	global_load_dwordx4 v[140:143], v224, s[14:15]
	global_load_dwordx4 v[144:147], v224, s[14:15] offset:64
	global_load_dwordx4 v[148:151], v224, s[14:15] offset:512
	global_load_dwordx4 v[152:155], v224, s[14:15] offset:576
	global_load_dwordx4 v[164:167], v225, s[14:15]
	global_load_dwordx4 v[168:171], v225, s[14:15] offset:64
	global_load_dwordx4 v[172:175], v225, s[14:15] offset:512
	global_load_dwordx4 v[176:179], v225, s[14:15] offset:576
	global_load_dwordx4 v[180:183], v226, s[14:15]
	global_load_dwordx4 v[184:187], v226, s[14:15] offset:64
	global_load_dwordx4 v[188:191], v226, s[14:15] offset:512
	global_load_dwordx4 v[192:195], v226, s[14:15] offset:576
	s_waitcnt vmcnt(12)
	v_pk_mul_f32 v[196:197], v[196:197], 0.5 op_sel_hi:[1,0]
	v_pk_mul_f32 v[198:199], v[198:199], 0.5 op_sel_hi:[1,0]
	v_pk_mul_f32 v[212:213], v[212:213], 0.5 op_sel_hi:[1,0]
	v_pk_mul_f32 v[214:215], v[214:215], 0.5 op_sel_hi:[1,0]
	v_pk_mul_f32 v[216:217], v[216:217], 0.5 op_sel_hi:[1,0]
	v_pk_mul_f32 v[218:219], v[218:219], 0.5 op_sel_hi:[1,0]
	v_pk_mul_f32 v[220:221], v[220:221], 0.5 op_sel_hi:[1,0]
	v_pk_mul_f32 v[222:223], v[222:223], 0.5 op_sel_hi:[1,0]
	s_waitcnt vmcnt(11)
	v_pk_fma_f32 v[124:125], v[124:125], v[196:197], v[140:141]
	v_pk_fma_f32 v[126:127], v[126:127], v[198:199], v[142:143]
	v_mul_f32_e32 v232, v124, v124
	v_fmac_f32_e32 v232, v125, v125
	v_fmac_f32_e32 v232, v126, v126
	v_fmac_f32_e32 v232, v127, v127
	s_waitcnt vmcnt(10)
	v_pk_fma_f32 v[120:121], v[120:121], v[212:213], v[144:145]
	v_pk_fma_f32 v[122:123], v[122:123], v[214:215], v[146:147]
	v_fmac_f32_e32 v232, v120, v120
	v_fmac_f32_e32 v232, v121, v121
	v_fmac_f32_e32 v232, v122, v122
	v_fmac_f32_e32 v232, v123, v123
	s_waitcnt vmcnt(9)
	v_pk_fma_f32 v[116:117], v[116:117], v[216:217], v[148:149]
	v_pk_fma_f32 v[118:119], v[118:119], v[218:219], v[150:151]
	v_fmac_f32_e32 v232, v116, v116
	v_fmac_f32_e32 v232, v117, v117
	v_fmac_f32_e32 v232, v118, v118
	v_fmac_f32_e32 v232, v119, v119
	s_waitcnt vmcnt(8)
	v_pk_fma_f32 v[112:113], v[112:113], v[220:221], v[152:153]
	v_pk_fma_f32 v[114:115], v[114:115], v[222:223], v[154:155]
	v_fmac_f32_e32 v232, v112, v112
	v_fmac_f32_e32 v232, v113, v113
	v_fmac_f32_e32 v232, v114, v114
	v_fmac_f32_e32 v232, v115, v115
	global_store_dwordx4 v224, v[124:127], s[14:15] sc1
	global_store_dwordx4 v224, v[120:123], s[14:15] offset:64 sc1
	global_store_dwordx4 v224, v[116:119], s[14:15] offset:512 sc1
	global_store_dwordx4 v224, v[112:115], s[14:15] offset:576 sc1
	global_load_dwordx4 v[140:143], v227, s[14:15]
	global_load_dwordx4 v[144:147], v227, s[14:15] offset:64
	global_load_dwordx4 v[148:151], v227, s[14:15] offset:512
	global_load_dwordx4 v[152:155], v227, s[14:15] offset:576
	s_waitcnt vmcnt(15)
	v_pk_fma_f32 v[108:109], v[108:109], v[196:197], v[164:165]
	v_pk_fma_f32 v[110:111], v[110:111], v[198:199], v[166:167]
	v_mul_f32_e32 v233, v108, v108
	v_fmac_f32_e32 v233, v109, v109
	v_fmac_f32_e32 v233, v110, v110
	v_fmac_f32_e32 v233, v111, v111
	s_waitcnt vmcnt(14)
	v_pk_fma_f32 v[104:105], v[104:105], v[212:213], v[168:169]
	v_pk_fma_f32 v[106:107], v[106:107], v[214:215], v[170:171]
	v_fmac_f32_e32 v233, v104, v104
	v_fmac_f32_e32 v233, v105, v105
	v_fmac_f32_e32 v233, v106, v106
	v_fmac_f32_e32 v233, v107, v107
	s_waitcnt vmcnt(13)
	v_pk_fma_f32 v[100:101], v[100:101], v[216:217], v[172:173]
	v_pk_fma_f32 v[102:103], v[102:103], v[218:219], v[174:175]
	v_fmac_f32_e32 v233, v100, v100
	v_fmac_f32_e32 v233, v101, v101
	v_fmac_f32_e32 v233, v102, v102
	v_fmac_f32_e32 v233, v103, v103
	s_waitcnt vmcnt(12)
	v_pk_fma_f32 v[96:97], v[96:97], v[220:221], v[176:177]
	v_pk_fma_f32 v[98:99], v[98:99], v[222:223], v[178:179]
	v_fmac_f32_e32 v233, v96, v96
	v_fmac_f32_e32 v233, v97, v97
	v_fmac_f32_e32 v233, v98, v98
	v_fmac_f32_e32 v233, v99, v99
	global_store_dwordx4 v225, v[108:111], s[14:15] sc1
	global_store_dwordx4 v225, v[104:107], s[14:15] offset:64 sc1
	global_store_dwordx4 v225, v[100:103], s[14:15] offset:512 sc1
	global_store_dwordx4 v225, v[96:99], s[14:15] offset:576 sc1
	global_load_dwordx4 v[164:167], v228, s[14:15]
	global_load_dwordx4 v[168:171], v228, s[14:15] offset:64
	global_load_dwordx4 v[172:175], v228, s[14:15] offset:512
	global_load_dwordx4 v[176:179], v228, s[14:15] offset:576
	s_waitcnt vmcnt(19)
	v_pk_fma_f32 v[92:93], v[92:93], v[196:197], v[180:181]
	v_pk_fma_f32 v[94:95], v[94:95], v[198:199], v[182:183]
	v_mul_f32_e32 v234, v92, v92
	v_fmac_f32_e32 v234, v93, v93
	v_fmac_f32_e32 v234, v94, v94
	v_fmac_f32_e32 v234, v95, v95
	s_waitcnt vmcnt(18)
	v_pk_fma_f32 v[88:89], v[88:89], v[212:213], v[184:185]
	v_pk_fma_f32 v[90:91], v[90:91], v[214:215], v[186:187]
	v_fmac_f32_e32 v234, v88, v88
	v_fmac_f32_e32 v234, v89, v89
	v_fmac_f32_e32 v234, v90, v90
	v_fmac_f32_e32 v234, v91, v91
	s_waitcnt vmcnt(17)
;     __device__ __forceinline__ void operator()(const f32x4 (&acc)[2][2][4][2], const Unit& u, int wr, int wc, int fr, int fq) const {
;     ...
;         for (int ai = 0; ai < 2; ++ai)
; #pragma unroll
;             for (int m = 0; m < 4; ++m) {
;                 const int row = u.pm * BM + ai * HALF + wr * 64 + m * 16 + fr;
;                 const float* s = row < MX_ ? src_main + (size_t)row * D_ : src_ctx + (size_t)(row - MX_) * D_;
;                 float* d = row < MX_ ? dst_main + (size_t)row * D_ : dst_ctx + (size_t)(row - MX_) * D_;
; #pragma unroll
;                 for (int bj = 0; bj < 2; ++bj)
; #pragma unroll
;                     for (int n = 0; n < 2; ++n) { const int off = col0 + bj * HALF + n * 16; const f32x4 xo = *(const f32x4*)(s + off); *(f32x4*)(d + off) = xo + gv[bj][n] * acc[ai][bj][m][n]; }
	v_pk_fma_f32 v[84:85], v[84:85], v[216:217], v[188:189]
	v_pk_fma_f32 v[86:87], v[86:87], v[218:219], v[190:191]
	v_fmac_f32_e32 v234, v84, v84
	v_fmac_f32_e32 v234, v85, v85
	v_fmac_f32_e32 v234, v86, v86
	v_fmac_f32_e32 v234, v87, v87
	s_waitcnt vmcnt(16)
	v_pk_fma_f32 v[80:81], v[80:81], v[220:221], v[192:193]
	v_pk_fma_f32 v[82:83], v[82:83], v[222:223], v[194:195]
	v_fmac_f32_e32 v234, v80, v80
	v_fmac_f32_e32 v234, v81, v81
	v_fmac_f32_e32 v234, v82, v82
	v_fmac_f32_e32 v234, v83, v83
	global_store_dwordx4 v226, v[92:95], s[14:15] sc1
	global_store_dwordx4 v226, v[88:91], s[14:15] offset:64 sc1
	global_store_dwordx4 v226, v[84:87], s[14:15] offset:512 sc1
	global_store_dwordx4 v226, v[80:83], s[14:15] offset:576 sc1
	global_load_dwordx4 v[180:183], v229, s[14:15]
	global_load_dwordx4 v[184:187], v229, s[14:15] offset:64
	global_load_dwordx4 v[188:191], v229, s[14:15] offset:512
	global_load_dwordx4 v[192:195], v229, s[14:15] offset:576
	s_waitcnt vmcnt(19)
	v_pk_fma_f32 v[76:77], v[76:77], v[196:197], v[140:141]
	v_pk_fma_f32 v[78:79], v[78:79], v[198:199], v[142:143]
	v_mul_f32_e32 v235, v76, v76
	v_fmac_f32_e32 v235, v77, v77
	v_fmac_f32_e32 v235, v78, v78
	v_fmac_f32_e32 v235, v79, v79
	s_waitcnt vmcnt(18)
	v_pk_fma_f32 v[72:73], v[72:73], v[212:213], v[144:145]
	v_pk_fma_f32 v[74:75], v[74:75], v[214:215], v[146:147]
	v_fmac_f32_e32 v235, v72, v72
	v_fmac_f32_e32 v235, v73, v73
	v_fmac_f32_e32 v235, v74, v74
	v_fmac_f32_e32 v235, v75, v75
	s_waitcnt vmcnt(17)
	v_pk_fma_f32 v[68:69], v[68:69], v[216:217], v[148:149]
	v_pk_fma_f32 v[70:71], v[70:71], v[218:219], v[150:151]
	v_fmac_f32_e32 v235, v68, v68
	v_fmac_f32_e32 v235, v69, v69
	v_fmac_f32_e32 v235, v70, v70
	v_fmac_f32_e32 v235, v71, v71
	s_waitcnt vmcnt(16)
	v_pk_fma_f32 v[64:65], v[64:65], v[220:221], v[152:153]
	v_pk_fma_f32 v[66:67], v[66:67], v[222:223], v[154:155]
	v_fmac_f32_e32 v235, v64, v64
	v_fmac_f32_e32 v235, v65, v65
	v_fmac_f32_e32 v235, v66, v66
	v_fmac_f32_e32 v235, v67, v67
	global_store_dwordx4 v227, v[76:79], s[14:15] sc1
	global_store_dwordx4 v227, v[72:75], s[14:15] offset:64 sc1
	global_store_dwordx4 v227, v[68:71], s[14:15] offset:512 sc1
	global_store_dwordx4 v227, v[64:67], s[14:15] offset:576 sc1
	global_load_dwordx4 v[140:143], v230, s[14:15]
	global_load_dwordx4 v[144:147], v230, s[14:15] offset:64
	global_load_dwordx4 v[148:151], v230, s[14:15] offset:512
	global_load_dwordx4 v[152:155], v230, s[14:15] offset:576
	s_waitcnt vmcnt(19)
	v_pk_fma_f32 v[60:61], v[60:61], v[196:197], v[164:165]
	v_pk_fma_f32 v[62:63], v[62:63], v[198:199], v[166:167]
	v_mul_f32_e32 v236, v60, v60
	v_fmac_f32_e32 v236, v61, v61
	v_fmac_f32_e32 v236, v62, v62
	v_fmac_f32_e32 v236, v63, v63
	s_waitcnt vmcnt(18)
	v_pk_fma_f32 v[56:57], v[56:57], v[212:213], v[168:169]
	v_pk_fma_f32 v[58:59], v[58:59], v[214:215], v[170:171]
	v_fmac_f32_e32 v236, v56, v56
	v_fmac_f32_e32 v236, v57, v57
	v_fmac_f32_e32 v236, v58, v58
	v_fmac_f32_e32 v236, v59, v59
	s_waitcnt vmcnt(17)
	v_pk_fma_f32 v[52:53], v[52:53], v[216:217], v[172:173]
	v_pk_fma_f32 v[54:55], v[54:55], v[218:219], v[174:175]
	v_fmac_f32_e32 v236, v52, v52
	v_fmac_f32_e32 v236, v53, v53
	v_fmac_f32_e32 v236, v54, v54
	v_fmac_f32_e32 v236, v55, v55
	s_waitcnt vmcnt(16)
	v_pk_fma_f32 v[48:49], v[48:49], v[220:221], v[176:177]
	v_pk_fma_f32 v[50:51], v[50:51], v[222:223], v[178:179]
	v_fmac_f32_e32 v236, v48, v48
	v_fmac_f32_e32 v236, v49, v49
	v_fmac_f32_e32 v236, v50, v50
	v_fmac_f32_e32 v236, v51, v51
	global_store_dwordx4 v228, v[60:63], s[14:15] sc1
	global_store_dwordx4 v228, v[56:59], s[14:15] offset:64 sc1
	global_store_dwordx4 v228, v[52:55], s[14:15] offset:512 sc1
	global_store_dwordx4 v228, v[48:51], s[14:15] offset:576 sc1
	global_load_dwordx4 v[164:167], v231, s[14:15]
	global_load_dwordx4 v[168:171], v231, s[14:15] offset:64
	global_load_dwordx4 v[172:175], v231, s[14:15] offset:512
	global_load_dwordx4 v[176:179], v231, s[14:15] offset:576
	s_waitcnt vmcnt(19)
	v_pk_fma_f32 v[44:45], v[44:45], v[196:197], v[180:181]
	v_pk_fma_f32 v[46:47], v[46:47], v[198:199], v[182:183]
	v_mul_f32_e32 v237, v44, v44
	v_fmac_f32_e32 v237, v45, v45
	v_fmac_f32_e32 v237, v46, v46
	v_fmac_f32_e32 v237, v47, v47
	s_waitcnt vmcnt(18)
	v_pk_fma_f32 v[40:41], v[40:41], v[212:213], v[184:185]
	v_pk_fma_f32 v[42:43], v[42:43], v[214:215], v[186:187]
	v_fmac_f32_e32 v237, v40, v40
	v_fmac_f32_e32 v237, v41, v41
	v_fmac_f32_e32 v237, v42, v42
	v_fmac_f32_e32 v237, v43, v43
	s_waitcnt vmcnt(17)
	v_pk_fma_f32 v[36:37], v[36:37], v[216:217], v[188:189]
	v_pk_fma_f32 v[38:39], v[38:39], v[218:219], v[190:191]
	v_fmac_f32_e32 v237, v36, v36
	v_fmac_f32_e32 v237, v37, v37
	v_fmac_f32_e32 v237, v38, v38
	v_fmac_f32_e32 v237, v39, v39
	s_waitcnt vmcnt(16)
	v_pk_fma_f32 v[32:33], v[32:33], v[220:221], v[192:193]
	v_pk_fma_f32 v[34:35], v[34:35], v[222:223], v[194:195]
	v_fmac_f32_e32 v237, v32, v32
	v_fmac_f32_e32 v237, v33, v33
	v_fmac_f32_e32 v237, v34, v34
	v_fmac_f32_e32 v237, v35, v35
	global_store_dwordx4 v229, v[44:47], s[14:15] sc1
	global_store_dwordx4 v229, v[40:43], s[14:15] offset:64 sc1
	global_store_dwordx4 v229, v[36:39], s[14:15] offset:512 sc1
	global_store_dwordx4 v229, v[32:35], s[14:15] offset:576 sc1
	s_waitcnt vmcnt(15)
;     __device__ __forceinline__ void operator()(const f32x4 (&acc)[2][2][4][2], const Unit& u, int wr, int wc, int fr, int fq) const {
;     ...
;         for (int ai = 0; ai < 2; ++ai)
; #pragma unroll
;             for (int m = 0; m < 4; ++m) {
;                 const int row = u.pm * BM + ai * HALF + wr * 64 + m * 16 + fr;
;                 const float* s = row < MX_ ? src_main + (size_t)row * D_ : src_ctx + (size_t)(row - MX_) * D_;
;                 float* d = row < MX_ ? dst_main + (size_t)row * D_ : dst_ctx + (size_t)(row - MX_) * D_;
; #pragma unroll
;                 for (int bj = 0; bj < 2; ++bj)
; #pragma unroll
;                     for (int n = 0; n < 2; ++n) { const int off = col0 + bj * HALF + n * 16; const f32x4 xo = *(const f32x4*)(s + off); *(f32x4*)(d + off) = xo + gv[bj][n] * acc[ai][bj][m][n]; }
; __device__ __forceinline__ void modpass(const float* xs_main, const float* xs_ctx, const float* mod_l, const float* g, int i, bf16_t* H, int nrows, int gw, int NGW, int lane) {
;     ...
;         float ss = 0.f;
; #pragma unroll
;         for (int j = 0; j < 2; ++j)
; #pragma unroll
;             for (int q = 0; q < 2; ++q) ss += (v[j][q][0] * v[j][q][0] + v[j][q][1] * v[j][q][1]) + (v[j][q][2] * v[j][q][2] + v[j][q][3] * v[j][q][3]);
;         const float rstd = 1.0f / sqrtf(wave_sum(ss) * (1.0f / D) + EPS);
	v_pk_fma_f32 v[28:29], v[28:29], v[196:197], v[140:141]
	v_pk_fma_f32 v[30:31], v[30:31], v[198:199], v[142:143]
	v_mul_f32_e32 v238, v28, v28
	v_fmac_f32_e32 v238, v29, v29
	v_fmac_f32_e32 v238, v30, v30
	v_fmac_f32_e32 v238, v31, v31
	s_waitcnt vmcnt(14)
	v_pk_fma_f32 v[24:25], v[24:25], v[212:213], v[144:145]
	v_pk_fma_f32 v[26:27], v[26:27], v[214:215], v[146:147]
	v_fmac_f32_e32 v238, v24, v24
	v_fmac_f32_e32 v238, v25, v25
	v_fmac_f32_e32 v238, v26, v26
	v_fmac_f32_e32 v238, v27, v27
	s_waitcnt vmcnt(13)
	v_pk_fma_f32 v[20:21], v[20:21], v[216:217], v[148:149]
	v_pk_fma_f32 v[22:23], v[22:23], v[218:219], v[150:151]
	v_fmac_f32_e32 v238, v20, v20
	v_fmac_f32_e32 v238, v21, v21
	v_fmac_f32_e32 v238, v22, v22
	v_fmac_f32_e32 v238, v23, v23
	s_waitcnt vmcnt(12)
	v_pk_fma_f32 v[16:17], v[16:17], v[220:221], v[152:153]
	v_pk_fma_f32 v[18:19], v[18:19], v[222:223], v[154:155]
	v_fmac_f32_e32 v238, v16, v16
	v_fmac_f32_e32 v238, v17, v17
	v_fmac_f32_e32 v238, v18, v18
	v_fmac_f32_e32 v238, v19, v19
	global_store_dwordx4 v230, v[28:31], s[14:15] sc1
	global_store_dwordx4 v230, v[24:27], s[14:15] offset:64 sc1
	global_store_dwordx4 v230, v[20:23], s[14:15] offset:512 sc1
	global_store_dwordx4 v230, v[16:19], s[14:15] offset:576 sc1
	s_waitcnt vmcnt(11)
	v_pk_fma_f32 v[12:13], v[12:13], v[196:197], v[164:165]
	v_pk_fma_f32 v[14:15], v[14:15], v[198:199], v[166:167]
	v_mul_f32_e32 v239, v12, v12
	v_fmac_f32_e32 v239, v13, v13
	v_fmac_f32_e32 v239, v14, v14
	v_fmac_f32_e32 v239, v15, v15
	s_waitcnt vmcnt(10)
	v_pk_fma_f32 v[8:9], v[8:9], v[212:213], v[168:169]
	v_pk_fma_f32 v[10:11], v[10:11], v[214:215], v[170:171]
	v_fmac_f32_e32 v239, v8, v8
	v_fmac_f32_e32 v239, v9, v9
	v_fmac_f32_e32 v239, v10, v10
	v_fmac_f32_e32 v239, v11, v11
	s_waitcnt vmcnt(9)
	v_pk_fma_f32 v[4:5], v[4:5], v[216:217], v[172:173]
	v_pk_fma_f32 v[6:7], v[6:7], v[218:219], v[174:175]
	v_fmac_f32_e32 v239, v4, v4
	v_fmac_f32_e32 v239, v5, v5
	v_fmac_f32_e32 v239, v6, v6
	v_fmac_f32_e32 v239, v7, v7
	s_waitcnt vmcnt(8)
	v_pk_fma_f32 v[0:1], v[0:1], v[220:221], v[176:177]
	v_pk_fma_f32 v[2:3], v[2:3], v[222:223], v[178:179]
	v_fmac_f32_e32 v239, v0, v0
	v_fmac_f32_e32 v239, v1, v1
	v_fmac_f32_e32 v239, v2, v2
	v_fmac_f32_e32 v239, v3, v3
	global_store_dwordx4 v231, v[12:15], s[14:15] sc1
	global_store_dwordx4 v231, v[8:11], s[14:15] offset:64 sc1
	global_store_dwordx4 v231, v[4:7], s[14:15] offset:512 sc1
	global_store_dwordx4 v231, v[0:3], s[14:15] offset:576 sc1
	v_mbcnt_lo_u32_b32 v240, -1, 0
	v_mbcnt_hi_u32_b32 v240, -1, v240
	v_xor_b32_e32 v241, 16, v240
	v_xor_b32_e32 v242, 32, v240
	v_lshlrev_b32_e32 v241, 2, v241
	v_lshlrev_b32_e32 v242, 2, v242
	s_waitcnt lgkmcnt(0)
	ds_bpermute_b32 v140, v241, v232
	ds_bpermute_b32 v141, v241, v233
	ds_bpermute_b32 v142, v241, v234
	ds_bpermute_b32 v143, v241, v235
	ds_bpermute_b32 v144, v241, v236
	ds_bpermute_b32 v145, v241, v237
	ds_bpermute_b32 v146, v241, v238
	ds_bpermute_b32 v147, v241, v239
	s_waitcnt lgkmcnt(7)
	v_add_f32_e32 v232, v232, v140
	s_waitcnt lgkmcnt(6)
	v_add_f32_e32 v233, v233, v141
	s_waitcnt lgkmcnt(5)
	v_add_f32_e32 v234, v234, v142
	s_waitcnt lgkmcnt(4)
	v_add_f32_e32 v235, v235, v143
	s_waitcnt lgkmcnt(3)
	v_add_f32_e32 v236, v236, v144
	s_waitcnt lgkmcnt(2)
	v_add_f32_e32 v237, v237, v145
	s_waitcnt lgkmcnt(1)
	v_add_f32_e32 v238, v238, v146
	s_waitcnt lgkmcnt(0)
	v_add_f32_e32 v239, v239, v147
	ds_bpermute_b32 v140, v242, v232
	ds_bpermute_b32 v141, v242, v233
	ds_bpermute_b32 v142, v242, v234
	ds_bpermute_b32 v143, v242, v235
	ds_bpermute_b32 v144, v242, v236
	ds_bpermute_b32 v145, v242, v237
	ds_bpermute_b32 v146, v242, v238
	ds_bpermute_b32 v147, v242, v239
	s_waitcnt lgkmcnt(7)
	v_add_f32_e32 v232, v232, v140
	s_waitcnt lgkmcnt(6)
	v_add_f32_e32 v233, v233, v141
	s_waitcnt lgkmcnt(5)
	v_add_f32_e32 v234, v234, v142
	s_waitcnt lgkmcnt(4)
	v_add_f32_e32 v235, v235, v143
	s_waitcnt lgkmcnt(3)
	v_add_f32_e32 v236, v236, v144
	s_waitcnt lgkmcnt(2)
	v_add_f32_e32 v237, v237, v145
	s_waitcnt lgkmcnt(1)
	v_add_f32_e32 v238, v238, v146
	s_waitcnt lgkmcnt(0)
	v_add_f32_e32 v239, v239, v147
	v_lshlrev_b32_e32 v243, 2, v156
	s_add_u32 s90, s76, 0x6500000
	s_addc_u32 s91, s77, 0
	s_add_u32 s76, s76, 0x3186000
	s_addc_u32 s77, s77, 0
	s_lshl_b32 s83, s6, 6
	s_add_u32 s78, s76, s83
	s_addc_u32 s79, s77, 0
	s_add_u32 s78, s78, 0x20000
	s_addc_u32 s79, s79, 0
	s_mov_b64 s[80:81], exec
	s_mov_b64 exec, 0xffff
	global_atomic_add_f32 v243, v232, s[76:77]
	global_atomic_add_f32 v243, v233, s[76:77] offset:64
	global_atomic_add_f32 v243, v234, s[76:77] offset:128
	global_atomic_add_f32 v243, v235, s[76:77] offset:192
	global_atomic_add_f32 v243, v236, s[76:77] offset:512
	global_atomic_add_f32 v243, v237, s[76:77] offset:576
	global_atomic_add_f32 v243, v238, s[76:77] offset:640
	global_atomic_add_f32 v243, v239, s[76:77] offset:704
	s_mov_b64 exec, s[80:81]
	s_add_u32 s86, s8, 0x1000
	s_addc_u32 s87, s9, 0
	s_add_u32 s88, s86, 0x1000
	s_addc_u32 s89, s87, 0
	s_add_u32 s92, s92, 0x4000
	s_addc_u32 s93, s93, 0
	s_mov_b32 s84, 0xffff0000
	s_mov_b32 s85, 0xffff0000
	s_waitcnt vmcnt(0)
	s_barrier
	v_readfirstlane_b32 s83, v206
	v_mov_b32_e32 v244, 0
	v_mov_b32_e32 v245, 1
	s_cmp_lg_u32 s83, 0
	s_cbranch_scc1 .Lfmes_wait_done
	s_mov_b64 exec, 1
	global_atomic_add v244, v245, s[78:79]
	s_mov_b32 s82, 0

; __device__ __forceinline__ unsigned cvtpk_s(float lo, float hi) { f32x2_t v = {lo, hi}; bf16x2_t b = __builtin_convertvector(v, bf16x2_t); return __builtin_bit_cast(unsigned, b); }
; __device__ __forceinline__ void modpass(const float* xs_main, const float* xs_ctx, const float* mod_l, const float* g, int i, bf16_t* H, int nrows, int gw, int NGW, int lane) {
;     ...
;         if (cond != cur) { cur = cond; const float* shift = mod_l + cond * 9216 + 3 * i * 1024; const float* scale = shift + 1024;
; #pragma unroll
;             for (int j = 0; j < 2; ++j)
; #pragma unroll
;                 for (int q = 0; q < 2; ++q) { const int c = 8 * lane + 512 * j + 4 * q; gm[j][q] = *(const f32x4*)(g + c) * (*(const f32x4*)(scale + c) + 1.0f); sh[j][q] = *(const f32x4*)(shift + c); } }
;         float ss = 0.f;
; #pragma unroll
;         for (int j = 0; j < 2; ++j)
; #pragma unroll
;             for (int q = 0; q < 2; ++q) ss += (v[j][q][0] * v[j][q][0] + v[j][q][1] * v[j][q][1]) + (v[j][q][2] * v[j][q][2] + v[j][q][3] * v[j][q][3]);
;         const float rstd = 1.0f / sqrtf(wave_sum(ss) * (1.0f / D) + EPS);
; #pragma unroll
;         for (int j = 0; j < 2; ++j) {
;             const f32x4 o0 = v[j][0] * rstd * gm[j][0] + sh[j][0], o1 = v[j][1] * rstd * gm[j][1] + sh[j][1];
;             u32x4 w; w.x = cvtpk_s(o0[0], o0[1]); w.y = cvtpk_s(o0[2], o0[3]); w.z = cvtpk_s(o1[0], o1[1]); w.w = cvtpk_s(o1[2], o1[3]);
;             *(u32x4*)(H + (size_t)row * D + 8 * lane + 512 * j) = w;
.Lfmes_wait_done:
	s_barrier
	global_load_dword v144, v243, s[76:77] sc1
	global_load_dword v145, v243, s[76:77] offset:64 sc1
	global_load_dword v146, v243, s[76:77] offset:128 sc1
	global_load_dword v147, v243, s[76:77] offset:192 sc1
	global_load_dword v148, v243, s[76:77] offset:512 sc1
	global_load_dword v149, v243, s[76:77] offset:576 sc1
	global_load_dword v150, v243, s[76:77] offset:640 sc1
	global_load_dword v151, v243, s[76:77] offset:704 sc1
	global_load_dwordx4 v[196:199], v201, s[86:87]
	global_load_dwordx4 v[212:215], v201, s[86:87] offset:64
	global_load_dwordx4 v[216:219], v201, s[86:87] offset:512
	global_load_dwordx4 v[220:223], v201, s[86:87] offset:576
	global_load_dwordx4 v[152:155], v201, s[88:89]
	global_load_dwordx4 v[164:167], v201, s[88:89] offset:64
	global_load_dwordx4 v[168:171], v201, s[88:89] offset:512
	global_load_dwordx4 v[172:175], v201, s[88:89] offset:576
	global_load_dwordx4 v[176:179], v201, s[92:93]
	global_load_dwordx4 v[180:183], v201, s[92:93] offset:64
	global_load_dwordx4 v[184:187], v201, s[92:93] offset:512
	global_load_dwordx4 v[188:191], v201, s[92:93] offset:576
	v_mov_b32_e32 v240, 12
	v_cndmask_b32_e64 v240, 0, v240, s[84:85]
	v_add_u32_e32 v240, v240, v157
	v_lshlrev_b32_e32 v240, 1, v240
	v_lshl_add_u32 v247, v156, 11, v240
	v_mov_b32_e32 v240, 0x358637bd
	s_waitcnt vmcnt(0)
	v_fmamk_f32 v144, v144, 0x3a800000, v240
	v_fmamk_f32 v145, v145, 0x3a800000, v240
	v_fmamk_f32 v146, v146, 0x3a800000, v240
	v_fmamk_f32 v147, v147, 0x3a800000, v240
	v_fmamk_f32 v148, v148, 0x3a800000, v240
	v_fmamk_f32 v149, v149, 0x3a800000, v240
	v_fmamk_f32 v150, v150, 0x3a800000, v240
	v_fmamk_f32 v151, v151, 0x3a800000, v240
	v_rsq_f32_e32 v144, v144
	v_rsq_f32_e32 v145, v145
	v_rsq_f32_e32 v146, v146
	v_rsq_f32_e32 v147, v147
	v_rsq_f32_e32 v148, v148
	v_rsq_f32_e32 v149, v149
	v_rsq_f32_e32 v150, v150
	v_rsq_f32_e32 v151, v151
	v_pk_add_f32 v[152:153], v[152:153], 1.0 op_sel_hi:[1,0]
	v_pk_mul_f32 v[152:153], v[176:177], v[152:153]
	v_pk_add_f32 v[154:155], v[154:155], 1.0 op_sel_hi:[1,0]
	v_pk_mul_f32 v[154:155], v[178:179], v[154:155]
	v_pk_add_f32 v[164:165], v[164:165], 1.0 op_sel_hi:[1,0]
	v_pk_mul_f32 v[164:165], v[180:181], v[164:165]
	v_pk_add_f32 v[166:167], v[166:167], 1.0 op_sel_hi:[1,0]
	v_pk_mul_f32 v[166:167], v[182:183], v[166:167]
	v_pk_add_f32 v[168:169], v[168:169], 1.0 op_sel_hi:[1,0]
	v_pk_mul_f32 v[168:169], v[184:185], v[168:169]
	v_pk_add_f32 v[170:171], v[170:171], 1.0 op_sel_hi:[1,0]
	v_pk_mul_f32 v[170:171], v[186:187], v[170:171]
	v_pk_add_f32 v[172:173], v[172:173], 1.0 op_sel_hi:[1,0]
	v_pk_mul_f32 v[172:173], v[188:189], v[172:173]
	v_pk_add_f32 v[174:175], v[174:175], 1.0 op_sel_hi:[1,0]
	v_pk_mul_f32 v[174:175], v[190:191], v[174:175]
	v_mul_f32_e32 v124, v124, v144
	v_mul_f32_e32 v125, v125, v144
	v_pk_fma_f32 v[124:125], v[152:153], v[124:125], v[196:197]
	v_mul_f32_e32 v126, v126, v144
	v_mul_f32_e32 v127, v127, v144
	v_pk_fma_f32 v[126:127], v[154:155], v[126:127], v[198:199]
	v_cvt_pk_bf16_f32 v184, v124, v125
	v_cvt_pk_bf16_f32 v185, v126, v127
	v_mul_f32_e32 v120, v120, v144
	v_mul_f32_e32 v121, v121, v144
	v_pk_fma_f32 v[120:121], v[164:165], v[120:121], v[212:213]
	v_mul_f32_e32 v122, v122, v144
	v_mul_f32_e32 v123, v123, v144
	v_pk_fma_f32 v[122:123], v[166:167], v[122:123], v[214:215]
	v_cvt_pk_bf16_f32 v186, v120, v121
	v_cvt_pk_bf16_f32 v187, v122, v123
	v_mul_f32_e32 v116, v116, v144
	v_mul_f32_e32 v117, v117, v144
	v_pk_fma_f32 v[116:117], v[168:169], v[116:117], v[216:217]
	v_mul_f32_e32 v118, v118, v144
	v_mul_f32_e32 v119, v119, v144
	v_pk_fma_f32 v[118:119], v[170:171], v[118:119], v[218:219]
	v_cvt_pk_bf16_f32 v188, v116, v117
	v_cvt_pk_bf16_f32 v189, v118, v119
	v_mul_f32_e32 v112, v112, v144
	v_mul_f32_e32 v113, v113, v144
	v_pk_fma_f32 v[112:113], v[172:173], v[112:113], v[220:221]
	v_mul_f32_e32 v114, v114, v144
	v_mul_f32_e32 v115, v115, v144
	v_pk_fma_f32 v[114:115], v[174:175], v[114:115], v[222:223]
	v_cvt_pk_bf16_f32 v190, v112, v113
	v_cvt_pk_bf16_f32 v191, v114, v115
	v_mov_b32_e32 v240, v247
	v_cndmask_b32_e64 v192, v186, v184, s[84:85]
	v_cndmask_b32_e64 v193, v187, v185, s[84:85]
	ds_bpermute_b32 v194, v241, v192
	ds_bpermute_b32 v195, v241, v193
	s_waitcnt lgkmcnt(0)
	v_cndmask_b32_e64 v176, v184, v194, s[84:85]
	v_cndmask_b32_e64 v177, v185, v195, s[84:85]
	v_cndmask_b32_e64 v178, v194, v186, s[84:85]
	v_cndmask_b32_e64 v179, v195, v187, s[84:85]
	global_store_dwordx4 v240, v[176:179], s[90:91] sc1
	v_cndmask_b32_e64 v192, v190, v188, s[84:85]
	v_cndmask_b32_e64 v193, v191, v189, s[84:85]
	ds_bpermute_b32 v194, v241, v192
	ds_bpermute_b32 v195, v241, v193
	s_waitcnt lgkmcnt(0)
	v_cndmask_b32_e64 v180, v188, v194, s[84:85]
	v_cndmask_b32_e64 v181, v189, v195, s[84:85]
	v_cndmask_b32_e64 v182, v194, v190, s[84:85]
	v_cndmask_b32_e64 v183, v195, v191, s[84:85]
	global_store_dwordx4 v240, v[180:183], s[90:91] offset:256 sc1
	v_mul_f32_e32 v108, v108, v145
	v_mul_f32_e32 v109, v109, v145
	v_pk_fma_f32 v[108:109], v[152:153], v[108:109], v[196:197]
	v_mul_f32_e32 v110, v110, v145
	v_mul_f32_e32 v111, v111, v145
	v_pk_fma_f32 v[110:111], v[154:155], v[110:111], v[198:199]
	v_cvt_pk_bf16_f32 v184, v108, v109
	v_cvt_pk_bf16_f32 v185, v110, v111
	v_mul_f32_e32 v104, v104, v145
	v_mul_f32_e32 v105, v105, v145
	v_pk_fma_f32 v[104:105], v[164:165], v[104:105], v[212:213]
	v_mul_f32_e32 v106, v106, v145
	v_mul_f32_e32 v107, v107, v145
	v_pk_fma_f32 v[106:107], v[166:167], v[106:107], v[214:215]
	v_cvt_pk_bf16_f32 v186, v104, v105
	v_cvt_pk_bf16_f32 v187, v106, v107
	v_mul_f32_e32 v100, v100, v145
	v_mul_f32_e32 v101, v101, v145
	v_pk_fma_f32 v[100:101], v[168:169], v[100:101], v[216:217]
	v_mul_f32_e32 v102, v102, v145
	v_mul_f32_e32 v103, v103, v145
	v_pk_fma_f32 v[102:103], v[170:171], v[102:103], v[218:219]
	v_cvt_pk_bf16_f32 v188, v100, v101
	v_cvt_pk_bf16_f32 v189, v102, v103
	v_mul_f32_e32 v96, v96, v145
	v_mul_f32_e32 v97, v97, v145
	v_pk_fma_f32 v[96:97], v[172:173], v[96:97], v[220:221]
	v_mul_f32_e32 v98, v98, v145
	v_mul_f32_e32 v99, v99, v145
	v_pk_fma_f32 v[98:99], v[174:175], v[98:99], v[222:223]
	v_cvt_pk_bf16_f32 v190, v96, v97
	v_cvt_pk_bf16_f32 v191, v98, v99
	v_add_u32_e32 v240, 0x8000, v247
	v_cndmask_b32_e64 v192, v186, v184, s[84:85]
	v_cndmask_b32_e64 v193, v187, v185, s[84:85]
	ds_bpermute_b32 v194, v241, v192
	ds_bpermute_b32 v195, v241, v193
	s_waitcnt lgkmcnt(0)
; __device__ __forceinline__ unsigned cvtpk_s(float lo, float hi) { f32x2_t v = {lo, hi}; bf16x2_t b = __builtin_convertvector(v, bf16x2_t); return __builtin_bit_cast(unsigned, b); }
; __device__ __forceinline__ u32x4 quad_swap(unsigned lo0, unsigned lo1, unsigned hi0, unsigned hi1, int fq, int& coloff) {
;     const bool odd = fq & 1;
;     const unsigned s0 = odd ? lo0 : hi0, s1 = odd ? lo1 : hi1;
;     const unsigned r0 = (unsigned)__shfl_xor((int)s0, 16), r1 = (unsigned)__shfl_xor((int)s1, 16);
;     coloff = odd ? 16 + 4 * (fq - 1) : 4 * fq;
;     u32x4 o; o.x = odd ? r0 : lo0; o.y = odd ? r1 : lo1; o.z = odd ? hi0 : r0; o.w = odd ? hi1 : r1; return o;
; __device__ __forceinline__ void modpass(const float* xs_main, const float* xs_ctx, const float* mod_l, const float* g, int i, bf16_t* H, int nrows, int gw, int NGW, int lane) {
;     ...
; #pragma unroll
;         for (int j = 0; j < 2; ++j) {
;             const f32x4 o0 = v[j][0] * rstd * gm[j][0] + sh[j][0], o1 = v[j][1] * rstd * gm[j][1] + sh[j][1];
;             u32x4 w; w.x = cvtpk_s(o0[0], o0[1]); w.y = cvtpk_s(o0[2], o0[3]); w.z = cvtpk_s(o1[0], o1[1]); w.w = cvtpk_s(o1[2], o1[3]);
;             *(u32x4*)(H + (size_t)row * D + 8 * lane + 512 * j) = w;
	v_cndmask_b32_e64 v176, v184, v194, s[84:85]
	v_cndmask_b32_e64 v177, v185, v195, s[84:85]
	v_cndmask_b32_e64 v178, v194, v186, s[84:85]
	v_cndmask_b32_e64 v179, v195, v187, s[84:85]
	global_store_dwordx4 v240, v[176:179], s[90:91] sc1
	v_cndmask_b32_e64 v192, v190, v188, s[84:85]
	v_cndmask_b32_e64 v193, v191, v189, s[84:85]
	ds_bpermute_b32 v194, v241, v192
	ds_bpermute_b32 v195, v241, v193
	s_waitcnt lgkmcnt(0)
	v_cndmask_b32_e64 v180, v188, v194, s[84:85]
	v_cndmask_b32_e64 v181, v189, v195, s[84:85]
	v_cndmask_b32_e64 v182, v194, v190, s[84:85]
	v_cndmask_b32_e64 v183, v195, v191, s[84:85]
	global_store_dwordx4 v240, v[180:183], s[90:91] offset:256 sc1
	v_mul_f32_e32 v92, v92, v146
	v_mul_f32_e32 v93, v93, v146
	v_pk_fma_f32 v[92:93], v[152:153], v[92:93], v[196:197]
	v_mul_f32_e32 v94, v94, v146
	v_mul_f32_e32 v95, v95, v146
	v_pk_fma_f32 v[94:95], v[154:155], v[94:95], v[198:199]
	v_cvt_pk_bf16_f32 v184, v92, v93
	v_cvt_pk_bf16_f32 v185, v94, v95
	v_mul_f32_e32 v88, v88, v146
	v_mul_f32_e32 v89, v89, v146
	v_pk_fma_f32 v[88:89], v[164:165], v[88:89], v[212:213]
	v_mul_f32_e32 v90, v90, v146
	v_mul_f32_e32 v91, v91, v146
	v_pk_fma_f32 v[90:91], v[166:167], v[90:91], v[214:215]
	v_cvt_pk_bf16_f32 v186, v88, v89
	v_cvt_pk_bf16_f32 v187, v90, v91
	v_mul_f32_e32 v84, v84, v146
	v_mul_f32_e32 v85, v85, v146
	v_pk_fma_f32 v[84:85], v[168:169], v[84:85], v[216:217]
	v_mul_f32_e32 v86, v86, v146
	v_mul_f32_e32 v87, v87, v146
	v_pk_fma_f32 v[86:87], v[170:171], v[86:87], v[218:219]
	v_cvt_pk_bf16_f32 v188, v84, v85
	v_cvt_pk_bf16_f32 v189, v86, v87
	v_mul_f32_e32 v80, v80, v146
	v_mul_f32_e32 v81, v81, v146
	v_pk_fma_f32 v[80:81], v[172:173], v[80:81], v[220:221]
	v_mul_f32_e32 v82, v82, v146
	v_mul_f32_e32 v83, v83, v146
	v_pk_fma_f32 v[82:83], v[174:175], v[82:83], v[222:223]
	v_cvt_pk_bf16_f32 v190, v80, v81
	v_cvt_pk_bf16_f32 v191, v82, v83
	v_add_u32_e32 v240, 0x10000, v247
	v_cndmask_b32_e64 v192, v186, v184, s[84:85]
	v_cndmask_b32_e64 v193, v187, v185, s[84:85]
	ds_bpermute_b32 v194, v241, v192
	ds_bpermute_b32 v195, v241, v193
	s_waitcnt lgkmcnt(0)
	v_cndmask_b32_e64 v176, v184, v194, s[84:85]
	v_cndmask_b32_e64 v177, v185, v195, s[84:85]
	v_cndmask_b32_e64 v178, v194, v186, s[84:85]
	v_cndmask_b32_e64 v179, v195, v187, s[84:85]
	global_store_dwordx4 v240, v[176:179], s[90:91] sc1
	v_cndmask_b32_e64 v192, v190, v188, s[84:85]
	v_cndmask_b32_e64 v193, v191, v189, s[84:85]
	ds_bpermute_b32 v194, v241, v192
	ds_bpermute_b32 v195, v241, v193
	s_waitcnt lgkmcnt(0)
	v_cndmask_b32_e64 v180, v188, v194, s[84:85]
	v_cndmask_b32_e64 v181, v189, v195, s[84:85]
	v_cndmask_b32_e64 v182, v194, v190, s[84:85]
	v_cndmask_b32_e64 v183, v195, v191, s[84:85]
	global_store_dwordx4 v240, v[180:183], s[90:91] offset:256 sc1
	v_mul_f32_e32 v76, v76, v147
	v_mul_f32_e32 v77, v77, v147
	v_pk_fma_f32 v[76:77], v[152:153], v[76:77], v[196:197]
	v_mul_f32_e32 v78, v78, v147
	v_mul_f32_e32 v79, v79, v147
	v_pk_fma_f32 v[78:79], v[154:155], v[78:79], v[198:199]
	v_cvt_pk_bf16_f32 v184, v76, v77
	v_cvt_pk_bf16_f32 v185, v78, v79
	v_mul_f32_e32 v72, v72, v147
	v_mul_f32_e32 v73, v73, v147
	v_pk_fma_f32 v[72:73], v[164:165], v[72:73], v[212:213]
	v_mul_f32_e32 v74, v74, v147
	v_mul_f32_e32 v75, v75, v147
	v_pk_fma_f32 v[74:75], v[166:167], v[74:75], v[214:215]
	v_cvt_pk_bf16_f32 v186, v72, v73
	v_cvt_pk_bf16_f32 v187, v74, v75
	v_mul_f32_e32 v68, v68, v147
	v_mul_f32_e32 v69, v69, v147
	v_pk_fma_f32 v[68:69], v[168:169], v[68:69], v[216:217]
	v_mul_f32_e32 v70, v70, v147
	v_mul_f32_e32 v71, v71, v147
	v_pk_fma_f32 v[70:71], v[170:171], v[70:71], v[218:219]
	v_cvt_pk_bf16_f32 v188, v68, v69
	v_cvt_pk_bf16_f32 v189, v70, v71
	v_mul_f32_e32 v64, v64, v147
	v_mul_f32_e32 v65, v65, v147
	v_pk_fma_f32 v[64:65], v[172:173], v[64:65], v[220:221]
	v_mul_f32_e32 v66, v66, v147
	v_mul_f32_e32 v67, v67, v147
	v_pk_fma_f32 v[66:67], v[174:175], v[66:67], v[222:223]
	v_cvt_pk_bf16_f32 v190, v64, v65
	v_cvt_pk_bf16_f32 v191, v66, v67
	v_add_u32_e32 v240, 0x18000, v247
	v_cndmask_b32_e64 v192, v186, v184, s[84:85]
	v_cndmask_b32_e64 v193, v187, v185, s[84:85]
	ds_bpermute_b32 v194, v241, v192
	ds_bpermute_b32 v195, v241, v193
	s_waitcnt lgkmcnt(0)
	v_cndmask_b32_e64 v176, v184, v194, s[84:85]
	v_cndmask_b32_e64 v177, v185, v195, s[84:85]
	v_cndmask_b32_e64 v178, v194, v186, s[84:85]
	v_cndmask_b32_e64 v179, v195, v187, s[84:85]
	global_store_dwordx4 v240, v[176:179], s[90:91] sc1
	v_cndmask_b32_e64 v192, v190, v188, s[84:85]
	v_cndmask_b32_e64 v193, v191, v189, s[84:85]
	ds_bpermute_b32 v194, v241, v192
	ds_bpermute_b32 v195, v241, v193
	s_waitcnt lgkmcnt(0)
	v_cndmask_b32_e64 v180, v188, v194, s[84:85]
	v_cndmask_b32_e64 v181, v189, v195, s[84:85]
	v_cndmask_b32_e64 v182, v194, v190, s[84:85]
	v_cndmask_b32_e64 v183, v195, v191, s[84:85]
	global_store_dwordx4 v240, v[180:183], s[90:91] offset:256 sc1
	v_mul_f32_e32 v60, v60, v148
	v_mul_f32_e32 v61, v61, v148
	v_pk_fma_f32 v[60:61], v[152:153], v[60:61], v[196:197]
	v_mul_f32_e32 v62, v62, v148
	v_mul_f32_e32 v63, v63, v148
	v_pk_fma_f32 v[62:63], v[154:155], v[62:63], v[198:199]
	v_cvt_pk_bf16_f32 v184, v60, v61
	v_cvt_pk_bf16_f32 v185, v62, v63
	v_mul_f32_e32 v56, v56, v148
	v_mul_f32_e32 v57, v57, v148
	v_pk_fma_f32 v[56:57], v[164:165], v[56:57], v[212:213]
	v_mul_f32_e32 v58, v58, v148
	v_mul_f32_e32 v59, v59, v148
	v_pk_fma_f32 v[58:59], v[166:167], v[58:59], v[214:215]
	v_cvt_pk_bf16_f32 v186, v56, v57
	v_cvt_pk_bf16_f32 v187, v58, v59
	v_mul_f32_e32 v52, v52, v148
	v_mul_f32_e32 v53, v53, v148
	v_pk_fma_f32 v[52:53], v[168:169], v[52:53], v[216:217]
	v_mul_f32_e32 v54, v54, v148
	v_mul_f32_e32 v55, v55, v148
	v_pk_fma_f32 v[54:55], v[170:171], v[54:55], v[218:219]
	v_cvt_pk_bf16_f32 v188, v52, v53
	v_cvt_pk_bf16_f32 v189, v54, v55
	v_mul_f32_e32 v48, v48, v148
	v_mul_f32_e32 v49, v49, v148
	v_pk_fma_f32 v[48:49], v[172:173], v[48:49], v[220:221]
	v_mul_f32_e32 v50, v50, v148
	v_mul_f32_e32 v51, v51, v148
	v_pk_fma_f32 v[50:51], v[174:175], v[50:51], v[222:223]
	v_cvt_pk_bf16_f32 v190, v48, v49
	v_cvt_pk_bf16_f32 v191, v50, v51
	v_add_u32_e32 v240, 0x40000, v247
	v_cndmask_b32_e64 v192, v186, v184, s[84:85]
	v_cndmask_b32_e64 v193, v187, v185, s[84:85]
	ds_bpermute_b32 v194, v241, v192
	ds_bpermute_b32 v195, v241, v193
	s_waitcnt lgkmcnt(0)
; __device__ __forceinline__ unsigned cvtpk_s(float lo, float hi) { f32x2_t v = {lo, hi}; bf16x2_t b = __builtin_convertvector(v, bf16x2_t); return __builtin_bit_cast(unsigned, b); }
; __device__ __forceinline__ u32x4 quad_swap(unsigned lo0, unsigned lo1, unsigned hi0, unsigned hi1, int fq, int& coloff) {
;     const bool odd = fq & 1;
;     const unsigned s0 = odd ? lo0 : hi0, s1 = odd ? lo1 : hi1;
;     const unsigned r0 = (unsigned)__shfl_xor((int)s0, 16), r1 = (unsigned)__shfl_xor((int)s1, 16);
;     coloff = odd ? 16 + 4 * (fq - 1) : 4 * fq;
;     u32x4 o; o.x = odd ? r0 : lo0; o.y = odd ? r1 : lo1; o.z = odd ? hi0 : r0; o.w = odd ? hi1 : r1; return o;
; __device__ __forceinline__ void modpass(const float* xs_main, const float* xs_ctx, const float* mod_l, const float* g, int i, bf16_t* H, int nrows, int gw, int NGW, int lane) {
;     ...
; #pragma unroll
;         for (int j = 0; j < 2; ++j) {
;             const f32x4 o0 = v[j][0] * rstd * gm[j][0] + sh[j][0], o1 = v[j][1] * rstd * gm[j][1] + sh[j][1];
;             u32x4 w; w.x = cvtpk_s(o0[0], o0[1]); w.y = cvtpk_s(o0[2], o0[3]); w.z = cvtpk_s(o1[0], o1[1]); w.w = cvtpk_s(o1[2], o1[3]);
;             *(u32x4*)(H + (size_t)row * D + 8 * lane + 512 * j) = w;
	v_cndmask_b32_e64 v176, v184, v194, s[84:85]
	v_cndmask_b32_e64 v177, v185, v195, s[84:85]
	v_cndmask_b32_e64 v178, v194, v186, s[84:85]
	v_cndmask_b32_e64 v179, v195, v187, s[84:85]
	global_store_dwordx4 v240, v[176:179], s[90:91] sc1
	v_cndmask_b32_e64 v192, v190, v188, s[84:85]
	v_cndmask_b32_e64 v193, v191, v189, s[84:85]
	ds_bpermute_b32 v194, v241, v192
	ds_bpermute_b32 v195, v241, v193
	s_waitcnt lgkmcnt(0)
	v_cndmask_b32_e64 v180, v188, v194, s[84:85]
	v_cndmask_b32_e64 v181, v189, v195, s[84:85]
	v_cndmask_b32_e64 v182, v194, v190, s[84:85]
	v_cndmask_b32_e64 v183, v195, v191, s[84:85]
	global_store_dwordx4 v240, v[180:183], s[90:91] offset:256 sc1
	v_mul_f32_e32 v44, v44, v149
	v_mul_f32_e32 v45, v45, v149
	v_pk_fma_f32 v[44:45], v[152:153], v[44:45], v[196:197]
	v_mul_f32_e32 v46, v46, v149
	v_mul_f32_e32 v47, v47, v149
	v_pk_fma_f32 v[46:47], v[154:155], v[46:47], v[198:199]
	v_cvt_pk_bf16_f32 v184, v44, v45
	v_cvt_pk_bf16_f32 v185, v46, v47
	v_mul_f32_e32 v40, v40, v149
	v_mul_f32_e32 v41, v41, v149
	v_pk_fma_f32 v[40:41], v[164:165], v[40:41], v[212:213]
	v_mul_f32_e32 v42, v42, v149
	v_mul_f32_e32 v43, v43, v149
	v_pk_fma_f32 v[42:43], v[166:167], v[42:43], v[214:215]
	v_cvt_pk_bf16_f32 v186, v40, v41
	v_cvt_pk_bf16_f32 v187, v42, v43
	v_mul_f32_e32 v36, v36, v149
	v_mul_f32_e32 v37, v37, v149
	v_pk_fma_f32 v[36:37], v[168:169], v[36:37], v[216:217]
	v_mul_f32_e32 v38, v38, v149
	v_mul_f32_e32 v39, v39, v149
	v_pk_fma_f32 v[38:39], v[170:171], v[38:39], v[218:219]
	v_cvt_pk_bf16_f32 v188, v36, v37
	v_cvt_pk_bf16_f32 v189, v38, v39
	v_mul_f32_e32 v32, v32, v149
	v_mul_f32_e32 v33, v33, v149
	v_pk_fma_f32 v[32:33], v[172:173], v[32:33], v[220:221]
	v_mul_f32_e32 v34, v34, v149
	v_mul_f32_e32 v35, v35, v149
	v_pk_fma_f32 v[34:35], v[174:175], v[34:35], v[222:223]
	v_cvt_pk_bf16_f32 v190, v32, v33
	v_cvt_pk_bf16_f32 v191, v34, v35
	v_add_u32_e32 v240, 0x48000, v247
	v_cndmask_b32_e64 v192, v186, v184, s[84:85]
	v_cndmask_b32_e64 v193, v187, v185, s[84:85]
	ds_bpermute_b32 v194, v241, v192
	ds_bpermute_b32 v195, v241, v193
	s_waitcnt lgkmcnt(0)
	v_cndmask_b32_e64 v176, v184, v194, s[84:85]
	v_cndmask_b32_e64 v177, v185, v195, s[84:85]
	v_cndmask_b32_e64 v178, v194, v186, s[84:85]
	v_cndmask_b32_e64 v179, v195, v187, s[84:85]
	global_store_dwordx4 v240, v[176:179], s[90:91] sc1
	v_cndmask_b32_e64 v192, v190, v188, s[84:85]
	v_cndmask_b32_e64 v193, v191, v189, s[84:85]
	ds_bpermute_b32 v194, v241, v192
	ds_bpermute_b32 v195, v241, v193
	s_waitcnt lgkmcnt(0)
	v_cndmask_b32_e64 v180, v188, v194, s[84:85]
	v_cndmask_b32_e64 v181, v189, v195, s[84:85]
	v_cndmask_b32_e64 v182, v194, v190, s[84:85]
	v_cndmask_b32_e64 v183, v195, v191, s[84:85]
	global_store_dwordx4 v240, v[180:183], s[90:91] offset:256 sc1
	v_mul_f32_e32 v28, v28, v150
	v_mul_f32_e32 v29, v29, v150
	v_pk_fma_f32 v[28:29], v[152:153], v[28:29], v[196:197]
	v_mul_f32_e32 v30, v30, v150
	v_mul_f32_e32 v31, v31, v150
	v_pk_fma_f32 v[30:31], v[154:155], v[30:31], v[198:199]
	v_cvt_pk_bf16_f32 v184, v28, v29
	v_cvt_pk_bf16_f32 v185, v30, v31
	v_mul_f32_e32 v24, v24, v150
	v_mul_f32_e32 v25, v25, v150
	v_pk_fma_f32 v[24:25], v[164:165], v[24:25], v[212:213]
	v_mul_f32_e32 v26, v26, v150
	v_mul_f32_e32 v27, v27, v150
	v_pk_fma_f32 v[26:27], v[166:167], v[26:27], v[214:215]
	v_cvt_pk_bf16_f32 v186, v24, v25
	v_cvt_pk_bf16_f32 v187, v26, v27
	v_mul_f32_e32 v20, v20, v150
	v_mul_f32_e32 v21, v21, v150
	v_pk_fma_f32 v[20:21], v[168:169], v[20:21], v[216:217]
	v_mul_f32_e32 v22, v22, v150
	v_mul_f32_e32 v23, v23, v150
	v_pk_fma_f32 v[22:23], v[170:171], v[22:23], v[218:219]
	v_cvt_pk_bf16_f32 v188, v20, v21
	v_cvt_pk_bf16_f32 v189, v22, v23
	v_mul_f32_e32 v16, v16, v150
	v_mul_f32_e32 v17, v17, v150
	v_pk_fma_f32 v[16:17], v[172:173], v[16:17], v[220:221]
	v_mul_f32_e32 v18, v18, v150
	v_mul_f32_e32 v19, v19, v150
	v_pk_fma_f32 v[18:19], v[174:175], v[18:19], v[222:223]
	v_cvt_pk_bf16_f32 v190, v16, v17
	v_cvt_pk_bf16_f32 v191, v18, v19
	v_add_u32_e32 v240, 0x50000, v247
	v_cndmask_b32_e64 v192, v186, v184, s[84:85]
	v_cndmask_b32_e64 v193, v187, v185, s[84:85]
	ds_bpermute_b32 v194, v241, v192
	ds_bpermute_b32 v195, v241, v193
	s_waitcnt lgkmcnt(0)
	v_cndmask_b32_e64 v176, v184, v194, s[84:85]
	v_cndmask_b32_e64 v177, v185, v195, s[84:85]
	v_cndmask_b32_e64 v178, v194, v186, s[84:85]
	v_cndmask_b32_e64 v179, v195, v187, s[84:85]
	global_store_dwordx4 v240, v[176:179], s[90:91] sc1
	v_cndmask_b32_e64 v192, v190, v188, s[84:85]
	v_cndmask_b32_e64 v193, v191, v189, s[84:85]
	ds_bpermute_b32 v194, v241, v192
	ds_bpermute_b32 v195, v241, v193
	s_waitcnt lgkmcnt(0)
	v_cndmask_b32_e64 v180, v188, v194, s[84:85]
	v_cndmask_b32_e64 v181, v189, v195, s[84:85]
	v_cndmask_b32_e64 v182, v194, v190, s[84:85]
	v_cndmask_b32_e64 v183, v195, v191, s[84:85]
	global_store_dwordx4 v240, v[180:183], s[90:91] offset:256 sc1
	v_mul_f32_e32 v12, v12, v151
	v_mul_f32_e32 v13, v13, v151
	v_pk_fma_f32 v[12:13], v[152:153], v[12:13], v[196:197]
	v_mul_f32_e32 v14, v14, v151
	v_mul_f32_e32 v15, v15, v151
	v_pk_fma_f32 v[14:15], v[154:155], v[14:15], v[198:199]
	v_cvt_pk_bf16_f32 v184, v12, v13
	v_cvt_pk_bf16_f32 v185, v14, v15
	v_mul_f32_e32 v8, v8, v151
	v_mul_f32_e32 v9, v9, v151
	v_pk_fma_f32 v[8:9], v[164:165], v[8:9], v[212:213]
	v_mul_f32_e32 v10, v10, v151
	v_mul_f32_e32 v11, v11, v151
	v_pk_fma_f32 v[10:11], v[166:167], v[10:11], v[214:215]
	v_cvt_pk_bf16_f32 v186, v8, v9
	v_cvt_pk_bf16_f32 v187, v10, v11
	v_mul_f32_e32 v4, v4, v151
	v_mul_f32_e32 v5, v5, v151
	v_pk_fma_f32 v[4:5], v[168:169], v[4:5], v[216:217]
	v_mul_f32_e32 v6, v6, v151
	v_mul_f32_e32 v7, v7, v151
	v_pk_fma_f32 v[6:7], v[170:171], v[6:7], v[218:219]
	v_cvt_pk_bf16_f32 v188, v4, v5
	v_cvt_pk_bf16_f32 v189, v6, v7
	v_mul_f32_e32 v0, v0, v151
	v_mul_f32_e32 v1, v1, v151
	v_pk_fma_f32 v[0:1], v[172:173], v[0:1], v[220:221]
	v_mul_f32_e32 v2, v2, v151
	v_mul_f32_e32 v3, v3, v151
	v_pk_fma_f32 v[2:3], v[174:175], v[2:3], v[222:223]
	v_cvt_pk_bf16_f32 v190, v0, v1
	v_cvt_pk_bf16_f32 v191, v2, v3
	v_add_u32_e32 v240, 0x58000, v247
	v_cndmask_b32_e64 v192, v186, v184, s[84:85]
	v_cndmask_b32_e64 v193, v187, v185, s[84:85]
	ds_bpermute_b32 v194, v241, v192
	ds_bpermute_b32 v195, v241, v193
	s_waitcnt lgkmcnt(0)
	v_cndmask_b32_e64 v176, v184, v194, s[84:85]
	v_cndmask_b32_e64 v177, v185, v195, s[84:85]
	v_cndmask_b32_e64 v178, v194, v186, s[84:85]
	v_cndmask_b32_e64 v179, v195, v187, s[84:85]
	global_store_dwordx4 v240, v[176:179], s[90:91] sc1
	v_cndmask_b32_e64 v192, v190, v188, s[84:85]
	v_cndmask_b32_e64 v193, v191, v189, s[84:85]
	ds_bpermute_b32 v194, v241, v192
	ds_bpermute_b32 v195, v241, v193
	s_waitcnt lgkmcnt(0)
	v_cndmask_b32_e64 v180, v188, v194, s[84:85]
	v_cndmask_b32_e64 v181, v189, v195, s[84:85]
	v_cndmask_b32_e64 v182, v194, v190, s[84:85]
	v_cndmask_b32_e64 v183, v195, v191, s[84:85]
	global_store_dwordx4 v240, v[180:183], s[90:91] offset:256 sc1
	s_and_b64 vcc, exec, s[10:11]
	s_mov_b64 s[10:11], -1
; #define PG8_BAR __builtin_amdgcn_s_barrier()
;     ...
;         if constexpr (ALIGN_EPI) { if (wr == 0) PG8_BAR; }
;         if constexpr (!Epi::AFTER_DRAIN) { E(acc, cur, wr, wc, fr, fq); S.done(cur); }
;         if (!has_next) break;
; #pragma unroll
;         for (int a = 0; a < 2; ++a)
; #pragma unroll
;             for (int b = 0; b < 2; ++b)
; #pragma unroll
;                 for (int m = 0; m < 4; ++m)
; #pragma unroll
;                     for (int n = 0; n < 2; ++n) acc[a][b][m][n] = (f32x4){0.f, 0.f, 0.f, 0.f};
;         cur = nxt; cA = nA; cB = nB; ++ui;
;         if constexpr (ALIGN_EPI) { if (wr == 1) PG8_BAR; }
.Lfmdone_e:
	s_cbranch_vccnz .LBB0_1551
	s_andn2_b64 vcc, exec, s[16:17]
	s_cbranch_vccnz .LBB0_1550
	s_barrier
	s_branch .LBB0_1550

;     __device__ __forceinline__ void operator()(const f32x4 (&acc)[2][2][4][2], const Unit& u, int wr, int wc, int fr, int fq) const {
;         const int cond = u.pm < 64 ? 0 : (u.pm < 128 ? 1 : 2);
;         const float* gate = gate_l + cond * 9216;
;         const int col0 = u.pn * BM + wc * 32 + 4 * fq;
;         f32x4 gv[2][2];
; #pragma unroll
;         for (int bj = 0; bj < 2; ++bj)
; #pragma unroll
;             for (int n = 0; n < 2; ++n) gv[bj][n] = *(const f32x4*)(gate + col0 + bj * HALF + n * 16) * coef;
; #pragma unroll
;         for (int ai = 0; ai < 2; ++ai)
; #pragma unroll
;             for (int m = 0; m < 4; ++m) {
;                 const int row = u.pm * BM + ai * HALF + wr * 64 + m * 16 + fr;
;                 const float* s = row < MX_ ? src_main + (size_t)row * D_ : src_ctx + (size_t)(row - MX_) * D_;
;                 float* d = row < MX_ ? dst_main + (size_t)row * D_ : dst_ctx + (size_t)(row - MX_) * D_;
; #pragma unroll
;                 for (int bj = 0; bj < 2; ++bj)
; #pragma unroll
;                     for (int n = 0; n < 2; ++n) { const int off = col0 + bj * HALF + n * 16; const f32x4 xo = *(const f32x4*)(s + off); *(f32x4*)(d + off) = xo + gv[bj][n] * acc[ai][bj][m][n]; }
.LBB0_2337:
	s_andn2_b64 vcc, exec, s[6:7]
	s_cbranch_vccnz .Lfmsel_f
	s_cmpk_lt_i32 s26, 0x80
	s_cselect_b32 s17, s63, 0x4800
	s_cmp_gt_i32 s26, 63
	s_cselect_b32 s17, s17, 0
	s_lshl_b32 s17, s17, 2
	s_add_u32 s34, s55, s17
	s_addc_u32 s35, s56, 0
	s_load_dwordx2 s[92:93], s[0:1], 0x30
	s_load_dwordx2 s[76:77], s[0:1], 0xb8
	v_lshl_add_u32 v156, s26, 8, v158
	v_lshl_or_b32 v157, s64, 8, v160
	v_lshlrev_b32_e32 v200, 2, v157
	v_lshl_add_u32 v201, v156, 12, v200
	global_load_dwordx4 v[196:199], v200, s[34:35]
	global_load_dwordx4 v[208:211], v200, s[34:35] offset:64
	global_load_dwordx4 v[212:215], v200, s[34:35] offset:512
	global_load_dwordx4 v[216:219], v200, s[34:35] offset:576
	v_add_u32_e32 v205, 0x10000, v201
	v_add_u32_e32 v207, 0x20000, v201
	v_add_u32_e32 v220, 0x30000, v201
	v_add_u32_e32 v221, 0x80000, v201
	v_add_u32_e32 v222, 0x90000, v201
	v_add_u32_e32 v223, 0xa0000, v201
	v_add_u32_e32 v224, 0xb0000, v201
	global_load_dwordx4 v[128:131], v201, s[8:9]
	global_load_dwordx4 v[132:135], v201, s[8:9] offset:64
	global_load_dwordx4 v[136:139], v201, s[8:9] offset:512
	global_load_dwordx4 v[140:143], v201, s[8:9] offset:576
	global_load_dwordx4 v[164:167], v205, s[8:9]
	global_load_dwordx4 v[168:171], v205, s[8:9] offset:64
	global_load_dwordx4 v[172:175], v205, s[8:9] offset:512
	global_load_dwordx4 v[176:179], v205, s[8:9] offset:576
	global_load_dwordx4 v[180:183], v207, s[8:9]
	global_load_dwordx4 v[184:187], v207, s[8:9] offset:64
	global_load_dwordx4 v[188:191], v207, s[8:9] offset:512
	global_load_dwordx4 v[192:195], v207, s[8:9] offset:576
	s_waitcnt vmcnt(12)
	s_waitcnt vmcnt(11)
	v_pk_fma_f32 v[124:125], v[124:125], v[196:197], v[128:129]
	v_pk_fma_f32 v[126:127], v[126:127], v[198:199], v[130:131]
	v_mul_f32_e32 v225, v124, v124
	v_fmac_f32_e32 v225, v125, v125
	v_fmac_f32_e32 v225, v126, v126
	v_fmac_f32_e32 v225, v127, v127
	s_waitcnt vmcnt(10)
	v_pk_fma_f32 v[120:121], v[120:121], v[208:209], v[132:133]
	v_pk_fma_f32 v[122:123], v[122:123], v[210:211], v[134:135]
	v_fmac_f32_e32 v225, v120, v120
	v_fmac_f32_e32 v225, v121, v121
	v_fmac_f32_e32 v225, v122, v122
	v_fmac_f32_e32 v225, v123, v123
	s_waitcnt vmcnt(9)
	v_pk_fma_f32 v[116:117], v[116:117], v[212:213], v[136:137]
	v_pk_fma_f32 v[118:119], v[118:119], v[214:215], v[138:139]
	v_fmac_f32_e32 v225, v116, v116
	v_fmac_f32_e32 v225, v117, v117
	v_fmac_f32_e32 v225, v118, v118
	v_fmac_f32_e32 v225, v119, v119
	s_waitcnt vmcnt(8)
	v_pk_fma_f32 v[112:113], v[112:113], v[216:217], v[140:141]
	v_pk_fma_f32 v[114:115], v[114:115], v[218:219], v[142:143]
	v_fmac_f32_e32 v225, v112, v112
	v_fmac_f32_e32 v225, v113, v113
	v_fmac_f32_e32 v225, v114, v114
	v_fmac_f32_e32 v225, v115, v115
	global_store_dwordx4 v201, v[124:127], s[8:9]
	global_store_dwordx4 v201, v[120:123], s[8:9] offset:64
	global_store_dwordx4 v201, v[116:119], s[8:9] offset:512
	global_store_dwordx4 v201, v[112:115], s[8:9] offset:576
	global_load_dwordx4 v[128:131], v220, s[8:9]
	global_load_dwordx4 v[132:135], v220, s[8:9] offset:64
	global_load_dwordx4 v[136:139], v220, s[8:9] offset:512
	global_load_dwordx4 v[140:143], v220, s[8:9] offset:576
	s_waitcnt vmcnt(15)
	v_pk_fma_f32 v[108:109], v[108:109], v[196:197], v[164:165]
	v_pk_fma_f32 v[110:111], v[110:111], v[198:199], v[166:167]
	v_mul_f32_e32 v226, v108, v108
	v_fmac_f32_e32 v226, v109, v109
	v_fmac_f32_e32 v226, v110, v110
	v_fmac_f32_e32 v226, v111, v111
	s_waitcnt vmcnt(14)
	v_pk_fma_f32 v[104:105], v[104:105], v[208:209], v[168:169]
	v_pk_fma_f32 v[106:107], v[106:107], v[210:211], v[170:171]
	v_fmac_f32_e32 v226, v104, v104
	v_fmac_f32_e32 v226, v105, v105
	v_fmac_f32_e32 v226, v106, v106
	v_fmac_f32_e32 v226, v107, v107
	s_waitcnt vmcnt(13)
	v_pk_fma_f32 v[100:101], v[100:101], v[212:213], v[172:173]
	v_pk_fma_f32 v[102:103], v[102:103], v[214:215], v[174:175]
	v_fmac_f32_e32 v226, v100, v100
	v_fmac_f32_e32 v226, v101, v101
	v_fmac_f32_e32 v226, v102, v102
	v_fmac_f32_e32 v226, v103, v103
	s_waitcnt vmcnt(12)
	v_pk_fma_f32 v[96:97], v[96:97], v[216:217], v[176:177]
	v_pk_fma_f32 v[98:99], v[98:99], v[218:219], v[178:179]
	v_fmac_f32_e32 v226, v96, v96
	v_fmac_f32_e32 v226, v97, v97
	v_fmac_f32_e32 v226, v98, v98
	v_fmac_f32_e32 v226, v99, v99
	global_store_dwordx4 v205, v[108:111], s[8:9]
	global_store_dwordx4 v205, v[104:107], s[8:9] offset:64
	global_store_dwordx4 v205, v[100:103], s[8:9] offset:512
	global_store_dwordx4 v205, v[96:99], s[8:9] offset:576
	global_load_dwordx4 v[164:167], v221, s[8:9]
	global_load_dwordx4 v[168:171], v221, s[8:9] offset:64
	global_load_dwordx4 v[172:175], v221, s[8:9] offset:512
	global_load_dwordx4 v[176:179], v221, s[8:9] offset:576
	s_waitcnt vmcnt(19)
	v_pk_fma_f32 v[92:93], v[92:93], v[196:197], v[180:181]
	v_pk_fma_f32 v[94:95], v[94:95], v[198:199], v[182:183]
	v_mul_f32_e32 v227, v92, v92
	v_fmac_f32_e32 v227, v93, v93
	v_fmac_f32_e32 v227, v94, v94
	v_fmac_f32_e32 v227, v95, v95
	s_waitcnt vmcnt(18)
	v_pk_fma_f32 v[88:89], v[88:89], v[208:209], v[184:185]
	v_pk_fma_f32 v[90:91], v[90:91], v[210:211], v[186:187]
	v_fmac_f32_e32 v227, v88, v88
	v_fmac_f32_e32 v227, v89, v89
	v_fmac_f32_e32 v227, v90, v90
	v_fmac_f32_e32 v227, v91, v91
	s_waitcnt vmcnt(17)
	v_pk_fma_f32 v[84:85], v[84:85], v[212:213], v[188:189]
	v_pk_fma_f32 v[86:87], v[86:87], v[214:215], v[190:191]
	v_fmac_f32_e32 v227, v84, v84
	v_fmac_f32_e32 v227, v85, v85
	v_fmac_f32_e32 v227, v86, v86
	v_fmac_f32_e32 v227, v87, v87
	s_waitcnt vmcnt(16)
;     __device__ __forceinline__ void operator()(const f32x4 (&acc)[2][2][4][2], const Unit& u, int wr, int wc, int fr, int fq) const {
;     ...
;         for (int ai = 0; ai < 2; ++ai)
; #pragma unroll
;             for (int m = 0; m < 4; ++m) {
;                 const int row = u.pm * BM + ai * HALF + wr * 64 + m * 16 + fr;
;                 const float* s = row < MX_ ? src_main + (size_t)row * D_ : src_ctx + (size_t)(row - MX_) * D_;
;                 float* d = row < MX_ ? dst_main + (size_t)row * D_ : dst_ctx + (size_t)(row - MX_) * D_;
; #pragma unroll
;                 for (int bj = 0; bj < 2; ++bj)
; #pragma unroll
;                     for (int n = 0; n < 2; ++n) { const int off = col0 + bj * HALF + n * 16; const f32x4 xo = *(const f32x4*)(s + off); *(f32x4*)(d + off) = xo + gv[bj][n] * acc[ai][bj][m][n]; }
	v_pk_fma_f32 v[80:81], v[80:81], v[216:217], v[192:193]
	v_pk_fma_f32 v[82:83], v[82:83], v[218:219], v[194:195]
	v_fmac_f32_e32 v227, v80, v80
	v_fmac_f32_e32 v227, v81, v81
	v_fmac_f32_e32 v227, v82, v82
	v_fmac_f32_e32 v227, v83, v83
	global_store_dwordx4 v207, v[92:95], s[8:9]
	global_store_dwordx4 v207, v[88:91], s[8:9] offset:64
	global_store_dwordx4 v207, v[84:87], s[8:9] offset:512
	global_store_dwordx4 v207, v[80:83], s[8:9] offset:576
	global_load_dwordx4 v[180:183], v222, s[8:9]
	global_load_dwordx4 v[184:187], v222, s[8:9] offset:64
	global_load_dwordx4 v[188:191], v222, s[8:9] offset:512
	global_load_dwordx4 v[192:195], v222, s[8:9] offset:576
	s_waitcnt vmcnt(19)
	v_pk_fma_f32 v[76:77], v[76:77], v[196:197], v[128:129]
	v_pk_fma_f32 v[78:79], v[78:79], v[198:199], v[130:131]
	v_mul_f32_e32 v228, v76, v76
	v_fmac_f32_e32 v228, v77, v77
	v_fmac_f32_e32 v228, v78, v78
	v_fmac_f32_e32 v228, v79, v79
	s_waitcnt vmcnt(18)
	v_pk_fma_f32 v[72:73], v[72:73], v[208:209], v[132:133]
	v_pk_fma_f32 v[74:75], v[74:75], v[210:211], v[134:135]
	v_fmac_f32_e32 v228, v72, v72
	v_fmac_f32_e32 v228, v73, v73
	v_fmac_f32_e32 v228, v74, v74
	v_fmac_f32_e32 v228, v75, v75
	s_waitcnt vmcnt(17)
	v_pk_fma_f32 v[68:69], v[68:69], v[212:213], v[136:137]
	v_pk_fma_f32 v[70:71], v[70:71], v[214:215], v[138:139]
	v_fmac_f32_e32 v228, v68, v68
	v_fmac_f32_e32 v228, v69, v69
	v_fmac_f32_e32 v228, v70, v70
	v_fmac_f32_e32 v228, v71, v71
	s_waitcnt vmcnt(16)
	v_pk_fma_f32 v[64:65], v[64:65], v[216:217], v[140:141]
	v_pk_fma_f32 v[66:67], v[66:67], v[218:219], v[142:143]
	v_fmac_f32_e32 v228, v64, v64
	v_fmac_f32_e32 v228, v65, v65
	v_fmac_f32_e32 v228, v66, v66
	v_fmac_f32_e32 v228, v67, v67
	global_store_dwordx4 v220, v[76:79], s[8:9]
	global_store_dwordx4 v220, v[72:75], s[8:9] offset:64
	global_store_dwordx4 v220, v[68:71], s[8:9] offset:512
	global_store_dwordx4 v220, v[64:67], s[8:9] offset:576
	global_load_dwordx4 v[128:131], v223, s[8:9]
	global_load_dwordx4 v[132:135], v223, s[8:9] offset:64
	global_load_dwordx4 v[136:139], v223, s[8:9] offset:512
	global_load_dwordx4 v[140:143], v223, s[8:9] offset:576
	s_waitcnt vmcnt(19)
	v_pk_fma_f32 v[60:61], v[60:61], v[196:197], v[164:165]
	v_pk_fma_f32 v[62:63], v[62:63], v[198:199], v[166:167]
	v_mul_f32_e32 v229, v60, v60
	v_fmac_f32_e32 v229, v61, v61
	v_fmac_f32_e32 v229, v62, v62
	v_fmac_f32_e32 v229, v63, v63
	s_waitcnt vmcnt(18)
	v_pk_fma_f32 v[56:57], v[56:57], v[208:209], v[168:169]
	v_pk_fma_f32 v[58:59], v[58:59], v[210:211], v[170:171]
	v_fmac_f32_e32 v229, v56, v56
	v_fmac_f32_e32 v229, v57, v57
	v_fmac_f32_e32 v229, v58, v58
	v_fmac_f32_e32 v229, v59, v59
	s_waitcnt vmcnt(17)
	v_pk_fma_f32 v[52:53], v[52:53], v[212:213], v[172:173]
	v_pk_fma_f32 v[54:55], v[54:55], v[214:215], v[174:175]
	v_fmac_f32_e32 v229, v52, v52
	v_fmac_f32_e32 v229, v53, v53
	v_fmac_f32_e32 v229, v54, v54
	v_fmac_f32_e32 v229, v55, v55
	s_waitcnt vmcnt(16)
	v_pk_fma_f32 v[48:49], v[48:49], v[216:217], v[176:177]
	v_pk_fma_f32 v[50:51], v[50:51], v[218:219], v[178:179]
	v_fmac_f32_e32 v229, v48, v48
	v_fmac_f32_e32 v229, v49, v49
	v_fmac_f32_e32 v229, v50, v50
	v_fmac_f32_e32 v229, v51, v51
	global_store_dwordx4 v221, v[60:63], s[8:9]
	global_store_dwordx4 v221, v[56:59], s[8:9] offset:64
	global_store_dwordx4 v221, v[52:55], s[8:9] offset:512
	global_store_dwordx4 v221, v[48:51], s[8:9] offset:576
	global_load_dwordx4 v[164:167], v224, s[8:9]
	global_load_dwordx4 v[168:171], v224, s[8:9] offset:64
	global_load_dwordx4 v[172:175], v224, s[8:9] offset:512
	global_load_dwordx4 v[176:179], v224, s[8:9] offset:576
	s_waitcnt vmcnt(19)
	v_pk_fma_f32 v[44:45], v[44:45], v[196:197], v[180:181]
	v_pk_fma_f32 v[46:47], v[46:47], v[198:199], v[182:183]
	v_mul_f32_e32 v230, v44, v44
	v_fmac_f32_e32 v230, v45, v45
	v_fmac_f32_e32 v230, v46, v46
	v_fmac_f32_e32 v230, v47, v47
	s_waitcnt vmcnt(18)
	v_pk_fma_f32 v[40:41], v[40:41], v[208:209], v[184:185]
	v_pk_fma_f32 v[42:43], v[42:43], v[210:211], v[186:187]
	v_fmac_f32_e32 v230, v40, v40
	v_fmac_f32_e32 v230, v41, v41
	v_fmac_f32_e32 v230, v42, v42
	v_fmac_f32_e32 v230, v43, v43
	s_waitcnt vmcnt(17)
	v_pk_fma_f32 v[36:37], v[36:37], v[212:213], v[188:189]
	v_pk_fma_f32 v[38:39], v[38:39], v[214:215], v[190:191]
	v_fmac_f32_e32 v230, v36, v36
	v_fmac_f32_e32 v230, v37, v37
	v_fmac_f32_e32 v230, v38, v38
	v_fmac_f32_e32 v230, v39, v39
	s_waitcnt vmcnt(16)
	v_pk_fma_f32 v[32:33], v[32:33], v[216:217], v[192:193]
	v_pk_fma_f32 v[34:35], v[34:35], v[218:219], v[194:195]
	v_fmac_f32_e32 v230, v32, v32
	v_fmac_f32_e32 v230, v33, v33
	v_fmac_f32_e32 v230, v34, v34
	v_fmac_f32_e32 v230, v35, v35
	global_store_dwordx4 v222, v[44:47], s[8:9]
	global_store_dwordx4 v222, v[40:43], s[8:9] offset:64
	global_store_dwordx4 v222, v[36:39], s[8:9] offset:512
	global_store_dwordx4 v222, v[32:35], s[8:9] offset:576
	s_waitcnt vmcnt(15)
	v_pk_fma_f32 v[28:29], v[28:29], v[196:197], v[128:129]
	v_pk_fma_f32 v[30:31], v[30:31], v[198:199], v[130:131]
	v_mul_f32_e32 v231, v28, v28
	v_fmac_f32_e32 v231, v29, v29
	v_fmac_f32_e32 v231, v30, v30
	v_fmac_f32_e32 v231, v31, v31
	s_waitcnt vmcnt(14)
;     __device__ __forceinline__ void operator()(const f32x4 (&acc)[2][2][4][2], const Unit& u, int wr, int wc, int fr, int fq) const {
;     ...
;         for (int ai = 0; ai < 2; ++ai)
; #pragma unroll
;             for (int m = 0; m < 4; ++m) {
;                 const int row = u.pm * BM + ai * HALF + wr * 64 + m * 16 + fr;
;                 const float* s = row < MX_ ? src_main + (size_t)row * D_ : src_ctx + (size_t)(row - MX_) * D_;
;                 float* d = row < MX_ ? dst_main + (size_t)row * D_ : dst_ctx + (size_t)(row - MX_) * D_;
; #pragma unroll
;                 for (int bj = 0; bj < 2; ++bj)
; #pragma unroll
;                     for (int n = 0; n < 2; ++n) { const int off = col0 + bj * HALF + n * 16; const f32x4 xo = *(const f32x4*)(s + off); *(f32x4*)(d + off) = xo + gv[bj][n] * acc[ai][bj][m][n]; }
; __device__ __forceinline__ void modpass(const float* xs_main, const float* xs_ctx, const float* mod_l, const float* g, int i, bf16_t* H, int nrows, int gw, int NGW, int lane) {
;     ...
;         float ss = 0.f;
; #pragma unroll
;         for (int j = 0; j < 2; ++j)
; #pragma unroll
;             for (int q = 0; q < 2; ++q) ss += (v[j][q][0] * v[j][q][0] + v[j][q][1] * v[j][q][1]) + (v[j][q][2] * v[j][q][2] + v[j][q][3] * v[j][q][3]);
;         const float rstd = 1.0f / sqrtf(wave_sum(ss) * (1.0f / D) + EPS);
	v_pk_fma_f32 v[24:25], v[24:25], v[208:209], v[132:133]
	v_pk_fma_f32 v[26:27], v[26:27], v[210:211], v[134:135]
	v_fmac_f32_e32 v231, v24, v24
	v_fmac_f32_e32 v231, v25, v25
	v_fmac_f32_e32 v231, v26, v26
	v_fmac_f32_e32 v231, v27, v27
	s_waitcnt vmcnt(13)
	v_pk_fma_f32 v[20:21], v[20:21], v[212:213], v[136:137]
	v_pk_fma_f32 v[22:23], v[22:23], v[214:215], v[138:139]
	v_fmac_f32_e32 v231, v20, v20
	v_fmac_f32_e32 v231, v21, v21
	v_fmac_f32_e32 v231, v22, v22
	v_fmac_f32_e32 v231, v23, v23
	s_waitcnt vmcnt(12)
	v_pk_fma_f32 v[16:17], v[16:17], v[216:217], v[140:141]
	v_pk_fma_f32 v[18:19], v[18:19], v[218:219], v[142:143]
	v_fmac_f32_e32 v231, v16, v16
	v_fmac_f32_e32 v231, v17, v17
	v_fmac_f32_e32 v231, v18, v18
	v_fmac_f32_e32 v231, v19, v19
	global_store_dwordx4 v223, v[28:31], s[8:9]
	global_store_dwordx4 v223, v[24:27], s[8:9] offset:64
	global_store_dwordx4 v223, v[20:23], s[8:9] offset:512
	global_store_dwordx4 v223, v[16:19], s[8:9] offset:576
	s_waitcnt vmcnt(11)
	v_pk_fma_f32 v[12:13], v[12:13], v[196:197], v[164:165]
	v_pk_fma_f32 v[14:15], v[14:15], v[198:199], v[166:167]
	v_mul_f32_e32 v232, v12, v12
	v_fmac_f32_e32 v232, v13, v13
	v_fmac_f32_e32 v232, v14, v14
	v_fmac_f32_e32 v232, v15, v15
	s_waitcnt vmcnt(10)
	v_pk_fma_f32 v[8:9], v[8:9], v[208:209], v[168:169]
	v_pk_fma_f32 v[10:11], v[10:11], v[210:211], v[170:171]
	v_fmac_f32_e32 v232, v8, v8
	v_fmac_f32_e32 v232, v9, v9
	v_fmac_f32_e32 v232, v10, v10
	v_fmac_f32_e32 v232, v11, v11
	s_waitcnt vmcnt(9)
	v_pk_fma_f32 v[4:5], v[4:5], v[212:213], v[172:173]
	v_pk_fma_f32 v[6:7], v[6:7], v[214:215], v[174:175]
	v_fmac_f32_e32 v232, v4, v4
	v_fmac_f32_e32 v232, v5, v5
	v_fmac_f32_e32 v232, v6, v6
	v_fmac_f32_e32 v232, v7, v7
	s_waitcnt vmcnt(8)
	v_pk_fma_f32 v[0:1], v[0:1], v[216:217], v[176:177]
	v_pk_fma_f32 v[2:3], v[2:3], v[218:219], v[178:179]
	v_fmac_f32_e32 v232, v0, v0
	v_fmac_f32_e32 v232, v1, v1
	v_fmac_f32_e32 v232, v2, v2
	v_fmac_f32_e32 v232, v3, v3
	global_store_dwordx4 v224, v[12:15], s[8:9]
	global_store_dwordx4 v224, v[8:11], s[8:9] offset:64
	global_store_dwordx4 v224, v[4:7], s[8:9] offset:512
	global_store_dwordx4 v224, v[0:3], s[8:9] offset:576
	v_mbcnt_lo_u32_b32 v233, -1, 0
	v_mbcnt_hi_u32_b32 v233, -1, v233
	v_xor_b32_e32 v234, 16, v233
	v_xor_b32_e32 v235, 32, v233
	v_lshlrev_b32_e32 v234, 2, v234
	v_lshlrev_b32_e32 v235, 2, v235
	s_waitcnt lgkmcnt(0)
	ds_bpermute_b32 v128, v234, v225
	ds_bpermute_b32 v129, v234, v226
	ds_bpermute_b32 v130, v234, v227
	ds_bpermute_b32 v131, v234, v228
	ds_bpermute_b32 v132, v234, v229
	ds_bpermute_b32 v133, v234, v230
	ds_bpermute_b32 v134, v234, v231
	ds_bpermute_b32 v135, v234, v232
	s_waitcnt lgkmcnt(7)
	v_add_f32_e32 v225, v225, v128
	s_waitcnt lgkmcnt(6)
	v_add_f32_e32 v226, v226, v129
	s_waitcnt lgkmcnt(5)
	v_add_f32_e32 v227, v227, v130
	s_waitcnt lgkmcnt(4)
	v_add_f32_e32 v228, v228, v131
	s_waitcnt lgkmcnt(3)
	v_add_f32_e32 v229, v229, v132
	s_waitcnt lgkmcnt(2)
	v_add_f32_e32 v230, v230, v133
	s_waitcnt lgkmcnt(1)
	v_add_f32_e32 v231, v231, v134
	s_waitcnt lgkmcnt(0)
	v_add_f32_e32 v232, v232, v135
	ds_bpermute_b32 v128, v235, v225
	ds_bpermute_b32 v129, v235, v226
	ds_bpermute_b32 v130, v235, v227
	ds_bpermute_b32 v131, v235, v228
	ds_bpermute_b32 v132, v235, v229
	ds_bpermute_b32 v133, v235, v230
	ds_bpermute_b32 v134, v235, v231
	ds_bpermute_b32 v135, v235, v232
	s_waitcnt lgkmcnt(7)
	v_add_f32_e32 v225, v225, v128
	s_waitcnt lgkmcnt(6)
	v_add_f32_e32 v226, v226, v129
	s_waitcnt lgkmcnt(5)
	v_add_f32_e32 v227, v227, v130
	s_waitcnt lgkmcnt(4)
	v_add_f32_e32 v228, v228, v131
	s_waitcnt lgkmcnt(3)
	v_add_f32_e32 v229, v229, v132
	s_waitcnt lgkmcnt(2)
	v_add_f32_e32 v230, v230, v133
	s_waitcnt lgkmcnt(1)
	v_add_f32_e32 v231, v231, v134
	s_waitcnt lgkmcnt(0)
	v_add_f32_e32 v232, v232, v135
	v_lshlrev_b32_e32 v236, 2, v156
	s_add_u32 s90, s76, 0x6500000
	s_addc_u32 s91, s77, 0
	s_add_u32 s76, s76, 0x31a8000
	s_addc_u32 s77, s77, 0
	s_lshl_b32 s83, s26, 6
	s_add_u32 s78, s76, s83
	s_addc_u32 s79, s77, 0
	s_add_u32 s78, s78, 0x20000
	s_addc_u32 s79, s79, 0
	s_mov_b64 s[80:81], exec
	s_mov_b64 exec, 0xffff
	global_atomic_add_f32 v236, v225, s[76:77]
	global_atomic_add_f32 v236, v226, s[76:77] offset:64
	global_atomic_add_f32 v236, v227, s[76:77] offset:128
	global_atomic_add_f32 v236, v228, s[76:77] offset:192
	global_atomic_add_f32 v236, v229, s[76:77] offset:512
	global_atomic_add_f32 v236, v230, s[76:77] offset:576
	global_atomic_add_f32 v236, v231, s[76:77] offset:640
	global_atomic_add_f32 v236, v232, s[76:77] offset:704
	s_mov_b64 exec, s[80:81]
	s_add_u32 s86, s34, 0x1000
	s_addc_u32 s87, s35, 0
	s_add_u32 s88, s86, 0x1000
	s_addc_u32 s89, s87, 0
	s_add_u32 s92, s92, 0x5000
	s_addc_u32 s93, s93, 0
	s_mov_b32 s84, 0xffff0000
	s_mov_b32 s85, 0xffff0000
	s_waitcnt vmcnt(0)
	s_barrier
	v_readfirstlane_b32 s83, v206
	v_mov_b32_e32 v237, 0
	v_mov_b32_e32 v238, 1
	s_cmp_lg_u32 s83, 0
	s_cbranch_scc1 .Lfmf_wait_done
	s_mov_b64 exec, 1
	global_atomic_add v237, v238, s[78:79]
	s_mov_b32 s82, 0

; __device__ __forceinline__ unsigned cvtpk_s(float lo, float hi) { f32x2_t v = {lo, hi}; bf16x2_t b = __builtin_convertvector(v, bf16x2_t); return __builtin_bit_cast(unsigned, b); }
; __device__ __forceinline__ void modpass(const float* xs_main, const float* xs_ctx, const float* mod_l, const float* g, int i, bf16_t* H, int nrows, int gw, int NGW, int lane) {
;     ...
;         if (cond != cur) { cur = cond; const float* shift = mod_l + cond * 9216 + 3 * i * 1024; const float* scale = shift + 1024;
; #pragma unroll
;             for (int j = 0; j < 2; ++j)
; #pragma unroll
;                 for (int q = 0; q < 2; ++q) { const int c = 8 * lane + 512 * j + 4 * q; gm[j][q] = *(const f32x4*)(g + c) * (*(const f32x4*)(scale + c) + 1.0f); sh[j][q] = *(const f32x4*)(shift + c); } }
;         float ss = 0.f;
; #pragma unroll
;         for (int j = 0; j < 2; ++j)
; #pragma unroll
;             for (int q = 0; q < 2; ++q) ss += (v[j][q][0] * v[j][q][0] + v[j][q][1] * v[j][q][1]) + (v[j][q][2] * v[j][q][2] + v[j][q][3] * v[j][q][3]);
;         const float rstd = 1.0f / sqrtf(wave_sum(ss) * (1.0f / D) + EPS);
; #pragma unroll
;         for (int j = 0; j < 2; ++j) {
;             const f32x4 o0 = v[j][0] * rstd * gm[j][0] + sh[j][0], o1 = v[j][1] * rstd * gm[j][1] + sh[j][1];
;             u32x4 w; w.x = cvtpk_s(o0[0], o0[1]); w.y = cvtpk_s(o0[2], o0[3]); w.z = cvtpk_s(o1[0], o1[1]); w.w = cvtpk_s(o1[2], o1[3]);
;             *(u32x4*)(H + (size_t)row * D + 8 * lane + 512 * j) = w;
.Lfmf_wait_done:
	s_barrier
	global_load_dword v132, v236, s[76:77] sc1
	global_load_dword v133, v236, s[76:77] offset:64 sc1
	global_load_dword v134, v236, s[76:77] offset:128 sc1
	global_load_dword v135, v236, s[76:77] offset:192 sc1
	global_load_dword v136, v236, s[76:77] offset:512 sc1
	global_load_dword v137, v236, s[76:77] offset:576 sc1
	global_load_dword v138, v236, s[76:77] offset:640 sc1
	global_load_dword v139, v236, s[76:77] offset:704 sc1
	global_load_dwordx4 v[196:199], v200, s[86:87]
	global_load_dwordx4 v[208:211], v200, s[86:87] offset:64
	global_load_dwordx4 v[212:215], v200, s[86:87] offset:512
	global_load_dwordx4 v[216:219], v200, s[86:87] offset:576
	global_load_dwordx4 v[140:143], v200, s[88:89]
	global_load_dwordx4 v[164:167], v200, s[88:89] offset:64
	global_load_dwordx4 v[168:171], v200, s[88:89] offset:512
	global_load_dwordx4 v[172:175], v200, s[88:89] offset:576
	global_load_dwordx4 v[176:179], v200, s[92:93]
	global_load_dwordx4 v[180:183], v200, s[92:93] offset:64
	global_load_dwordx4 v[184:187], v200, s[92:93] offset:512
	global_load_dwordx4 v[188:191], v200, s[92:93] offset:576
	v_mov_b32_e32 v233, 12
	v_cndmask_b32_e64 v233, 0, v233, s[84:85]
	v_add_u32_e32 v233, v233, v157
	v_lshlrev_b32_e32 v233, 1, v233
	v_lshl_add_u32 v240, v156, 11, v233
	v_mov_b32_e32 v233, 0x358637bd
	s_waitcnt vmcnt(0)
	v_fmamk_f32 v132, v132, 0x3a800000, v233
	v_fmamk_f32 v133, v133, 0x3a800000, v233
	v_fmamk_f32 v134, v134, 0x3a800000, v233
	v_fmamk_f32 v135, v135, 0x3a800000, v233
	v_fmamk_f32 v136, v136, 0x3a800000, v233
	v_fmamk_f32 v137, v137, 0x3a800000, v233
	v_fmamk_f32 v138, v138, 0x3a800000, v233
	v_fmamk_f32 v139, v139, 0x3a800000, v233
	v_rsq_f32_e32 v132, v132
	v_rsq_f32_e32 v133, v133
	v_rsq_f32_e32 v134, v134
	v_rsq_f32_e32 v135, v135
	v_rsq_f32_e32 v136, v136
	v_rsq_f32_e32 v137, v137
	v_rsq_f32_e32 v138, v138
	v_rsq_f32_e32 v139, v139
	v_pk_add_f32 v[140:141], v[140:141], 1.0 op_sel_hi:[1,0]
	v_pk_mul_f32 v[140:141], v[176:177], v[140:141]
	v_pk_add_f32 v[142:143], v[142:143], 1.0 op_sel_hi:[1,0]
	v_pk_mul_f32 v[142:143], v[178:179], v[142:143]
	v_pk_add_f32 v[164:165], v[164:165], 1.0 op_sel_hi:[1,0]
	v_pk_mul_f32 v[164:165], v[180:181], v[164:165]
	v_pk_add_f32 v[166:167], v[166:167], 1.0 op_sel_hi:[1,0]
	v_pk_mul_f32 v[166:167], v[182:183], v[166:167]
	v_pk_add_f32 v[168:169], v[168:169], 1.0 op_sel_hi:[1,0]
	v_pk_mul_f32 v[168:169], v[184:185], v[168:169]
	v_pk_add_f32 v[170:171], v[170:171], 1.0 op_sel_hi:[1,0]
	v_pk_mul_f32 v[170:171], v[186:187], v[170:171]
	v_pk_add_f32 v[172:173], v[172:173], 1.0 op_sel_hi:[1,0]
	v_pk_mul_f32 v[172:173], v[188:189], v[172:173]
	v_pk_add_f32 v[174:175], v[174:175], 1.0 op_sel_hi:[1,0]
	v_pk_mul_f32 v[174:175], v[190:191], v[174:175]
	v_mul_f32_e32 v124, v124, v132
	v_mul_f32_e32 v125, v125, v132
	v_pk_fma_f32 v[124:125], v[140:141], v[124:125], v[196:197]
	v_mul_f32_e32 v126, v126, v132
	v_mul_f32_e32 v127, v127, v132
	v_pk_fma_f32 v[126:127], v[142:143], v[126:127], v[198:199]
	v_cvt_pk_bf16_f32 v184, v124, v125
	v_cvt_pk_bf16_f32 v185, v126, v127
	v_mul_f32_e32 v120, v120, v132
	v_mul_f32_e32 v121, v121, v132
	v_pk_fma_f32 v[120:121], v[164:165], v[120:121], v[208:209]
	v_mul_f32_e32 v122, v122, v132
	v_mul_f32_e32 v123, v123, v132
	v_pk_fma_f32 v[122:123], v[166:167], v[122:123], v[210:211]
	v_cvt_pk_bf16_f32 v186, v120, v121
	v_cvt_pk_bf16_f32 v187, v122, v123
	v_mul_f32_e32 v116, v116, v132
	v_mul_f32_e32 v117, v117, v132
	v_pk_fma_f32 v[116:117], v[168:169], v[116:117], v[212:213]
	v_mul_f32_e32 v118, v118, v132
	v_mul_f32_e32 v119, v119, v132
	v_pk_fma_f32 v[118:119], v[170:171], v[118:119], v[214:215]
	v_cvt_pk_bf16_f32 v188, v116, v117
	v_cvt_pk_bf16_f32 v189, v118, v119
	v_mul_f32_e32 v112, v112, v132
	v_mul_f32_e32 v113, v113, v132
	v_pk_fma_f32 v[112:113], v[172:173], v[112:113], v[216:217]
	v_mul_f32_e32 v114, v114, v132
	v_mul_f32_e32 v115, v115, v132
	v_pk_fma_f32 v[114:115], v[174:175], v[114:115], v[218:219]
	v_cvt_pk_bf16_f32 v190, v112, v113
	v_cvt_pk_bf16_f32 v191, v114, v115
	v_mov_b32_e32 v233, v240
	v_cndmask_b32_e64 v192, v186, v184, s[84:85]
	v_cndmask_b32_e64 v193, v187, v185, s[84:85]
	ds_bpermute_b32 v194, v234, v192
	ds_bpermute_b32 v195, v234, v193
	s_waitcnt lgkmcnt(0)
	v_cndmask_b32_e64 v176, v184, v194, s[84:85]
	v_cndmask_b32_e64 v177, v185, v195, s[84:85]
	v_cndmask_b32_e64 v178, v194, v186, s[84:85]
	v_cndmask_b32_e64 v179, v195, v187, s[84:85]
	global_store_dwordx4 v233, v[176:179], s[90:91]
	v_cndmask_b32_e64 v192, v190, v188, s[84:85]
	v_cndmask_b32_e64 v193, v191, v189, s[84:85]
	ds_bpermute_b32 v194, v234, v192
	ds_bpermute_b32 v195, v234, v193
	s_waitcnt lgkmcnt(0)
	v_cndmask_b32_e64 v180, v188, v194, s[84:85]
	v_cndmask_b32_e64 v181, v189, v195, s[84:85]
	v_cndmask_b32_e64 v182, v194, v190, s[84:85]
	v_cndmask_b32_e64 v183, v195, v191, s[84:85]
	global_store_dwordx4 v233, v[180:183], s[90:91] offset:256
	v_mul_f32_e32 v108, v108, v133
	v_mul_f32_e32 v109, v109, v133
	v_pk_fma_f32 v[108:109], v[140:141], v[108:109], v[196:197]
	v_mul_f32_e32 v110, v110, v133
	v_mul_f32_e32 v111, v111, v133
	v_pk_fma_f32 v[110:111], v[142:143], v[110:111], v[198:199]
	v_cvt_pk_bf16_f32 v184, v108, v109
	v_cvt_pk_bf16_f32 v185, v110, v111
	v_mul_f32_e32 v104, v104, v133
	v_mul_f32_e32 v105, v105, v133
	v_pk_fma_f32 v[104:105], v[164:165], v[104:105], v[208:209]
	v_mul_f32_e32 v106, v106, v133
	v_mul_f32_e32 v107, v107, v133
	v_pk_fma_f32 v[106:107], v[166:167], v[106:107], v[210:211]
	v_cvt_pk_bf16_f32 v186, v104, v105
	v_cvt_pk_bf16_f32 v187, v106, v107
	v_mul_f32_e32 v100, v100, v133
	v_mul_f32_e32 v101, v101, v133
	v_pk_fma_f32 v[100:101], v[168:169], v[100:101], v[212:213]
	v_mul_f32_e32 v102, v102, v133
	v_mul_f32_e32 v103, v103, v133
	v_pk_fma_f32 v[102:103], v[170:171], v[102:103], v[214:215]
	v_cvt_pk_bf16_f32 v188, v100, v101
	v_cvt_pk_bf16_f32 v189, v102, v103
	v_mul_f32_e32 v96, v96, v133
	v_mul_f32_e32 v97, v97, v133
	v_pk_fma_f32 v[96:97], v[172:173], v[96:97], v[216:217]
	v_mul_f32_e32 v98, v98, v133
	v_mul_f32_e32 v99, v99, v133
	v_pk_fma_f32 v[98:99], v[174:175], v[98:99], v[218:219]
	v_cvt_pk_bf16_f32 v190, v96, v97
	v_cvt_pk_bf16_f32 v191, v98, v99
	v_add_u32_e32 v233, 0x8000, v240
	v_cndmask_b32_e64 v192, v186, v184, s[84:85]
	v_cndmask_b32_e64 v193, v187, v185, s[84:85]
	ds_bpermute_b32 v194, v234, v192
	ds_bpermute_b32 v195, v234, v193
	s_waitcnt lgkmcnt(0)
; __device__ __forceinline__ unsigned cvtpk_s(float lo, float hi) { f32x2_t v = {lo, hi}; bf16x2_t b = __builtin_convertvector(v, bf16x2_t); return __builtin_bit_cast(unsigned, b); }
; __device__ __forceinline__ u32x4 quad_swap(unsigned lo0, unsigned lo1, unsigned hi0, unsigned hi1, int fq, int& coloff) {
;     const bool odd = fq & 1;
;     const unsigned s0 = odd ? lo0 : hi0, s1 = odd ? lo1 : hi1;
;     const unsigned r0 = (unsigned)__shfl_xor((int)s0, 16), r1 = (unsigned)__shfl_xor((int)s1, 16);
;     coloff = odd ? 16 + 4 * (fq - 1) : 4 * fq;
;     u32x4 o; o.x = odd ? r0 : lo0; o.y = odd ? r1 : lo1; o.z = odd ? hi0 : r0; o.w = odd ? hi1 : r1; return o;
; __device__ __forceinline__ void modpass(const float* xs_main, const float* xs_ctx, const float* mod_l, const float* g, int i, bf16_t* H, int nrows, int gw, int NGW, int lane) {
;     ...
; #pragma unroll
;         for (int j = 0; j < 2; ++j) {
;             const f32x4 o0 = v[j][0] * rstd * gm[j][0] + sh[j][0], o1 = v[j][1] * rstd * gm[j][1] + sh[j][1];
;             u32x4 w; w.x = cvtpk_s(o0[0], o0[1]); w.y = cvtpk_s(o0[2], o0[3]); w.z = cvtpk_s(o1[0], o1[1]); w.w = cvtpk_s(o1[2], o1[3]);
;             *(u32x4*)(H + (size_t)row * D + 8 * lane + 512 * j) = w;
	v_cndmask_b32_e64 v176, v184, v194, s[84:85]
	v_cndmask_b32_e64 v177, v185, v195, s[84:85]
	v_cndmask_b32_e64 v178, v194, v186, s[84:85]
	v_cndmask_b32_e64 v179, v195, v187, s[84:85]
	global_store_dwordx4 v233, v[176:179], s[90:91]
	v_cndmask_b32_e64 v192, v190, v188, s[84:85]
	v_cndmask_b32_e64 v193, v191, v189, s[84:85]
	ds_bpermute_b32 v194, v234, v192
	ds_bpermute_b32 v195, v234, v193
	s_waitcnt lgkmcnt(0)
	v_cndmask_b32_e64 v180, v188, v194, s[84:85]
	v_cndmask_b32_e64 v181, v189, v195, s[84:85]
	v_cndmask_b32_e64 v182, v194, v190, s[84:85]
	v_cndmask_b32_e64 v183, v195, v191, s[84:85]
	global_store_dwordx4 v233, v[180:183], s[90:91] offset:256
	v_mul_f32_e32 v92, v92, v134
	v_mul_f32_e32 v93, v93, v134
	v_pk_fma_f32 v[92:93], v[140:141], v[92:93], v[196:197]
	v_mul_f32_e32 v94, v94, v134
	v_mul_f32_e32 v95, v95, v134
	v_pk_fma_f32 v[94:95], v[142:143], v[94:95], v[198:199]
	v_cvt_pk_bf16_f32 v184, v92, v93
	v_cvt_pk_bf16_f32 v185, v94, v95
	v_mul_f32_e32 v88, v88, v134
	v_mul_f32_e32 v89, v89, v134
	v_pk_fma_f32 v[88:89], v[164:165], v[88:89], v[208:209]
	v_mul_f32_e32 v90, v90, v134
	v_mul_f32_e32 v91, v91, v134
	v_pk_fma_f32 v[90:91], v[166:167], v[90:91], v[210:211]
	v_cvt_pk_bf16_f32 v186, v88, v89
	v_cvt_pk_bf16_f32 v187, v90, v91
	v_mul_f32_e32 v84, v84, v134
	v_mul_f32_e32 v85, v85, v134
	v_pk_fma_f32 v[84:85], v[168:169], v[84:85], v[212:213]
	v_mul_f32_e32 v86, v86, v134
	v_mul_f32_e32 v87, v87, v134
	v_pk_fma_f32 v[86:87], v[170:171], v[86:87], v[214:215]
	v_cvt_pk_bf16_f32 v188, v84, v85
	v_cvt_pk_bf16_f32 v189, v86, v87
	v_mul_f32_e32 v80, v80, v134
	v_mul_f32_e32 v81, v81, v134
	v_pk_fma_f32 v[80:81], v[172:173], v[80:81], v[216:217]
	v_mul_f32_e32 v82, v82, v134
	v_mul_f32_e32 v83, v83, v134
	v_pk_fma_f32 v[82:83], v[174:175], v[82:83], v[218:219]
	v_cvt_pk_bf16_f32 v190, v80, v81
	v_cvt_pk_bf16_f32 v191, v82, v83
	v_add_u32_e32 v233, 0x10000, v240
	v_cndmask_b32_e64 v192, v186, v184, s[84:85]
	v_cndmask_b32_e64 v193, v187, v185, s[84:85]
	ds_bpermute_b32 v194, v234, v192
	ds_bpermute_b32 v195, v234, v193
	s_waitcnt lgkmcnt(0)
	v_cndmask_b32_e64 v176, v184, v194, s[84:85]
	v_cndmask_b32_e64 v177, v185, v195, s[84:85]
	v_cndmask_b32_e64 v178, v194, v186, s[84:85]
	v_cndmask_b32_e64 v179, v195, v187, s[84:85]
	global_store_dwordx4 v233, v[176:179], s[90:91]
	v_cndmask_b32_e64 v192, v190, v188, s[84:85]
	v_cndmask_b32_e64 v193, v191, v189, s[84:85]
	ds_bpermute_b32 v194, v234, v192
	ds_bpermute_b32 v195, v234, v193
	s_waitcnt lgkmcnt(0)
	v_cndmask_b32_e64 v180, v188, v194, s[84:85]
	v_cndmask_b32_e64 v181, v189, v195, s[84:85]
	v_cndmask_b32_e64 v182, v194, v190, s[84:85]
	v_cndmask_b32_e64 v183, v195, v191, s[84:85]
	global_store_dwordx4 v233, v[180:183], s[90:91] offset:256
	v_mul_f32_e32 v76, v76, v135
	v_mul_f32_e32 v77, v77, v135
	v_pk_fma_f32 v[76:77], v[140:141], v[76:77], v[196:197]
	v_mul_f32_e32 v78, v78, v135
	v_mul_f32_e32 v79, v79, v135
	v_pk_fma_f32 v[78:79], v[142:143], v[78:79], v[198:199]
	v_cvt_pk_bf16_f32 v184, v76, v77
	v_cvt_pk_bf16_f32 v185, v78, v79
	v_mul_f32_e32 v72, v72, v135
	v_mul_f32_e32 v73, v73, v135
	v_pk_fma_f32 v[72:73], v[164:165], v[72:73], v[208:209]
	v_mul_f32_e32 v74, v74, v135
	v_mul_f32_e32 v75, v75, v135
	v_pk_fma_f32 v[74:75], v[166:167], v[74:75], v[210:211]
	v_cvt_pk_bf16_f32 v186, v72, v73
	v_cvt_pk_bf16_f32 v187, v74, v75
	v_mul_f32_e32 v68, v68, v135
	v_mul_f32_e32 v69, v69, v135
	v_pk_fma_f32 v[68:69], v[168:169], v[68:69], v[212:213]
	v_mul_f32_e32 v70, v70, v135
	v_mul_f32_e32 v71, v71, v135
	v_pk_fma_f32 v[70:71], v[170:171], v[70:71], v[214:215]
	v_cvt_pk_bf16_f32 v188, v68, v69
	v_cvt_pk_bf16_f32 v189, v70, v71
	v_mul_f32_e32 v64, v64, v135
	v_mul_f32_e32 v65, v65, v135
	v_pk_fma_f32 v[64:65], v[172:173], v[64:65], v[216:217]
	v_mul_f32_e32 v66, v66, v135
	v_mul_f32_e32 v67, v67, v135
	v_pk_fma_f32 v[66:67], v[174:175], v[66:67], v[218:219]
	v_cvt_pk_bf16_f32 v190, v64, v65
	v_cvt_pk_bf16_f32 v191, v66, v67
	v_add_u32_e32 v233, 0x18000, v240
	v_cndmask_b32_e64 v192, v186, v184, s[84:85]
	v_cndmask_b32_e64 v193, v187, v185, s[84:85]
	ds_bpermute_b32 v194, v234, v192
	ds_bpermute_b32 v195, v234, v193
	s_waitcnt lgkmcnt(0)
	v_cndmask_b32_e64 v176, v184, v194, s[84:85]
	v_cndmask_b32_e64 v177, v185, v195, s[84:85]
	v_cndmask_b32_e64 v178, v194, v186, s[84:85]
	v_cndmask_b32_e64 v179, v195, v187, s[84:85]
	global_store_dwordx4 v233, v[176:179], s[90:91]
	v_cndmask_b32_e64 v192, v190, v188, s[84:85]
	v_cndmask_b32_e64 v193, v191, v189, s[84:85]
	ds_bpermute_b32 v194, v234, v192
	ds_bpermute_b32 v195, v234, v193
	s_waitcnt lgkmcnt(0)
	v_cndmask_b32_e64 v180, v188, v194, s[84:85]
	v_cndmask_b32_e64 v181, v189, v195, s[84:85]
	v_cndmask_b32_e64 v182, v194, v190, s[84:85]
	v_cndmask_b32_e64 v183, v195, v191, s[84:85]
	global_store_dwordx4 v233, v[180:183], s[90:91] offset:256
	v_mul_f32_e32 v60, v60, v136
	v_mul_f32_e32 v61, v61, v136
	v_pk_fma_f32 v[60:61], v[140:141], v[60:61], v[196:197]
	v_mul_f32_e32 v62, v62, v136
	v_mul_f32_e32 v63, v63, v136
	v_pk_fma_f32 v[62:63], v[142:143], v[62:63], v[198:199]
	v_cvt_pk_bf16_f32 v184, v60, v61
	v_cvt_pk_bf16_f32 v185, v62, v63
	v_mul_f32_e32 v56, v56, v136
	v_mul_f32_e32 v57, v57, v136
	v_pk_fma_f32 v[56:57], v[164:165], v[56:57], v[208:209]
	v_mul_f32_e32 v58, v58, v136
	v_mul_f32_e32 v59, v59, v136
	v_pk_fma_f32 v[58:59], v[166:167], v[58:59], v[210:211]
	v_cvt_pk_bf16_f32 v186, v56, v57
	v_cvt_pk_bf16_f32 v187, v58, v59
	v_mul_f32_e32 v52, v52, v136
	v_mul_f32_e32 v53, v53, v136
	v_pk_fma_f32 v[52:53], v[168:169], v[52:53], v[212:213]
	v_mul_f32_e32 v54, v54, v136
	v_mul_f32_e32 v55, v55, v136
	v_pk_fma_f32 v[54:55], v[170:171], v[54:55], v[214:215]
	v_cvt_pk_bf16_f32 v188, v52, v53
	v_cvt_pk_bf16_f32 v189, v54, v55
	v_mul_f32_e32 v48, v48, v136
	v_mul_f32_e32 v49, v49, v136
	v_pk_fma_f32 v[48:49], v[172:173], v[48:49], v[216:217]
	v_mul_f32_e32 v50, v50, v136
	v_mul_f32_e32 v51, v51, v136
	v_pk_fma_f32 v[50:51], v[174:175], v[50:51], v[218:219]
	v_cvt_pk_bf16_f32 v190, v48, v49
	v_cvt_pk_bf16_f32 v191, v50, v51
	v_add_u32_e32 v233, 0x40000, v240
	v_cndmask_b32_e64 v192, v186, v184, s[84:85]
	v_cndmask_b32_e64 v193, v187, v185, s[84:85]
	ds_bpermute_b32 v194, v234, v192
	ds_bpermute_b32 v195, v234, v193
	s_waitcnt lgkmcnt(0)
; __device__ __forceinline__ unsigned cvtpk_s(float lo, float hi) { f32x2_t v = {lo, hi}; bf16x2_t b = __builtin_convertvector(v, bf16x2_t); return __builtin_bit_cast(unsigned, b); }
; __device__ __forceinline__ u32x4 quad_swap(unsigned lo0, unsigned lo1, unsigned hi0, unsigned hi1, int fq, int& coloff) {
;     const bool odd = fq & 1;
;     const unsigned s0 = odd ? lo0 : hi0, s1 = odd ? lo1 : hi1;
;     const unsigned r0 = (unsigned)__shfl_xor((int)s0, 16), r1 = (unsigned)__shfl_xor((int)s1, 16);
;     coloff = odd ? 16 + 4 * (fq - 1) : 4 * fq;
;     u32x4 o; o.x = odd ? r0 : lo0; o.y = odd ? r1 : lo1; o.z = odd ? hi0 : r0; o.w = odd ? hi1 : r1; return o;
; __device__ __forceinline__ void modpass(const float* xs_main, const float* xs_ctx, const float* mod_l, const float* g, int i, bf16_t* H, int nrows, int gw, int NGW, int lane) {
;     ...
; #pragma unroll
;         for (int j = 0; j < 2; ++j) {
;             const f32x4 o0 = v[j][0] * rstd * gm[j][0] + sh[j][0], o1 = v[j][1] * rstd * gm[j][1] + sh[j][1];
;             u32x4 w; w.x = cvtpk_s(o0[0], o0[1]); w.y = cvtpk_s(o0[2], o0[3]); w.z = cvtpk_s(o1[0], o1[1]); w.w = cvtpk_s(o1[2], o1[3]);
;             *(u32x4*)(H + (size_t)row * D + 8 * lane + 512 * j) = w;
	v_cndmask_b32_e64 v176, v184, v194, s[84:85]
	v_cndmask_b32_e64 v177, v185, v195, s[84:85]
	v_cndmask_b32_e64 v178, v194, v186, s[84:85]
	v_cndmask_b32_e64 v179, v195, v187, s[84:85]
	global_store_dwordx4 v233, v[176:179], s[90:91]
	v_cndmask_b32_e64 v192, v190, v188, s[84:85]
	v_cndmask_b32_e64 v193, v191, v189, s[84:85]
	ds_bpermute_b32 v194, v234, v192
	ds_bpermute_b32 v195, v234, v193
	s_waitcnt lgkmcnt(0)
	v_cndmask_b32_e64 v180, v188, v194, s[84:85]
	v_cndmask_b32_e64 v181, v189, v195, s[84:85]
	v_cndmask_b32_e64 v182, v194, v190, s[84:85]
	v_cndmask_b32_e64 v183, v195, v191, s[84:85]
	global_store_dwordx4 v233, v[180:183], s[90:91] offset:256
	v_mul_f32_e32 v44, v44, v137
	v_mul_f32_e32 v45, v45, v137
	v_pk_fma_f32 v[44:45], v[140:141], v[44:45], v[196:197]
	v_mul_f32_e32 v46, v46, v137
	v_mul_f32_e32 v47, v47, v137
	v_pk_fma_f32 v[46:47], v[142:143], v[46:47], v[198:199]
	v_cvt_pk_bf16_f32 v184, v44, v45
	v_cvt_pk_bf16_f32 v185, v46, v47
	v_mul_f32_e32 v40, v40, v137
	v_mul_f32_e32 v41, v41, v137
	v_pk_fma_f32 v[40:41], v[164:165], v[40:41], v[208:209]
	v_mul_f32_e32 v42, v42, v137
	v_mul_f32_e32 v43, v43, v137
	v_pk_fma_f32 v[42:43], v[166:167], v[42:43], v[210:211]
	v_cvt_pk_bf16_f32 v186, v40, v41
	v_cvt_pk_bf16_f32 v187, v42, v43
	v_mul_f32_e32 v36, v36, v137
	v_mul_f32_e32 v37, v37, v137
	v_pk_fma_f32 v[36:37], v[168:169], v[36:37], v[212:213]
	v_mul_f32_e32 v38, v38, v137
	v_mul_f32_e32 v39, v39, v137
	v_pk_fma_f32 v[38:39], v[170:171], v[38:39], v[214:215]
	v_cvt_pk_bf16_f32 v188, v36, v37
	v_cvt_pk_bf16_f32 v189, v38, v39
	v_mul_f32_e32 v32, v32, v137
	v_mul_f32_e32 v33, v33, v137
	v_pk_fma_f32 v[32:33], v[172:173], v[32:33], v[216:217]
	v_mul_f32_e32 v34, v34, v137
	v_mul_f32_e32 v35, v35, v137
	v_pk_fma_f32 v[34:35], v[174:175], v[34:35], v[218:219]
	v_cvt_pk_bf16_f32 v190, v32, v33
	v_cvt_pk_bf16_f32 v191, v34, v35
	v_add_u32_e32 v233, 0x48000, v240
	v_cndmask_b32_e64 v192, v186, v184, s[84:85]
	v_cndmask_b32_e64 v193, v187, v185, s[84:85]
	ds_bpermute_b32 v194, v234, v192
	ds_bpermute_b32 v195, v234, v193
	s_waitcnt lgkmcnt(0)
	v_cndmask_b32_e64 v176, v184, v194, s[84:85]
	v_cndmask_b32_e64 v177, v185, v195, s[84:85]
	v_cndmask_b32_e64 v178, v194, v186, s[84:85]
	v_cndmask_b32_e64 v179, v195, v187, s[84:85]
	global_store_dwordx4 v233, v[176:179], s[90:91]
	v_cndmask_b32_e64 v192, v190, v188, s[84:85]
	v_cndmask_b32_e64 v193, v191, v189, s[84:85]
	ds_bpermute_b32 v194, v234, v192
	ds_bpermute_b32 v195, v234, v193
	s_waitcnt lgkmcnt(0)
	v_cndmask_b32_e64 v180, v188, v194, s[84:85]
	v_cndmask_b32_e64 v181, v189, v195, s[84:85]
	v_cndmask_b32_e64 v182, v194, v190, s[84:85]
	v_cndmask_b32_e64 v183, v195, v191, s[84:85]
	global_store_dwordx4 v233, v[180:183], s[90:91] offset:256
	v_mul_f32_e32 v28, v28, v138
	v_mul_f32_e32 v29, v29, v138
	v_pk_fma_f32 v[28:29], v[140:141], v[28:29], v[196:197]
	v_mul_f32_e32 v30, v30, v138
	v_mul_f32_e32 v31, v31, v138
	v_pk_fma_f32 v[30:31], v[142:143], v[30:31], v[198:199]
	v_cvt_pk_bf16_f32 v184, v28, v29
	v_cvt_pk_bf16_f32 v185, v30, v31
	v_mul_f32_e32 v24, v24, v138
	v_mul_f32_e32 v25, v25, v138
	v_pk_fma_f32 v[24:25], v[164:165], v[24:25], v[208:209]
	v_mul_f32_e32 v26, v26, v138
	v_mul_f32_e32 v27, v27, v138
	v_pk_fma_f32 v[26:27], v[166:167], v[26:27], v[210:211]
	v_cvt_pk_bf16_f32 v186, v24, v25
	v_cvt_pk_bf16_f32 v187, v26, v27
	v_mul_f32_e32 v20, v20, v138
	v_mul_f32_e32 v21, v21, v138
	v_pk_fma_f32 v[20:21], v[168:169], v[20:21], v[212:213]
	v_mul_f32_e32 v22, v22, v138
	v_mul_f32_e32 v23, v23, v138
	v_pk_fma_f32 v[22:23], v[170:171], v[22:23], v[214:215]
	v_cvt_pk_bf16_f32 v188, v20, v21
	v_cvt_pk_bf16_f32 v189, v22, v23
	v_mul_f32_e32 v16, v16, v138
	v_mul_f32_e32 v17, v17, v138
	v_pk_fma_f32 v[16:17], v[172:173], v[16:17], v[216:217]
	v_mul_f32_e32 v18, v18, v138
	v_mul_f32_e32 v19, v19, v138
	v_pk_fma_f32 v[18:19], v[174:175], v[18:19], v[218:219]
	v_cvt_pk_bf16_f32 v190, v16, v17
	v_cvt_pk_bf16_f32 v191, v18, v19
	v_add_u32_e32 v233, 0x50000, v240
	v_cndmask_b32_e64 v192, v186, v184, s[84:85]
	v_cndmask_b32_e64 v193, v187, v185, s[84:85]
	ds_bpermute_b32 v194, v234, v192
	ds_bpermute_b32 v195, v234, v193
	s_waitcnt lgkmcnt(0)
	v_cndmask_b32_e64 v176, v184, v194, s[84:85]
	v_cndmask_b32_e64 v177, v185, v195, s[84:85]
	v_cndmask_b32_e64 v178, v194, v186, s[84:85]
	v_cndmask_b32_e64 v179, v195, v187, s[84:85]
	global_store_dwordx4 v233, v[176:179], s[90:91]
	v_cndmask_b32_e64 v192, v190, v188, s[84:85]
	v_cndmask_b32_e64 v193, v191, v189, s[84:85]
	ds_bpermute_b32 v194, v234, v192
	ds_bpermute_b32 v195, v234, v193
	s_waitcnt lgkmcnt(0)
	v_cndmask_b32_e64 v180, v188, v194, s[84:85]
	v_cndmask_b32_e64 v181, v189, v195, s[84:85]
	v_cndmask_b32_e64 v182, v194, v190, s[84:85]
	v_cndmask_b32_e64 v183, v195, v191, s[84:85]
	global_store_dwordx4 v233, v[180:183], s[90:91] offset:256
	v_mul_f32_e32 v12, v12, v139
	v_mul_f32_e32 v13, v13, v139
	v_pk_fma_f32 v[12:13], v[140:141], v[12:13], v[196:197]
	v_mul_f32_e32 v14, v14, v139
	v_mul_f32_e32 v15, v15, v139
	v_pk_fma_f32 v[14:15], v[142:143], v[14:15], v[198:199]
	v_cvt_pk_bf16_f32 v184, v12, v13
	v_cvt_pk_bf16_f32 v185, v14, v15
	v_mul_f32_e32 v8, v8, v139
	v_mul_f32_e32 v9, v9, v139
	v_pk_fma_f32 v[8:9], v[164:165], v[8:9], v[208:209]
	v_mul_f32_e32 v10, v10, v139
	v_mul_f32_e32 v11, v11, v139
	v_pk_fma_f32 v[10:11], v[166:167], v[10:11], v[210:211]
	v_cvt_pk_bf16_f32 v186, v8, v9
	v_cvt_pk_bf16_f32 v187, v10, v11
	v_mul_f32_e32 v4, v4, v139
	v_mul_f32_e32 v5, v5, v139
	v_pk_fma_f32 v[4:5], v[168:169], v[4:5], v[212:213]
	v_mul_f32_e32 v6, v6, v139
	v_mul_f32_e32 v7, v7, v139
	v_pk_fma_f32 v[6:7], v[170:171], v[6:7], v[214:215]
	v_cvt_pk_bf16_f32 v188, v4, v5
	v_cvt_pk_bf16_f32 v189, v6, v7
	v_mul_f32_e32 v0, v0, v139
	v_mul_f32_e32 v1, v1, v139
	v_pk_fma_f32 v[0:1], v[172:173], v[0:1], v[216:217]
	v_mul_f32_e32 v2, v2, v139
	v_mul_f32_e32 v3, v3, v139
	v_pk_fma_f32 v[2:3], v[174:175], v[2:3], v[218:219]
	v_cvt_pk_bf16_f32 v190, v0, v1
	v_cvt_pk_bf16_f32 v191, v2, v3
	v_add_u32_e32 v233, 0x58000, v240
	v_cndmask_b32_e64 v192, v186, v184, s[84:85]
	v_cndmask_b32_e64 v193, v187, v185, s[84:85]
	ds_bpermute_b32 v194, v234, v192
	ds_bpermute_b32 v195, v234, v193
	s_waitcnt lgkmcnt(0)
	v_cndmask_b32_e64 v176, v184, v194, s[84:85]
	v_cndmask_b32_e64 v177, v185, v195, s[84:85]
	v_cndmask_b32_e64 v178, v194, v186, s[84:85]
	v_cndmask_b32_e64 v179, v195, v187, s[84:85]
	global_store_dwordx4 v233, v[176:179], s[90:91]
	v_cndmask_b32_e64 v192, v190, v188, s[84:85]
	v_cndmask_b32_e64 v193, v191, v189, s[84:85]
	ds_bpermute_b32 v194, v234, v192
	ds_bpermute_b32 v195, v234, v193
	s_waitcnt lgkmcnt(0)
	v_cndmask_b32_e64 v180, v188, v194, s[84:85]
	v_cndmask_b32_e64 v181, v189, v195, s[84:85]
	v_cndmask_b32_e64 v182, v194, v190, s[84:85]
	v_cndmask_b32_e64 v183, v195, v191, s[84:85]
	global_store_dwordx4 v233, v[180:183], s[90:91] offset:256
	s_andn2_b64 vcc, exec, s[6:7]
	s_mov_b64 s[6:7], -1
	s_branch .Lfmdone_f
;     __device__ __forceinline__ void operator()(const f32x4 (&acc)[2][2][4][2], const Unit& u, int wr, int wc, int fr, int fq) const {
;         const int cond = u.pm < 64 ? 0 : (u.pm < 128 ? 1 : 2);
;         const float* gate = gate_l + cond * 9216;
;         const int col0 = u.pn * BM + wc * 32 + 4 * fq;
;         f32x4 gv[2][2];
; #pragma unroll
;         for (int bj = 0; bj < 2; ++bj)
; #pragma unroll
;             for (int n = 0; n < 2; ++n) gv[bj][n] = *(const f32x4*)(gate + col0 + bj * HALF + n * 16) * coef;
; #pragma unroll
;         for (int ai = 0; ai < 2; ++ai)
; #pragma unroll
;             for (int m = 0; m < 4; ++m) {
;                 const int row = u.pm * BM + ai * HALF + wr * 64 + m * 16 + fr;
;                 const float* s = row < MX_ ? src_main + (size_t)row * D_ : src_ctx + (size_t)(row - MX_) * D_;
;                 float* d = row < MX_ ? dst_main + (size_t)row * D_ : dst_ctx + (size_t)(row - MX_) * D_;
; #pragma unroll
;                 for (int bj = 0; bj < 2; ++bj)
; #pragma unroll
;                     for (int n = 0; n < 2; ++n) { const int off = col0 + bj * HALF + n * 16; const f32x4 xo = *(const f32x4*)(s + off); *(f32x4*)(d + off) = xo + gv[bj][n] * acc[ai][bj][m][n]; }
.Lfmsel_f:
	s_cmpk_lt_i32 s26, 0x80
	s_cselect_b32 s17, s63, 0x4800
	s_cmp_gt_i32 s26, 63
	s_cselect_b32 s17, s17, 0
	s_lshl_b32 s17, s17, 2
	s_add_u32 s34, s55, s17
	s_addc_u32 s35, s56, 0
	s_load_dwordx2 s[92:93], s[0:1], 0x30
	s_load_dwordx2 s[76:77], s[0:1], 0xb8
	v_lshl_add_u32 v156, s26, 8, v158
	v_lshl_or_b32 v157, s64, 8, v160
	v_lshlrev_b32_e32 v200, 2, v157
	v_lshl_add_u32 v201, v156, 12, v200
	global_load_dwordx4 v[196:199], v200, s[34:35]
	global_load_dwordx4 v[208:211], v200, s[34:35] offset:64
	global_load_dwordx4 v[212:215], v200, s[34:35] offset:512
	global_load_dwordx4 v[216:219], v200, s[34:35] offset:576
	v_add_u32_e32 v205, 0x10000, v201
	v_add_u32_e32 v207, 0x20000, v201
	v_add_u32_e32 v220, 0x30000, v201
	v_add_u32_e32 v221, 0x80000, v201
	v_add_u32_e32 v222, 0x90000, v201
	v_add_u32_e32 v223, 0xa0000, v201
	v_add_u32_e32 v224, 0xb0000, v201
	global_load_dwordx4 v[128:131], v201, s[8:9]
	global_load_dwordx4 v[132:135], v201, s[8:9] offset:64
	global_load_dwordx4 v[136:139], v201, s[8:9] offset:512
	global_load_dwordx4 v[140:143], v201, s[8:9] offset:576
	global_load_dwordx4 v[164:167], v205, s[8:9]
	global_load_dwordx4 v[168:171], v205, s[8:9] offset:64
	global_load_dwordx4 v[172:175], v205, s[8:9] offset:512
	global_load_dwordx4 v[176:179], v205, s[8:9] offset:576
	global_load_dwordx4 v[180:183], v207, s[8:9]
	global_load_dwordx4 v[184:187], v207, s[8:9] offset:64
	global_load_dwordx4 v[188:191], v207, s[8:9] offset:512
	global_load_dwordx4 v[192:195], v207, s[8:9] offset:576
	s_waitcnt vmcnt(12)
	s_waitcnt vmcnt(11)
	v_pk_fma_f32 v[124:125], v[124:125], v[196:197], v[128:129]
	v_pk_fma_f32 v[126:127], v[126:127], v[198:199], v[130:131]
	v_mul_f32_e32 v225, v124, v124
	v_fmac_f32_e32 v225, v125, v125
	v_fmac_f32_e32 v225, v126, v126
	v_fmac_f32_e32 v225, v127, v127
	s_waitcnt vmcnt(10)
	v_pk_fma_f32 v[120:121], v[120:121], v[208:209], v[132:133]
	v_pk_fma_f32 v[122:123], v[122:123], v[210:211], v[134:135]
	v_fmac_f32_e32 v225, v120, v120
	v_fmac_f32_e32 v225, v121, v121
	v_fmac_f32_e32 v225, v122, v122
	v_fmac_f32_e32 v225, v123, v123
	s_waitcnt vmcnt(9)
	v_pk_fma_f32 v[116:117], v[116:117], v[212:213], v[136:137]
	v_pk_fma_f32 v[118:119], v[118:119], v[214:215], v[138:139]
	v_fmac_f32_e32 v225, v116, v116
	v_fmac_f32_e32 v225, v117, v117
	v_fmac_f32_e32 v225, v118, v118
	v_fmac_f32_e32 v225, v119, v119
	s_waitcnt vmcnt(8)
	v_pk_fma_f32 v[112:113], v[112:113], v[216:217], v[140:141]
	v_pk_fma_f32 v[114:115], v[114:115], v[218:219], v[142:143]
	v_fmac_f32_e32 v225, v112, v112
	v_fmac_f32_e32 v225, v113, v113
	v_fmac_f32_e32 v225, v114, v114
	v_fmac_f32_e32 v225, v115, v115
	global_store_dwordx4 v201, v[124:127], s[8:9] sc1
	global_store_dwordx4 v201, v[120:123], s[8:9] offset:64 sc1
	global_store_dwordx4 v201, v[116:119], s[8:9] offset:512 sc1
	global_store_dwordx4 v201, v[112:115], s[8:9] offset:576 sc1
	global_load_dwordx4 v[128:131], v220, s[8:9]
	global_load_dwordx4 v[132:135], v220, s[8:9] offset:64
	global_load_dwordx4 v[136:139], v220, s[8:9] offset:512
	global_load_dwordx4 v[140:143], v220, s[8:9] offset:576
	s_waitcnt vmcnt(15)
	v_pk_fma_f32 v[108:109], v[108:109], v[196:197], v[164:165]
	v_pk_fma_f32 v[110:111], v[110:111], v[198:199], v[166:167]
	v_mul_f32_e32 v226, v108, v108
	v_fmac_f32_e32 v226, v109, v109
	v_fmac_f32_e32 v226, v110, v110
	v_fmac_f32_e32 v226, v111, v111
	s_waitcnt vmcnt(14)
	v_pk_fma_f32 v[104:105], v[104:105], v[208:209], v[168:169]
	v_pk_fma_f32 v[106:107], v[106:107], v[210:211], v[170:171]
	v_fmac_f32_e32 v226, v104, v104
	v_fmac_f32_e32 v226, v105, v105
	v_fmac_f32_e32 v226, v106, v106
	v_fmac_f32_e32 v226, v107, v107
	s_waitcnt vmcnt(13)
	v_pk_fma_f32 v[100:101], v[100:101], v[212:213], v[172:173]
	v_pk_fma_f32 v[102:103], v[102:103], v[214:215], v[174:175]
	v_fmac_f32_e32 v226, v100, v100
	v_fmac_f32_e32 v226, v101, v101
	v_fmac_f32_e32 v226, v102, v102
	v_fmac_f32_e32 v226, v103, v103
	s_waitcnt vmcnt(12)
	v_pk_fma_f32 v[96:97], v[96:97], v[216:217], v[176:177]
	v_pk_fma_f32 v[98:99], v[98:99], v[218:219], v[178:179]
	v_fmac_f32_e32 v226, v96, v96
	v_fmac_f32_e32 v226, v97, v97
	v_fmac_f32_e32 v226, v98, v98
	v_fmac_f32_e32 v226, v99, v99
	global_store_dwordx4 v205, v[108:111], s[8:9] sc1
	global_store_dwordx4 v205, v[104:107], s[8:9] offset:64 sc1
	global_store_dwordx4 v205, v[100:103], s[8:9] offset:512 sc1
	global_store_dwordx4 v205, v[96:99], s[8:9] offset:576 sc1
	global_load_dwordx4 v[164:167], v221, s[8:9]
	global_load_dwordx4 v[168:171], v221, s[8:9] offset:64
	global_load_dwordx4 v[172:175], v221, s[8:9] offset:512
	global_load_dwordx4 v[176:179], v221, s[8:9] offset:576
	s_waitcnt vmcnt(19)
	v_pk_fma_f32 v[92:93], v[92:93], v[196:197], v[180:181]
	v_pk_fma_f32 v[94:95], v[94:95], v[198:199], v[182:183]
	v_mul_f32_e32 v227, v92, v92
	v_fmac_f32_e32 v227, v93, v93
	v_fmac_f32_e32 v227, v94, v94
	v_fmac_f32_e32 v227, v95, v95
	s_waitcnt vmcnt(18)
	v_pk_fma_f32 v[88:89], v[88:89], v[208:209], v[184:185]
	v_pk_fma_f32 v[90:91], v[90:91], v[210:211], v[186:187]
	v_fmac_f32_e32 v227, v88, v88
	v_fmac_f32_e32 v227, v89, v89
	v_fmac_f32_e32 v227, v90, v90
	v_fmac_f32_e32 v227, v91, v91
	s_waitcnt vmcnt(17)
	v_pk_fma_f32 v[84:85], v[84:85], v[212:213], v[188:189]
	v_pk_fma_f32 v[86:87], v[86:87], v[214:215], v[190:191]
	v_fmac_f32_e32 v227, v84, v84
	v_fmac_f32_e32 v227, v85, v85
	v_fmac_f32_e32 v227, v86, v86
	v_fmac_f32_e32 v227, v87, v87
	s_waitcnt vmcnt(16)
;     __device__ __forceinline__ void operator()(const f32x4 (&acc)[2][2][4][2], const Unit& u, int wr, int wc, int fr, int fq) const {
;     ...
;             for (int m = 0; m < 4; ++m) {
;                 const int row = u.pm * BM + ai * HALF + wr * 64 + m * 16 + fr;
;                 const float* s = row < MX_ ? src_main + (size_t)row * D_ : src_ctx + (size_t)(row - MX_) * D_;
;                 float* d = row < MX_ ? dst_main + (size_t)row * D_ : dst_ctx + (size_t)(row - MX_) * D_;
; #pragma unroll
;                 for (int bj = 0; bj < 2; ++bj)
; #pragma unroll
;                     for (int n = 0; n < 2; ++n) { const int off = col0 + bj * HALF + n * 16; const f32x4 xo = *(const f32x4*)(s + off); *(f32x4*)(d + off) = xo + gv[bj][n] * acc[ai][bj][m][n]; }
; __device__ __forceinline__ void modpass(const float* xs_main, const float* xs_ctx, const float* mod_l, const float* g, int i, bf16_t* H, int nrows, int gw, int NGW, int lane) {
;     ...
;         float ss = 0.f;
; #pragma unroll
;         for (int j = 0; j < 2; ++j)
; #pragma unroll
;             for (int q = 0; q < 2; ++q) ss += (v[j][q][0] * v[j][q][0] + v[j][q][1] * v[j][q][1]) + (v[j][q][2] * v[j][q][2] + v[j][q][3] * v[j][q][3]);
	v_pk_fma_f32 v[80:81], v[80:81], v[216:217], v[192:193]
	v_pk_fma_f32 v[82:83], v[82:83], v[218:219], v[194:195]
	v_fmac_f32_e32 v227, v80, v80
	v_fmac_f32_e32 v227, v81, v81
	v_fmac_f32_e32 v227, v82, v82
	v_fmac_f32_e32 v227, v83, v83
	global_store_dwordx4 v207, v[92:95], s[8:9] sc1
	global_store_dwordx4 v207, v[88:91], s[8:9] offset:64 sc1
	global_store_dwordx4 v207, v[84:87], s[8:9] offset:512 sc1
	global_store_dwordx4 v207, v[80:83], s[8:9] offset:576 sc1
	global_load_dwordx4 v[180:183], v222, s[8:9]
	global_load_dwordx4 v[184:187], v222, s[8:9] offset:64
	global_load_dwordx4 v[188:191], v222, s[8:9] offset:512
	global_load_dwordx4 v[192:195], v222, s[8:9] offset:576
	s_waitcnt vmcnt(19)
	v_pk_fma_f32 v[76:77], v[76:77], v[196:197], v[128:129]
	v_pk_fma_f32 v[78:79], v[78:79], v[198:199], v[130:131]
	v_mul_f32_e32 v228, v76, v76
	v_fmac_f32_e32 v228, v77, v77
	v_fmac_f32_e32 v228, v78, v78
	v_fmac_f32_e32 v228, v79, v79
	s_waitcnt vmcnt(18)
	v_pk_fma_f32 v[72:73], v[72:73], v[208:209], v[132:133]
	v_pk_fma_f32 v[74:75], v[74:75], v[210:211], v[134:135]
	v_fmac_f32_e32 v228, v72, v72
	v_fmac_f32_e32 v228, v73, v73
	v_fmac_f32_e32 v228, v74, v74
	v_fmac_f32_e32 v228, v75, v75
	s_waitcnt vmcnt(17)
	v_pk_fma_f32 v[68:69], v[68:69], v[212:213], v[136:137]
	v_pk_fma_f32 v[70:71], v[70:71], v[214:215], v[138:139]
	v_fmac_f32_e32 v228, v68, v68
	v_fmac_f32_e32 v228, v69, v69
	v_fmac_f32_e32 v228, v70, v70
	v_fmac_f32_e32 v228, v71, v71
	s_waitcnt vmcnt(16)
	v_pk_fma_f32 v[64:65], v[64:65], v[216:217], v[140:141]
	v_pk_fma_f32 v[66:67], v[66:67], v[218:219], v[142:143]
	v_fmac_f32_e32 v228, v64, v64
	v_fmac_f32_e32 v228, v65, v65
	v_fmac_f32_e32 v228, v66, v66
	v_fmac_f32_e32 v228, v67, v67
	global_store_dwordx4 v220, v[76:79], s[8:9] sc1
	global_store_dwordx4 v220, v[72:75], s[8:9] offset:64 sc1
	global_store_dwordx4 v220, v[68:71], s[8:9] offset:512 sc1
	global_store_dwordx4 v220, v[64:67], s[8:9] offset:576 sc1
	global_load_dwordx4 v[128:131], v223, s[8:9]
	global_load_dwordx4 v[132:135], v223, s[8:9] offset:64
	global_load_dwordx4 v[136:139], v223, s[8:9] offset:512
	global_load_dwordx4 v[140:143], v223, s[8:9] offset:576
	s_waitcnt vmcnt(19)
	v_pk_fma_f32 v[60:61], v[60:61], v[196:197], v[164:165]
	v_pk_fma_f32 v[62:63], v[62:63], v[198:199], v[166:167]
	v_mul_f32_e32 v229, v60, v60
	v_fmac_f32_e32 v229, v61, v61
	v_fmac_f32_e32 v229, v62, v62
	v_fmac_f32_e32 v229, v63, v63
	s_waitcnt vmcnt(18)
	v_pk_fma_f32 v[56:57], v[56:57], v[208:209], v[168:169]
	v_pk_fma_f32 v[58:59], v[58:59], v[210:211], v[170:171]
	v_fmac_f32_e32 v229, v56, v56
	v_fmac_f32_e32 v229, v57, v57
	v_fmac_f32_e32 v229, v58, v58
	v_fmac_f32_e32 v229, v59, v59
	s_waitcnt vmcnt(17)
	v_pk_fma_f32 v[52:53], v[52:53], v[212:213], v[172:173]
	v_pk_fma_f32 v[54:55], v[54:55], v[214:215], v[174:175]
	v_fmac_f32_e32 v229, v52, v52
	v_fmac_f32_e32 v229, v53, v53
	v_fmac_f32_e32 v229, v54, v54
	v_fmac_f32_e32 v229, v55, v55
	s_waitcnt vmcnt(16)
	v_pk_fma_f32 v[48:49], v[48:49], v[216:217], v[176:177]
	v_pk_fma_f32 v[50:51], v[50:51], v[218:219], v[178:179]
	v_fmac_f32_e32 v229, v48, v48
	v_fmac_f32_e32 v229, v49, v49
	v_fmac_f32_e32 v229, v50, v50
	v_fmac_f32_e32 v229, v51, v51
	global_store_dwordx4 v221, v[60:63], s[8:9] sc1
	global_store_dwordx4 v221, v[56:59], s[8:9] offset:64 sc1
	global_store_dwordx4 v221, v[52:55], s[8:9] offset:512 sc1
	global_store_dwordx4 v221, v[48:51], s[8:9] offset:576 sc1
	global_load_dwordx4 v[164:167], v224, s[8:9]
	global_load_dwordx4 v[168:171], v224, s[8:9] offset:64
	global_load_dwordx4 v[172:175], v224, s[8:9] offset:512
	global_load_dwordx4 v[176:179], v224, s[8:9] offset:576
	s_waitcnt vmcnt(19)
	v_pk_fma_f32 v[44:45], v[44:45], v[196:197], v[180:181]
	v_pk_fma_f32 v[46:47], v[46:47], v[198:199], v[182:183]
	v_mul_f32_e32 v230, v44, v44
	v_fmac_f32_e32 v230, v45, v45
	v_fmac_f32_e32 v230, v46, v46
	v_fmac_f32_e32 v230, v47, v47
	s_waitcnt vmcnt(18)
	v_pk_fma_f32 v[40:41], v[40:41], v[208:209], v[184:185]
	v_pk_fma_f32 v[42:43], v[42:43], v[210:211], v[186:187]
	v_fmac_f32_e32 v230, v40, v40
	v_fmac_f32_e32 v230, v41, v41
	v_fmac_f32_e32 v230, v42, v42
	v_fmac_f32_e32 v230, v43, v43
	s_waitcnt vmcnt(17)
	v_pk_fma_f32 v[36:37], v[36:37], v[212:213], v[188:189]
	v_pk_fma_f32 v[38:39], v[38:39], v[214:215], v[190:191]
	v_fmac_f32_e32 v230, v36, v36
	v_fmac_f32_e32 v230, v37, v37
	v_fmac_f32_e32 v230, v38, v38
	v_fmac_f32_e32 v230, v39, v39
	s_waitcnt vmcnt(16)
	v_pk_fma_f32 v[32:33], v[32:33], v[216:217], v[192:193]
	v_pk_fma_f32 v[34:35], v[34:35], v[218:219], v[194:195]
	v_fmac_f32_e32 v230, v32, v32
	v_fmac_f32_e32 v230, v33, v33
	v_fmac_f32_e32 v230, v34, v34
	v_fmac_f32_e32 v230, v35, v35
	global_store_dwordx4 v222, v[44:47], s[8:9] sc1
	global_store_dwordx4 v222, v[40:43], s[8:9] offset:64 sc1
	global_store_dwordx4 v222, v[36:39], s[8:9] offset:512 sc1
	global_store_dwordx4 v222, v[32:35], s[8:9] offset:576 sc1
	s_waitcnt vmcnt(15)
	v_pk_fma_f32 v[28:29], v[28:29], v[196:197], v[128:129]
	v_pk_fma_f32 v[30:31], v[30:31], v[198:199], v[130:131]
	v_mul_f32_e32 v231, v28, v28
	v_fmac_f32_e32 v231, v29, v29
	v_fmac_f32_e32 v231, v30, v30
	v_fmac_f32_e32 v231, v31, v31
	s_waitcnt vmcnt(14)
;     __device__ __forceinline__ void operator()(const f32x4 (&acc)[2][2][4][2], const Unit& u, int wr, int wc, int fr, int fq) const {
;     ...
;                 for (int bj = 0; bj < 2; ++bj)
; #pragma unroll
;                     for (int n = 0; n < 2; ++n) { const int off = col0 + bj * HALF + n * 16; const f32x4 xo = *(const f32x4*)(s + off); *(f32x4*)(d + off) = xo + gv[bj][n] * acc[ai][bj][m][n]; }
; __device__ __forceinline__ void modpass(const float* xs_main, const float* xs_ctx, const float* mod_l, const float* g, int i, bf16_t* H, int nrows, int gw, int NGW, int lane) {
;     ...
;         float ss = 0.f;
; #pragma unroll
;         for (int j = 0; j < 2; ++j)
; #pragma unroll
;             for (int q = 0; q < 2; ++q) ss += (v[j][q][0] * v[j][q][0] + v[j][q][1] * v[j][q][1]) + (v[j][q][2] * v[j][q][2] + v[j][q][3] * v[j][q][3]);
;         const float rstd = 1.0f / sqrtf(wave_sum(ss) * (1.0f / D) + EPS);
	v_pk_fma_f32 v[24:25], v[24:25], v[208:209], v[132:133]
	v_pk_fma_f32 v[26:27], v[26:27], v[210:211], v[134:135]
	v_fmac_f32_e32 v231, v24, v24
	v_fmac_f32_e32 v231, v25, v25
	v_fmac_f32_e32 v231, v26, v26
	v_fmac_f32_e32 v231, v27, v27
	s_waitcnt vmcnt(13)
	v_pk_fma_f32 v[20:21], v[20:21], v[212:213], v[136:137]
	v_pk_fma_f32 v[22:23], v[22:23], v[214:215], v[138:139]
	v_fmac_f32_e32 v231, v20, v20
	v_fmac_f32_e32 v231, v21, v21
	v_fmac_f32_e32 v231, v22, v22
	v_fmac_f32_e32 v231, v23, v23
	s_waitcnt vmcnt(12)
	v_pk_fma_f32 v[16:17], v[16:17], v[216:217], v[140:141]
	v_pk_fma_f32 v[18:19], v[18:19], v[218:219], v[142:143]
	v_fmac_f32_e32 v231, v16, v16
	v_fmac_f32_e32 v231, v17, v17
	v_fmac_f32_e32 v231, v18, v18
	v_fmac_f32_e32 v231, v19, v19
	global_store_dwordx4 v223, v[28:31], s[8:9] sc1
	global_store_dwordx4 v223, v[24:27], s[8:9] offset:64 sc1
	global_store_dwordx4 v223, v[20:23], s[8:9] offset:512 sc1
	global_store_dwordx4 v223, v[16:19], s[8:9] offset:576 sc1
	s_waitcnt vmcnt(11)
	v_pk_fma_f32 v[12:13], v[12:13], v[196:197], v[164:165]
	v_pk_fma_f32 v[14:15], v[14:15], v[198:199], v[166:167]
	v_mul_f32_e32 v232, v12, v12
	v_fmac_f32_e32 v232, v13, v13
	v_fmac_f32_e32 v232, v14, v14
	v_fmac_f32_e32 v232, v15, v15
	s_waitcnt vmcnt(10)
	v_pk_fma_f32 v[8:9], v[8:9], v[208:209], v[168:169]
	v_pk_fma_f32 v[10:11], v[10:11], v[210:211], v[170:171]
	v_fmac_f32_e32 v232, v8, v8
	v_fmac_f32_e32 v232, v9, v9
	v_fmac_f32_e32 v232, v10, v10
	v_fmac_f32_e32 v232, v11, v11
	s_waitcnt vmcnt(9)
	v_pk_fma_f32 v[4:5], v[4:5], v[212:213], v[172:173]
	v_pk_fma_f32 v[6:7], v[6:7], v[214:215], v[174:175]
	v_fmac_f32_e32 v232, v4, v4
	v_fmac_f32_e32 v232, v5, v5
	v_fmac_f32_e32 v232, v6, v6
	v_fmac_f32_e32 v232, v7, v7
	s_waitcnt vmcnt(8)
	v_pk_fma_f32 v[0:1], v[0:1], v[216:217], v[176:177]
	v_pk_fma_f32 v[2:3], v[2:3], v[218:219], v[178:179]
	v_fmac_f32_e32 v232, v0, v0
	v_fmac_f32_e32 v232, v1, v1
	v_fmac_f32_e32 v232, v2, v2
	v_fmac_f32_e32 v232, v3, v3
	global_store_dwordx4 v224, v[12:15], s[8:9] sc1
	global_store_dwordx4 v224, v[8:11], s[8:9] offset:64 sc1
	global_store_dwordx4 v224, v[4:7], s[8:9] offset:512 sc1
	global_store_dwordx4 v224, v[0:3], s[8:9] offset:576 sc1
	v_mbcnt_lo_u32_b32 v233, -1, 0
	v_mbcnt_hi_u32_b32 v233, -1, v233
	v_xor_b32_e32 v234, 16, v233
	v_xor_b32_e32 v235, 32, v233
	v_lshlrev_b32_e32 v234, 2, v234
	v_lshlrev_b32_e32 v235, 2, v235
	s_waitcnt lgkmcnt(0)
	ds_bpermute_b32 v128, v234, v225
	ds_bpermute_b32 v129, v234, v226
	ds_bpermute_b32 v130, v234, v227
	ds_bpermute_b32 v131, v234, v228
	ds_bpermute_b32 v132, v234, v229
	ds_bpermute_b32 v133, v234, v230
	ds_bpermute_b32 v134, v234, v231
	ds_bpermute_b32 v135, v234, v232
	s_waitcnt lgkmcnt(7)
	v_add_f32_e32 v225, v225, v128
	s_waitcnt lgkmcnt(6)
	v_add_f32_e32 v226, v226, v129
	s_waitcnt lgkmcnt(5)
	v_add_f32_e32 v227, v227, v130
	s_waitcnt lgkmcnt(4)
	v_add_f32_e32 v228, v228, v131
	s_waitcnt lgkmcnt(3)
	v_add_f32_e32 v229, v229, v132
	s_waitcnt lgkmcnt(2)
	v_add_f32_e32 v230, v230, v133
	s_waitcnt lgkmcnt(1)
	v_add_f32_e32 v231, v231, v134
	s_waitcnt lgkmcnt(0)
	v_add_f32_e32 v232, v232, v135
	ds_bpermute_b32 v128, v235, v225
	ds_bpermute_b32 v129, v235, v226
	ds_bpermute_b32 v130, v235, v227
	ds_bpermute_b32 v131, v235, v228
	ds_bpermute_b32 v132, v235, v229
	ds_bpermute_b32 v133, v235, v230
	ds_bpermute_b32 v134, v235, v231
	ds_bpermute_b32 v135, v235, v232
	s_waitcnt lgkmcnt(7)
	v_add_f32_e32 v225, v225, v128
	s_waitcnt lgkmcnt(6)
	v_add_f32_e32 v226, v226, v129
	s_waitcnt lgkmcnt(5)
	v_add_f32_e32 v227, v227, v130
	s_waitcnt lgkmcnt(4)
	v_add_f32_e32 v228, v228, v131
	s_waitcnt lgkmcnt(3)
	v_add_f32_e32 v229, v229, v132
	s_waitcnt lgkmcnt(2)
	v_add_f32_e32 v230, v230, v133
	s_waitcnt lgkmcnt(1)
	v_add_f32_e32 v231, v231, v134
	s_waitcnt lgkmcnt(0)
	v_add_f32_e32 v232, v232, v135
	v_lshlrev_b32_e32 v236, 2, v156
	s_add_u32 s90, s76, 0x6500000
	s_addc_u32 s91, s77, 0
	s_add_u32 s76, s76, 0x31a8000
	s_addc_u32 s77, s77, 0
	s_lshl_b32 s83, s26, 6
	s_add_u32 s78, s76, s83
	s_addc_u32 s79, s77, 0
	s_add_u32 s78, s78, 0x20000
	s_addc_u32 s79, s79, 0
	s_mov_b64 s[80:81], exec
	s_mov_b64 exec, 0xffff
	global_atomic_add_f32 v236, v225, s[76:77]
	global_atomic_add_f32 v236, v226, s[76:77] offset:64
	global_atomic_add_f32 v236, v227, s[76:77] offset:128
	global_atomic_add_f32 v236, v228, s[76:77] offset:192
	global_atomic_add_f32 v236, v229, s[76:77] offset:512
	global_atomic_add_f32 v236, v230, s[76:77] offset:576
	global_atomic_add_f32 v236, v231, s[76:77] offset:640
	global_atomic_add_f32 v236, v232, s[76:77] offset:704
	s_mov_b64 exec, s[80:81]
	s_add_u32 s86, s34, 0x1000
	s_addc_u32 s87, s35, 0
	s_add_u32 s88, s86, 0x1000
	s_addc_u32 s89, s87, 0
	s_add_u32 s92, s92, 0x5000
	s_addc_u32 s93, s93, 0
	s_mov_b32 s84, 0xffff0000
	s_mov_b32 s85, 0xffff0000
	s_waitcnt vmcnt(0)
	s_barrier
	v_readfirstlane_b32 s83, v206
	v_mov_b32_e32 v237, 0
	v_mov_b32_e32 v238, 1
	s_cmp_lg_u32 s83, 0
	s_cbranch_scc1 .Lfmfs_wait_done
	s_mov_b64 exec, 1
	global_atomic_add v237, v238, s[78:79]
	s_mov_b32 s82, 0

; __device__ __forceinline__ unsigned cvtpk_s(float lo, float hi) { f32x2_t v = {lo, hi}; bf16x2_t b = __builtin_convertvector(v, bf16x2_t); return __builtin_bit_cast(unsigned, b); }
; __device__ __forceinline__ u32x4 quad_swap(unsigned lo0, unsigned lo1, unsigned hi0, unsigned hi1, int fq, int& coloff) {
;     const bool odd = fq & 1;
;     const unsigned s0 = odd ? lo0 : hi0, s1 = odd ? lo1 : hi1;
;     const unsigned r0 = (unsigned)__shfl_xor((int)s0, 16), r1 = (unsigned)__shfl_xor((int)s1, 16);
;     coloff = odd ? 16 + 4 * (fq - 1) : 4 * fq;
;     u32x4 o; o.x = odd ? r0 : lo0; o.y = odd ? r1 : lo1; o.z = odd ? hi0 : r0; o.w = odd ? hi1 : r1; return o;
; __device__ __forceinline__ void modpass(const float* xs_main, const float* xs_ctx, const float* mod_l, const float* g, int i, bf16_t* H, int nrows, int gw, int NGW, int lane) {
;     ...
;         if (cond != cur) { cur = cond; const float* shift = mod_l + cond * 9216 + 3 * i * 1024; const float* scale = shift + 1024;
; #pragma unroll
;             for (int j = 0; j < 2; ++j)
; #pragma unroll
;                 for (int q = 0; q < 2; ++q) { const int c = 8 * lane + 512 * j + 4 * q; gm[j][q] = *(const f32x4*)(g + c) * (*(const f32x4*)(scale + c) + 1.0f); sh[j][q] = *(const f32x4*)(shift + c); } }
;         float ss = 0.f;
; #pragma unroll
;         for (int j = 0; j < 2; ++j)
; #pragma unroll
;             for (int q = 0; q < 2; ++q) ss += (v[j][q][0] * v[j][q][0] + v[j][q][1] * v[j][q][1]) + (v[j][q][2] * v[j][q][2] + v[j][q][3] * v[j][q][3]);
;         const float rstd = 1.0f / sqrtf(wave_sum(ss) * (1.0f / D) + EPS);
; #pragma unroll
;         for (int j = 0; j < 2; ++j) {
;             const f32x4 o0 = v[j][0] * rstd * gm[j][0] + sh[j][0], o1 = v[j][1] * rstd * gm[j][1] + sh[j][1];
;             u32x4 w; w.x = cvtpk_s(o0[0], o0[1]); w.y = cvtpk_s(o0[2], o0[3]); w.z = cvtpk_s(o1[0], o1[1]); w.w = cvtpk_s(o1[2], o1[3]);
;             *(u32x4*)(H + (size_t)row * D + 8 * lane + 512 * j) = w;
.Lfmfs_wait_done:
	s_barrier
	global_load_dword v132, v236, s[76:77] sc1
	global_load_dword v133, v236, s[76:77] offset:64 sc1
	global_load_dword v134, v236, s[76:77] offset:128 sc1
	global_load_dword v135, v236, s[76:77] offset:192 sc1
	global_load_dword v136, v236, s[76:77] offset:512 sc1
	global_load_dword v137, v236, s[76:77] offset:576 sc1
	global_load_dword v138, v236, s[76:77] offset:640 sc1
	global_load_dword v139, v236, s[76:77] offset:704 sc1
	global_load_dwordx4 v[196:199], v200, s[86:87]
	global_load_dwordx4 v[208:211], v200, s[86:87] offset:64
	global_load_dwordx4 v[212:215], v200, s[86:87] offset:512
	global_load_dwordx4 v[216:219], v200, s[86:87] offset:576
	global_load_dwordx4 v[140:143], v200, s[88:89]
	global_load_dwordx4 v[164:167], v200, s[88:89] offset:64
	global_load_dwordx4 v[168:171], v200, s[88:89] offset:512
	global_load_dwordx4 v[172:175], v200, s[88:89] offset:576
	global_load_dwordx4 v[176:179], v200, s[92:93]
	global_load_dwordx4 v[180:183], v200, s[92:93] offset:64
	global_load_dwordx4 v[184:187], v200, s[92:93] offset:512
	global_load_dwordx4 v[188:191], v200, s[92:93] offset:576
	v_mov_b32_e32 v233, 12
	v_cndmask_b32_e64 v233, 0, v233, s[84:85]
	v_add_u32_e32 v233, v233, v157
	v_lshlrev_b32_e32 v233, 1, v233
	v_lshl_add_u32 v240, v156, 11, v233
	v_mov_b32_e32 v233, 0x358637bd
	s_waitcnt vmcnt(0)
	v_fmamk_f32 v132, v132, 0x3a800000, v233
	v_fmamk_f32 v133, v133, 0x3a800000, v233
	v_fmamk_f32 v134, v134, 0x3a800000, v233
	v_fmamk_f32 v135, v135, 0x3a800000, v233
	v_fmamk_f32 v136, v136, 0x3a800000, v233
	v_fmamk_f32 v137, v137, 0x3a800000, v233
	v_fmamk_f32 v138, v138, 0x3a800000, v233
	v_fmamk_f32 v139, v139, 0x3a800000, v233
	v_rsq_f32_e32 v132, v132
	v_rsq_f32_e32 v133, v133
	v_rsq_f32_e32 v134, v134
	v_rsq_f32_e32 v135, v135
	v_rsq_f32_e32 v136, v136
	v_rsq_f32_e32 v137, v137
	v_rsq_f32_e32 v138, v138
	v_rsq_f32_e32 v139, v139
	v_pk_add_f32 v[140:141], v[140:141], 1.0 op_sel_hi:[1,0]
	v_pk_mul_f32 v[140:141], v[176:177], v[140:141]
	v_pk_add_f32 v[142:143], v[142:143], 1.0 op_sel_hi:[1,0]
	v_pk_mul_f32 v[142:143], v[178:179], v[142:143]
	v_pk_add_f32 v[164:165], v[164:165], 1.0 op_sel_hi:[1,0]
	v_pk_mul_f32 v[164:165], v[180:181], v[164:165]
	v_pk_add_f32 v[166:167], v[166:167], 1.0 op_sel_hi:[1,0]
	v_pk_mul_f32 v[166:167], v[182:183], v[166:167]
	v_pk_add_f32 v[168:169], v[168:169], 1.0 op_sel_hi:[1,0]
	v_pk_mul_f32 v[168:169], v[184:185], v[168:169]
	v_pk_add_f32 v[170:171], v[170:171], 1.0 op_sel_hi:[1,0]
	v_pk_mul_f32 v[170:171], v[186:187], v[170:171]
	v_pk_add_f32 v[172:173], v[172:173], 1.0 op_sel_hi:[1,0]
	v_pk_mul_f32 v[172:173], v[188:189], v[172:173]
	v_pk_add_f32 v[174:175], v[174:175], 1.0 op_sel_hi:[1,0]
	v_pk_mul_f32 v[174:175], v[190:191], v[174:175]
	v_mul_f32_e32 v124, v124, v132
	v_mul_f32_e32 v125, v125, v132
	v_pk_fma_f32 v[124:125], v[140:141], v[124:125], v[196:197]
	v_mul_f32_e32 v126, v126, v132
	v_mul_f32_e32 v127, v127, v132
	v_pk_fma_f32 v[126:127], v[142:143], v[126:127], v[198:199]
	v_cvt_pk_bf16_f32 v184, v124, v125
	v_cvt_pk_bf16_f32 v185, v126, v127
	v_mul_f32_e32 v120, v120, v132
	v_mul_f32_e32 v121, v121, v132
	v_pk_fma_f32 v[120:121], v[164:165], v[120:121], v[208:209]
	v_mul_f32_e32 v122, v122, v132
	v_mul_f32_e32 v123, v123, v132
	v_pk_fma_f32 v[122:123], v[166:167], v[122:123], v[210:211]
	v_cvt_pk_bf16_f32 v186, v120, v121
	v_cvt_pk_bf16_f32 v187, v122, v123
	v_mul_f32_e32 v116, v116, v132
	v_mul_f32_e32 v117, v117, v132
	v_pk_fma_f32 v[116:117], v[168:169], v[116:117], v[212:213]
	v_mul_f32_e32 v118, v118, v132
	v_mul_f32_e32 v119, v119, v132
	v_pk_fma_f32 v[118:119], v[170:171], v[118:119], v[214:215]
	v_cvt_pk_bf16_f32 v188, v116, v117
	v_cvt_pk_bf16_f32 v189, v118, v119
	v_mul_f32_e32 v112, v112, v132
	v_mul_f32_e32 v113, v113, v132
	v_pk_fma_f32 v[112:113], v[172:173], v[112:113], v[216:217]
	v_mul_f32_e32 v114, v114, v132
	v_mul_f32_e32 v115, v115, v132
	v_pk_fma_f32 v[114:115], v[174:175], v[114:115], v[218:219]
	v_cvt_pk_bf16_f32 v190, v112, v113
	v_cvt_pk_bf16_f32 v191, v114, v115
	v_mov_b32_e32 v233, v240
	v_cndmask_b32_e64 v192, v186, v184, s[84:85]
	v_cndmask_b32_e64 v193, v187, v185, s[84:85]
	ds_bpermute_b32 v194, v234, v192
	ds_bpermute_b32 v195, v234, v193
	s_waitcnt lgkmcnt(0)
	v_cndmask_b32_e64 v176, v184, v194, s[84:85]
	v_cndmask_b32_e64 v177, v185, v195, s[84:85]
	v_cndmask_b32_e64 v178, v194, v186, s[84:85]
	v_cndmask_b32_e64 v179, v195, v187, s[84:85]
	global_store_dwordx4 v233, v[176:179], s[90:91] sc1
	v_cndmask_b32_e64 v192, v190, v188, s[84:85]
	v_cndmask_b32_e64 v193, v191, v189, s[84:85]
	ds_bpermute_b32 v194, v234, v192
	ds_bpermute_b32 v195, v234, v193
	s_waitcnt lgkmcnt(0)
	v_cndmask_b32_e64 v180, v188, v194, s[84:85]
	v_cndmask_b32_e64 v181, v189, v195, s[84:85]
	v_cndmask_b32_e64 v182, v194, v190, s[84:85]
	v_cndmask_b32_e64 v183, v195, v191, s[84:85]
	global_store_dwordx4 v233, v[180:183], s[90:91] offset:256 sc1
	v_mul_f32_e32 v108, v108, v133
	v_mul_f32_e32 v109, v109, v133
	v_pk_fma_f32 v[108:109], v[140:141], v[108:109], v[196:197]
	v_mul_f32_e32 v110, v110, v133
	v_mul_f32_e32 v111, v111, v133
	v_pk_fma_f32 v[110:111], v[142:143], v[110:111], v[198:199]
	v_cvt_pk_bf16_f32 v184, v108, v109
	v_cvt_pk_bf16_f32 v185, v110, v111
	v_mul_f32_e32 v104, v104, v133
	v_mul_f32_e32 v105, v105, v133
	v_pk_fma_f32 v[104:105], v[164:165], v[104:105], v[208:209]
	v_mul_f32_e32 v106, v106, v133
	v_mul_f32_e32 v107, v107, v133
	v_pk_fma_f32 v[106:107], v[166:167], v[106:107], v[210:211]
	v_cvt_pk_bf16_f32 v186, v104, v105
	v_cvt_pk_bf16_f32 v187, v106, v107
	v_mul_f32_e32 v100, v100, v133
	v_mul_f32_e32 v101, v101, v133
	v_pk_fma_f32 v[100:101], v[168:169], v[100:101], v[212:213]
	v_mul_f32_e32 v102, v102, v133
	v_mul_f32_e32 v103, v103, v133
	v_pk_fma_f32 v[102:103], v[170:171], v[102:103], v[214:215]
	v_cvt_pk_bf16_f32 v188, v100, v101
	v_cvt_pk_bf16_f32 v189, v102, v103
	v_mul_f32_e32 v96, v96, v133
	v_mul_f32_e32 v97, v97, v133
	v_pk_fma_f32 v[96:97], v[172:173], v[96:97], v[216:217]
	v_mul_f32_e32 v98, v98, v133
	v_mul_f32_e32 v99, v99, v133
	v_pk_fma_f32 v[98:99], v[174:175], v[98:99], v[218:219]
	v_cvt_pk_bf16_f32 v190, v96, v97
	v_cvt_pk_bf16_f32 v191, v98, v99
	v_add_u32_e32 v233, 0x8000, v240
	v_cndmask_b32_e64 v192, v186, v184, s[84:85]
	v_cndmask_b32_e64 v193, v187, v185, s[84:85]
	ds_bpermute_b32 v194, v234, v192
	ds_bpermute_b32 v195, v234, v193
	s_waitcnt lgkmcnt(0)
; __device__ __forceinline__ unsigned cvtpk_s(float lo, float hi) { f32x2_t v = {lo, hi}; bf16x2_t b = __builtin_convertvector(v, bf16x2_t); return __builtin_bit_cast(unsigned, b); }
; __device__ __forceinline__ u32x4 quad_swap(unsigned lo0, unsigned lo1, unsigned hi0, unsigned hi1, int fq, int& coloff) {
;     const bool odd = fq & 1;
;     const unsigned s0 = odd ? lo0 : hi0, s1 = odd ? lo1 : hi1;
;     const unsigned r0 = (unsigned)__shfl_xor((int)s0, 16), r1 = (unsigned)__shfl_xor((int)s1, 16);
;     coloff = odd ? 16 + 4 * (fq - 1) : 4 * fq;
;     u32x4 o; o.x = odd ? r0 : lo0; o.y = odd ? r1 : lo1; o.z = odd ? hi0 : r0; o.w = odd ? hi1 : r1; return o;
; __device__ __forceinline__ void modpass(const float* xs_main, const float* xs_ctx, const float* mod_l, const float* g, int i, bf16_t* H, int nrows, int gw, int NGW, int lane) {
;     ...
;         for (int j = 0; j < 2; ++j) {
;             const f32x4 o0 = v[j][0] * rstd * gm[j][0] + sh[j][0], o1 = v[j][1] * rstd * gm[j][1] + sh[j][1];
;             u32x4 w; w.x = cvtpk_s(o0[0], o0[1]); w.y = cvtpk_s(o0[2], o0[3]); w.z = cvtpk_s(o1[0], o1[1]); w.w = cvtpk_s(o1[2], o1[3]);
;             *(u32x4*)(H + (size_t)row * D + 8 * lane + 512 * j) = w;
	v_cndmask_b32_e64 v176, v184, v194, s[84:85]
	v_cndmask_b32_e64 v177, v185, v195, s[84:85]
	v_cndmask_b32_e64 v178, v194, v186, s[84:85]
	v_cndmask_b32_e64 v179, v195, v187, s[84:85]
	global_store_dwordx4 v233, v[176:179], s[90:91] sc1
	v_cndmask_b32_e64 v192, v190, v188, s[84:85]
	v_cndmask_b32_e64 v193, v191, v189, s[84:85]
	ds_bpermute_b32 v194, v234, v192
	ds_bpermute_b32 v195, v234, v193
	s_waitcnt lgkmcnt(0)
	v_cndmask_b32_e64 v180, v188, v194, s[84:85]
	v_cndmask_b32_e64 v181, v189, v195, s[84:85]
	v_cndmask_b32_e64 v182, v194, v190, s[84:85]
	v_cndmask_b32_e64 v183, v195, v191, s[84:85]
	global_store_dwordx4 v233, v[180:183], s[90:91] offset:256 sc1
	v_mul_f32_e32 v92, v92, v134
	v_mul_f32_e32 v93, v93, v134
	v_pk_fma_f32 v[92:93], v[140:141], v[92:93], v[196:197]
	v_mul_f32_e32 v94, v94, v134
	v_mul_f32_e32 v95, v95, v134
	v_pk_fma_f32 v[94:95], v[142:143], v[94:95], v[198:199]
	v_cvt_pk_bf16_f32 v184, v92, v93
	v_cvt_pk_bf16_f32 v185, v94, v95
	v_mul_f32_e32 v88, v88, v134
	v_mul_f32_e32 v89, v89, v134
	v_pk_fma_f32 v[88:89], v[164:165], v[88:89], v[208:209]
	v_mul_f32_e32 v90, v90, v134
	v_mul_f32_e32 v91, v91, v134
	v_pk_fma_f32 v[90:91], v[166:167], v[90:91], v[210:211]
	v_cvt_pk_bf16_f32 v186, v88, v89
	v_cvt_pk_bf16_f32 v187, v90, v91
	v_mul_f32_e32 v84, v84, v134
	v_mul_f32_e32 v85, v85, v134
	v_pk_fma_f32 v[84:85], v[168:169], v[84:85], v[212:213]
	v_mul_f32_e32 v86, v86, v134
	v_mul_f32_e32 v87, v87, v134
	v_pk_fma_f32 v[86:87], v[170:171], v[86:87], v[214:215]
	v_cvt_pk_bf16_f32 v188, v84, v85
	v_cvt_pk_bf16_f32 v189, v86, v87
	v_mul_f32_e32 v80, v80, v134
	v_mul_f32_e32 v81, v81, v134
	v_pk_fma_f32 v[80:81], v[172:173], v[80:81], v[216:217]
	v_mul_f32_e32 v82, v82, v134
	v_mul_f32_e32 v83, v83, v134
	v_pk_fma_f32 v[82:83], v[174:175], v[82:83], v[218:219]
	v_cvt_pk_bf16_f32 v190, v80, v81
	v_cvt_pk_bf16_f32 v191, v82, v83
	v_add_u32_e32 v233, 0x10000, v240
	v_cndmask_b32_e64 v192, v186, v184, s[84:85]
	v_cndmask_b32_e64 v193, v187, v185, s[84:85]
	ds_bpermute_b32 v194, v234, v192
	ds_bpermute_b32 v195, v234, v193
	s_waitcnt lgkmcnt(0)
	v_cndmask_b32_e64 v176, v184, v194, s[84:85]
	v_cndmask_b32_e64 v177, v185, v195, s[84:85]
	v_cndmask_b32_e64 v178, v194, v186, s[84:85]
	v_cndmask_b32_e64 v179, v195, v187, s[84:85]
	global_store_dwordx4 v233, v[176:179], s[90:91] sc1
	v_cndmask_b32_e64 v192, v190, v188, s[84:85]
	v_cndmask_b32_e64 v193, v191, v189, s[84:85]
	ds_bpermute_b32 v194, v234, v192
	ds_bpermute_b32 v195, v234, v193
	s_waitcnt lgkmcnt(0)
	v_cndmask_b32_e64 v180, v188, v194, s[84:85]
	v_cndmask_b32_e64 v181, v189, v195, s[84:85]
	v_cndmask_b32_e64 v182, v194, v190, s[84:85]
	v_cndmask_b32_e64 v183, v195, v191, s[84:85]
	global_store_dwordx4 v233, v[180:183], s[90:91] offset:256 sc1
	v_mul_f32_e32 v76, v76, v135
	v_mul_f32_e32 v77, v77, v135
	v_pk_fma_f32 v[76:77], v[140:141], v[76:77], v[196:197]
	v_mul_f32_e32 v78, v78, v135
	v_mul_f32_e32 v79, v79, v135
	v_pk_fma_f32 v[78:79], v[142:143], v[78:79], v[198:199]
	v_cvt_pk_bf16_f32 v184, v76, v77
	v_cvt_pk_bf16_f32 v185, v78, v79
	v_mul_f32_e32 v72, v72, v135
	v_mul_f32_e32 v73, v73, v135
	v_pk_fma_f32 v[72:73], v[164:165], v[72:73], v[208:209]
	v_mul_f32_e32 v74, v74, v135
	v_mul_f32_e32 v75, v75, v135
	v_pk_fma_f32 v[74:75], v[166:167], v[74:75], v[210:211]
	v_cvt_pk_bf16_f32 v186, v72, v73
	v_cvt_pk_bf16_f32 v187, v74, v75
	v_mul_f32_e32 v68, v68, v135
	v_mul_f32_e32 v69, v69, v135
	v_pk_fma_f32 v[68:69], v[168:169], v[68:69], v[212:213]
	v_mul_f32_e32 v70, v70, v135
	v_mul_f32_e32 v71, v71, v135
	v_pk_fma_f32 v[70:71], v[170:171], v[70:71], v[214:215]
	v_cvt_pk_bf16_f32 v188, v68, v69
	v_cvt_pk_bf16_f32 v189, v70, v71
	v_mul_f32_e32 v64, v64, v135
	v_mul_f32_e32 v65, v65, v135
	v_pk_fma_f32 v[64:65], v[172:173], v[64:65], v[216:217]
	v_mul_f32_e32 v66, v66, v135
	v_mul_f32_e32 v67, v67, v135
	v_pk_fma_f32 v[66:67], v[174:175], v[66:67], v[218:219]
	v_cvt_pk_bf16_f32 v190, v64, v65
	v_cvt_pk_bf16_f32 v191, v66, v67
	v_add_u32_e32 v233, 0x18000, v240
	v_cndmask_b32_e64 v192, v186, v184, s[84:85]
	v_cndmask_b32_e64 v193, v187, v185, s[84:85]
	ds_bpermute_b32 v194, v234, v192
	ds_bpermute_b32 v195, v234, v193
	s_waitcnt lgkmcnt(0)
	v_cndmask_b32_e64 v176, v184, v194, s[84:85]
	v_cndmask_b32_e64 v177, v185, v195, s[84:85]
	v_cndmask_b32_e64 v178, v194, v186, s[84:85]
	v_cndmask_b32_e64 v179, v195, v187, s[84:85]
	global_store_dwordx4 v233, v[176:179], s[90:91] sc1
	v_cndmask_b32_e64 v192, v190, v188, s[84:85]
	v_cndmask_b32_e64 v193, v191, v189, s[84:85]
	ds_bpermute_b32 v194, v234, v192
	ds_bpermute_b32 v195, v234, v193
	s_waitcnt lgkmcnt(0)
	v_cndmask_b32_e64 v180, v188, v194, s[84:85]
	v_cndmask_b32_e64 v181, v189, v195, s[84:85]
	v_cndmask_b32_e64 v182, v194, v190, s[84:85]
	v_cndmask_b32_e64 v183, v195, v191, s[84:85]
	global_store_dwordx4 v233, v[180:183], s[90:91] offset:256 sc1
	v_mul_f32_e32 v60, v60, v136
	v_mul_f32_e32 v61, v61, v136
	v_pk_fma_f32 v[60:61], v[140:141], v[60:61], v[196:197]
	v_mul_f32_e32 v62, v62, v136
	v_mul_f32_e32 v63, v63, v136
	v_pk_fma_f32 v[62:63], v[142:143], v[62:63], v[198:199]
	v_cvt_pk_bf16_f32 v184, v60, v61
	v_cvt_pk_bf16_f32 v185, v62, v63
	v_mul_f32_e32 v56, v56, v136
	v_mul_f32_e32 v57, v57, v136
	v_pk_fma_f32 v[56:57], v[164:165], v[56:57], v[208:209]
	v_mul_f32_e32 v58, v58, v136
	v_mul_f32_e32 v59, v59, v136
	v_pk_fma_f32 v[58:59], v[166:167], v[58:59], v[210:211]
	v_cvt_pk_bf16_f32 v186, v56, v57
	v_cvt_pk_bf16_f32 v187, v58, v59
	v_mul_f32_e32 v52, v52, v136
	v_mul_f32_e32 v53, v53, v136
	v_pk_fma_f32 v[52:53], v[168:169], v[52:53], v[212:213]
	v_mul_f32_e32 v54, v54, v136
	v_mul_f32_e32 v55, v55, v136
	v_pk_fma_f32 v[54:55], v[170:171], v[54:55], v[214:215]
	v_cvt_pk_bf16_f32 v188, v52, v53
	v_cvt_pk_bf16_f32 v189, v54, v55
	v_mul_f32_e32 v48, v48, v136
	v_mul_f32_e32 v49, v49, v136
	v_pk_fma_f32 v[48:49], v[172:173], v[48:49], v[216:217]
	v_mul_f32_e32 v50, v50, v136
	v_mul_f32_e32 v51, v51, v136
	v_pk_fma_f32 v[50:51], v[174:175], v[50:51], v[218:219]
	v_cvt_pk_bf16_f32 v190, v48, v49
	v_cvt_pk_bf16_f32 v191, v50, v51
	v_add_u32_e32 v233, 0x40000, v240
	v_cndmask_b32_e64 v192, v186, v184, s[84:85]
	v_cndmask_b32_e64 v193, v187, v185, s[84:85]
	ds_bpermute_b32 v194, v234, v192
	ds_bpermute_b32 v195, v234, v193
	s_waitcnt lgkmcnt(0)
; __device__ __forceinline__ unsigned cvtpk_s(float lo, float hi) { f32x2_t v = {lo, hi}; bf16x2_t b = __builtin_convertvector(v, bf16x2_t); return __builtin_bit_cast(unsigned, b); }
; __device__ __forceinline__ u32x4 quad_swap(unsigned lo0, unsigned lo1, unsigned hi0, unsigned hi1, int fq, int& coloff) {
;     const bool odd = fq & 1;
;     const unsigned s0 = odd ? lo0 : hi0, s1 = odd ? lo1 : hi1;
;     const unsigned r0 = (unsigned)__shfl_xor((int)s0, 16), r1 = (unsigned)__shfl_xor((int)s1, 16);
;     coloff = odd ? 16 + 4 * (fq - 1) : 4 * fq;
;     u32x4 o; o.x = odd ? r0 : lo0; o.y = odd ? r1 : lo1; o.z = odd ? hi0 : r0; o.w = odd ? hi1 : r1; return o;
; __device__ __forceinline__ void modpass(const float* xs_main, const float* xs_ctx, const float* mod_l, const float* g, int i, bf16_t* H, int nrows, int gw, int NGW, int lane) {
;     ...
;         for (int j = 0; j < 2; ++j) {
;             const f32x4 o0 = v[j][0] * rstd * gm[j][0] + sh[j][0], o1 = v[j][1] * rstd * gm[j][1] + sh[j][1];
;             u32x4 w; w.x = cvtpk_s(o0[0], o0[1]); w.y = cvtpk_s(o0[2], o0[3]); w.z = cvtpk_s(o1[0], o1[1]); w.w = cvtpk_s(o1[2], o1[3]);
;             *(u32x4*)(H + (size_t)row * D + 8 * lane + 512 * j) = w;
	v_cndmask_b32_e64 v176, v184, v194, s[84:85]
	v_cndmask_b32_e64 v177, v185, v195, s[84:85]
	v_cndmask_b32_e64 v178, v194, v186, s[84:85]
	v_cndmask_b32_e64 v179, v195, v187, s[84:85]
	global_store_dwordx4 v233, v[176:179], s[90:91] sc1
	v_cndmask_b32_e64 v192, v190, v188, s[84:85]
	v_cndmask_b32_e64 v193, v191, v189, s[84:85]
	ds_bpermute_b32 v194, v234, v192
	ds_bpermute_b32 v195, v234, v193
	s_waitcnt lgkmcnt(0)
	v_cndmask_b32_e64 v180, v188, v194, s[84:85]
	v_cndmask_b32_e64 v181, v189, v195, s[84:85]
	v_cndmask_b32_e64 v182, v194, v190, s[84:85]
	v_cndmask_b32_e64 v183, v195, v191, s[84:85]
	global_store_dwordx4 v233, v[180:183], s[90:91] offset:256 sc1
	v_mul_f32_e32 v44, v44, v137
	v_mul_f32_e32 v45, v45, v137
	v_pk_fma_f32 v[44:45], v[140:141], v[44:45], v[196:197]
	v_mul_f32_e32 v46, v46, v137
	v_mul_f32_e32 v47, v47, v137
	v_pk_fma_f32 v[46:47], v[142:143], v[46:47], v[198:199]
	v_cvt_pk_bf16_f32 v184, v44, v45
	v_cvt_pk_bf16_f32 v185, v46, v47
	v_mul_f32_e32 v40, v40, v137
	v_mul_f32_e32 v41, v41, v137
	v_pk_fma_f32 v[40:41], v[164:165], v[40:41], v[208:209]
	v_mul_f32_e32 v42, v42, v137
	v_mul_f32_e32 v43, v43, v137
	v_pk_fma_f32 v[42:43], v[166:167], v[42:43], v[210:211]
	v_cvt_pk_bf16_f32 v186, v40, v41
	v_cvt_pk_bf16_f32 v187, v42, v43
	v_mul_f32_e32 v36, v36, v137
	v_mul_f32_e32 v37, v37, v137
	v_pk_fma_f32 v[36:37], v[168:169], v[36:37], v[212:213]
	v_mul_f32_e32 v38, v38, v137
	v_mul_f32_e32 v39, v39, v137
	v_pk_fma_f32 v[38:39], v[170:171], v[38:39], v[214:215]
	v_cvt_pk_bf16_f32 v188, v36, v37
	v_cvt_pk_bf16_f32 v189, v38, v39
	v_mul_f32_e32 v32, v32, v137
	v_mul_f32_e32 v33, v33, v137
	v_pk_fma_f32 v[32:33], v[172:173], v[32:33], v[216:217]
	v_mul_f32_e32 v34, v34, v137
	v_mul_f32_e32 v35, v35, v137
	v_pk_fma_f32 v[34:35], v[174:175], v[34:35], v[218:219]
	v_cvt_pk_bf16_f32 v190, v32, v33
	v_cvt_pk_bf16_f32 v191, v34, v35
	v_add_u32_e32 v233, 0x48000, v240
	v_cndmask_b32_e64 v192, v186, v184, s[84:85]
	v_cndmask_b32_e64 v193, v187, v185, s[84:85]
	ds_bpermute_b32 v194, v234, v192
	ds_bpermute_b32 v195, v234, v193
	s_waitcnt lgkmcnt(0)
	v_cndmask_b32_e64 v176, v184, v194, s[84:85]
	v_cndmask_b32_e64 v177, v185, v195, s[84:85]
	v_cndmask_b32_e64 v178, v194, v186, s[84:85]
	v_cndmask_b32_e64 v179, v195, v187, s[84:85]
	global_store_dwordx4 v233, v[176:179], s[90:91] sc1
	v_cndmask_b32_e64 v192, v190, v188, s[84:85]
	v_cndmask_b32_e64 v193, v191, v189, s[84:85]
	ds_bpermute_b32 v194, v234, v192
	ds_bpermute_b32 v195, v234, v193
	s_waitcnt lgkmcnt(0)
	v_cndmask_b32_e64 v180, v188, v194, s[84:85]
	v_cndmask_b32_e64 v181, v189, v195, s[84:85]
	v_cndmask_b32_e64 v182, v194, v190, s[84:85]
	v_cndmask_b32_e64 v183, v195, v191, s[84:85]
	global_store_dwordx4 v233, v[180:183], s[90:91] offset:256 sc1
	v_mul_f32_e32 v28, v28, v138
	v_mul_f32_e32 v29, v29, v138
	v_pk_fma_f32 v[28:29], v[140:141], v[28:29], v[196:197]
	v_mul_f32_e32 v30, v30, v138
	v_mul_f32_e32 v31, v31, v138
	v_pk_fma_f32 v[30:31], v[142:143], v[30:31], v[198:199]
	v_cvt_pk_bf16_f32 v184, v28, v29
	v_cvt_pk_bf16_f32 v185, v30, v31
	v_mul_f32_e32 v24, v24, v138
	v_mul_f32_e32 v25, v25, v138
	v_pk_fma_f32 v[24:25], v[164:165], v[24:25], v[208:209]
	v_mul_f32_e32 v26, v26, v138
	v_mul_f32_e32 v27, v27, v138
	v_pk_fma_f32 v[26:27], v[166:167], v[26:27], v[210:211]
	v_cvt_pk_bf16_f32 v186, v24, v25
	v_cvt_pk_bf16_f32 v187, v26, v27
	v_mul_f32_e32 v20, v20, v138
	v_mul_f32_e32 v21, v21, v138
	v_pk_fma_f32 v[20:21], v[168:169], v[20:21], v[212:213]
	v_mul_f32_e32 v22, v22, v138
	v_mul_f32_e32 v23, v23, v138
	v_pk_fma_f32 v[22:23], v[170:171], v[22:23], v[214:215]
	v_cvt_pk_bf16_f32 v188, v20, v21
	v_cvt_pk_bf16_f32 v189, v22, v23
	v_mul_f32_e32 v16, v16, v138
	v_mul_f32_e32 v17, v17, v138
	v_pk_fma_f32 v[16:17], v[172:173], v[16:17], v[216:217]
	v_mul_f32_e32 v18, v18, v138
	v_mul_f32_e32 v19, v19, v138
	v_pk_fma_f32 v[18:19], v[174:175], v[18:19], v[218:219]
	v_cvt_pk_bf16_f32 v190, v16, v17
	v_cvt_pk_bf16_f32 v191, v18, v19
	v_add_u32_e32 v233, 0x50000, v240
	v_cndmask_b32_e64 v192, v186, v184, s[84:85]
	v_cndmask_b32_e64 v193, v187, v185, s[84:85]
	ds_bpermute_b32 v194, v234, v192
	ds_bpermute_b32 v195, v234, v193
	s_waitcnt lgkmcnt(0)
	v_cndmask_b32_e64 v176, v184, v194, s[84:85]
	v_cndmask_b32_e64 v177, v185, v195, s[84:85]
	v_cndmask_b32_e64 v178, v194, v186, s[84:85]
	v_cndmask_b32_e64 v179, v195, v187, s[84:85]
	global_store_dwordx4 v233, v[176:179], s[90:91] sc1
	v_cndmask_b32_e64 v192, v190, v188, s[84:85]
	v_cndmask_b32_e64 v193, v191, v189, s[84:85]
	ds_bpermute_b32 v194, v234, v192
	ds_bpermute_b32 v195, v234, v193
	s_waitcnt lgkmcnt(0)
	v_cndmask_b32_e64 v180, v188, v194, s[84:85]
	v_cndmask_b32_e64 v181, v189, v195, s[84:85]
	v_cndmask_b32_e64 v182, v194, v190, s[84:85]
	v_cndmask_b32_e64 v183, v195, v191, s[84:85]
	global_store_dwordx4 v233, v[180:183], s[90:91] offset:256 sc1
	v_mul_f32_e32 v12, v12, v139
	v_mul_f32_e32 v13, v13, v139
	v_pk_fma_f32 v[12:13], v[140:141], v[12:13], v[196:197]
	v_mul_f32_e32 v14, v14, v139
	v_mul_f32_e32 v15, v15, v139
	v_pk_fma_f32 v[14:15], v[142:143], v[14:15], v[198:199]
	v_cvt_pk_bf16_f32 v184, v12, v13
	v_cvt_pk_bf16_f32 v185, v14, v15
	v_mul_f32_e32 v8, v8, v139
	v_mul_f32_e32 v9, v9, v139
	v_pk_fma_f32 v[8:9], v[164:165], v[8:9], v[208:209]
	v_mul_f32_e32 v10, v10, v139
	v_mul_f32_e32 v11, v11, v139
	v_pk_fma_f32 v[10:11], v[166:167], v[10:11], v[210:211]
	v_cvt_pk_bf16_f32 v186, v8, v9
	v_cvt_pk_bf16_f32 v187, v10, v11
	v_mul_f32_e32 v4, v4, v139
	v_mul_f32_e32 v5, v5, v139
	v_pk_fma_f32 v[4:5], v[168:169], v[4:5], v[212:213]
	v_mul_f32_e32 v6, v6, v139
	v_mul_f32_e32 v7, v7, v139
	v_pk_fma_f32 v[6:7], v[170:171], v[6:7], v[214:215]
	v_cvt_pk_bf16_f32 v188, v4, v5
	v_cvt_pk_bf16_f32 v189, v6, v7
	v_mul_f32_e32 v0, v0, v139
	v_mul_f32_e32 v1, v1, v139
	v_pk_fma_f32 v[0:1], v[172:173], v[0:1], v[216:217]
	v_mul_f32_e32 v2, v2, v139
	v_mul_f32_e32 v3, v3, v139
	v_pk_fma_f32 v[2:3], v[174:175], v[2:3], v[218:219]
	v_cvt_pk_bf16_f32 v190, v0, v1
	v_cvt_pk_bf16_f32 v191, v2, v3
	v_add_u32_e32 v233, 0x58000, v240
	v_cndmask_b32_e64 v192, v186, v184, s[84:85]
	v_cndmask_b32_e64 v193, v187, v185, s[84:85]
	ds_bpermute_b32 v194, v234, v192
	ds_bpermute_b32 v195, v234, v193
	s_waitcnt lgkmcnt(0)
	v_cndmask_b32_e64 v176, v184, v194, s[84:85]
	v_cndmask_b32_e64 v177, v185, v195, s[84:85]
	v_cndmask_b32_e64 v178, v194, v186, s[84:85]
	v_cndmask_b32_e64 v179, v195, v187, s[84:85]
	global_store_dwordx4 v233, v[176:179], s[90:91] sc1
	v_cndmask_b32_e64 v192, v190, v188, s[84:85]
	v_cndmask_b32_e64 v193, v191, v189, s[84:85]
	ds_bpermute_b32 v194, v234, v192
	ds_bpermute_b32 v195, v234, v193
	s_waitcnt lgkmcnt(0)
	v_cndmask_b32_e64 v180, v188, v194, s[84:85]
	v_cndmask_b32_e64 v181, v189, v195, s[84:85]
	v_cndmask_b32_e64 v182, v194, v190, s[84:85]
	v_cndmask_b32_e64 v183, v195, v191, s[84:85]
	global_store_dwordx4 v233, v[180:183], s[90:91] offset:256 sc1
	s_andn2_b64 vcc, exec, s[6:7]
	s_mov_b64 s[6:7], -1
; #define PG8_BAR __builtin_amdgcn_s_barrier()
;     ...
;         if (!has_next) break;
; #pragma unroll
;         for (int a = 0; a < 2; ++a)
; #pragma unroll
;             for (int b = 0; b < 2; ++b)
; #pragma unroll
;                 for (int m = 0; m < 4; ++m)
; #pragma unroll
;                     for (int n = 0; n < 2; ++n) acc[a][b][m][n] = (f32x4){0.f, 0.f, 0.f, 0.f};
;         cur = nxt; cA = nA; cB = nB; ++ui;
;         if constexpr (ALIGN_EPI) { if (wr == 1) PG8_BAR; }
;     }
.Lfmdone_f:
	s_cbranch_vccnz .LBB0_2326
	s_andn2_b64 vcc, exec, s[10:11]
	s_cbranch_vccnz .LBB0_2325
	s_barrier
	s_branch .LBB0_2325
